# write-through (sc1) stores for the non-fused GEMM epilogues and mixer-phase outputs so the grid-barrier release fence has less dirty L2 to flush
# baseline (speedup 1.0000x reference)
; __device__ __forceinline__ f32x2 gelu_pk(f32x2 v) {
;     const f32x2 av = __builtin_elementwise_abs(v), d = av * 0.2316418882f + 1.0f;
;     f32x2 t; t.x = __builtin_amdgcn_rcpf(d.x); t.y = __builtin_amdgcn_rcpf(d.y);
;     f32x2 q = t * 0.5307027145f + (-0.7265760135f); q = q * t + 0.7107068705f; q = q * t + (-0.142248368f); q = q * t + 0.127414796f; q = q * t;
;     const f32x2 s = (v * v) * (-0.72134752044f);
;     f32x2 e; e.x = __builtin_amdgcn_exp2f(s.x); e.y = __builtin_amdgcn_exp2f(s.y);
;     const f32x2 m = v * (q * e), r = v - m;
;     f32x2 o; o.x = v.x < 0.f ? m.x : r.x; o.y = v.y < 0.f ? m.y : r.y; return o;
;     DI void operator()(const f32x4 (&acc)[2][2][4][2], const Unit& u, int wr, int wc, int fr, int fq) const {
;     ...
;         const int pn = u.pn; const bool isv = pn >= 8;
;         bf16* base = isv ? VB : U; const int colt = (isv ? pn - 8 : pn) * 256 + 32 * wc + 8 * fq;
; #pragma unroll
;         for (int ai = 0; ai < 2; ++ai)
; #pragma unroll
;             for (int m = 0; m < 4; ++m) {
;                 const int r = u.pm * BM + ai * HALF + wr * 64 + m * 16 + fr; float s = 0.f, q = 0.f; const float rs = RS[r];
; #pragma unroll
;                 for (int bj = 0; bj < 2; ++bj) { const f32x4 a0 = acc[ai][bj][m][0] * rs, a1 = acc[ai][bj][m][1] * rs;
;                     const f32x2 g0 = gelu_pk((f32x2){a0[0], a0[1]}), g1 = gelu_pk((f32x2){a0[2], a0[3]}), g2 = gelu_pk((f32x2){a1[0], a1[1]}), g3 = gelu_pk((f32x2){a1[2], a1[3]});
.LBB0_224:
	s_add_i32 s23, s33, -8
	s_cmp_gt_i32 s33, 7
	s_cselect_b64 s[28:29], -1, 0
	s_and_b64 s[0:1], s[28:29], exec
	s_mov_b32 s0, 0x1fe00000
	s_cselect_b32 s0, s0, 0x1de00000
	s_cselect_b32 s25, s23, s33
	s_add_u32 s4, s6, s0
	v_mov_b32_e32 v138, v148
	v_mov_b32_e32 v142, v149
	s_addc_u32 s5, s7, 0
	s_lshl_b32 s0, s45, 8
	s_add_i32 s0, s0, s40
	v_add_u32_e32 v138, s0, v138
	v_ashrrev_i32_e32 v139, 31, v138
	v_lshl_add_u64 v[140:141], v[138:139], 2, s[14:15]
	global_load_dword v146, v[140:141], off
	v_mov_b64_e32 v[144:145], s[80:81]
	s_mov_b32 s48, 0xbe11a98e
	s_mov_b32 s50, 0x3e027906
	s_mov_b32 s52, 0xbf38aa3b
	s_lshl_b32 s25, s25, 8
	s_or_b32 s25, s25, s41
	v_lshl_add_u32 v140, v142, 3, s25
	v_ashrrev_i32_e32 v141, 31, v140
	v_cmp_eq_u32_e64 s[0:1], 0, v142
	v_lshl_add_u64 v[140:141], v[140:141], 1, s[4:5]
	v_lshlrev_b64 v[142:143], 12, v[138:139]
	v_lshl_add_u64 v[142:143], v[140:141], 0, v[142:143]
	s_lshl_b32 s23, s23, 2
	s_or_b32 s72, s23, s39
	s_cmp_lt_i32 s33, 8
	s_waitcnt vmcnt(0)
	v_pk_mul_f32 v[126:127], v[126:127], v[146:147] op_sel_hi:[1,0]
	s_nop 0
	v_and_b32_e32 v171, 0x7fffffff, v127
	v_and_b32_e32 v170, 0x7fffffff, v126
	v_pk_fma_f32 v[170:171], v[170:171], s[76:77], 1.0 op_sel_hi:[1,0,0]
	v_pk_mul_f32 v[124:125], v[124:125], v[146:147] op_sel_hi:[1,0]
	v_rcp_f32_e32 v170, v170
	v_rcp_f32_e32 v171, v171
	v_pk_mul_f32 v[164:165], v[120:121], v[146:147] op_sel_hi:[1,0]
	v_pk_mul_f32 v[116:117], v[116:117], v[146:147] op_sel_hi:[1,0]
	v_and_b32_e32 v121, 0x7fffffff, v125
	v_and_b32_e32 v120, 0x7fffffff, v124
	v_and_b32_e32 v181, 0x7fffffff, v117
	v_and_b32_e32 v180, 0x7fffffff, v116
	v_pk_fma_f32 v[120:121], v[120:121], s[76:77], 1.0 op_sel_hi:[1,0,0]
	v_pk_fma_f32 v[180:181], v[180:181], s[76:77], 1.0 op_sel_hi:[1,0,0]
	v_rcp_f32_e32 v120, v120
	v_rcp_f32_e32 v121, v121
	v_pk_fma_f32 v[184:185], v[170:171], s[78:79], v[144:145] op_sel_hi:[1,0,0]
	v_rcp_f32_e32 v180, v180
	v_rcp_f32_e32 v181, v181
	v_pk_fma_f32 v[184:185], v[170:171], v[184:185], s[96:97] op_sel_hi:[1,1,0]
	v_pk_fma_f32 v[182:183], v[120:121], s[78:79], v[144:145] op_sel_hi:[1,0,0]
	v_pk_fma_f32 v[184:185], v[170:171], v[184:185], s[48:49] op_sel_hi:[1,1,0]
	v_and_b32_e32 v173, 0x7fffffff, v165
	v_pk_fma_f32 v[184:185], v[170:171], v[184:185], s[50:51] op_sel_hi:[1,1,0]
	v_and_b32_e32 v172, 0x7fffffff, v164
	v_pk_fma_f32 v[182:183], v[120:121], v[182:183], s[96:97] op_sel_hi:[1,1,0]
	v_pk_mul_f32 v[170:171], v[170:171], v[184:185]
	v_pk_mul_f32 v[184:185], v[112:113], v[146:147] op_sel_hi:[1,0]
	v_pk_fma_f32 v[112:113], v[180:181], s[78:79], v[144:145] op_sel_hi:[1,0,0]
	v_pk_fma_f32 v[172:173], v[172:173], s[76:77], 1.0 op_sel_hi:[1,0,0]
	v_pk_fma_f32 v[182:183], v[120:121], v[182:183], s[48:49] op_sel_hi:[1,1,0]
	v_pk_fma_f32 v[112:113], v[180:181], v[112:113], s[96:97] op_sel_hi:[1,1,0]
	v_rcp_f32_e32 v172, v172
	v_rcp_f32_e32 v173, v173
	v_pk_fma_f32 v[182:183], v[120:121], v[182:183], s[50:51] op_sel_hi:[1,1,0]
	v_pk_fma_f32 v[112:113], v[180:181], v[112:113], s[48:49] op_sel_hi:[1,1,0]
	v_pk_mul_f32 v[122:123], v[122:123], v[146:147] op_sel_hi:[1,0]
	v_pk_mul_f32 v[120:121], v[120:121], v[182:183]
	v_pk_mul_f32 v[118:119], v[118:119], v[146:147] op_sel_hi:[1,0]
	v_pk_mul_f32 v[182:183], v[114:115], v[146:147] op_sel_hi:[1,0]
	v_pk_fma_f32 v[112:113], v[180:181], v[112:113], s[50:51] op_sel_hi:[1,1,0]
	v_pk_mul_f32 v[146:147], v[116:117], v[116:117]
	v_pk_mul_f32 v[112:113], v[180:181], v[112:113]
	v_pk_mul_f32 v[146:147], v[146:147], s[52:53] op_sel_hi:[1,0]
	v_and_b32_e32 v181, 0x7fffffff, v119
	v_and_b32_e32 v180, 0x7fffffff, v118
	v_exp_f32_e32 v146, v146
	v_exp_f32_e32 v147, v147
	v_pk_fma_f32 v[180:181], v[180:181], s[76:77], 1.0 op_sel_hi:[1,0,0]
	v_and_b32_e32 v179, 0x7fffffff, v123
	v_and_b32_e32 v178, 0x7fffffff, v122
	v_pk_fma_f32 v[186:187], v[172:173], s[78:79], v[144:145] op_sel_hi:[1,0,0]
	v_rcp_f32_e32 v180, v180
	v_rcp_f32_e32 v181, v181
	v_pk_fma_f32 v[178:179], v[178:179], s[76:77], 1.0 op_sel_hi:[1,0,0]
	v_pk_fma_f32 v[186:187], v[172:173], v[186:187], s[96:97] op_sel_hi:[1,1,0]
	v_pk_mul_f32 v[168:169], v[124:125], v[124:125]
	v_rcp_f32_e32 v178, v178
	v_rcp_f32_e32 v179, v179
	v_pk_fma_f32 v[186:187], v[172:173], v[186:187], s[48:49] op_sel_hi:[1,1,0]
	v_pk_mul_f32 v[176:177], v[164:165], v[164:165]
	v_pk_mul_f32 v[168:169], v[168:169], s[52:53] op_sel_hi:[1,0]
	v_pk_fma_f32 v[186:187], v[172:173], v[186:187], s[50:51] op_sel_hi:[1,1,0]
	v_pk_mul_f32 v[114:115], v[118:119], v[118:119]
	v_pk_mul_f32 v[112:113], v[146:147], v[112:113]
	v_pk_mul_f32 v[176:177], v[176:177], s[52:53] op_sel_hi:[1,0]
	v_exp_f32_e32 v168, v168
	v_exp_f32_e32 v169, v169
	v_pk_mul_f32 v[172:173], v[172:173], v[186:187]
	v_pk_mul_f32 v[146:147], v[116:117], v[112:113]
	v_pk_fma_f32 v[186:187], v[116:117], v[112:113], v[116:117] neg_lo:[1,0,0] neg_hi:[1,0,0]
	v_pk_fma_f32 v[112:113], v[180:181], s[78:79], v[144:145] op_sel_hi:[1,0,0]
	v_pk_mul_f32 v[114:115], v[114:115], s[52:53] op_sel_hi:[1,0]
	v_pk_mul_f32 v[166:167], v[126:127], v[126:127]
	v_exp_f32_e32 v176, v176
	v_exp_f32_e32 v177, v177
	v_pk_fma_f32 v[112:113], v[180:181], v[112:113], s[96:97] op_sel_hi:[1,1,0]
	v_exp_f32_e32 v114, v114
	v_exp_f32_e32 v115, v115
	v_pk_mul_f32 v[174:175], v[122:123], v[122:123]
	v_pk_mul_f32 v[166:167], v[166:167], s[52:53] op_sel_hi:[1,0]
	v_pk_fma_f32 v[188:189], v[178:179], s[78:79], v[144:145] op_sel_hi:[1,0,0]
	v_pk_fma_f32 v[112:113], v[180:181], v[112:113], s[48:49] op_sel_hi:[1,1,0]
	v_pk_mul_f32 v[174:175], v[174:175], s[52:53] op_sel_hi:[1,0]
	v_exp_f32_e32 v166, v166
	v_exp_f32_e32 v167, v167
	v_pk_fma_f32 v[188:189], v[178:179], v[188:189], s[96:97] op_sel_hi:[1,1,0]
; DI unsigned pk2(float a, float b) { f32x2 v = {a, b}; hbf16x2 r = __builtin_convertvector(v, hbf16x2); return __builtin_bit_cast(unsigned, r); }
; __device__ __forceinline__ f32x2 gelu_pk(f32x2 v) {
;     const f32x2 av = __builtin_elementwise_abs(v), d = av * 0.2316418882f + 1.0f;
;     f32x2 t; t.x = __builtin_amdgcn_rcpf(d.x); t.y = __builtin_amdgcn_rcpf(d.y);
;     f32x2 q = t * 0.5307027145f + (-0.7265760135f); q = q * t + 0.7107068705f; q = q * t + (-0.142248368f); q = q * t + 0.127414796f; q = q * t;
;     const f32x2 s = (v * v) * (-0.72134752044f);
;     f32x2 e; e.x = __builtin_amdgcn_exp2f(s.x); e.y = __builtin_amdgcn_exp2f(s.y);
;     const f32x2 m = v * (q * e), r = v - m;
;     f32x2 o; o.x = v.x < 0.f ? m.x : r.x; o.y = v.y < 0.f ? m.y : r.y; return o;
;     DI void operator()(const f32x4 (&acc)[2][2][4][2], const Unit& u, int wr, int wc, int fr, int fq) const {
;     ...
;                 for (int bj = 0; bj < 2; ++bj) { const f32x4 a0 = acc[ai][bj][m][0] * rs, a1 = acc[ai][bj][m][1] * rs;
;                     const f32x2 g0 = gelu_pk((f32x2){a0[0], a0[1]}), g1 = gelu_pk((f32x2){a0[2], a0[3]}), g2 = gelu_pk((f32x2){a1[0], a1[1]}), g3 = gelu_pk((f32x2){a1[2], a1[3]});
;                     s += ((g0.x + g0.y) + (g1.x + g1.y)) + ((g2.x + g2.y) + (g3.x + g3.y));
;                     q += ((g0.x * g0.x + g0.y * g0.y) + (g1.x * g1.x + g1.y * g1.y)) + ((g2.x * g2.x + g2.y * g2.y) + (g3.x * g3.x + g3.y * g3.y));
;                     u32x4 w; w.x = pk2(g0.x, g0.y); w.y = pk2(g1.x, g1.y); w.z = pk2(g2.x, g2.y); w.w = pk2(g3.x, g3.y);
;                     *(u32x4*)(base + (size_t)r * 2048 + colt + bj * HALF) = w; }
	v_pk_fma_f32 v[112:113], v[180:181], v[112:113], s[50:51] op_sel_hi:[1,1,0]
	v_exp_f32_e32 v174, v174
	v_exp_f32_e32 v175, v175
	v_pk_fma_f32 v[188:189], v[178:179], v[188:189], s[48:49] op_sel_hi:[1,1,0]
	v_pk_mul_f32 v[120:121], v[168:169], v[120:121]
	v_pk_mul_f32 v[112:113], v[180:181], v[112:113]
	v_pk_fma_f32 v[188:189], v[178:179], v[188:189], s[50:51] op_sel_hi:[1,1,0]
	v_pk_mul_f32 v[168:169], v[176:177], v[172:173]
	v_pk_mul_f32 v[172:173], v[124:125], v[120:121]
	v_pk_fma_f32 v[120:121], v[124:125], v[120:121], v[124:125] neg_lo:[1,0,0] neg_hi:[1,0,0]
	v_pk_mul_f32 v[112:113], v[114:115], v[112:113]
	v_cmp_gt_f32_e32 vcc, 0, v124
	v_pk_mul_f32 v[178:179], v[178:179], v[188:189]
	v_pk_mul_f32 v[180:181], v[118:119], v[112:113]
	v_pk_fma_f32 v[188:189], v[118:119], v[112:113], v[118:119] neg_lo:[1,0,0] neg_hi:[1,0,0]
	v_cndmask_b32_e32 v112, v120, v172, vcc
	v_cmp_gt_f32_e32 vcc, 0, v116
	v_pk_mul_f32 v[166:167], v[166:167], v[170:171]
	v_pk_mul_f32 v[170:171], v[174:175], v[178:179]
	v_cndmask_b32_e32 v113, v186, v146, vcc
	v_cmp_gt_f32_e32 vcc, 0, v125
	v_pk_mul_f32 v[174:175], v[126:127], v[166:167]
	v_pk_fma_f32 v[166:167], v[126:127], v[166:167], v[126:127] neg_lo:[1,0,0] neg_hi:[1,0,0]
	v_cndmask_b32_e32 v120, v121, v173, vcc
	v_cmp_gt_f32_e32 vcc, 0, v126
	v_pk_mul_f32 v[176:177], v[164:165], v[168:169]
	v_pk_fma_f32 v[168:169], v[164:165], v[168:169], v[164:165] neg_lo:[1,0,0] neg_hi:[1,0,0]
	v_cndmask_b32_e32 v114, v166, v174, vcc
	v_cmp_gt_f32_e32 vcc, 0, v117
	v_pk_mul_f32 v[178:179], v[122:123], v[170:171]
	v_pk_fma_f32 v[170:171], v[122:123], v[170:171], v[122:123] neg_lo:[1,0,0] neg_hi:[1,0,0]
	v_cndmask_b32_e32 v115, v187, v147, vcc
	v_cmp_gt_f32_e32 vcc, 0, v127
	v_and_b32_e32 v147, 0x7fffffff, v185
	v_and_b32_e32 v146, 0x7fffffff, v184
	v_cndmask_b32_e32 v124, v167, v175, vcc
	v_cmp_gt_f32_e32 vcc, 0, v164
	v_pk_fma_f32 v[146:147], v[146:147], s[76:77], 1.0 op_sel_hi:[1,0,0]
	v_cvt_pk_bf16_f32 v164, v112, v120
	v_cndmask_b32_e32 v116, v168, v176, vcc
	v_cmp_gt_f32_e32 vcc, 0, v118
	v_rcp_f32_e32 v146, v146
	v_rcp_f32_e32 v147, v147
	v_cndmask_b32_e32 v117, v188, v180, vcc
	v_cmp_gt_f32_e32 vcc, 0, v165
	v_cvt_pk_bf16_f32 v165, v114, v124
	v_and_b32_e32 v168, 0x7fffffff, v182
	v_cndmask_b32_e32 v126, v169, v177, vcc
	v_cmp_gt_f32_e32 vcc, 0, v122
	v_cvt_pk_bf16_f32 v166, v116, v126
	v_and_b32_e32 v169, 0x7fffffff, v183
	v_cndmask_b32_e32 v118, v170, v178, vcc
	v_cmp_gt_f32_e32 vcc, 0, v119
	v_pk_fma_f32 v[168:169], v[168:169], s[76:77], 1.0 op_sel_hi:[1,0,0]
	s_nop 0
	v_cndmask_b32_e32 v119, v189, v181, vcc
	v_cmp_gt_f32_e32 vcc, 0, v123
	v_rcp_f32_e32 v168, v168
	v_rcp_f32_e32 v169, v169
	v_cndmask_b32_e32 v122, v171, v179, vcc
	v_cvt_pk_bf16_f32 v167, v118, v122
	global_store_dwordx4 v[142:143], v[164:167], off sc1
	v_cmp_gt_f32_e32 vcc, 0, v182
	s_nop 0
	v_pk_mul_f32 v[166:167], v[184:185], v[184:185]
	v_pk_fma_f32 v[164:165], v[146:147], s[78:79], v[144:145] op_sel_hi:[1,0,0]
	v_pk_mul_f32 v[166:167], v[166:167], s[52:53] op_sel_hi:[1,0]
	v_pk_fma_f32 v[164:165], v[146:147], v[164:165], s[96:97] op_sel_hi:[1,1,0]
	v_exp_f32_e32 v166, v166
	v_exp_f32_e32 v167, v167
	v_pk_fma_f32 v[164:165], v[146:147], v[164:165], s[48:49] op_sel_hi:[1,1,0]
	v_pk_fma_f32 v[144:145], v[168:169], s[78:79], v[144:145] op_sel_hi:[1,0,0]
	v_pk_fma_f32 v[164:165], v[146:147], v[164:165], s[50:51] op_sel_hi:[1,1,0]
	v_pk_fma_f32 v[144:145], v[168:169], v[144:145], s[96:97] op_sel_hi:[1,1,0]
	v_pk_mul_f32 v[146:147], v[146:147], v[164:165]
	v_pk_mul_f32 v[164:165], v[182:183], v[182:183]
	v_pk_mul_f32 v[146:147], v[166:167], v[146:147]
	v_pk_fma_f32 v[144:145], v[168:169], v[144:145], s[48:49] op_sel_hi:[1,1,0]
	v_pk_mul_f32 v[166:167], v[184:185], v[146:147]
	v_pk_fma_f32 v[170:171], v[184:185], v[146:147], v[184:185] neg_lo:[1,0,0] neg_hi:[1,0,0]
	v_pk_mul_f32 v[146:147], v[164:165], s[52:53] op_sel_hi:[1,0]
	v_pk_fma_f32 v[144:145], v[168:169], v[144:145], s[50:51] op_sel_hi:[1,1,0]
	v_exp_f32_e32 v146, v146
	v_exp_f32_e32 v147, v147
	v_pk_mul_f32 v[144:145], v[168:169], v[144:145]
	s_nop 0
	v_pk_mul_f32 v[144:145], v[146:147], v[144:145]
	s_nop 0
	v_pk_mul_f32 v[146:147], v[182:183], v[144:145]
	v_pk_fma_f32 v[164:165], v[182:183], v[144:145], v[182:183] neg_lo:[1,0,0] neg_hi:[1,0,0]
	s_nop 0
	v_cndmask_b32_e32 v145, v164, v146, vcc
	v_cmp_gt_f32_e32 vcc, 0, v184
	v_cvt_pk_bf16_f32 v164, v113, v115
	s_nop 0
	v_cndmask_b32_e32 v144, v170, v166, vcc
	v_cmp_gt_f32_e32 vcc, 0, v183
	s_nop 1
	v_cndmask_b32_e32 v147, v165, v147, vcc
	v_cmp_gt_f32_e32 vcc, 0, v185
	v_cvt_pk_bf16_f32 v165, v117, v119
	s_nop 0
	v_cndmask_b32_e32 v146, v171, v167, vcc
	v_cvt_pk_bf16_f32 v166, v144, v146
	v_cvt_pk_bf16_f32 v167, v145, v147
	global_store_dwordx4 v[142:143], v[164:167], off offset:256 sc1
	s_cbranch_scc1 .LBB0_228
; DI unsigned pk2(float a, float b) { f32x2 v = {a, b}; hbf16x2 r = __builtin_convertvector(v, hbf16x2); return __builtin_bit_cast(unsigned, r); }
;     DI void operator()(const f32x4 (&acc)[2][2][4][2], const Unit& u, int wr, int wc, int fr, int fq) const {
;     ...
;                     s += ((g0.x + g0.y) + (g1.x + g1.y)) + ((g2.x + g2.y) + (g3.x + g3.y));
;                     q += ((g0.x * g0.x + g0.y * g0.y) + (g1.x * g1.x + g1.y * g1.y)) + ((g2.x * g2.x + g2.y * g2.y) + (g3.x * g3.x + g3.y * g3.y));
;                     u32x4 w; w.x = pk2(g0.x, g0.y); w.y = pk2(g1.x, g1.y); w.z = pk2(g2.x, g2.y); w.w = pk2(g3.x, g3.y);
;                     *(u32x4*)(base + (size_t)r * 2048 + colt + bj * HALF) = w; }
;                 if (isv) { s += __shfl_xor(s, 16); s += __shfl_xor(s, 32); q += __shfl_xor(q, 16); q += __shfl_xor(q, 32);
;                     if (fq == 0) *(f32x2*)(STATS + ((size_t)r * 32 + (pn - 8) * 4 + wc) * 2) = (f32x2){s, q}; }
	v_mov_b32_e32 v121, v113
	v_mov_b32_e32 v125, v115
	v_pk_mul_f32 v[164:165], v[120:121], v[120:121]
	v_pk_add_f32 v[178:179], v[112:113], v[120:121]
	v_pk_mul_f32 v[120:121], v[112:113], v[120:121]
	v_mov_b32_e32 v127, v117
	v_pk_mul_f32 v[142:143], v[112:113], v[112:113]
	v_pk_mul_f32 v[168:169], v[124:125], v[124:125]
	v_mov_b32_e32 v179, v121
	v_pk_add_f32 v[120:121], v[114:115], v[124:125]
	v_pk_mul_f32 v[124:125], v[114:115], v[124:125]
	v_mov_b32_e32 v123, v119
	v_pk_mul_f32 v[166:167], v[114:115], v[114:115]
	v_pk_mul_f32 v[172:173], v[126:127], v[126:127]
	v_mov_b32_e32 v121, v125
	v_pk_add_f32 v[124:125], v[116:117], v[126:127]
	v_pk_mul_f32 v[126:127], v[116:117], v[126:127]
	v_pk_mov_b32 v[112:113], v[112:113], v[142:143] op_sel:[1,0]
	v_pk_mov_b32 v[114:115], v[114:115], v[164:165] op_sel:[1,0]
	v_pk_mul_f32 v[170:171], v[116:117], v[116:117]
	v_pk_mul_f32 v[176:177], v[122:123], v[122:123]
	v_mov_b32_e32 v125, v127
	v_pk_add_f32 v[126:127], v[118:119], v[122:123]
	v_pk_mul_f32 v[122:123], v[118:119], v[122:123]
	v_pk_add_f32 v[112:113], v[112:113], v[114:115]
	v_pk_mov_b32 v[114:115], v[116:117], v[166:167] op_sel:[1,0]
	v_pk_mov_b32 v[116:117], v[118:119], v[168:169] op_sel:[1,0]
	v_mov_b32_e32 v127, v123
	v_pk_mul_f32 v[122:123], v[146:147], v[146:147]
	v_pk_add_f32 v[114:115], v[114:115], v[116:117]
	v_pk_mul_f32 v[174:175], v[118:119], v[118:119]
	v_pk_fma_f32 v[122:123], v[144:145], v[144:145], v[122:123]
	v_pk_add_f32 v[112:113], v[112:113], v[114:115]
	v_mov_b32_e32 v114, v144
	v_mov_b32_e32 v115, v170
	v_mov_b32_e32 v116, v146
	v_mov_b32_e32 v117, v172
	v_pk_add_f32 v[122:123], v[122:123], v[122:123] op_sel_hi:[0,1]
	v_cmp_lt_i32_e32 vcc, v248, v243
	v_pk_add_f32 v[114:115], v[114:115], v[116:117]
	v_pk_mov_b32 v[116:117], v[144:145], v[174:175] op_sel:[1,0]
	v_pk_mov_b32 v[118:119], v[146:147], v[176:177] op_sel:[1,0]
	v_cndmask_b32_e32 v122, v241, v248, vcc
	v_pk_add_f32 v[120:121], v[178:179], v[120:121]
	v_pk_add_f32 v[124:125], v[124:125], v[126:127]
	v_pk_add_f32 v[116:117], v[116:117], v[118:119]
	v_lshlrev_b32_e32 v171, 2, v122
	v_pk_add_f32 v[120:121], v[120:121], v[124:125]
	v_mov_b32_e32 v122, v153
	v_pk_add_f32 v[114:115], v[114:115], v[116:117]
	v_pk_add_f32 v[120:121], v[120:121], v[122:123]
	v_pk_add_f32 v[112:113], v[112:113], v[114:115]
	v_cmp_lt_i32_e32 vcc, v249, v243
	v_pk_add_f32 v[112:113], v[112:113], v[120:121]
	ds_bpermute_b32 v114, v171, v112
	ds_bpermute_b32 v115, v171, v113
	v_cndmask_b32_e32 v116, v241, v249, vcc
	v_lshlrev_b32_e32 v116, 2, v116
	s_waitcnt lgkmcnt(0)
	v_pk_add_f32 v[112:113], v[112:113], v[114:115]
	ds_bpermute_b32 v114, v116, v112
	ds_bpermute_b32 v115, v116, v113
	s_and_saveexec_b64 s[4:5], s[0:1]
	s_cbranch_execz .LBB0_227
	v_lshlrev_b64 v[116:117], 8, v[138:139]
	s_waitcnt lgkmcnt(0)
	v_pk_add_f32 v[112:113], v[112:113], v[114:115]
	v_lshl_add_u64 v[114:115], s[18:19], 0, v[116:117]
	v_lshl_add_u64 v[114:115], s[72:73], 3, v[114:115]
	global_store_dwordx2 v[114:115], v[112:113], off

; __device__ __forceinline__ f32x2 gelu_pk(f32x2 v) {
;     const f32x2 av = __builtin_elementwise_abs(v), d = av * 0.2316418882f + 1.0f;
;     f32x2 t; t.x = __builtin_amdgcn_rcpf(d.x); t.y = __builtin_amdgcn_rcpf(d.y);
;     f32x2 q = t * 0.5307027145f + (-0.7265760135f); q = q * t + 0.7107068705f; q = q * t + (-0.142248368f); q = q * t + 0.127414796f; q = q * t;
;     const f32x2 s = (v * v) * (-0.72134752044f);
;     f32x2 e; e.x = __builtin_amdgcn_exp2f(s.x); e.y = __builtin_amdgcn_exp2f(s.y);
;     const f32x2 m = v * (q * e), r = v - m;
;     f32x2 o; o.x = v.x < 0.f ? m.x : r.x; o.y = v.y < 0.f ? m.y : r.y; return o;
;     DI void operator()(const f32x4 (&acc)[2][2][4][2], const Unit& u, int wr, int wc, int fr, int fq) const {
;     ...
;                 const int r = u.pm * BM + ai * HALF + wr * 64 + m * 16 + fr; float s = 0.f, q = 0.f; const float rs = RS[r];
; #pragma unroll
;                 for (int bj = 0; bj < 2; ++bj) { const f32x4 a0 = acc[ai][bj][m][0] * rs, a1 = acc[ai][bj][m][1] * rs;
;                     const f32x2 g0 = gelu_pk((f32x2){a0[0], a0[1]}), g1 = gelu_pk((f32x2){a0[2], a0[3]}), g2 = gelu_pk((f32x2){a1[0], a1[1]}), g3 = gelu_pk((f32x2){a1[2], a1[3]});
.LBB0_228:
	v_add_u32_e32 v112, 16, v138
	v_ashrrev_i32_e32 v113, 31, v112
	s_waitcnt lgkmcnt(0)
	v_lshl_add_u64 v[114:115], v[112:113], 2, s[14:15]
	global_load_dword v118, v[114:115], off
	v_mov_b64_e32 v[116:117], s[80:81]
	v_lshlrev_b64 v[114:115], 12, v[112:113]
	v_lshl_add_u64 v[114:115], v[140:141], 0, v[114:115]
	s_waitcnt vmcnt(0)
	v_pk_mul_f32 v[108:109], v[108:109], v[118:119] op_sel_hi:[1,0]
	v_pk_mul_f32 v[110:111], v[110:111], v[118:119] op_sel_hi:[1,0]
	v_pk_mul_f32 v[106:107], v[106:107], v[118:119] op_sel_hi:[1,0]
	v_pk_mul_f32 v[120:121], v[104:105], v[118:119] op_sel_hi:[1,0]
	v_pk_mul_f32 v[124:125], v[96:97], v[118:119] op_sel_hi:[1,0]
	v_and_b32_e32 v97, 0x7fffffff, v109
	v_and_b32_e32 v96, 0x7fffffff, v108
	v_pk_mul_f32 v[102:103], v[102:103], v[118:119] op_sel_hi:[1,0]
	v_pk_mul_f32 v[100:101], v[100:101], v[118:119] op_sel_hi:[1,0]
	v_pk_mul_f32 v[122:123], v[98:99], v[118:119] op_sel_hi:[1,0]
	v_and_b32_e32 v119, 0x7fffffff, v111
	v_and_b32_e32 v118, 0x7fffffff, v110
	v_and_b32_e32 v127, 0x7fffffff, v121
	v_and_b32_e32 v126, 0x7fffffff, v120
	v_and_b32_e32 v147, 0x7fffffff, v107
	v_and_b32_e32 v146, 0x7fffffff, v106
	v_pk_fma_f32 v[96:97], v[96:97], s[76:77], 1.0 op_sel_hi:[1,0,0]
	v_pk_fma_f32 v[118:119], v[118:119], s[76:77], 1.0 op_sel_hi:[1,0,0]
	v_pk_fma_f32 v[126:127], v[126:127], s[76:77], 1.0 op_sel_hi:[1,0,0]
	v_pk_fma_f32 v[146:147], v[146:147], s[76:77], 1.0 op_sel_hi:[1,0,0]
	v_rcp_f32_e32 v96, v96
	v_rcp_f32_e32 v97, v97
	v_rcp_f32_e32 v118, v118
	v_rcp_f32_e32 v119, v119
	v_rcp_f32_e32 v126, v126
	v_rcp_f32_e32 v127, v127
	v_rcp_f32_e32 v146, v146
	v_rcp_f32_e32 v147, v147
	v_pk_mul_f32 v[104:105], v[108:109], v[108:109]
	v_pk_mul_f32 v[98:99], v[110:111], v[110:111]
	v_pk_mul_f32 v[142:143], v[106:107], v[106:107]
	v_pk_mul_f32 v[144:145], v[120:121], v[120:121]
	v_pk_mul_f32 v[104:105], v[104:105], s[52:53] op_sel_hi:[1,0]
	v_pk_fma_f32 v[170:171], v[96:97], s[78:79], v[116:117] op_sel_hi:[1,0,0]
	v_pk_mul_f32 v[98:99], v[98:99], s[52:53] op_sel_hi:[1,0]
	v_pk_mul_f32 v[144:145], v[144:145], s[52:53] op_sel_hi:[1,0]
	v_pk_mul_f32 v[142:143], v[142:143], s[52:53] op_sel_hi:[1,0]
	v_exp_f32_e32 v104, v104
	v_exp_f32_e32 v105, v105
	v_pk_fma_f32 v[172:173], v[118:119], s[78:79], v[116:117] op_sel_hi:[1,0,0]
	v_pk_fma_f32 v[174:175], v[126:127], s[78:79], v[116:117] op_sel_hi:[1,0,0]
	v_pk_fma_f32 v[176:177], v[146:147], s[78:79], v[116:117] op_sel_hi:[1,0,0]
	v_pk_fma_f32 v[170:171], v[96:97], v[170:171], s[96:97] op_sel_hi:[1,1,0]
	v_exp_f32_e32 v98, v98
	v_exp_f32_e32 v99, v99
	v_exp_f32_e32 v144, v144
	v_exp_f32_e32 v145, v145
	v_exp_f32_e32 v142, v142
	v_exp_f32_e32 v143, v143
	v_pk_fma_f32 v[172:173], v[118:119], v[172:173], s[96:97] op_sel_hi:[1,1,0]
	v_pk_fma_f32 v[174:175], v[126:127], v[174:175], s[96:97] op_sel_hi:[1,1,0]
	v_pk_fma_f32 v[176:177], v[146:147], v[176:177], s[96:97] op_sel_hi:[1,1,0]
	v_pk_fma_f32 v[170:171], v[96:97], v[170:171], s[48:49] op_sel_hi:[1,1,0]
	v_pk_fma_f32 v[172:173], v[118:119], v[172:173], s[48:49] op_sel_hi:[1,1,0]
	v_pk_fma_f32 v[174:175], v[126:127], v[174:175], s[48:49] op_sel_hi:[1,1,0]
	v_pk_fma_f32 v[176:177], v[146:147], v[176:177], s[48:49] op_sel_hi:[1,1,0]
	v_pk_fma_f32 v[170:171], v[96:97], v[170:171], s[50:51] op_sel_hi:[1,1,0]
	v_pk_fma_f32 v[172:173], v[118:119], v[172:173], s[50:51] op_sel_hi:[1,1,0]
	v_pk_fma_f32 v[174:175], v[126:127], v[174:175], s[50:51] op_sel_hi:[1,1,0]
	v_pk_fma_f32 v[176:177], v[146:147], v[176:177], s[50:51] op_sel_hi:[1,1,0]
	v_pk_mul_f32 v[96:97], v[96:97], v[170:171]
	v_pk_mul_f32 v[118:119], v[118:119], v[172:173]
	v_pk_mul_f32 v[126:127], v[126:127], v[174:175]
	v_pk_mul_f32 v[146:147], v[146:147], v[176:177]
	v_pk_mul_f32 v[96:97], v[104:105], v[96:97]
	v_and_b32_e32 v165, 0x7fffffff, v101
	v_and_b32_e32 v164, 0x7fffffff, v100
	v_pk_mul_f32 v[98:99], v[98:99], v[118:119]
	v_pk_mul_f32 v[104:105], v[144:145], v[126:127]
	v_pk_mul_f32 v[118:119], v[142:143], v[146:147]
	v_pk_mul_f32 v[126:127], v[108:109], v[96:97]
	v_pk_fma_f32 v[142:143], v[108:109], v[96:97], v[108:109] neg_lo:[1,0,0] neg_hi:[1,0,0]
	v_and_b32_e32 v97, 0x7fffffff, v103
	v_and_b32_e32 v96, 0x7fffffff, v102
	v_pk_fma_f32 v[164:165], v[164:165], s[76:77], 1.0 op_sel_hi:[1,0,0]
	v_pk_fma_f32 v[96:97], v[96:97], s[76:77], 1.0 op_sel_hi:[1,0,0]
	v_rcp_f32_e32 v164, v164
	v_rcp_f32_e32 v165, v165
	v_rcp_f32_e32 v96, v96
	v_rcp_f32_e32 v97, v97
	v_pk_mul_f32 v[166:167], v[102:103], v[102:103]
	v_pk_mul_f32 v[168:169], v[100:101], v[100:101]
	v_pk_fma_f32 v[178:179], v[164:165], s[78:79], v[116:117] op_sel_hi:[1,0,0]
	v_pk_mul_f32 v[168:169], v[168:169], s[52:53] op_sel_hi:[1,0]
	v_pk_mul_f32 v[170:171], v[120:121], v[104:105]
	v_pk_fma_f32 v[172:173], v[120:121], v[104:105], v[120:121] neg_lo:[1,0,0] neg_hi:[1,0,0]
	v_pk_fma_f32 v[104:105], v[96:97], s[78:79], v[116:117] op_sel_hi:[1,0,0]
	v_pk_mul_f32 v[166:167], v[166:167], s[52:53] op_sel_hi:[1,0]
	v_exp_f32_e32 v168, v168
	v_pk_fma_f32 v[178:179], v[164:165], v[178:179], s[96:97] op_sel_hi:[1,1,0]
	v_exp_f32_e32 v169, v169
	v_pk_fma_f32 v[104:105], v[96:97], v[104:105], s[96:97] op_sel_hi:[1,1,0]
	v_exp_f32_e32 v166, v166
	v_exp_f32_e32 v167, v167
	v_pk_fma_f32 v[178:179], v[164:165], v[178:179], s[48:49] op_sel_hi:[1,1,0]
	v_pk_fma_f32 v[104:105], v[96:97], v[104:105], s[48:49] op_sel_hi:[1,1,0]
	v_pk_fma_f32 v[178:179], v[164:165], v[178:179], s[50:51] op_sel_hi:[1,1,0]
	v_pk_fma_f32 v[104:105], v[96:97], v[104:105], s[50:51] op_sel_hi:[1,1,0]
	v_pk_mul_f32 v[164:165], v[164:165], v[178:179]
	v_pk_mul_f32 v[96:97], v[96:97], v[104:105]
	v_pk_mul_f32 v[144:145], v[110:111], v[98:99]
; DI unsigned pk2(float a, float b) { f32x2 v = {a, b}; hbf16x2 r = __builtin_convertvector(v, hbf16x2); return __builtin_bit_cast(unsigned, r); }
; __device__ __forceinline__ f32x2 gelu_pk(f32x2 v) {
;     const f32x2 av = __builtin_elementwise_abs(v), d = av * 0.2316418882f + 1.0f;
;     f32x2 t; t.x = __builtin_amdgcn_rcpf(d.x); t.y = __builtin_amdgcn_rcpf(d.y);
;     f32x2 q = t * 0.5307027145f + (-0.7265760135f); q = q * t + 0.7107068705f; q = q * t + (-0.142248368f); q = q * t + 0.127414796f; q = q * t;
;     const f32x2 s = (v * v) * (-0.72134752044f);
;     f32x2 e; e.x = __builtin_amdgcn_exp2f(s.x); e.y = __builtin_amdgcn_exp2f(s.y);
;     const f32x2 m = v * (q * e), r = v - m;
;     f32x2 o; o.x = v.x < 0.f ? m.x : r.x; o.y = v.y < 0.f ? m.y : r.y; return o;
;     DI void operator()(const f32x4 (&acc)[2][2][4][2], const Unit& u, int wr, int wc, int fr, int fq) const {
;     ...
;                 for (int bj = 0; bj < 2; ++bj) { const f32x4 a0 = acc[ai][bj][m][0] * rs, a1 = acc[ai][bj][m][1] * rs;
;                     const f32x2 g0 = gelu_pk((f32x2){a0[0], a0[1]}), g1 = gelu_pk((f32x2){a0[2], a0[3]}), g2 = gelu_pk((f32x2){a1[0], a1[1]}), g3 = gelu_pk((f32x2){a1[2], a1[3]});
;                     s += ((g0.x + g0.y) + (g1.x + g1.y)) + ((g2.x + g2.y) + (g3.x + g3.y));
;                     q += ((g0.x * g0.x + g0.y * g0.y) + (g1.x * g1.x + g1.y * g1.y)) + ((g2.x * g2.x + g2.y * g2.y) + (g3.x * g3.x + g3.y * g3.y));
;                     u32x4 w; w.x = pk2(g0.x, g0.y); w.y = pk2(g1.x, g1.y); w.z = pk2(g2.x, g2.y); w.w = pk2(g3.x, g3.y);
;                     *(u32x4*)(base + (size_t)r * 2048 + colt + bj * HALF) = w; }
	v_pk_fma_f32 v[146:147], v[110:111], v[98:99], v[110:111] neg_lo:[1,0,0] neg_hi:[1,0,0]
	v_pk_mul_f32 v[98:99], v[168:169], v[164:165]
	v_pk_mul_f32 v[96:97], v[166:167], v[96:97]
	v_cmp_gt_f32_e32 vcc, 0, v108
	v_pk_mul_f32 v[164:165], v[100:101], v[98:99]
	v_pk_fma_f32 v[98:99], v[100:101], v[98:99], v[100:101] neg_lo:[1,0,0] neg_hi:[1,0,0]
	v_pk_mul_f32 v[166:167], v[102:103], v[96:97]
	v_pk_fma_f32 v[168:169], v[102:103], v[96:97], v[102:103] neg_lo:[1,0,0] neg_hi:[1,0,0]
	v_cndmask_b32_e32 v96, v142, v126, vcc
	v_cmp_gt_f32_e32 vcc, 0, v100
	v_pk_mul_f32 v[174:175], v[106:107], v[118:119]
	v_pk_fma_f32 v[118:119], v[106:107], v[118:119], v[106:107] neg_lo:[1,0,0] neg_hi:[1,0,0]
	v_cndmask_b32_e32 v97, v98, v164, vcc
	v_cmp_gt_f32_e32 vcc, 0, v109
	v_and_b32_e32 v142, 0x7fffffff, v122
	s_nop 0
	v_cndmask_b32_e32 v104, v143, v127, vcc
	v_cmp_gt_f32_e32 vcc, 0, v110
	v_and_b32_e32 v143, 0x7fffffff, v123
	v_pk_fma_f32 v[142:143], v[142:143], s[76:77], 1.0 op_sel_hi:[1,0,0]
	v_cndmask_b32_e32 v98, v146, v144, vcc
	v_cmp_gt_f32_e32 vcc, 0, v101
	v_rcp_f32_e32 v142, v142
	v_rcp_f32_e32 v143, v143
	v_cndmask_b32_e32 v99, v99, v165, vcc
	v_cmp_gt_f32_e32 vcc, 0, v111
	s_nop 1
	v_cndmask_b32_e32 v108, v147, v145, vcc
	v_cmp_gt_f32_e32 vcc, 0, v120
	v_and_b32_e32 v120, 0x7fffffff, v124
	s_nop 0
	v_cndmask_b32_e32 v100, v172, v170, vcc
	v_cmp_gt_f32_e32 vcc, 0, v102
	s_nop 1
	v_cndmask_b32_e32 v101, v168, v166, vcc
	v_cmp_gt_f32_e32 vcc, 0, v121
	v_and_b32_e32 v121, 0x7fffffff, v125
	v_pk_fma_f32 v[120:121], v[120:121], s[76:77], 1.0 op_sel_hi:[1,0,0]
	v_cndmask_b32_e32 v110, v173, v171, vcc
	v_cmp_gt_f32_e32 vcc, 0, v106
	v_rcp_f32_e32 v126, v120
	v_rcp_f32_e32 v127, v121
	v_cndmask_b32_e32 v102, v118, v174, vcc
	v_cmp_gt_f32_e32 vcc, 0, v103
	v_cvt_pk_bf16_f32 v118, v96, v104
	v_cvt_pk_bf16_f32 v120, v100, v110
	v_cndmask_b32_e32 v103, v169, v167, vcc
	v_cmp_gt_f32_e32 vcc, 0, v107
	s_nop 1
	v_cndmask_b32_e32 v106, v119, v175, vcc
	v_cvt_pk_bf16_f32 v119, v98, v108
	v_cvt_pk_bf16_f32 v121, v102, v106
	global_store_dwordx4 v[114:115], v[118:121], off sc1
	v_cmp_gt_f32_e32 vcc, 0, v122
	s_nop 0
	v_pk_fma_f32 v[118:119], v[126:127], s[78:79], v[116:117] op_sel_hi:[1,0,0]
	v_pk_mul_f32 v[120:121], v[122:123], v[122:123]
	v_pk_fma_f32 v[118:119], v[126:127], v[118:119], s[96:97] op_sel_hi:[1,1,0]
	v_pk_fma_f32 v[116:117], v[142:143], s[78:79], v[116:117] op_sel_hi:[1,0,0]
	v_pk_fma_f32 v[118:119], v[126:127], v[118:119], s[48:49] op_sel_hi:[1,1,0]
	v_pk_fma_f32 v[116:117], v[142:143], v[116:117], s[96:97] op_sel_hi:[1,1,0]
	v_pk_fma_f32 v[118:119], v[126:127], v[118:119], s[50:51] op_sel_hi:[1,1,0]
	v_pk_fma_f32 v[116:117], v[142:143], v[116:117], s[48:49] op_sel_hi:[1,1,0]
	v_pk_mul_f32 v[118:119], v[126:127], v[118:119]
	v_pk_mul_f32 v[126:127], v[124:125], v[124:125]
	v_pk_fma_f32 v[116:117], v[142:143], v[116:117], s[50:51] op_sel_hi:[1,1,0]
	v_pk_mul_f32 v[126:127], v[126:127], s[52:53] op_sel_hi:[1,0]
	v_pk_mul_f32 v[116:117], v[142:143], v[116:117]
	v_exp_f32_e32 v126, v126
	v_exp_f32_e32 v127, v127
	s_nop 0
	v_pk_mul_f32 v[118:119], v[126:127], v[118:119]
	s_nop 0
	v_pk_mul_f32 v[126:127], v[124:125], v[118:119]
	v_pk_fma_f32 v[144:145], v[124:125], v[118:119], v[124:125] neg_lo:[1,0,0] neg_hi:[1,0,0]
	v_pk_mul_f32 v[118:119], v[120:121], s[52:53] op_sel_hi:[1,0]
	s_nop 0
	v_exp_f32_e32 v118, v118
	v_exp_f32_e32 v119, v119
	s_nop 0
	v_pk_mul_f32 v[116:117], v[118:119], v[116:117]
	s_nop 0
	v_pk_mul_f32 v[118:119], v[122:123], v[116:117]
	v_pk_fma_f32 v[120:121], v[122:123], v[116:117], v[122:123] neg_lo:[1,0,0] neg_hi:[1,0,0]
	s_nop 0
	v_cndmask_b32_e32 v117, v120, v118, vcc
	v_cmp_gt_f32_e32 vcc, 0, v124
	v_cndmask_b32_e64 v124, 0, 1, s[28:29]
	v_cvt_pk_bf16_f32 v120, v97, v99
	v_cndmask_b32_e32 v116, v144, v126, vcc
	v_cmp_gt_f32_e32 vcc, 0, v123
	v_cmp_ne_u32_e64 s[4:5], 1, v124
	s_nop 0
	v_cndmask_b32_e32 v119, v121, v119, vcc
	v_cmp_gt_f32_e32 vcc, 0, v125
	v_cvt_pk_bf16_f32 v121, v101, v103
	v_cvt_pk_bf16_f32 v123, v117, v119
	v_cndmask_b32_e32 v118, v145, v127, vcc
	v_cvt_pk_bf16_f32 v122, v116, v118
	s_andn2_b64 vcc, exec, s[28:29]
	global_store_dwordx4 v[114:115], v[120:123], off offset:256 sc1
	s_cbranch_vccnz .LBB0_232
; DI unsigned pk2(float a, float b) { f32x2 v = {a, b}; hbf16x2 r = __builtin_convertvector(v, hbf16x2); return __builtin_bit_cast(unsigned, r); }
;     DI void operator()(const f32x4 (&acc)[2][2][4][2], const Unit& u, int wr, int wc, int fr, int fq) const {
;     ...
;                     s += ((g0.x + g0.y) + (g1.x + g1.y)) + ((g2.x + g2.y) + (g3.x + g3.y));
;                     q += ((g0.x * g0.x + g0.y * g0.y) + (g1.x * g1.x + g1.y * g1.y)) + ((g2.x * g2.x + g2.y * g2.y) + (g3.x * g3.x + g3.y * g3.y));
;                     u32x4 w; w.x = pk2(g0.x, g0.y); w.y = pk2(g1.x, g1.y); w.z = pk2(g2.x, g2.y); w.w = pk2(g3.x, g3.y);
;                     *(u32x4*)(base + (size_t)r * 2048 + colt + bj * HALF) = w; }
;                 if (isv) { s += __shfl_xor(s, 16); s += __shfl_xor(s, 32); q += __shfl_xor(q, 16); q += __shfl_xor(q, 32);
;                     if (fq == 0) *(f32x2*)(STATS + ((size_t)r * 32 + (pn - 8) * 4 + wc) * 2) = (f32x2){s, q}; }
	v_mov_b32_e32 v105, v97
	v_mov_b32_e32 v109, v99
	v_pk_mul_f32 v[120:121], v[104:105], v[104:105]
	v_pk_add_f32 v[164:165], v[96:97], v[104:105]
	v_pk_mul_f32 v[104:105], v[96:97], v[104:105]
	v_mov_b32_e32 v111, v101
	v_pk_mul_f32 v[114:115], v[96:97], v[96:97]
	v_pk_mul_f32 v[124:125], v[108:109], v[108:109]
	v_mov_b32_e32 v165, v105
	v_pk_add_f32 v[104:105], v[98:99], v[108:109]
	v_pk_mul_f32 v[108:109], v[98:99], v[108:109]
	v_mov_b32_e32 v107, v103
	v_pk_mul_f32 v[122:123], v[98:99], v[98:99]
	v_pk_mul_f32 v[142:143], v[110:111], v[110:111]
	v_mov_b32_e32 v105, v109
	v_pk_add_f32 v[108:109], v[100:101], v[110:111]
	v_pk_mul_f32 v[110:111], v[100:101], v[110:111]
	v_pk_mov_b32 v[96:97], v[96:97], v[114:115] op_sel:[1,0]
	v_pk_mov_b32 v[98:99], v[98:99], v[120:121] op_sel:[1,0]
	v_pk_mul_f32 v[126:127], v[100:101], v[100:101]
	v_pk_mul_f32 v[146:147], v[106:107], v[106:107]
	v_mov_b32_e32 v109, v111
	v_pk_add_f32 v[110:111], v[102:103], v[106:107]
	v_pk_mul_f32 v[106:107], v[102:103], v[106:107]
	v_pk_add_f32 v[96:97], v[96:97], v[98:99]
	v_pk_mov_b32 v[98:99], v[100:101], v[122:123] op_sel:[1,0]
	v_pk_mov_b32 v[100:101], v[102:103], v[124:125] op_sel:[1,0]
	v_mov_b32_e32 v111, v107
	v_pk_mul_f32 v[106:107], v[118:119], v[118:119]
	v_pk_add_f32 v[98:99], v[98:99], v[100:101]
	v_pk_mul_f32 v[144:145], v[102:103], v[102:103]
	v_pk_fma_f32 v[106:107], v[116:117], v[116:117], v[106:107]
	v_pk_add_f32 v[96:97], v[96:97], v[98:99]
	v_mov_b32_e32 v98, v116
	v_mov_b32_e32 v99, v126
	v_mov_b32_e32 v100, v118
	v_mov_b32_e32 v101, v142
	v_pk_add_f32 v[106:107], v[106:107], v[106:107] op_sel_hi:[0,1]
	v_cmp_lt_i32_e32 vcc, v248, v243
	v_pk_add_f32 v[98:99], v[98:99], v[100:101]
	v_pk_mov_b32 v[100:101], v[116:117], v[144:145] op_sel:[1,0]
	v_pk_mov_b32 v[102:103], v[118:119], v[146:147] op_sel:[1,0]
	v_cndmask_b32_e32 v106, v241, v248, vcc
	v_pk_add_f32 v[104:105], v[164:165], v[104:105]
	v_pk_add_f32 v[108:109], v[108:109], v[110:111]
	v_pk_add_f32 v[100:101], v[100:101], v[102:103]
	v_lshlrev_b32_e32 v127, 2, v106
	v_pk_add_f32 v[104:105], v[104:105], v[108:109]
	v_mov_b32_e32 v106, v153
	v_pk_add_f32 v[98:99], v[98:99], v[100:101]
	v_pk_add_f32 v[104:105], v[104:105], v[106:107]
	v_pk_add_f32 v[96:97], v[96:97], v[98:99]
	v_cmp_lt_i32_e32 vcc, v249, v243
	v_pk_add_f32 v[96:97], v[96:97], v[104:105]
	ds_bpermute_b32 v98, v127, v96
	ds_bpermute_b32 v99, v127, v97
	v_cndmask_b32_e32 v100, v241, v249, vcc
	v_lshlrev_b32_e32 v100, 2, v100
	s_waitcnt lgkmcnt(0)
	v_pk_add_f32 v[96:97], v[96:97], v[98:99]
	ds_bpermute_b32 v98, v100, v96
	ds_bpermute_b32 v99, v100, v97
	s_and_saveexec_b64 s[28:29], s[0:1]
	s_cbranch_execz .LBB0_231
	v_lshlrev_b64 v[100:101], 8, v[112:113]
	s_waitcnt lgkmcnt(0)
	v_pk_add_f32 v[96:97], v[96:97], v[98:99]
	v_lshl_add_u64 v[98:99], s[18:19], 0, v[100:101]
	v_lshl_add_u64 v[98:99], s[72:73], 3, v[98:99]
	global_store_dwordx2 v[98:99], v[96:97], off

; __device__ __forceinline__ f32x2 gelu_pk(f32x2 v) {
;     const f32x2 av = __builtin_elementwise_abs(v), d = av * 0.2316418882f + 1.0f;
;     f32x2 t; t.x = __builtin_amdgcn_rcpf(d.x); t.y = __builtin_amdgcn_rcpf(d.y);
;     f32x2 q = t * 0.5307027145f + (-0.7265760135f); q = q * t + 0.7107068705f; q = q * t + (-0.142248368f); q = q * t + 0.127414796f; q = q * t;
;     const f32x2 s = (v * v) * (-0.72134752044f);
;     f32x2 e; e.x = __builtin_amdgcn_exp2f(s.x); e.y = __builtin_amdgcn_exp2f(s.y);
;     const f32x2 m = v * (q * e), r = v - m;
;     f32x2 o; o.x = v.x < 0.f ? m.x : r.x; o.y = v.y < 0.f ? m.y : r.y; return o;
;     DI void operator()(const f32x4 (&acc)[2][2][4][2], const Unit& u, int wr, int wc, int fr, int fq) const {
;     ...
;                 const int r = u.pm * BM + ai * HALF + wr * 64 + m * 16 + fr; float s = 0.f, q = 0.f; const float rs = RS[r];
; #pragma unroll
;                 for (int bj = 0; bj < 2; ++bj) { const f32x4 a0 = acc[ai][bj][m][0] * rs, a1 = acc[ai][bj][m][1] * rs;
;                     const f32x2 g0 = gelu_pk((f32x2){a0[0], a0[1]}), g1 = gelu_pk((f32x2){a0[2], a0[3]}), g2 = gelu_pk((f32x2){a1[0], a1[1]}), g3 = gelu_pk((f32x2){a1[2], a1[3]});
.LBB0_232:
	v_add_u32_e32 v96, 32, v138
	v_ashrrev_i32_e32 v97, 31, v96
	s_waitcnt lgkmcnt(0)
	v_lshl_add_u64 v[98:99], v[96:97], 2, s[14:15]
	global_load_dword v102, v[98:99], off
	v_mov_b64_e32 v[100:101], s[80:81]
	v_lshlrev_b64 v[98:99], 12, v[96:97]
	v_lshl_add_u64 v[98:99], v[140:141], 0, v[98:99]
	s_waitcnt vmcnt(0)
	v_pk_mul_f32 v[92:93], v[92:93], v[102:103] op_sel_hi:[1,0]
	v_pk_mul_f32 v[94:95], v[94:95], v[102:103] op_sel_hi:[1,0]
	v_pk_mul_f32 v[90:91], v[90:91], v[102:103] op_sel_hi:[1,0]
	v_pk_mul_f32 v[104:105], v[88:89], v[102:103] op_sel_hi:[1,0]
	v_pk_mul_f32 v[108:109], v[80:81], v[102:103] op_sel_hi:[1,0]
	v_and_b32_e32 v81, 0x7fffffff, v93
	v_and_b32_e32 v80, 0x7fffffff, v92
	v_pk_mul_f32 v[86:87], v[86:87], v[102:103] op_sel_hi:[1,0]
	v_pk_mul_f32 v[84:85], v[84:85], v[102:103] op_sel_hi:[1,0]
	v_pk_mul_f32 v[106:107], v[82:83], v[102:103] op_sel_hi:[1,0]
	v_and_b32_e32 v103, 0x7fffffff, v95
	v_and_b32_e32 v102, 0x7fffffff, v94
	v_and_b32_e32 v111, 0x7fffffff, v105
	v_and_b32_e32 v110, 0x7fffffff, v104
	v_and_b32_e32 v117, 0x7fffffff, v91
	v_and_b32_e32 v116, 0x7fffffff, v90
	v_pk_fma_f32 v[80:81], v[80:81], s[76:77], 1.0 op_sel_hi:[1,0,0]
	v_pk_fma_f32 v[102:103], v[102:103], s[76:77], 1.0 op_sel_hi:[1,0,0]
	v_pk_fma_f32 v[110:111], v[110:111], s[76:77], 1.0 op_sel_hi:[1,0,0]
	v_pk_fma_f32 v[116:117], v[116:117], s[76:77], 1.0 op_sel_hi:[1,0,0]
	v_rcp_f32_e32 v80, v80
	v_rcp_f32_e32 v81, v81
	v_rcp_f32_e32 v102, v102
	v_rcp_f32_e32 v103, v103
	v_rcp_f32_e32 v110, v110
	v_rcp_f32_e32 v111, v111
	v_rcp_f32_e32 v116, v116
	v_rcp_f32_e32 v117, v117
	v_pk_mul_f32 v[88:89], v[92:93], v[92:93]
	v_pk_mul_f32 v[82:83], v[94:95], v[94:95]
	v_pk_mul_f32 v[112:113], v[90:91], v[90:91]
	v_pk_mul_f32 v[114:115], v[104:105], v[104:105]
	v_pk_mul_f32 v[88:89], v[88:89], s[52:53] op_sel_hi:[1,0]
	v_pk_fma_f32 v[124:125], v[80:81], s[78:79], v[100:101] op_sel_hi:[1,0,0]
	v_pk_mul_f32 v[82:83], v[82:83], s[52:53] op_sel_hi:[1,0]
	v_pk_mul_f32 v[114:115], v[114:115], s[52:53] op_sel_hi:[1,0]
	v_pk_mul_f32 v[112:113], v[112:113], s[52:53] op_sel_hi:[1,0]
	v_exp_f32_e32 v88, v88
	v_exp_f32_e32 v89, v89
	v_pk_fma_f32 v[126:127], v[102:103], s[78:79], v[100:101] op_sel_hi:[1,0,0]
	v_pk_fma_f32 v[142:143], v[110:111], s[78:79], v[100:101] op_sel_hi:[1,0,0]
	v_pk_fma_f32 v[144:145], v[116:117], s[78:79], v[100:101] op_sel_hi:[1,0,0]
	v_pk_fma_f32 v[124:125], v[80:81], v[124:125], s[96:97] op_sel_hi:[1,1,0]
	v_exp_f32_e32 v82, v82
	v_exp_f32_e32 v83, v83
	v_exp_f32_e32 v114, v114
	v_exp_f32_e32 v115, v115
	v_exp_f32_e32 v112, v112
	v_exp_f32_e32 v113, v113
	v_pk_fma_f32 v[126:127], v[102:103], v[126:127], s[96:97] op_sel_hi:[1,1,0]
	v_pk_fma_f32 v[142:143], v[110:111], v[142:143], s[96:97] op_sel_hi:[1,1,0]
	v_pk_fma_f32 v[144:145], v[116:117], v[144:145], s[96:97] op_sel_hi:[1,1,0]
	v_pk_fma_f32 v[124:125], v[80:81], v[124:125], s[48:49] op_sel_hi:[1,1,0]
	v_pk_fma_f32 v[126:127], v[102:103], v[126:127], s[48:49] op_sel_hi:[1,1,0]
	v_pk_fma_f32 v[142:143], v[110:111], v[142:143], s[48:49] op_sel_hi:[1,1,0]
	v_pk_fma_f32 v[144:145], v[116:117], v[144:145], s[48:49] op_sel_hi:[1,1,0]
	v_pk_fma_f32 v[124:125], v[80:81], v[124:125], s[50:51] op_sel_hi:[1,1,0]
	v_pk_fma_f32 v[126:127], v[102:103], v[126:127], s[50:51] op_sel_hi:[1,1,0]
	v_pk_fma_f32 v[142:143], v[110:111], v[142:143], s[50:51] op_sel_hi:[1,1,0]
	v_pk_fma_f32 v[144:145], v[116:117], v[144:145], s[50:51] op_sel_hi:[1,1,0]
	v_pk_mul_f32 v[80:81], v[80:81], v[124:125]
	v_pk_mul_f32 v[102:103], v[102:103], v[126:127]
	v_pk_mul_f32 v[110:111], v[110:111], v[142:143]
	v_pk_mul_f32 v[116:117], v[116:117], v[144:145]
	v_pk_mul_f32 v[80:81], v[88:89], v[80:81]
	v_and_b32_e32 v119, 0x7fffffff, v85
	v_and_b32_e32 v118, 0x7fffffff, v84
	v_pk_mul_f32 v[82:83], v[82:83], v[102:103]
	v_pk_mul_f32 v[88:89], v[114:115], v[110:111]
	v_pk_mul_f32 v[102:103], v[112:113], v[116:117]
	v_pk_mul_f32 v[110:111], v[92:93], v[80:81]
	v_pk_fma_f32 v[112:113], v[92:93], v[80:81], v[92:93] neg_lo:[1,0,0] neg_hi:[1,0,0]
	v_and_b32_e32 v81, 0x7fffffff, v87
	v_and_b32_e32 v80, 0x7fffffff, v86
	v_pk_fma_f32 v[118:119], v[118:119], s[76:77], 1.0 op_sel_hi:[1,0,0]
	v_pk_fma_f32 v[80:81], v[80:81], s[76:77], 1.0 op_sel_hi:[1,0,0]
	v_rcp_f32_e32 v118, v118
	v_rcp_f32_e32 v119, v119
	v_rcp_f32_e32 v80, v80
	v_rcp_f32_e32 v81, v81
	v_pk_mul_f32 v[120:121], v[86:87], v[86:87]
	v_pk_mul_f32 v[122:123], v[84:85], v[84:85]
	v_pk_fma_f32 v[146:147], v[118:119], s[78:79], v[100:101] op_sel_hi:[1,0,0]
	v_pk_mul_f32 v[122:123], v[122:123], s[52:53] op_sel_hi:[1,0]
	v_pk_mul_f32 v[124:125], v[104:105], v[88:89]
	v_pk_fma_f32 v[126:127], v[104:105], v[88:89], v[104:105] neg_lo:[1,0,0] neg_hi:[1,0,0]
	v_pk_fma_f32 v[88:89], v[80:81], s[78:79], v[100:101] op_sel_hi:[1,0,0]
	v_pk_mul_f32 v[120:121], v[120:121], s[52:53] op_sel_hi:[1,0]
	v_exp_f32_e32 v122, v122
	v_pk_fma_f32 v[146:147], v[118:119], v[146:147], s[96:97] op_sel_hi:[1,1,0]
	v_exp_f32_e32 v123, v123
	v_pk_fma_f32 v[88:89], v[80:81], v[88:89], s[96:97] op_sel_hi:[1,1,0]
	v_exp_f32_e32 v120, v120
	v_exp_f32_e32 v121, v121
	v_pk_fma_f32 v[146:147], v[118:119], v[146:147], s[48:49] op_sel_hi:[1,1,0]
	v_pk_fma_f32 v[88:89], v[80:81], v[88:89], s[48:49] op_sel_hi:[1,1,0]
	v_pk_fma_f32 v[146:147], v[118:119], v[146:147], s[50:51] op_sel_hi:[1,1,0]
	v_pk_fma_f32 v[88:89], v[80:81], v[88:89], s[50:51] op_sel_hi:[1,1,0]
	v_pk_mul_f32 v[118:119], v[118:119], v[146:147]
	v_pk_mul_f32 v[80:81], v[80:81], v[88:89]
	v_pk_mul_f32 v[114:115], v[94:95], v[82:83]
	v_pk_fma_f32 v[116:117], v[94:95], v[82:83], v[94:95] neg_lo:[1,0,0] neg_hi:[1,0,0]
	v_pk_mul_f32 v[82:83], v[122:123], v[118:119]
; DI unsigned pk2(float a, float b) { f32x2 v = {a, b}; hbf16x2 r = __builtin_convertvector(v, hbf16x2); return __builtin_bit_cast(unsigned, r); }
; __device__ __forceinline__ f32x2 gelu_pk(f32x2 v) {
;     const f32x2 av = __builtin_elementwise_abs(v), d = av * 0.2316418882f + 1.0f;
;     f32x2 t; t.x = __builtin_amdgcn_rcpf(d.x); t.y = __builtin_amdgcn_rcpf(d.y);
;     f32x2 q = t * 0.5307027145f + (-0.7265760135f); q = q * t + 0.7107068705f; q = q * t + (-0.142248368f); q = q * t + 0.127414796f; q = q * t;
;     const f32x2 s = (v * v) * (-0.72134752044f);
;     f32x2 e; e.x = __builtin_amdgcn_exp2f(s.x); e.y = __builtin_amdgcn_exp2f(s.y);
;     const f32x2 m = v * (q * e), r = v - m;
;     f32x2 o; o.x = v.x < 0.f ? m.x : r.x; o.y = v.y < 0.f ? m.y : r.y; return o;
;     DI void operator()(const f32x4 (&acc)[2][2][4][2], const Unit& u, int wr, int wc, int fr, int fq) const {
;     ...
;                 for (int bj = 0; bj < 2; ++bj) { const f32x4 a0 = acc[ai][bj][m][0] * rs, a1 = acc[ai][bj][m][1] * rs;
;                     const f32x2 g0 = gelu_pk((f32x2){a0[0], a0[1]}), g1 = gelu_pk((f32x2){a0[2], a0[3]}), g2 = gelu_pk((f32x2){a1[0], a1[1]}), g3 = gelu_pk((f32x2){a1[2], a1[3]});
;                     s += ((g0.x + g0.y) + (g1.x + g1.y)) + ((g2.x + g2.y) + (g3.x + g3.y));
;                     q += ((g0.x * g0.x + g0.y * g0.y) + (g1.x * g1.x + g1.y * g1.y)) + ((g2.x * g2.x + g2.y * g2.y) + (g3.x * g3.x + g3.y * g3.y));
;                     u32x4 w; w.x = pk2(g0.x, g0.y); w.y = pk2(g1.x, g1.y); w.z = pk2(g2.x, g2.y); w.w = pk2(g3.x, g3.y);
;                     *(u32x4*)(base + (size_t)r * 2048 + colt + bj * HALF) = w; }
;                 if (isv) { s += __shfl_xor(s, 16); s += __shfl_xor(s, 32); q += __shfl_xor(q, 16); q += __shfl_xor(q, 32);
;                     if (fq == 0) *(f32x2*)(STATS + ((size_t)r * 32 + (pn - 8) * 4 + wc) * 2) = (f32x2){s, q}; }
	v_pk_mul_f32 v[80:81], v[120:121], v[80:81]
	v_cmp_gt_f32_e32 vcc, 0, v92
	v_pk_mul_f32 v[118:119], v[84:85], v[82:83]
	v_pk_fma_f32 v[82:83], v[84:85], v[82:83], v[84:85] neg_lo:[1,0,0] neg_hi:[1,0,0]
	v_pk_mul_f32 v[120:121], v[86:87], v[80:81]
	v_pk_fma_f32 v[122:123], v[86:87], v[80:81], v[86:87] neg_lo:[1,0,0] neg_hi:[1,0,0]
	v_cndmask_b32_e32 v80, v112, v110, vcc
	v_cmp_gt_f32_e32 vcc, 0, v84
	v_pk_mul_f32 v[142:143], v[90:91], v[102:103]
	v_pk_fma_f32 v[102:103], v[90:91], v[102:103], v[90:91] neg_lo:[1,0,0] neg_hi:[1,0,0]
	v_cndmask_b32_e32 v81, v82, v118, vcc
	v_cmp_gt_f32_e32 vcc, 0, v93
	v_and_b32_e32 v112, 0x7fffffff, v106
	s_nop 0
	v_cndmask_b32_e32 v88, v113, v111, vcc
	v_cmp_gt_f32_e32 vcc, 0, v94
	v_and_b32_e32 v113, 0x7fffffff, v107
	v_pk_fma_f32 v[112:113], v[112:113], s[76:77], 1.0 op_sel_hi:[1,0,0]
	v_cndmask_b32_e32 v82, v116, v114, vcc
	v_cmp_gt_f32_e32 vcc, 0, v85
	v_rcp_f32_e32 v112, v112
	v_rcp_f32_e32 v113, v113
	v_cndmask_b32_e32 v83, v83, v119, vcc
	v_cmp_gt_f32_e32 vcc, 0, v95
	s_nop 1
	v_cndmask_b32_e32 v92, v117, v115, vcc
	v_cmp_gt_f32_e32 vcc, 0, v104
	v_and_b32_e32 v104, 0x7fffffff, v108
	s_nop 0
	v_cndmask_b32_e32 v84, v126, v124, vcc
	v_cmp_gt_f32_e32 vcc, 0, v86
	s_nop 1
	v_cndmask_b32_e32 v85, v122, v120, vcc
	v_cmp_gt_f32_e32 vcc, 0, v105
	v_and_b32_e32 v105, 0x7fffffff, v109
	v_pk_fma_f32 v[104:105], v[104:105], s[76:77], 1.0 op_sel_hi:[1,0,0]
	v_cndmask_b32_e32 v94, v127, v125, vcc
	v_cmp_gt_f32_e32 vcc, 0, v90
	v_rcp_f32_e32 v110, v104
	v_rcp_f32_e32 v111, v105
	v_cndmask_b32_e32 v86, v102, v142, vcc
	v_cmp_gt_f32_e32 vcc, 0, v87
	v_cvt_pk_bf16_f32 v102, v80, v88
	v_cvt_pk_bf16_f32 v104, v84, v94
	v_cndmask_b32_e32 v87, v123, v121, vcc
	v_cmp_gt_f32_e32 vcc, 0, v91
	s_nop 1
	v_cndmask_b32_e32 v90, v103, v143, vcc
	v_cvt_pk_bf16_f32 v103, v82, v92
	v_cvt_pk_bf16_f32 v105, v86, v90
	global_store_dwordx4 v[98:99], v[102:105], off sc1
	v_cmp_gt_f32_e32 vcc, 0, v106
	s_nop 0
	v_pk_fma_f32 v[102:103], v[110:111], s[78:79], v[100:101] op_sel_hi:[1,0,0]
	v_pk_mul_f32 v[104:105], v[106:107], v[106:107]
	v_pk_fma_f32 v[102:103], v[110:111], v[102:103], s[96:97] op_sel_hi:[1,1,0]
	v_pk_fma_f32 v[100:101], v[112:113], s[78:79], v[100:101] op_sel_hi:[1,0,0]
	v_pk_fma_f32 v[102:103], v[110:111], v[102:103], s[48:49] op_sel_hi:[1,1,0]
	v_pk_fma_f32 v[100:101], v[112:113], v[100:101], s[96:97] op_sel_hi:[1,1,0]
	v_pk_fma_f32 v[102:103], v[110:111], v[102:103], s[50:51] op_sel_hi:[1,1,0]
	v_pk_fma_f32 v[100:101], v[112:113], v[100:101], s[48:49] op_sel_hi:[1,1,0]
	v_pk_mul_f32 v[102:103], v[110:111], v[102:103]
	v_pk_mul_f32 v[110:111], v[108:109], v[108:109]
	v_pk_fma_f32 v[100:101], v[112:113], v[100:101], s[50:51] op_sel_hi:[1,1,0]
	v_pk_mul_f32 v[110:111], v[110:111], s[52:53] op_sel_hi:[1,0]
	v_pk_mul_f32 v[100:101], v[112:113], v[100:101]
	v_exp_f32_e32 v110, v110
	v_exp_f32_e32 v111, v111
	s_nop 0
	v_pk_mul_f32 v[102:103], v[110:111], v[102:103]
	s_nop 0
	v_pk_mul_f32 v[110:111], v[108:109], v[102:103]
	v_pk_fma_f32 v[114:115], v[108:109], v[102:103], v[108:109] neg_lo:[1,0,0] neg_hi:[1,0,0]
	v_pk_mul_f32 v[102:103], v[104:105], s[52:53] op_sel_hi:[1,0]
	s_nop 0
	v_exp_f32_e32 v102, v102
	v_exp_f32_e32 v103, v103
	s_nop 0
	v_pk_mul_f32 v[100:101], v[102:103], v[100:101]
	s_nop 0
	v_pk_mul_f32 v[102:103], v[106:107], v[100:101]
	v_pk_fma_f32 v[104:105], v[106:107], v[100:101], v[106:107] neg_lo:[1,0,0] neg_hi:[1,0,0]
	s_nop 0
	v_cndmask_b32_e32 v101, v104, v102, vcc
	v_cmp_gt_f32_e32 vcc, 0, v108
	v_cvt_pk_bf16_f32 v104, v81, v83
	s_nop 0
	v_cndmask_b32_e32 v100, v114, v110, vcc
	v_cmp_gt_f32_e32 vcc, 0, v107
	s_nop 1
	v_cndmask_b32_e32 v103, v105, v103, vcc
	v_cmp_gt_f32_e32 vcc, 0, v109
	v_cvt_pk_bf16_f32 v105, v85, v87
	v_cvt_pk_bf16_f32 v107, v101, v103
	v_cndmask_b32_e32 v102, v115, v111, vcc
	v_cvt_pk_bf16_f32 v106, v100, v102
	s_and_b64 vcc, exec, s[4:5]
	global_store_dwordx4 v[98:99], v[104:107], off offset:256 sc1
	s_cbranch_vccnz .LBB0_236
	v_mov_b32_e32 v89, v81
	v_mov_b32_e32 v93, v83
	v_pk_mul_f32 v[104:105], v[88:89], v[88:89]
	v_pk_add_f32 v[118:119], v[80:81], v[88:89]
	v_pk_mul_f32 v[88:89], v[80:81], v[88:89]
	v_mov_b32_e32 v95, v85
	v_pk_mul_f32 v[98:99], v[80:81], v[80:81]
	v_pk_mul_f32 v[108:109], v[92:93], v[92:93]
	v_mov_b32_e32 v119, v89
	v_pk_add_f32 v[88:89], v[82:83], v[92:93]
	v_pk_mul_f32 v[92:93], v[82:83], v[92:93]
	v_mov_b32_e32 v91, v87
	v_pk_mul_f32 v[106:107], v[82:83], v[82:83]
	v_pk_mul_f32 v[112:113], v[94:95], v[94:95]
	v_mov_b32_e32 v89, v93
	v_pk_add_f32 v[92:93], v[84:85], v[94:95]
	v_pk_mul_f32 v[94:95], v[84:85], v[94:95]
	v_pk_mov_b32 v[80:81], v[80:81], v[98:99] op_sel:[1,0]
	v_pk_mov_b32 v[82:83], v[82:83], v[104:105] op_sel:[1,0]
	v_pk_mul_f32 v[110:111], v[84:85], v[84:85]
	v_pk_mul_f32 v[116:117], v[90:91], v[90:91]
	v_mov_b32_e32 v93, v95
	v_pk_add_f32 v[94:95], v[86:87], v[90:91]
	v_pk_mul_f32 v[90:91], v[86:87], v[90:91]
	v_pk_add_f32 v[80:81], v[80:81], v[82:83]
	v_pk_mov_b32 v[82:83], v[84:85], v[106:107] op_sel:[1,0]
	v_pk_mov_b32 v[84:85], v[86:87], v[108:109] op_sel:[1,0]
	v_mov_b32_e32 v95, v91
	v_pk_mul_f32 v[90:91], v[102:103], v[102:103]
	v_pk_add_f32 v[82:83], v[82:83], v[84:85]
	v_pk_mul_f32 v[114:115], v[86:87], v[86:87]
	v_pk_fma_f32 v[90:91], v[100:101], v[100:101], v[90:91]
	v_pk_add_f32 v[80:81], v[80:81], v[82:83]
	v_mov_b32_e32 v82, v100
	v_mov_b32_e32 v83, v110
	v_mov_b32_e32 v84, v102
	v_mov_b32_e32 v85, v112
	v_pk_add_f32 v[90:91], v[90:91], v[90:91] op_sel_hi:[0,1]
	v_cmp_lt_i32_e32 vcc, v248, v243
	v_pk_add_f32 v[82:83], v[82:83], v[84:85]
	v_pk_mov_b32 v[84:85], v[100:101], v[114:115] op_sel:[1,0]
	v_pk_mov_b32 v[86:87], v[102:103], v[116:117] op_sel:[1,0]
	v_cndmask_b32_e32 v90, v241, v248, vcc
	v_pk_add_f32 v[88:89], v[118:119], v[88:89]
	v_pk_add_f32 v[92:93], v[92:93], v[94:95]
	v_pk_add_f32 v[84:85], v[84:85], v[86:87]
	v_lshlrev_b32_e32 v111, 2, v90
	v_pk_add_f32 v[88:89], v[88:89], v[92:93]
	v_mov_b32_e32 v90, v153
	v_pk_add_f32 v[82:83], v[82:83], v[84:85]
	v_pk_add_f32 v[88:89], v[88:89], v[90:91]
	v_pk_add_f32 v[80:81], v[80:81], v[82:83]
	v_cmp_lt_i32_e32 vcc, v249, v243
	v_pk_add_f32 v[80:81], v[80:81], v[88:89]
	ds_bpermute_b32 v82, v111, v80
	ds_bpermute_b32 v83, v111, v81
	v_cndmask_b32_e32 v84, v241, v249, vcc
	v_lshlrev_b32_e32 v84, 2, v84
	s_waitcnt lgkmcnt(0)
	v_pk_add_f32 v[80:81], v[80:81], v[82:83]
	ds_bpermute_b32 v82, v84, v80
	ds_bpermute_b32 v83, v84, v81
	s_and_saveexec_b64 s[28:29], s[0:1]
	s_cbranch_execz .LBB0_235
	v_lshlrev_b64 v[84:85], 8, v[96:97]
	s_waitcnt lgkmcnt(0)
	v_pk_add_f32 v[80:81], v[80:81], v[82:83]
	v_lshl_add_u64 v[82:83], s[18:19], 0, v[84:85]
	v_lshl_add_u64 v[82:83], s[72:73], 3, v[82:83]
	global_store_dwordx2 v[82:83], v[80:81], off

; __device__ __forceinline__ f32x2 gelu_pk(f32x2 v) {
;     const f32x2 av = __builtin_elementwise_abs(v), d = av * 0.2316418882f + 1.0f;
;     f32x2 t; t.x = __builtin_amdgcn_rcpf(d.x); t.y = __builtin_amdgcn_rcpf(d.y);
;     f32x2 q = t * 0.5307027145f + (-0.7265760135f); q = q * t + 0.7107068705f; q = q * t + (-0.142248368f); q = q * t + 0.127414796f; q = q * t;
;     const f32x2 s = (v * v) * (-0.72134752044f);
;     f32x2 e; e.x = __builtin_amdgcn_exp2f(s.x); e.y = __builtin_amdgcn_exp2f(s.y);
;     const f32x2 m = v * (q * e), r = v - m;
;     f32x2 o; o.x = v.x < 0.f ? m.x : r.x; o.y = v.y < 0.f ? m.y : r.y; return o;
;     DI void operator()(const f32x4 (&acc)[2][2][4][2], const Unit& u, int wr, int wc, int fr, int fq) const {
;     ...
;                 const int r = u.pm * BM + ai * HALF + wr * 64 + m * 16 + fr; float s = 0.f, q = 0.f; const float rs = RS[r];
; #pragma unroll
;                 for (int bj = 0; bj < 2; ++bj) { const f32x4 a0 = acc[ai][bj][m][0] * rs, a1 = acc[ai][bj][m][1] * rs;
;                     const f32x2 g0 = gelu_pk((f32x2){a0[0], a0[1]}), g1 = gelu_pk((f32x2){a0[2], a0[3]}), g2 = gelu_pk((f32x2){a1[0], a1[1]}), g3 = gelu_pk((f32x2){a1[2], a1[3]});
.LBB0_236:
	v_add_u32_e32 v80, 48, v138
	v_ashrrev_i32_e32 v81, 31, v80
	s_waitcnt lgkmcnt(0)
	v_lshl_add_u64 v[82:83], v[80:81], 2, s[14:15]
	global_load_dword v86, v[82:83], off
	v_mov_b64_e32 v[84:85], s[80:81]
	v_lshlrev_b64 v[82:83], 12, v[80:81]
	v_lshl_add_u64 v[82:83], v[140:141], 0, v[82:83]
	s_waitcnt vmcnt(0)
	v_pk_mul_f32 v[76:77], v[76:77], v[86:87] op_sel_hi:[1,0]
	v_pk_mul_f32 v[78:79], v[78:79], v[86:87] op_sel_hi:[1,0]
	v_pk_mul_f32 v[74:75], v[74:75], v[86:87] op_sel_hi:[1,0]
	v_pk_mul_f32 v[88:89], v[72:73], v[86:87] op_sel_hi:[1,0]
	v_pk_mul_f32 v[92:93], v[64:65], v[86:87] op_sel_hi:[1,0]
	v_and_b32_e32 v65, 0x7fffffff, v77
	v_and_b32_e32 v64, 0x7fffffff, v76
	v_pk_mul_f32 v[70:71], v[70:71], v[86:87] op_sel_hi:[1,0]
	v_pk_mul_f32 v[68:69], v[68:69], v[86:87] op_sel_hi:[1,0]
	v_pk_mul_f32 v[90:91], v[66:67], v[86:87] op_sel_hi:[1,0]
	v_and_b32_e32 v87, 0x7fffffff, v79
	v_and_b32_e32 v86, 0x7fffffff, v78
	v_and_b32_e32 v95, 0x7fffffff, v89
	v_and_b32_e32 v94, 0x7fffffff, v88
	v_and_b32_e32 v101, 0x7fffffff, v75
	v_and_b32_e32 v100, 0x7fffffff, v74
	v_pk_fma_f32 v[64:65], v[64:65], s[76:77], 1.0 op_sel_hi:[1,0,0]
	v_pk_fma_f32 v[86:87], v[86:87], s[76:77], 1.0 op_sel_hi:[1,0,0]
	v_pk_fma_f32 v[94:95], v[94:95], s[76:77], 1.0 op_sel_hi:[1,0,0]
	v_pk_fma_f32 v[100:101], v[100:101], s[76:77], 1.0 op_sel_hi:[1,0,0]
	v_rcp_f32_e32 v64, v64
	v_rcp_f32_e32 v65, v65
	v_rcp_f32_e32 v86, v86
	v_rcp_f32_e32 v87, v87
	v_rcp_f32_e32 v94, v94
	v_rcp_f32_e32 v95, v95
	v_rcp_f32_e32 v100, v100
	v_rcp_f32_e32 v101, v101
	v_pk_mul_f32 v[72:73], v[76:77], v[76:77]
	v_pk_mul_f32 v[66:67], v[78:79], v[78:79]
	v_pk_mul_f32 v[96:97], v[74:75], v[74:75]
	v_pk_mul_f32 v[98:99], v[88:89], v[88:89]
	v_pk_mul_f32 v[72:73], v[72:73], s[52:53] op_sel_hi:[1,0]
	v_pk_fma_f32 v[108:109], v[64:65], s[78:79], v[84:85] op_sel_hi:[1,0,0]
	v_pk_mul_f32 v[66:67], v[66:67], s[52:53] op_sel_hi:[1,0]
	v_pk_mul_f32 v[98:99], v[98:99], s[52:53] op_sel_hi:[1,0]
	v_pk_mul_f32 v[96:97], v[96:97], s[52:53] op_sel_hi:[1,0]
	v_exp_f32_e32 v72, v72
	v_exp_f32_e32 v73, v73
	v_pk_fma_f32 v[110:111], v[86:87], s[78:79], v[84:85] op_sel_hi:[1,0,0]
	v_pk_fma_f32 v[112:113], v[94:95], s[78:79], v[84:85] op_sel_hi:[1,0,0]
	v_pk_fma_f32 v[114:115], v[100:101], s[78:79], v[84:85] op_sel_hi:[1,0,0]
	v_pk_fma_f32 v[108:109], v[64:65], v[108:109], s[96:97] op_sel_hi:[1,1,0]
	v_exp_f32_e32 v66, v66
	v_exp_f32_e32 v67, v67
	v_exp_f32_e32 v98, v98
	v_exp_f32_e32 v99, v99
	v_exp_f32_e32 v96, v96
	v_exp_f32_e32 v97, v97
	v_pk_fma_f32 v[110:111], v[86:87], v[110:111], s[96:97] op_sel_hi:[1,1,0]
	v_pk_fma_f32 v[112:113], v[94:95], v[112:113], s[96:97] op_sel_hi:[1,1,0]
	v_pk_fma_f32 v[114:115], v[100:101], v[114:115], s[96:97] op_sel_hi:[1,1,0]
	v_pk_fma_f32 v[108:109], v[64:65], v[108:109], s[48:49] op_sel_hi:[1,1,0]
	v_pk_fma_f32 v[110:111], v[86:87], v[110:111], s[48:49] op_sel_hi:[1,1,0]
	v_pk_fma_f32 v[112:113], v[94:95], v[112:113], s[48:49] op_sel_hi:[1,1,0]
	v_pk_fma_f32 v[114:115], v[100:101], v[114:115], s[48:49] op_sel_hi:[1,1,0]
	v_pk_fma_f32 v[108:109], v[64:65], v[108:109], s[50:51] op_sel_hi:[1,1,0]
	v_pk_fma_f32 v[110:111], v[86:87], v[110:111], s[50:51] op_sel_hi:[1,1,0]
	v_pk_fma_f32 v[112:113], v[94:95], v[112:113], s[50:51] op_sel_hi:[1,1,0]
	v_pk_fma_f32 v[114:115], v[100:101], v[114:115], s[50:51] op_sel_hi:[1,1,0]
	v_pk_mul_f32 v[64:65], v[64:65], v[108:109]
	v_pk_mul_f32 v[86:87], v[86:87], v[110:111]
	v_pk_mul_f32 v[94:95], v[94:95], v[112:113]
	v_pk_mul_f32 v[100:101], v[100:101], v[114:115]
	v_pk_mul_f32 v[64:65], v[72:73], v[64:65]
	v_and_b32_e32 v103, 0x7fffffff, v69
	v_and_b32_e32 v102, 0x7fffffff, v68
	v_pk_mul_f32 v[66:67], v[66:67], v[86:87]
	v_pk_mul_f32 v[72:73], v[98:99], v[94:95]
	v_pk_mul_f32 v[86:87], v[96:97], v[100:101]
	v_pk_mul_f32 v[94:95], v[76:77], v[64:65]
	v_pk_fma_f32 v[96:97], v[76:77], v[64:65], v[76:77] neg_lo:[1,0,0] neg_hi:[1,0,0]
	v_and_b32_e32 v65, 0x7fffffff, v71
	v_and_b32_e32 v64, 0x7fffffff, v70
	v_pk_fma_f32 v[102:103], v[102:103], s[76:77], 1.0 op_sel_hi:[1,0,0]
	v_pk_fma_f32 v[64:65], v[64:65], s[76:77], 1.0 op_sel_hi:[1,0,0]
	v_rcp_f32_e32 v102, v102
	v_rcp_f32_e32 v103, v103
	v_rcp_f32_e32 v64, v64
	v_rcp_f32_e32 v65, v65
	v_pk_mul_f32 v[104:105], v[70:71], v[70:71]
	v_pk_mul_f32 v[106:107], v[68:69], v[68:69]
	v_pk_fma_f32 v[116:117], v[102:103], s[78:79], v[84:85] op_sel_hi:[1,0,0]
	v_pk_mul_f32 v[106:107], v[106:107], s[52:53] op_sel_hi:[1,0]
	v_pk_mul_f32 v[108:109], v[88:89], v[72:73]
	v_pk_fma_f32 v[110:111], v[88:89], v[72:73], v[88:89] neg_lo:[1,0,0] neg_hi:[1,0,0]
	v_pk_fma_f32 v[72:73], v[64:65], s[78:79], v[84:85] op_sel_hi:[1,0,0]
	v_pk_mul_f32 v[104:105], v[104:105], s[52:53] op_sel_hi:[1,0]
	v_exp_f32_e32 v106, v106
	v_pk_fma_f32 v[116:117], v[102:103], v[116:117], s[96:97] op_sel_hi:[1,1,0]
	v_exp_f32_e32 v107, v107
	v_pk_fma_f32 v[72:73], v[64:65], v[72:73], s[96:97] op_sel_hi:[1,1,0]
	v_exp_f32_e32 v104, v104
	v_exp_f32_e32 v105, v105
	v_pk_fma_f32 v[116:117], v[102:103], v[116:117], s[48:49] op_sel_hi:[1,1,0]
	v_pk_fma_f32 v[72:73], v[64:65], v[72:73], s[48:49] op_sel_hi:[1,1,0]
	v_pk_fma_f32 v[116:117], v[102:103], v[116:117], s[50:51] op_sel_hi:[1,1,0]
	v_pk_fma_f32 v[72:73], v[64:65], v[72:73], s[50:51] op_sel_hi:[1,1,0]
	v_pk_mul_f32 v[102:103], v[102:103], v[116:117]
	v_pk_mul_f32 v[64:65], v[64:65], v[72:73]
	v_pk_mul_f32 v[98:99], v[78:79], v[66:67]
	v_pk_fma_f32 v[100:101], v[78:79], v[66:67], v[78:79] neg_lo:[1,0,0] neg_hi:[1,0,0]
	v_pk_mul_f32 v[66:67], v[106:107], v[102:103]
	v_pk_mul_f32 v[64:65], v[104:105], v[64:65]
	v_cmp_gt_f32_e32 vcc, 0, v76
	v_pk_mul_f32 v[102:103], v[68:69], v[66:67]
; DI unsigned pk2(float a, float b) { f32x2 v = {a, b}; hbf16x2 r = __builtin_convertvector(v, hbf16x2); return __builtin_bit_cast(unsigned, r); }
; __device__ __forceinline__ f32x2 gelu_pk(f32x2 v) {
;     const f32x2 av = __builtin_elementwise_abs(v), d = av * 0.2316418882f + 1.0f;
;     f32x2 t; t.x = __builtin_amdgcn_rcpf(d.x); t.y = __builtin_amdgcn_rcpf(d.y);
;     f32x2 q = t * 0.5307027145f + (-0.7265760135f); q = q * t + 0.7107068705f; q = q * t + (-0.142248368f); q = q * t + 0.127414796f; q = q * t;
;     const f32x2 s = (v * v) * (-0.72134752044f);
;     f32x2 e; e.x = __builtin_amdgcn_exp2f(s.x); e.y = __builtin_amdgcn_exp2f(s.y);
;     const f32x2 m = v * (q * e), r = v - m;
;     f32x2 o; o.x = v.x < 0.f ? m.x : r.x; o.y = v.y < 0.f ? m.y : r.y; return o;
;     DI void operator()(const f32x4 (&acc)[2][2][4][2], const Unit& u, int wr, int wc, int fr, int fq) const {
;     ...
;                 for (int bj = 0; bj < 2; ++bj) { const f32x4 a0 = acc[ai][bj][m][0] * rs, a1 = acc[ai][bj][m][1] * rs;
;                     const f32x2 g0 = gelu_pk((f32x2){a0[0], a0[1]}), g1 = gelu_pk((f32x2){a0[2], a0[3]}), g2 = gelu_pk((f32x2){a1[0], a1[1]}), g3 = gelu_pk((f32x2){a1[2], a1[3]});
;                     s += ((g0.x + g0.y) + (g1.x + g1.y)) + ((g2.x + g2.y) + (g3.x + g3.y));
;                     q += ((g0.x * g0.x + g0.y * g0.y) + (g1.x * g1.x + g1.y * g1.y)) + ((g2.x * g2.x + g2.y * g2.y) + (g3.x * g3.x + g3.y * g3.y));
;                     u32x4 w; w.x = pk2(g0.x, g0.y); w.y = pk2(g1.x, g1.y); w.z = pk2(g2.x, g2.y); w.w = pk2(g3.x, g3.y);
;                     *(u32x4*)(base + (size_t)r * 2048 + colt + bj * HALF) = w; }
;                 if (isv) { s += __shfl_xor(s, 16); s += __shfl_xor(s, 32); q += __shfl_xor(q, 16); q += __shfl_xor(q, 32);
;                     if (fq == 0) *(f32x2*)(STATS + ((size_t)r * 32 + (pn - 8) * 4 + wc) * 2) = (f32x2){s, q}; }
	v_pk_fma_f32 v[66:67], v[68:69], v[66:67], v[68:69] neg_lo:[1,0,0] neg_hi:[1,0,0]
	v_pk_mul_f32 v[104:105], v[70:71], v[64:65]
	v_pk_fma_f32 v[106:107], v[70:71], v[64:65], v[70:71] neg_lo:[1,0,0] neg_hi:[1,0,0]
	v_cndmask_b32_e32 v64, v96, v94, vcc
	v_cmp_gt_f32_e32 vcc, 0, v68
	v_pk_mul_f32 v[112:113], v[74:75], v[86:87]
	v_pk_fma_f32 v[86:87], v[74:75], v[86:87], v[74:75] neg_lo:[1,0,0] neg_hi:[1,0,0]
	v_cndmask_b32_e32 v65, v66, v102, vcc
	v_cmp_gt_f32_e32 vcc, 0, v77
	v_and_b32_e32 v96, 0x7fffffff, v90
	s_nop 0
	v_cndmask_b32_e32 v72, v97, v95, vcc
	v_cmp_gt_f32_e32 vcc, 0, v78
	v_and_b32_e32 v97, 0x7fffffff, v91
	v_pk_fma_f32 v[96:97], v[96:97], s[76:77], 1.0 op_sel_hi:[1,0,0]
	v_cndmask_b32_e32 v66, v100, v98, vcc
	v_cmp_gt_f32_e32 vcc, 0, v69
	v_rcp_f32_e32 v96, v96
	v_rcp_f32_e32 v97, v97
	v_cndmask_b32_e32 v67, v67, v103, vcc
	v_cmp_gt_f32_e32 vcc, 0, v79
	s_nop 1
	v_cndmask_b32_e32 v76, v101, v99, vcc
	v_cmp_gt_f32_e32 vcc, 0, v88
	v_and_b32_e32 v88, 0x7fffffff, v92
	s_nop 0
	v_cndmask_b32_e32 v68, v110, v108, vcc
	v_cmp_gt_f32_e32 vcc, 0, v70
	s_nop 1
	v_cndmask_b32_e32 v69, v106, v104, vcc
	v_cmp_gt_f32_e32 vcc, 0, v89
	v_and_b32_e32 v89, 0x7fffffff, v93
	v_pk_fma_f32 v[88:89], v[88:89], s[76:77], 1.0 op_sel_hi:[1,0,0]
	v_cndmask_b32_e32 v78, v111, v109, vcc
	v_cmp_gt_f32_e32 vcc, 0, v74
	v_rcp_f32_e32 v94, v88
	v_rcp_f32_e32 v95, v89
	v_cndmask_b32_e32 v70, v86, v112, vcc
	v_cmp_gt_f32_e32 vcc, 0, v71
	v_cvt_pk_bf16_f32 v86, v64, v72
	v_cvt_pk_bf16_f32 v88, v68, v78
	v_cndmask_b32_e32 v71, v107, v105, vcc
	v_cmp_gt_f32_e32 vcc, 0, v75
	s_nop 1
	v_cndmask_b32_e32 v74, v87, v113, vcc
	v_cvt_pk_bf16_f32 v87, v66, v76
	v_cvt_pk_bf16_f32 v89, v70, v74
	global_store_dwordx4 v[82:83], v[86:89], off sc1
	v_cmp_gt_f32_e32 vcc, 0, v90
	s_nop 0
	v_pk_fma_f32 v[86:87], v[94:95], s[78:79], v[84:85] op_sel_hi:[1,0,0]
	v_pk_mul_f32 v[88:89], v[90:91], v[90:91]
	v_pk_fma_f32 v[86:87], v[94:95], v[86:87], s[96:97] op_sel_hi:[1,1,0]
	v_pk_fma_f32 v[84:85], v[96:97], s[78:79], v[84:85] op_sel_hi:[1,0,0]
	v_pk_fma_f32 v[86:87], v[94:95], v[86:87], s[48:49] op_sel_hi:[1,1,0]
	v_pk_fma_f32 v[84:85], v[96:97], v[84:85], s[96:97] op_sel_hi:[1,1,0]
	v_pk_fma_f32 v[86:87], v[94:95], v[86:87], s[50:51] op_sel_hi:[1,1,0]
	v_pk_fma_f32 v[84:85], v[96:97], v[84:85], s[48:49] op_sel_hi:[1,1,0]
	v_pk_mul_f32 v[86:87], v[94:95], v[86:87]
	v_pk_mul_f32 v[94:95], v[92:93], v[92:93]
	v_pk_fma_f32 v[84:85], v[96:97], v[84:85], s[50:51] op_sel_hi:[1,1,0]
	v_pk_mul_f32 v[94:95], v[94:95], s[52:53] op_sel_hi:[1,0]
	v_pk_mul_f32 v[84:85], v[96:97], v[84:85]
	v_exp_f32_e32 v94, v94
	v_exp_f32_e32 v95, v95
	s_nop 0
	v_pk_mul_f32 v[86:87], v[94:95], v[86:87]
	s_nop 0
	v_pk_mul_f32 v[94:95], v[92:93], v[86:87]
	v_pk_fma_f32 v[98:99], v[92:93], v[86:87], v[92:93] neg_lo:[1,0,0] neg_hi:[1,0,0]
	v_pk_mul_f32 v[86:87], v[88:89], s[52:53] op_sel_hi:[1,0]
	s_nop 0
	v_exp_f32_e32 v86, v86
	v_exp_f32_e32 v87, v87
	s_nop 0
	v_pk_mul_f32 v[84:85], v[86:87], v[84:85]
	s_nop 0
	v_pk_mul_f32 v[86:87], v[90:91], v[84:85]
	v_pk_fma_f32 v[88:89], v[90:91], v[84:85], v[90:91] neg_lo:[1,0,0] neg_hi:[1,0,0]
	s_nop 0
	v_cndmask_b32_e32 v85, v88, v86, vcc
	v_cmp_gt_f32_e32 vcc, 0, v92
	v_cvt_pk_bf16_f32 v88, v65, v67
	s_nop 0
	v_cndmask_b32_e32 v84, v98, v94, vcc
	v_cmp_gt_f32_e32 vcc, 0, v91
	s_nop 1
	v_cndmask_b32_e32 v87, v89, v87, vcc
	v_cmp_gt_f32_e32 vcc, 0, v93
	v_cvt_pk_bf16_f32 v89, v69, v71
	v_cvt_pk_bf16_f32 v91, v85, v87
	v_cndmask_b32_e32 v86, v99, v95, vcc
	v_cvt_pk_bf16_f32 v90, v84, v86
	s_and_b64 vcc, exec, s[4:5]
	global_store_dwordx4 v[82:83], v[88:91], off offset:256 sc1
	s_cbranch_vccnz .LBB0_240
	v_mov_b32_e32 v73, v65
	v_mov_b32_e32 v77, v67
	v_pk_mul_f32 v[88:89], v[72:73], v[72:73]
	v_pk_add_f32 v[102:103], v[64:65], v[72:73]
	v_pk_mul_f32 v[72:73], v[64:65], v[72:73]
	v_mov_b32_e32 v79, v69
	v_pk_mul_f32 v[82:83], v[64:65], v[64:65]
	v_pk_mul_f32 v[92:93], v[76:77], v[76:77]
	v_mov_b32_e32 v103, v73
	v_pk_add_f32 v[72:73], v[66:67], v[76:77]
	v_pk_mul_f32 v[76:77], v[66:67], v[76:77]
	v_mov_b32_e32 v75, v71
	v_pk_mul_f32 v[90:91], v[66:67], v[66:67]
	v_pk_mul_f32 v[96:97], v[78:79], v[78:79]
	v_mov_b32_e32 v73, v77
	v_pk_add_f32 v[76:77], v[68:69], v[78:79]
	v_pk_mul_f32 v[78:79], v[68:69], v[78:79]
	v_pk_mov_b32 v[64:65], v[64:65], v[82:83] op_sel:[1,0]
	v_pk_mov_b32 v[66:67], v[66:67], v[88:89] op_sel:[1,0]
	v_pk_mul_f32 v[94:95], v[68:69], v[68:69]
	v_pk_mul_f32 v[100:101], v[74:75], v[74:75]
	v_mov_b32_e32 v77, v79
	v_pk_add_f32 v[78:79], v[70:71], v[74:75]
	v_pk_mul_f32 v[74:75], v[70:71], v[74:75]
	v_pk_add_f32 v[64:65], v[64:65], v[66:67]
	v_pk_mov_b32 v[66:67], v[68:69], v[90:91] op_sel:[1,0]
	v_pk_mov_b32 v[68:69], v[70:71], v[92:93] op_sel:[1,0]
	v_mov_b32_e32 v79, v75
	v_pk_mul_f32 v[74:75], v[86:87], v[86:87]
	v_pk_add_f32 v[66:67], v[66:67], v[68:69]
	v_pk_mul_f32 v[98:99], v[70:71], v[70:71]
	v_pk_fma_f32 v[74:75], v[84:85], v[84:85], v[74:75]
	v_pk_add_f32 v[64:65], v[64:65], v[66:67]
	v_mov_b32_e32 v66, v84
	v_mov_b32_e32 v67, v94
	v_mov_b32_e32 v68, v86
	v_mov_b32_e32 v69, v96
	v_pk_add_f32 v[74:75], v[74:75], v[74:75] op_sel_hi:[0,1]
	v_cmp_lt_i32_e32 vcc, v248, v243
	v_pk_add_f32 v[66:67], v[66:67], v[68:69]
	v_pk_mov_b32 v[68:69], v[84:85], v[98:99] op_sel:[1,0]
	v_pk_mov_b32 v[70:71], v[86:87], v[100:101] op_sel:[1,0]
	v_cndmask_b32_e32 v74, v241, v248, vcc
	v_pk_add_f32 v[72:73], v[102:103], v[72:73]
	v_pk_add_f32 v[76:77], v[76:77], v[78:79]
	v_pk_add_f32 v[68:69], v[68:69], v[70:71]
	v_lshlrev_b32_e32 v95, 2, v74
	v_pk_add_f32 v[72:73], v[72:73], v[76:77]
	v_mov_b32_e32 v74, v153
	v_pk_add_f32 v[66:67], v[66:67], v[68:69]
	v_pk_add_f32 v[72:73], v[72:73], v[74:75]
	v_pk_add_f32 v[64:65], v[64:65], v[66:67]
	v_cmp_lt_i32_e32 vcc, v249, v243
	v_pk_add_f32 v[64:65], v[64:65], v[72:73]
	ds_bpermute_b32 v66, v95, v64
	ds_bpermute_b32 v67, v95, v65
	v_cndmask_b32_e32 v68, v241, v249, vcc
	v_lshlrev_b32_e32 v68, 2, v68
	s_waitcnt lgkmcnt(0)
	v_pk_add_f32 v[64:65], v[64:65], v[66:67]
	ds_bpermute_b32 v66, v68, v64
	ds_bpermute_b32 v67, v68, v65
	s_and_saveexec_b64 s[28:29], s[0:1]
	s_cbranch_execz .LBB0_239
	v_lshlrev_b64 v[68:69], 8, v[80:81]
	s_waitcnt lgkmcnt(0)
	v_pk_add_f32 v[64:65], v[64:65], v[66:67]
	v_lshl_add_u64 v[66:67], s[18:19], 0, v[68:69]
	v_lshl_add_u64 v[66:67], s[72:73], 3, v[66:67]
	global_store_dwordx2 v[66:67], v[64:65], off

; __device__ __forceinline__ f32x2 gelu_pk(f32x2 v) {
;     const f32x2 av = __builtin_elementwise_abs(v), d = av * 0.2316418882f + 1.0f;
;     f32x2 t; t.x = __builtin_amdgcn_rcpf(d.x); t.y = __builtin_amdgcn_rcpf(d.y);
;     f32x2 q = t * 0.5307027145f + (-0.7265760135f); q = q * t + 0.7107068705f; q = q * t + (-0.142248368f); q = q * t + 0.127414796f; q = q * t;
;     const f32x2 s = (v * v) * (-0.72134752044f);
;     f32x2 e; e.x = __builtin_amdgcn_exp2f(s.x); e.y = __builtin_amdgcn_exp2f(s.y);
;     const f32x2 m = v * (q * e), r = v - m;
;     f32x2 o; o.x = v.x < 0.f ? m.x : r.x; o.y = v.y < 0.f ? m.y : r.y; return o;
;     DI void operator()(const f32x4 (&acc)[2][2][4][2], const Unit& u, int wr, int wc, int fr, int fq) const {
;     ...
;                 const int r = u.pm * BM + ai * HALF + wr * 64 + m * 16 + fr; float s = 0.f, q = 0.f; const float rs = RS[r];
; #pragma unroll
;                 for (int bj = 0; bj < 2; ++bj) { const f32x4 a0 = acc[ai][bj][m][0] * rs, a1 = acc[ai][bj][m][1] * rs;
;                     const f32x2 g0 = gelu_pk((f32x2){a0[0], a0[1]}), g1 = gelu_pk((f32x2){a0[2], a0[3]}), g2 = gelu_pk((f32x2){a1[0], a1[1]}), g3 = gelu_pk((f32x2){a1[2], a1[3]});
.LBB0_240:
	v_add_u32_e32 v64, 0x80, v138
	v_ashrrev_i32_e32 v65, 31, v64
	s_waitcnt lgkmcnt(0)
	v_lshl_add_u64 v[66:67], v[64:65], 2, s[14:15]
	global_load_dword v70, v[66:67], off
	v_mov_b64_e32 v[68:69], s[80:81]
	v_lshlrev_b64 v[66:67], 12, v[64:65]
	v_lshl_add_u64 v[66:67], v[140:141], 0, v[66:67]
	s_waitcnt vmcnt(0)
	v_pk_mul_f32 v[60:61], v[60:61], v[70:71] op_sel_hi:[1,0]
	v_pk_mul_f32 v[62:63], v[62:63], v[70:71] op_sel_hi:[1,0]
	v_pk_mul_f32 v[58:59], v[58:59], v[70:71] op_sel_hi:[1,0]
	v_pk_mul_f32 v[72:73], v[56:57], v[70:71] op_sel_hi:[1,0]
	v_pk_mul_f32 v[76:77], v[48:49], v[70:71] op_sel_hi:[1,0]
	v_and_b32_e32 v49, 0x7fffffff, v61
	v_and_b32_e32 v48, 0x7fffffff, v60
	v_pk_mul_f32 v[54:55], v[54:55], v[70:71] op_sel_hi:[1,0]
	v_pk_mul_f32 v[52:53], v[52:53], v[70:71] op_sel_hi:[1,0]
	v_pk_mul_f32 v[74:75], v[50:51], v[70:71] op_sel_hi:[1,0]
	v_and_b32_e32 v71, 0x7fffffff, v63
	v_and_b32_e32 v70, 0x7fffffff, v62
	v_and_b32_e32 v79, 0x7fffffff, v73
	v_and_b32_e32 v78, 0x7fffffff, v72
	v_and_b32_e32 v85, 0x7fffffff, v59
	v_and_b32_e32 v84, 0x7fffffff, v58
	v_pk_fma_f32 v[48:49], v[48:49], s[76:77], 1.0 op_sel_hi:[1,0,0]
	v_pk_fma_f32 v[70:71], v[70:71], s[76:77], 1.0 op_sel_hi:[1,0,0]
	v_pk_fma_f32 v[78:79], v[78:79], s[76:77], 1.0 op_sel_hi:[1,0,0]
	v_pk_fma_f32 v[84:85], v[84:85], s[76:77], 1.0 op_sel_hi:[1,0,0]
	v_rcp_f32_e32 v48, v48
	v_rcp_f32_e32 v49, v49
	v_rcp_f32_e32 v70, v70
	v_rcp_f32_e32 v71, v71
	v_rcp_f32_e32 v78, v78
	v_rcp_f32_e32 v79, v79
	v_rcp_f32_e32 v84, v84
	v_rcp_f32_e32 v85, v85
	v_pk_mul_f32 v[56:57], v[60:61], v[60:61]
	v_pk_mul_f32 v[50:51], v[62:63], v[62:63]
	v_pk_mul_f32 v[80:81], v[58:59], v[58:59]
	v_pk_mul_f32 v[82:83], v[72:73], v[72:73]
	v_pk_mul_f32 v[56:57], v[56:57], s[52:53] op_sel_hi:[1,0]
	v_pk_fma_f32 v[92:93], v[48:49], s[78:79], v[68:69] op_sel_hi:[1,0,0]
	v_pk_mul_f32 v[50:51], v[50:51], s[52:53] op_sel_hi:[1,0]
	v_pk_mul_f32 v[82:83], v[82:83], s[52:53] op_sel_hi:[1,0]
	v_pk_mul_f32 v[80:81], v[80:81], s[52:53] op_sel_hi:[1,0]
	v_exp_f32_e32 v56, v56
	v_exp_f32_e32 v57, v57
	v_pk_fma_f32 v[94:95], v[70:71], s[78:79], v[68:69] op_sel_hi:[1,0,0]
	v_pk_fma_f32 v[96:97], v[78:79], s[78:79], v[68:69] op_sel_hi:[1,0,0]
	v_pk_fma_f32 v[98:99], v[84:85], s[78:79], v[68:69] op_sel_hi:[1,0,0]
	v_pk_fma_f32 v[92:93], v[48:49], v[92:93], s[96:97] op_sel_hi:[1,1,0]
	v_exp_f32_e32 v50, v50
	v_exp_f32_e32 v51, v51
	v_exp_f32_e32 v82, v82
	v_exp_f32_e32 v83, v83
	v_exp_f32_e32 v80, v80
	v_exp_f32_e32 v81, v81
	v_pk_fma_f32 v[94:95], v[70:71], v[94:95], s[96:97] op_sel_hi:[1,1,0]
	v_pk_fma_f32 v[96:97], v[78:79], v[96:97], s[96:97] op_sel_hi:[1,1,0]
	v_pk_fma_f32 v[98:99], v[84:85], v[98:99], s[96:97] op_sel_hi:[1,1,0]
	v_pk_fma_f32 v[92:93], v[48:49], v[92:93], s[48:49] op_sel_hi:[1,1,0]
	v_pk_fma_f32 v[94:95], v[70:71], v[94:95], s[48:49] op_sel_hi:[1,1,0]
	v_pk_fma_f32 v[96:97], v[78:79], v[96:97], s[48:49] op_sel_hi:[1,1,0]
	v_pk_fma_f32 v[98:99], v[84:85], v[98:99], s[48:49] op_sel_hi:[1,1,0]
	v_pk_fma_f32 v[92:93], v[48:49], v[92:93], s[50:51] op_sel_hi:[1,1,0]
	v_pk_fma_f32 v[94:95], v[70:71], v[94:95], s[50:51] op_sel_hi:[1,1,0]
	v_pk_fma_f32 v[96:97], v[78:79], v[96:97], s[50:51] op_sel_hi:[1,1,0]
	v_pk_fma_f32 v[98:99], v[84:85], v[98:99], s[50:51] op_sel_hi:[1,1,0]
	v_pk_mul_f32 v[48:49], v[48:49], v[92:93]
	v_pk_mul_f32 v[70:71], v[70:71], v[94:95]
	v_pk_mul_f32 v[78:79], v[78:79], v[96:97]
	v_pk_mul_f32 v[84:85], v[84:85], v[98:99]
	v_pk_mul_f32 v[48:49], v[56:57], v[48:49]
	v_and_b32_e32 v87, 0x7fffffff, v53
	v_and_b32_e32 v86, 0x7fffffff, v52
	v_pk_mul_f32 v[50:51], v[50:51], v[70:71]
	v_pk_mul_f32 v[56:57], v[82:83], v[78:79]
	v_pk_mul_f32 v[70:71], v[80:81], v[84:85]
	v_pk_mul_f32 v[78:79], v[60:61], v[48:49]
	v_pk_fma_f32 v[80:81], v[60:61], v[48:49], v[60:61] neg_lo:[1,0,0] neg_hi:[1,0,0]
	v_and_b32_e32 v49, 0x7fffffff, v55
	v_and_b32_e32 v48, 0x7fffffff, v54
	v_pk_fma_f32 v[86:87], v[86:87], s[76:77], 1.0 op_sel_hi:[1,0,0]
	v_pk_fma_f32 v[48:49], v[48:49], s[76:77], 1.0 op_sel_hi:[1,0,0]
	v_rcp_f32_e32 v86, v86
	v_rcp_f32_e32 v87, v87
	v_rcp_f32_e32 v48, v48
	v_rcp_f32_e32 v49, v49
	v_pk_mul_f32 v[88:89], v[54:55], v[54:55]
	v_pk_mul_f32 v[90:91], v[52:53], v[52:53]
	v_pk_fma_f32 v[100:101], v[86:87], s[78:79], v[68:69] op_sel_hi:[1,0,0]
	v_pk_mul_f32 v[90:91], v[90:91], s[52:53] op_sel_hi:[1,0]
	v_pk_mul_f32 v[92:93], v[72:73], v[56:57]
	v_pk_fma_f32 v[94:95], v[72:73], v[56:57], v[72:73] neg_lo:[1,0,0] neg_hi:[1,0,0]
	v_pk_fma_f32 v[56:57], v[48:49], s[78:79], v[68:69] op_sel_hi:[1,0,0]
	v_pk_mul_f32 v[88:89], v[88:89], s[52:53] op_sel_hi:[1,0]
	v_exp_f32_e32 v90, v90
	v_pk_fma_f32 v[100:101], v[86:87], v[100:101], s[96:97] op_sel_hi:[1,1,0]
	v_exp_f32_e32 v91, v91
	v_pk_fma_f32 v[56:57], v[48:49], v[56:57], s[96:97] op_sel_hi:[1,1,0]
	v_exp_f32_e32 v88, v88
	v_exp_f32_e32 v89, v89
	v_pk_fma_f32 v[100:101], v[86:87], v[100:101], s[48:49] op_sel_hi:[1,1,0]
	v_pk_fma_f32 v[56:57], v[48:49], v[56:57], s[48:49] op_sel_hi:[1,1,0]
	v_pk_fma_f32 v[100:101], v[86:87], v[100:101], s[50:51] op_sel_hi:[1,1,0]
	v_pk_fma_f32 v[56:57], v[48:49], v[56:57], s[50:51] op_sel_hi:[1,1,0]
	v_pk_mul_f32 v[86:87], v[86:87], v[100:101]
	v_pk_mul_f32 v[48:49], v[48:49], v[56:57]
	v_pk_mul_f32 v[82:83], v[62:63], v[50:51]
	v_pk_fma_f32 v[84:85], v[62:63], v[50:51], v[62:63] neg_lo:[1,0,0] neg_hi:[1,0,0]
	v_pk_mul_f32 v[50:51], v[90:91], v[86:87]
	v_pk_mul_f32 v[48:49], v[88:89], v[48:49]
	v_cmp_gt_f32_e32 vcc, 0, v60
	v_pk_mul_f32 v[86:87], v[52:53], v[50:51]
	v_pk_fma_f32 v[50:51], v[52:53], v[50:51], v[52:53] neg_lo:[1,0,0] neg_hi:[1,0,0]
	v_pk_mul_f32 v[88:89], v[54:55], v[48:49]
; DI unsigned pk2(float a, float b) { f32x2 v = {a, b}; hbf16x2 r = __builtin_convertvector(v, hbf16x2); return __builtin_bit_cast(unsigned, r); }
; __device__ __forceinline__ f32x2 gelu_pk(f32x2 v) {
;     const f32x2 av = __builtin_elementwise_abs(v), d = av * 0.2316418882f + 1.0f;
;     f32x2 t; t.x = __builtin_amdgcn_rcpf(d.x); t.y = __builtin_amdgcn_rcpf(d.y);
;     f32x2 q = t * 0.5307027145f + (-0.7265760135f); q = q * t + 0.7107068705f; q = q * t + (-0.142248368f); q = q * t + 0.127414796f; q = q * t;
;     const f32x2 s = (v * v) * (-0.72134752044f);
;     f32x2 e; e.x = __builtin_amdgcn_exp2f(s.x); e.y = __builtin_amdgcn_exp2f(s.y);
;     const f32x2 m = v * (q * e), r = v - m;
;     f32x2 o; o.x = v.x < 0.f ? m.x : r.x; o.y = v.y < 0.f ? m.y : r.y; return o;
;     DI void operator()(const f32x4 (&acc)[2][2][4][2], const Unit& u, int wr, int wc, int fr, int fq) const {
;     ...
;                 for (int bj = 0; bj < 2; ++bj) { const f32x4 a0 = acc[ai][bj][m][0] * rs, a1 = acc[ai][bj][m][1] * rs;
;                     const f32x2 g0 = gelu_pk((f32x2){a0[0], a0[1]}), g1 = gelu_pk((f32x2){a0[2], a0[3]}), g2 = gelu_pk((f32x2){a1[0], a1[1]}), g3 = gelu_pk((f32x2){a1[2], a1[3]});
;                     s += ((g0.x + g0.y) + (g1.x + g1.y)) + ((g2.x + g2.y) + (g3.x + g3.y));
;                     q += ((g0.x * g0.x + g0.y * g0.y) + (g1.x * g1.x + g1.y * g1.y)) + ((g2.x * g2.x + g2.y * g2.y) + (g3.x * g3.x + g3.y * g3.y));
;                     u32x4 w; w.x = pk2(g0.x, g0.y); w.y = pk2(g1.x, g1.y); w.z = pk2(g2.x, g2.y); w.w = pk2(g3.x, g3.y);
;                     *(u32x4*)(base + (size_t)r * 2048 + colt + bj * HALF) = w; }
;                 if (isv) { s += __shfl_xor(s, 16); s += __shfl_xor(s, 32); q += __shfl_xor(q, 16); q += __shfl_xor(q, 32);
;                     if (fq == 0) *(f32x2*)(STATS + ((size_t)r * 32 + (pn - 8) * 4 + wc) * 2) = (f32x2){s, q}; }
	v_pk_fma_f32 v[90:91], v[54:55], v[48:49], v[54:55] neg_lo:[1,0,0] neg_hi:[1,0,0]
	v_cndmask_b32_e32 v48, v80, v78, vcc
	v_cmp_gt_f32_e32 vcc, 0, v52
	v_pk_mul_f32 v[96:97], v[58:59], v[70:71]
	v_pk_fma_f32 v[70:71], v[58:59], v[70:71], v[58:59] neg_lo:[1,0,0] neg_hi:[1,0,0]
	v_cndmask_b32_e32 v49, v50, v86, vcc
	v_cmp_gt_f32_e32 vcc, 0, v61
	v_and_b32_e32 v80, 0x7fffffff, v74
	s_nop 0
	v_cndmask_b32_e32 v56, v81, v79, vcc
	v_cmp_gt_f32_e32 vcc, 0, v62
	v_and_b32_e32 v81, 0x7fffffff, v75
	v_pk_fma_f32 v[80:81], v[80:81], s[76:77], 1.0 op_sel_hi:[1,0,0]
	v_cndmask_b32_e32 v50, v84, v82, vcc
	v_cmp_gt_f32_e32 vcc, 0, v53
	v_rcp_f32_e32 v80, v80
	v_rcp_f32_e32 v81, v81
	v_cndmask_b32_e32 v51, v51, v87, vcc
	v_cmp_gt_f32_e32 vcc, 0, v63
	s_nop 1
	v_cndmask_b32_e32 v60, v85, v83, vcc
	v_cmp_gt_f32_e32 vcc, 0, v72
	v_and_b32_e32 v72, 0x7fffffff, v76
	s_nop 0
	v_cndmask_b32_e32 v52, v94, v92, vcc
	v_cmp_gt_f32_e32 vcc, 0, v54
	s_nop 1
	v_cndmask_b32_e32 v53, v90, v88, vcc
	v_cmp_gt_f32_e32 vcc, 0, v73
	v_and_b32_e32 v73, 0x7fffffff, v77
	v_pk_fma_f32 v[72:73], v[72:73], s[76:77], 1.0 op_sel_hi:[1,0,0]
	v_cndmask_b32_e32 v62, v95, v93, vcc
	v_cmp_gt_f32_e32 vcc, 0, v58
	v_rcp_f32_e32 v78, v72
	v_rcp_f32_e32 v79, v73
	v_cndmask_b32_e32 v54, v70, v96, vcc
	v_cmp_gt_f32_e32 vcc, 0, v55
	v_cvt_pk_bf16_f32 v70, v48, v56
	v_cvt_pk_bf16_f32 v72, v52, v62
	v_cndmask_b32_e32 v55, v91, v89, vcc
	v_cmp_gt_f32_e32 vcc, 0, v59
	s_nop 1
	v_cndmask_b32_e32 v58, v71, v97, vcc
	v_cvt_pk_bf16_f32 v71, v50, v60
	v_cvt_pk_bf16_f32 v73, v54, v58
	global_store_dwordx4 v[66:67], v[70:73], off sc1
	v_cmp_gt_f32_e32 vcc, 0, v74
	s_nop 0
	v_pk_fma_f32 v[70:71], v[78:79], s[78:79], v[68:69] op_sel_hi:[1,0,0]
	v_pk_mul_f32 v[72:73], v[74:75], v[74:75]
	v_pk_fma_f32 v[70:71], v[78:79], v[70:71], s[96:97] op_sel_hi:[1,1,0]
	v_pk_fma_f32 v[68:69], v[80:81], s[78:79], v[68:69] op_sel_hi:[1,0,0]
	v_pk_fma_f32 v[70:71], v[78:79], v[70:71], s[48:49] op_sel_hi:[1,1,0]
	v_pk_fma_f32 v[68:69], v[80:81], v[68:69], s[96:97] op_sel_hi:[1,1,0]
	v_pk_fma_f32 v[70:71], v[78:79], v[70:71], s[50:51] op_sel_hi:[1,1,0]
	v_pk_fma_f32 v[68:69], v[80:81], v[68:69], s[48:49] op_sel_hi:[1,1,0]
	v_pk_mul_f32 v[70:71], v[78:79], v[70:71]
	v_pk_mul_f32 v[78:79], v[76:77], v[76:77]
	v_pk_fma_f32 v[68:69], v[80:81], v[68:69], s[50:51] op_sel_hi:[1,1,0]
	v_pk_mul_f32 v[78:79], v[78:79], s[52:53] op_sel_hi:[1,0]
	v_pk_mul_f32 v[68:69], v[80:81], v[68:69]
	v_exp_f32_e32 v78, v78
	v_exp_f32_e32 v79, v79
	s_nop 0
	v_pk_mul_f32 v[70:71], v[78:79], v[70:71]
	s_nop 0
	v_pk_mul_f32 v[78:79], v[76:77], v[70:71]
	v_pk_fma_f32 v[82:83], v[76:77], v[70:71], v[76:77] neg_lo:[1,0,0] neg_hi:[1,0,0]
	v_pk_mul_f32 v[70:71], v[72:73], s[52:53] op_sel_hi:[1,0]
	s_nop 0
	v_exp_f32_e32 v70, v70
	v_exp_f32_e32 v71, v71
	s_nop 0
	v_pk_mul_f32 v[68:69], v[70:71], v[68:69]
	s_nop 0
	v_pk_mul_f32 v[70:71], v[74:75], v[68:69]
	v_pk_fma_f32 v[72:73], v[74:75], v[68:69], v[74:75] neg_lo:[1,0,0] neg_hi:[1,0,0]
	s_nop 0
	v_cndmask_b32_e32 v69, v72, v70, vcc
	v_cmp_gt_f32_e32 vcc, 0, v76
	v_cvt_pk_bf16_f32 v72, v49, v51
	s_nop 0
	v_cndmask_b32_e32 v68, v82, v78, vcc
	v_cmp_gt_f32_e32 vcc, 0, v75
	s_nop 1
	v_cndmask_b32_e32 v71, v73, v71, vcc
	v_cmp_gt_f32_e32 vcc, 0, v77
	v_cvt_pk_bf16_f32 v73, v53, v55
	v_cvt_pk_bf16_f32 v75, v69, v71
	v_cndmask_b32_e32 v70, v83, v79, vcc
	v_cvt_pk_bf16_f32 v74, v68, v70
	s_and_b64 vcc, exec, s[4:5]
	global_store_dwordx4 v[66:67], v[72:75], off offset:256 sc1
	s_cbranch_vccnz .LBB0_244
	v_mov_b32_e32 v57, v49
	v_mov_b32_e32 v61, v51
	v_pk_mul_f32 v[72:73], v[56:57], v[56:57]
	v_pk_add_f32 v[86:87], v[48:49], v[56:57]
	v_pk_mul_f32 v[56:57], v[48:49], v[56:57]
	v_mov_b32_e32 v63, v53
	v_pk_mul_f32 v[66:67], v[48:49], v[48:49]
	v_pk_mul_f32 v[76:77], v[60:61], v[60:61]
	v_mov_b32_e32 v87, v57
	v_pk_add_f32 v[56:57], v[50:51], v[60:61]
	v_pk_mul_f32 v[60:61], v[50:51], v[60:61]
	v_mov_b32_e32 v59, v55
	v_pk_mul_f32 v[74:75], v[50:51], v[50:51]
	v_pk_mul_f32 v[80:81], v[62:63], v[62:63]
	v_mov_b32_e32 v57, v61
	v_pk_add_f32 v[60:61], v[52:53], v[62:63]
	v_pk_mul_f32 v[62:63], v[52:53], v[62:63]
	v_pk_mov_b32 v[48:49], v[48:49], v[66:67] op_sel:[1,0]
	v_pk_mov_b32 v[50:51], v[50:51], v[72:73] op_sel:[1,0]
	v_pk_mul_f32 v[78:79], v[52:53], v[52:53]
	v_pk_mul_f32 v[84:85], v[58:59], v[58:59]
	v_mov_b32_e32 v61, v63
	v_pk_add_f32 v[62:63], v[54:55], v[58:59]
	v_pk_mul_f32 v[58:59], v[54:55], v[58:59]
	v_pk_add_f32 v[48:49], v[48:49], v[50:51]
	v_pk_mov_b32 v[50:51], v[52:53], v[74:75] op_sel:[1,0]
	v_pk_mov_b32 v[52:53], v[54:55], v[76:77] op_sel:[1,0]
	v_mov_b32_e32 v63, v59
	v_pk_mul_f32 v[58:59], v[70:71], v[70:71]
	v_pk_add_f32 v[50:51], v[50:51], v[52:53]
	v_pk_mul_f32 v[82:83], v[54:55], v[54:55]
	v_pk_fma_f32 v[58:59], v[68:69], v[68:69], v[58:59]
	v_pk_add_f32 v[48:49], v[48:49], v[50:51]
	v_mov_b32_e32 v50, v68
	v_mov_b32_e32 v51, v78
	v_mov_b32_e32 v52, v70
	v_mov_b32_e32 v53, v80
	v_pk_add_f32 v[58:59], v[58:59], v[58:59] op_sel_hi:[0,1]
	v_cmp_lt_i32_e32 vcc, v248, v243
	v_pk_add_f32 v[50:51], v[50:51], v[52:53]
	v_pk_mov_b32 v[52:53], v[68:69], v[82:83] op_sel:[1,0]
	v_pk_mov_b32 v[54:55], v[70:71], v[84:85] op_sel:[1,0]
	v_cndmask_b32_e32 v58, v241, v248, vcc
	v_pk_add_f32 v[56:57], v[86:87], v[56:57]
	v_pk_add_f32 v[60:61], v[60:61], v[62:63]
	v_pk_add_f32 v[52:53], v[52:53], v[54:55]
	v_lshlrev_b32_e32 v79, 2, v58
	v_pk_add_f32 v[56:57], v[56:57], v[60:61]
	v_mov_b32_e32 v58, v153
	v_pk_add_f32 v[50:51], v[50:51], v[52:53]
	v_pk_add_f32 v[56:57], v[56:57], v[58:59]
	v_pk_add_f32 v[48:49], v[48:49], v[50:51]
	v_cmp_lt_i32_e32 vcc, v249, v243
	v_pk_add_f32 v[48:49], v[48:49], v[56:57]
	ds_bpermute_b32 v50, v79, v48
	ds_bpermute_b32 v51, v79, v49
	v_cndmask_b32_e32 v52, v241, v249, vcc
	v_lshlrev_b32_e32 v52, 2, v52
	s_waitcnt lgkmcnt(0)
	v_pk_add_f32 v[48:49], v[48:49], v[50:51]
	ds_bpermute_b32 v50, v52, v48
	ds_bpermute_b32 v51, v52, v49
	s_and_saveexec_b64 s[28:29], s[0:1]
	s_cbranch_execz .LBB0_243
	v_lshlrev_b64 v[52:53], 8, v[64:65]
	s_waitcnt lgkmcnt(0)
	v_pk_add_f32 v[48:49], v[48:49], v[50:51]
	v_lshl_add_u64 v[50:51], s[18:19], 0, v[52:53]
	v_lshl_add_u64 v[50:51], s[72:73], 3, v[50:51]
	global_store_dwordx2 v[50:51], v[48:49], off

; __device__ __forceinline__ f32x2 gelu_pk(f32x2 v) {
;     const f32x2 av = __builtin_elementwise_abs(v), d = av * 0.2316418882f + 1.0f;
;     f32x2 t; t.x = __builtin_amdgcn_rcpf(d.x); t.y = __builtin_amdgcn_rcpf(d.y);
;     f32x2 q = t * 0.5307027145f + (-0.7265760135f); q = q * t + 0.7107068705f; q = q * t + (-0.142248368f); q = q * t + 0.127414796f; q = q * t;
;     const f32x2 s = (v * v) * (-0.72134752044f);
;     f32x2 e; e.x = __builtin_amdgcn_exp2f(s.x); e.y = __builtin_amdgcn_exp2f(s.y);
;     const f32x2 m = v * (q * e), r = v - m;
;     f32x2 o; o.x = v.x < 0.f ? m.x : r.x; o.y = v.y < 0.f ? m.y : r.y; return o;
;     DI void operator()(const f32x4 (&acc)[2][2][4][2], const Unit& u, int wr, int wc, int fr, int fq) const {
;     ...
;                 const int r = u.pm * BM + ai * HALF + wr * 64 + m * 16 + fr; float s = 0.f, q = 0.f; const float rs = RS[r];
; #pragma unroll
;                 for (int bj = 0; bj < 2; ++bj) { const f32x4 a0 = acc[ai][bj][m][0] * rs, a1 = acc[ai][bj][m][1] * rs;
;                     const f32x2 g0 = gelu_pk((f32x2){a0[0], a0[1]}), g1 = gelu_pk((f32x2){a0[2], a0[3]}), g2 = gelu_pk((f32x2){a1[0], a1[1]}), g3 = gelu_pk((f32x2){a1[2], a1[3]});
.LBB0_244:
	v_add_u32_e32 v48, 0x90, v138
	v_ashrrev_i32_e32 v49, 31, v48
	s_waitcnt lgkmcnt(0)
	v_lshl_add_u64 v[50:51], v[48:49], 2, s[14:15]
	global_load_dword v54, v[50:51], off
	v_mov_b64_e32 v[52:53], s[80:81]
	v_lshlrev_b64 v[50:51], 12, v[48:49]
	v_lshl_add_u64 v[50:51], v[140:141], 0, v[50:51]
	s_waitcnt vmcnt(0)
	v_pk_mul_f32 v[44:45], v[44:45], v[54:55] op_sel_hi:[1,0]
	v_pk_mul_f32 v[46:47], v[46:47], v[54:55] op_sel_hi:[1,0]
	v_pk_mul_f32 v[42:43], v[42:43], v[54:55] op_sel_hi:[1,0]
	v_pk_mul_f32 v[56:57], v[40:41], v[54:55] op_sel_hi:[1,0]
	v_pk_mul_f32 v[60:61], v[32:33], v[54:55] op_sel_hi:[1,0]
	v_and_b32_e32 v33, 0x7fffffff, v45
	v_and_b32_e32 v32, 0x7fffffff, v44
	v_pk_mul_f32 v[38:39], v[38:39], v[54:55] op_sel_hi:[1,0]
	v_pk_mul_f32 v[36:37], v[36:37], v[54:55] op_sel_hi:[1,0]
	v_pk_mul_f32 v[58:59], v[34:35], v[54:55] op_sel_hi:[1,0]
	v_and_b32_e32 v55, 0x7fffffff, v47
	v_and_b32_e32 v54, 0x7fffffff, v46
	v_and_b32_e32 v63, 0x7fffffff, v57
	v_and_b32_e32 v62, 0x7fffffff, v56
	v_and_b32_e32 v69, 0x7fffffff, v43
	v_and_b32_e32 v68, 0x7fffffff, v42
	v_pk_fma_f32 v[32:33], v[32:33], s[76:77], 1.0 op_sel_hi:[1,0,0]
	v_pk_fma_f32 v[54:55], v[54:55], s[76:77], 1.0 op_sel_hi:[1,0,0]
	v_pk_fma_f32 v[62:63], v[62:63], s[76:77], 1.0 op_sel_hi:[1,0,0]
	v_pk_fma_f32 v[68:69], v[68:69], s[76:77], 1.0 op_sel_hi:[1,0,0]
	v_rcp_f32_e32 v32, v32
	v_rcp_f32_e32 v33, v33
	v_rcp_f32_e32 v54, v54
	v_rcp_f32_e32 v55, v55
	v_rcp_f32_e32 v62, v62
	v_rcp_f32_e32 v63, v63
	v_rcp_f32_e32 v68, v68
	v_rcp_f32_e32 v69, v69
	v_pk_mul_f32 v[40:41], v[44:45], v[44:45]
	v_pk_mul_f32 v[34:35], v[46:47], v[46:47]
	v_pk_mul_f32 v[64:65], v[42:43], v[42:43]
	v_pk_mul_f32 v[66:67], v[56:57], v[56:57]
	v_pk_mul_f32 v[40:41], v[40:41], s[52:53] op_sel_hi:[1,0]
	v_pk_fma_f32 v[76:77], v[32:33], s[78:79], v[52:53] op_sel_hi:[1,0,0]
	v_pk_mul_f32 v[34:35], v[34:35], s[52:53] op_sel_hi:[1,0]
	v_pk_mul_f32 v[66:67], v[66:67], s[52:53] op_sel_hi:[1,0]
	v_pk_mul_f32 v[64:65], v[64:65], s[52:53] op_sel_hi:[1,0]
	v_exp_f32_e32 v40, v40
	v_exp_f32_e32 v41, v41
	v_pk_fma_f32 v[78:79], v[54:55], s[78:79], v[52:53] op_sel_hi:[1,0,0]
	v_pk_fma_f32 v[80:81], v[62:63], s[78:79], v[52:53] op_sel_hi:[1,0,0]
	v_pk_fma_f32 v[82:83], v[68:69], s[78:79], v[52:53] op_sel_hi:[1,0,0]
	v_pk_fma_f32 v[76:77], v[32:33], v[76:77], s[96:97] op_sel_hi:[1,1,0]
	v_exp_f32_e32 v34, v34
	v_exp_f32_e32 v35, v35
	v_exp_f32_e32 v66, v66
	v_exp_f32_e32 v67, v67
	v_exp_f32_e32 v64, v64
	v_exp_f32_e32 v65, v65
	v_pk_fma_f32 v[78:79], v[54:55], v[78:79], s[96:97] op_sel_hi:[1,1,0]
	v_pk_fma_f32 v[80:81], v[62:63], v[80:81], s[96:97] op_sel_hi:[1,1,0]
	v_pk_fma_f32 v[82:83], v[68:69], v[82:83], s[96:97] op_sel_hi:[1,1,0]
	v_pk_fma_f32 v[76:77], v[32:33], v[76:77], s[48:49] op_sel_hi:[1,1,0]
	v_pk_fma_f32 v[78:79], v[54:55], v[78:79], s[48:49] op_sel_hi:[1,1,0]
	v_pk_fma_f32 v[80:81], v[62:63], v[80:81], s[48:49] op_sel_hi:[1,1,0]
	v_pk_fma_f32 v[82:83], v[68:69], v[82:83], s[48:49] op_sel_hi:[1,1,0]
	v_pk_fma_f32 v[76:77], v[32:33], v[76:77], s[50:51] op_sel_hi:[1,1,0]
	v_pk_fma_f32 v[78:79], v[54:55], v[78:79], s[50:51] op_sel_hi:[1,1,0]
	v_pk_fma_f32 v[80:81], v[62:63], v[80:81], s[50:51] op_sel_hi:[1,1,0]
	v_pk_fma_f32 v[82:83], v[68:69], v[82:83], s[50:51] op_sel_hi:[1,1,0]
	v_pk_mul_f32 v[32:33], v[32:33], v[76:77]
	v_pk_mul_f32 v[54:55], v[54:55], v[78:79]
	v_pk_mul_f32 v[62:63], v[62:63], v[80:81]
	v_pk_mul_f32 v[68:69], v[68:69], v[82:83]
	v_pk_mul_f32 v[32:33], v[40:41], v[32:33]
	v_and_b32_e32 v71, 0x7fffffff, v37
	v_and_b32_e32 v70, 0x7fffffff, v36
	v_pk_mul_f32 v[34:35], v[34:35], v[54:55]
	v_pk_mul_f32 v[40:41], v[66:67], v[62:63]
	v_pk_mul_f32 v[54:55], v[64:65], v[68:69]
	v_pk_mul_f32 v[62:63], v[44:45], v[32:33]
	v_pk_fma_f32 v[64:65], v[44:45], v[32:33], v[44:45] neg_lo:[1,0,0] neg_hi:[1,0,0]
	v_and_b32_e32 v33, 0x7fffffff, v39
	v_and_b32_e32 v32, 0x7fffffff, v38
	v_pk_fma_f32 v[70:71], v[70:71], s[76:77], 1.0 op_sel_hi:[1,0,0]
	v_pk_fma_f32 v[32:33], v[32:33], s[76:77], 1.0 op_sel_hi:[1,0,0]
	v_rcp_f32_e32 v70, v70
	v_rcp_f32_e32 v71, v71
	v_rcp_f32_e32 v32, v32
	v_rcp_f32_e32 v33, v33
	v_pk_mul_f32 v[72:73], v[38:39], v[38:39]
	v_pk_mul_f32 v[74:75], v[36:37], v[36:37]
	v_pk_fma_f32 v[84:85], v[70:71], s[78:79], v[52:53] op_sel_hi:[1,0,0]
	v_pk_mul_f32 v[74:75], v[74:75], s[52:53] op_sel_hi:[1,0]
	v_pk_mul_f32 v[76:77], v[56:57], v[40:41]
	v_pk_fma_f32 v[78:79], v[56:57], v[40:41], v[56:57] neg_lo:[1,0,0] neg_hi:[1,0,0]
	v_pk_fma_f32 v[40:41], v[32:33], s[78:79], v[52:53] op_sel_hi:[1,0,0]
	v_pk_mul_f32 v[72:73], v[72:73], s[52:53] op_sel_hi:[1,0]
	v_exp_f32_e32 v74, v74
	v_pk_fma_f32 v[84:85], v[70:71], v[84:85], s[96:97] op_sel_hi:[1,1,0]
	v_exp_f32_e32 v75, v75
	v_pk_fma_f32 v[40:41], v[32:33], v[40:41], s[96:97] op_sel_hi:[1,1,0]
	v_exp_f32_e32 v72, v72
	v_exp_f32_e32 v73, v73
	v_pk_fma_f32 v[84:85], v[70:71], v[84:85], s[48:49] op_sel_hi:[1,1,0]
	v_pk_fma_f32 v[40:41], v[32:33], v[40:41], s[48:49] op_sel_hi:[1,1,0]
	v_pk_fma_f32 v[84:85], v[70:71], v[84:85], s[50:51] op_sel_hi:[1,1,0]
	v_pk_fma_f32 v[40:41], v[32:33], v[40:41], s[50:51] op_sel_hi:[1,1,0]
	v_pk_mul_f32 v[70:71], v[70:71], v[84:85]
	v_pk_mul_f32 v[32:33], v[32:33], v[40:41]
	v_pk_mul_f32 v[66:67], v[46:47], v[34:35]
	v_pk_fma_f32 v[68:69], v[46:47], v[34:35], v[46:47] neg_lo:[1,0,0] neg_hi:[1,0,0]
	v_pk_mul_f32 v[34:35], v[74:75], v[70:71]
	v_pk_mul_f32 v[32:33], v[72:73], v[32:33]
	v_cmp_gt_f32_e32 vcc, 0, v44
	v_pk_mul_f32 v[70:71], v[36:37], v[34:35]
	v_pk_fma_f32 v[34:35], v[36:37], v[34:35], v[36:37] neg_lo:[1,0,0] neg_hi:[1,0,0]
	v_pk_mul_f32 v[72:73], v[38:39], v[32:33]
; DI unsigned pk2(float a, float b) { f32x2 v = {a, b}; hbf16x2 r = __builtin_convertvector(v, hbf16x2); return __builtin_bit_cast(unsigned, r); }
; __device__ __forceinline__ f32x2 gelu_pk(f32x2 v) {
;     const f32x2 av = __builtin_elementwise_abs(v), d = av * 0.2316418882f + 1.0f;
;     f32x2 t; t.x = __builtin_amdgcn_rcpf(d.x); t.y = __builtin_amdgcn_rcpf(d.y);
;     f32x2 q = t * 0.5307027145f + (-0.7265760135f); q = q * t + 0.7107068705f; q = q * t + (-0.142248368f); q = q * t + 0.127414796f; q = q * t;
;     const f32x2 s = (v * v) * (-0.72134752044f);
;     f32x2 e; e.x = __builtin_amdgcn_exp2f(s.x); e.y = __builtin_amdgcn_exp2f(s.y);
;     const f32x2 m = v * (q * e), r = v - m;
;     f32x2 o; o.x = v.x < 0.f ? m.x : r.x; o.y = v.y < 0.f ? m.y : r.y; return o;
;     DI void operator()(const f32x4 (&acc)[2][2][4][2], const Unit& u, int wr, int wc, int fr, int fq) const {
;     ...
;                 for (int bj = 0; bj < 2; ++bj) { const f32x4 a0 = acc[ai][bj][m][0] * rs, a1 = acc[ai][bj][m][1] * rs;
;                     const f32x2 g0 = gelu_pk((f32x2){a0[0], a0[1]}), g1 = gelu_pk((f32x2){a0[2], a0[3]}), g2 = gelu_pk((f32x2){a1[0], a1[1]}), g3 = gelu_pk((f32x2){a1[2], a1[3]});
;                     s += ((g0.x + g0.y) + (g1.x + g1.y)) + ((g2.x + g2.y) + (g3.x + g3.y));
;                     q += ((g0.x * g0.x + g0.y * g0.y) + (g1.x * g1.x + g1.y * g1.y)) + ((g2.x * g2.x + g2.y * g2.y) + (g3.x * g3.x + g3.y * g3.y));
;                     u32x4 w; w.x = pk2(g0.x, g0.y); w.y = pk2(g1.x, g1.y); w.z = pk2(g2.x, g2.y); w.w = pk2(g3.x, g3.y);
;                     *(u32x4*)(base + (size_t)r * 2048 + colt + bj * HALF) = w; }
;                 if (isv) { s += __shfl_xor(s, 16); s += __shfl_xor(s, 32); q += __shfl_xor(q, 16); q += __shfl_xor(q, 32);
;                     if (fq == 0) *(f32x2*)(STATS + ((size_t)r * 32 + (pn - 8) * 4 + wc) * 2) = (f32x2){s, q}; }
	v_pk_fma_f32 v[74:75], v[38:39], v[32:33], v[38:39] neg_lo:[1,0,0] neg_hi:[1,0,0]
	v_cndmask_b32_e32 v32, v64, v62, vcc
	v_cmp_gt_f32_e32 vcc, 0, v36
	v_pk_mul_f32 v[80:81], v[42:43], v[54:55]
	v_pk_fma_f32 v[54:55], v[42:43], v[54:55], v[42:43] neg_lo:[1,0,0] neg_hi:[1,0,0]
	v_cndmask_b32_e32 v33, v34, v70, vcc
	v_cmp_gt_f32_e32 vcc, 0, v45
	v_and_b32_e32 v64, 0x7fffffff, v58
	s_nop 0
	v_cndmask_b32_e32 v40, v65, v63, vcc
	v_cmp_gt_f32_e32 vcc, 0, v46
	v_and_b32_e32 v65, 0x7fffffff, v59
	v_pk_fma_f32 v[64:65], v[64:65], s[76:77], 1.0 op_sel_hi:[1,0,0]
	v_cndmask_b32_e32 v34, v68, v66, vcc
	v_cmp_gt_f32_e32 vcc, 0, v37
	v_rcp_f32_e32 v64, v64
	v_rcp_f32_e32 v65, v65
	v_cndmask_b32_e32 v35, v35, v71, vcc
	v_cmp_gt_f32_e32 vcc, 0, v47
	s_nop 1
	v_cndmask_b32_e32 v44, v69, v67, vcc
	v_cmp_gt_f32_e32 vcc, 0, v56
	v_and_b32_e32 v56, 0x7fffffff, v60
	s_nop 0
	v_cndmask_b32_e32 v36, v78, v76, vcc
	v_cmp_gt_f32_e32 vcc, 0, v38
	s_nop 1
	v_cndmask_b32_e32 v37, v74, v72, vcc
	v_cmp_gt_f32_e32 vcc, 0, v57
	v_and_b32_e32 v57, 0x7fffffff, v61
	v_pk_fma_f32 v[56:57], v[56:57], s[76:77], 1.0 op_sel_hi:[1,0,0]
	v_cndmask_b32_e32 v46, v79, v77, vcc
	v_cmp_gt_f32_e32 vcc, 0, v42
	v_rcp_f32_e32 v62, v56
	v_rcp_f32_e32 v63, v57
	v_cndmask_b32_e32 v38, v54, v80, vcc
	v_cmp_gt_f32_e32 vcc, 0, v39
	v_cvt_pk_bf16_f32 v54, v32, v40
	v_cvt_pk_bf16_f32 v56, v36, v46
	v_cndmask_b32_e32 v39, v75, v73, vcc
	v_cmp_gt_f32_e32 vcc, 0, v43
	s_nop 1
	v_cndmask_b32_e32 v42, v55, v81, vcc
	v_cvt_pk_bf16_f32 v55, v34, v44
	v_cvt_pk_bf16_f32 v57, v38, v42
	global_store_dwordx4 v[50:51], v[54:57], off sc1
	v_cmp_gt_f32_e32 vcc, 0, v58
	s_nop 0
	v_pk_fma_f32 v[54:55], v[62:63], s[78:79], v[52:53] op_sel_hi:[1,0,0]
	v_pk_mul_f32 v[56:57], v[58:59], v[58:59]
	v_pk_fma_f32 v[54:55], v[62:63], v[54:55], s[96:97] op_sel_hi:[1,1,0]
	v_pk_fma_f32 v[52:53], v[64:65], s[78:79], v[52:53] op_sel_hi:[1,0,0]
	v_pk_fma_f32 v[54:55], v[62:63], v[54:55], s[48:49] op_sel_hi:[1,1,0]
	v_pk_fma_f32 v[52:53], v[64:65], v[52:53], s[96:97] op_sel_hi:[1,1,0]
	v_pk_fma_f32 v[54:55], v[62:63], v[54:55], s[50:51] op_sel_hi:[1,1,0]
	v_pk_fma_f32 v[52:53], v[64:65], v[52:53], s[48:49] op_sel_hi:[1,1,0]
	v_pk_mul_f32 v[54:55], v[62:63], v[54:55]
	v_pk_mul_f32 v[62:63], v[60:61], v[60:61]
	v_pk_fma_f32 v[52:53], v[64:65], v[52:53], s[50:51] op_sel_hi:[1,1,0]
	v_pk_mul_f32 v[62:63], v[62:63], s[52:53] op_sel_hi:[1,0]
	v_pk_mul_f32 v[52:53], v[64:65], v[52:53]
	v_exp_f32_e32 v62, v62
	v_exp_f32_e32 v63, v63
	s_nop 0
	v_pk_mul_f32 v[54:55], v[62:63], v[54:55]
	s_nop 0
	v_pk_mul_f32 v[62:63], v[60:61], v[54:55]
	v_pk_fma_f32 v[66:67], v[60:61], v[54:55], v[60:61] neg_lo:[1,0,0] neg_hi:[1,0,0]
	v_pk_mul_f32 v[54:55], v[56:57], s[52:53] op_sel_hi:[1,0]
	s_nop 0
	v_exp_f32_e32 v54, v54
	v_exp_f32_e32 v55, v55
	s_nop 0
	v_pk_mul_f32 v[52:53], v[54:55], v[52:53]
	s_nop 0
	v_pk_mul_f32 v[54:55], v[58:59], v[52:53]
	v_pk_fma_f32 v[56:57], v[58:59], v[52:53], v[58:59] neg_lo:[1,0,0] neg_hi:[1,0,0]
	s_nop 0
	v_cndmask_b32_e32 v53, v56, v54, vcc
	v_cmp_gt_f32_e32 vcc, 0, v60
	v_cvt_pk_bf16_f32 v56, v33, v35
	s_nop 0
	v_cndmask_b32_e32 v52, v66, v62, vcc
	v_cmp_gt_f32_e32 vcc, 0, v59
	s_nop 1
	v_cndmask_b32_e32 v55, v57, v55, vcc
	v_cmp_gt_f32_e32 vcc, 0, v61
	v_cvt_pk_bf16_f32 v57, v37, v39
	v_cvt_pk_bf16_f32 v59, v53, v55
	v_cndmask_b32_e32 v54, v67, v63, vcc
	v_cvt_pk_bf16_f32 v58, v52, v54
	s_and_b64 vcc, exec, s[4:5]
	global_store_dwordx4 v[50:51], v[56:59], off offset:256 sc1
	s_cbranch_vccnz .LBB0_248
	v_mov_b32_e32 v41, v33
	v_mov_b32_e32 v45, v35
	v_pk_mul_f32 v[56:57], v[40:41], v[40:41]
	v_pk_add_f32 v[70:71], v[32:33], v[40:41]
	v_pk_mul_f32 v[40:41], v[32:33], v[40:41]
	v_mov_b32_e32 v47, v37
	v_pk_mul_f32 v[50:51], v[32:33], v[32:33]
	v_pk_mul_f32 v[60:61], v[44:45], v[44:45]
	v_mov_b32_e32 v71, v41
	v_pk_add_f32 v[40:41], v[34:35], v[44:45]
	v_pk_mul_f32 v[44:45], v[34:35], v[44:45]
	v_mov_b32_e32 v43, v39
	v_pk_mul_f32 v[58:59], v[34:35], v[34:35]
	v_pk_mul_f32 v[64:65], v[46:47], v[46:47]
	v_mov_b32_e32 v41, v45
	v_pk_add_f32 v[44:45], v[36:37], v[46:47]
	v_pk_mul_f32 v[46:47], v[36:37], v[46:47]
	v_pk_mov_b32 v[32:33], v[32:33], v[50:51] op_sel:[1,0]
	v_pk_mov_b32 v[34:35], v[34:35], v[56:57] op_sel:[1,0]
	v_pk_mul_f32 v[62:63], v[36:37], v[36:37]
	v_pk_mul_f32 v[68:69], v[42:43], v[42:43]
	v_mov_b32_e32 v45, v47
	v_pk_add_f32 v[46:47], v[38:39], v[42:43]
	v_pk_mul_f32 v[42:43], v[38:39], v[42:43]
	v_pk_add_f32 v[32:33], v[32:33], v[34:35]
	v_pk_mov_b32 v[34:35], v[36:37], v[58:59] op_sel:[1,0]
	v_pk_mov_b32 v[36:37], v[38:39], v[60:61] op_sel:[1,0]
	v_mov_b32_e32 v47, v43
	v_pk_mul_f32 v[42:43], v[54:55], v[54:55]
	v_pk_add_f32 v[34:35], v[34:35], v[36:37]
	v_pk_mul_f32 v[66:67], v[38:39], v[38:39]
	v_pk_fma_f32 v[42:43], v[52:53], v[52:53], v[42:43]
	v_pk_add_f32 v[32:33], v[32:33], v[34:35]
	v_mov_b32_e32 v34, v52
	v_mov_b32_e32 v35, v62
	v_mov_b32_e32 v36, v54
	v_mov_b32_e32 v37, v64
	v_pk_add_f32 v[42:43], v[42:43], v[42:43] op_sel_hi:[0,1]
	v_cmp_lt_i32_e32 vcc, v248, v243
	v_pk_add_f32 v[34:35], v[34:35], v[36:37]
	v_pk_mov_b32 v[36:37], v[52:53], v[66:67] op_sel:[1,0]
	v_pk_mov_b32 v[38:39], v[54:55], v[68:69] op_sel:[1,0]
	v_cndmask_b32_e32 v42, v241, v248, vcc
	v_pk_add_f32 v[40:41], v[70:71], v[40:41]
	v_pk_add_f32 v[44:45], v[44:45], v[46:47]
	v_pk_add_f32 v[36:37], v[36:37], v[38:39]
	v_lshlrev_b32_e32 v63, 2, v42
	v_pk_add_f32 v[40:41], v[40:41], v[44:45]
	v_mov_b32_e32 v42, v153
	v_pk_add_f32 v[34:35], v[34:35], v[36:37]
	v_pk_add_f32 v[40:41], v[40:41], v[42:43]
	v_pk_add_f32 v[32:33], v[32:33], v[34:35]
	v_cmp_lt_i32_e32 vcc, v249, v243
	v_pk_add_f32 v[32:33], v[32:33], v[40:41]
	ds_bpermute_b32 v34, v63, v32
	ds_bpermute_b32 v35, v63, v33
	v_cndmask_b32_e32 v36, v241, v249, vcc
	v_lshlrev_b32_e32 v36, 2, v36
	s_waitcnt lgkmcnt(0)
	v_pk_add_f32 v[32:33], v[32:33], v[34:35]
	ds_bpermute_b32 v34, v36, v32
	ds_bpermute_b32 v35, v36, v33
	s_and_saveexec_b64 s[28:29], s[0:1]
	s_cbranch_execz .LBB0_247
	v_lshlrev_b64 v[36:37], 8, v[48:49]
	s_waitcnt lgkmcnt(0)
	v_pk_add_f32 v[32:33], v[32:33], v[34:35]
	v_lshl_add_u64 v[34:35], s[18:19], 0, v[36:37]
	v_lshl_add_u64 v[34:35], s[72:73], 3, v[34:35]
	global_store_dwordx2 v[34:35], v[32:33], off

; __device__ __forceinline__ f32x2 gelu_pk(f32x2 v) {
;     const f32x2 av = __builtin_elementwise_abs(v), d = av * 0.2316418882f + 1.0f;
;     f32x2 t; t.x = __builtin_amdgcn_rcpf(d.x); t.y = __builtin_amdgcn_rcpf(d.y);
;     f32x2 q = t * 0.5307027145f + (-0.7265760135f); q = q * t + 0.7107068705f; q = q * t + (-0.142248368f); q = q * t + 0.127414796f; q = q * t;
;     const f32x2 s = (v * v) * (-0.72134752044f);
;     f32x2 e; e.x = __builtin_amdgcn_exp2f(s.x); e.y = __builtin_amdgcn_exp2f(s.y);
;     const f32x2 m = v * (q * e), r = v - m;
;     f32x2 o; o.x = v.x < 0.f ? m.x : r.x; o.y = v.y < 0.f ? m.y : r.y; return o;
;     DI void operator()(const f32x4 (&acc)[2][2][4][2], const Unit& u, int wr, int wc, int fr, int fq) const {
;     ...
;                 const int r = u.pm * BM + ai * HALF + wr * 64 + m * 16 + fr; float s = 0.f, q = 0.f; const float rs = RS[r];
; #pragma unroll
;                 for (int bj = 0; bj < 2; ++bj) { const f32x4 a0 = acc[ai][bj][m][0] * rs, a1 = acc[ai][bj][m][1] * rs;
;                     const f32x2 g0 = gelu_pk((f32x2){a0[0], a0[1]}), g1 = gelu_pk((f32x2){a0[2], a0[3]}), g2 = gelu_pk((f32x2){a1[0], a1[1]}), g3 = gelu_pk((f32x2){a1[2], a1[3]});
.LBB0_248:
	v_add_u32_e32 v32, 0xa0, v138
	v_ashrrev_i32_e32 v33, 31, v32
	s_waitcnt lgkmcnt(0)
	v_lshl_add_u64 v[34:35], v[32:33], 2, s[14:15]
	global_load_dword v38, v[34:35], off
	v_mov_b64_e32 v[36:37], s[80:81]
	v_lshlrev_b64 v[34:35], 12, v[32:33]
	v_lshl_add_u64 v[34:35], v[140:141], 0, v[34:35]
	s_waitcnt vmcnt(0)
	v_pk_mul_f32 v[28:29], v[28:29], v[38:39] op_sel_hi:[1,0]
	v_pk_mul_f32 v[30:31], v[30:31], v[38:39] op_sel_hi:[1,0]
	v_pk_mul_f32 v[26:27], v[26:27], v[38:39] op_sel_hi:[1,0]
	v_pk_mul_f32 v[40:41], v[24:25], v[38:39] op_sel_hi:[1,0]
	v_pk_mul_f32 v[44:45], v[16:17], v[38:39] op_sel_hi:[1,0]
	v_and_b32_e32 v17, 0x7fffffff, v29
	v_and_b32_e32 v16, 0x7fffffff, v28
	v_pk_mul_f32 v[22:23], v[22:23], v[38:39] op_sel_hi:[1,0]
	v_pk_mul_f32 v[20:21], v[20:21], v[38:39] op_sel_hi:[1,0]
	v_pk_mul_f32 v[42:43], v[18:19], v[38:39] op_sel_hi:[1,0]
	v_and_b32_e32 v39, 0x7fffffff, v31
	v_and_b32_e32 v38, 0x7fffffff, v30
	v_and_b32_e32 v47, 0x7fffffff, v41
	v_and_b32_e32 v46, 0x7fffffff, v40
	v_and_b32_e32 v53, 0x7fffffff, v27
	v_and_b32_e32 v52, 0x7fffffff, v26
	v_pk_fma_f32 v[16:17], v[16:17], s[76:77], 1.0 op_sel_hi:[1,0,0]
	v_pk_fma_f32 v[38:39], v[38:39], s[76:77], 1.0 op_sel_hi:[1,0,0]
	v_pk_fma_f32 v[46:47], v[46:47], s[76:77], 1.0 op_sel_hi:[1,0,0]
	v_pk_fma_f32 v[52:53], v[52:53], s[76:77], 1.0 op_sel_hi:[1,0,0]
	v_rcp_f32_e32 v16, v16
	v_rcp_f32_e32 v17, v17
	v_rcp_f32_e32 v38, v38
	v_rcp_f32_e32 v39, v39
	v_rcp_f32_e32 v46, v46
	v_rcp_f32_e32 v47, v47
	v_rcp_f32_e32 v52, v52
	v_rcp_f32_e32 v53, v53
	v_pk_mul_f32 v[24:25], v[28:29], v[28:29]
	v_pk_mul_f32 v[18:19], v[30:31], v[30:31]
	v_pk_mul_f32 v[48:49], v[26:27], v[26:27]
	v_pk_mul_f32 v[50:51], v[40:41], v[40:41]
	v_pk_mul_f32 v[24:25], v[24:25], s[52:53] op_sel_hi:[1,0]
	v_pk_fma_f32 v[60:61], v[16:17], s[78:79], v[36:37] op_sel_hi:[1,0,0]
	v_pk_mul_f32 v[18:19], v[18:19], s[52:53] op_sel_hi:[1,0]
	v_pk_mul_f32 v[50:51], v[50:51], s[52:53] op_sel_hi:[1,0]
	v_pk_mul_f32 v[48:49], v[48:49], s[52:53] op_sel_hi:[1,0]
	v_exp_f32_e32 v24, v24
	v_exp_f32_e32 v25, v25
	v_pk_fma_f32 v[62:63], v[38:39], s[78:79], v[36:37] op_sel_hi:[1,0,0]
	v_pk_fma_f32 v[64:65], v[46:47], s[78:79], v[36:37] op_sel_hi:[1,0,0]
	v_pk_fma_f32 v[66:67], v[52:53], s[78:79], v[36:37] op_sel_hi:[1,0,0]
	v_pk_fma_f32 v[60:61], v[16:17], v[60:61], s[96:97] op_sel_hi:[1,1,0]
	v_exp_f32_e32 v18, v18
	v_exp_f32_e32 v19, v19
	v_exp_f32_e32 v50, v50
	v_exp_f32_e32 v51, v51
	v_exp_f32_e32 v48, v48
	v_exp_f32_e32 v49, v49
	v_pk_fma_f32 v[62:63], v[38:39], v[62:63], s[96:97] op_sel_hi:[1,1,0]
	v_pk_fma_f32 v[64:65], v[46:47], v[64:65], s[96:97] op_sel_hi:[1,1,0]
	v_pk_fma_f32 v[66:67], v[52:53], v[66:67], s[96:97] op_sel_hi:[1,1,0]
	v_pk_fma_f32 v[60:61], v[16:17], v[60:61], s[48:49] op_sel_hi:[1,1,0]
	v_pk_fma_f32 v[62:63], v[38:39], v[62:63], s[48:49] op_sel_hi:[1,1,0]
	v_pk_fma_f32 v[64:65], v[46:47], v[64:65], s[48:49] op_sel_hi:[1,1,0]
	v_pk_fma_f32 v[66:67], v[52:53], v[66:67], s[48:49] op_sel_hi:[1,1,0]
	v_pk_fma_f32 v[60:61], v[16:17], v[60:61], s[50:51] op_sel_hi:[1,1,0]
	v_pk_fma_f32 v[62:63], v[38:39], v[62:63], s[50:51] op_sel_hi:[1,1,0]
	v_pk_fma_f32 v[64:65], v[46:47], v[64:65], s[50:51] op_sel_hi:[1,1,0]
	v_pk_fma_f32 v[66:67], v[52:53], v[66:67], s[50:51] op_sel_hi:[1,1,0]
	v_pk_mul_f32 v[16:17], v[16:17], v[60:61]
	v_pk_mul_f32 v[38:39], v[38:39], v[62:63]
	v_pk_mul_f32 v[46:47], v[46:47], v[64:65]
	v_pk_mul_f32 v[52:53], v[52:53], v[66:67]
	v_pk_mul_f32 v[16:17], v[24:25], v[16:17]
	v_and_b32_e32 v55, 0x7fffffff, v21
	v_and_b32_e32 v54, 0x7fffffff, v20
	v_pk_mul_f32 v[18:19], v[18:19], v[38:39]
	v_pk_mul_f32 v[24:25], v[50:51], v[46:47]
	v_pk_mul_f32 v[38:39], v[48:49], v[52:53]
	v_pk_mul_f32 v[46:47], v[28:29], v[16:17]
	v_pk_fma_f32 v[48:49], v[28:29], v[16:17], v[28:29] neg_lo:[1,0,0] neg_hi:[1,0,0]
	v_and_b32_e32 v17, 0x7fffffff, v23
	v_and_b32_e32 v16, 0x7fffffff, v22
	v_pk_fma_f32 v[54:55], v[54:55], s[76:77], 1.0 op_sel_hi:[1,0,0]
	v_pk_fma_f32 v[16:17], v[16:17], s[76:77], 1.0 op_sel_hi:[1,0,0]
	v_rcp_f32_e32 v54, v54
	v_rcp_f32_e32 v55, v55
	v_rcp_f32_e32 v16, v16
	v_rcp_f32_e32 v17, v17
	v_pk_mul_f32 v[56:57], v[22:23], v[22:23]
	v_pk_mul_f32 v[58:59], v[20:21], v[20:21]
	v_pk_fma_f32 v[68:69], v[54:55], s[78:79], v[36:37] op_sel_hi:[1,0,0]
	v_pk_mul_f32 v[58:59], v[58:59], s[52:53] op_sel_hi:[1,0]
	v_pk_mul_f32 v[60:61], v[40:41], v[24:25]
	v_pk_fma_f32 v[62:63], v[40:41], v[24:25], v[40:41] neg_lo:[1,0,0] neg_hi:[1,0,0]
	v_pk_fma_f32 v[24:25], v[16:17], s[78:79], v[36:37] op_sel_hi:[1,0,0]
	v_pk_mul_f32 v[56:57], v[56:57], s[52:53] op_sel_hi:[1,0]
	v_exp_f32_e32 v58, v58
	v_pk_fma_f32 v[68:69], v[54:55], v[68:69], s[96:97] op_sel_hi:[1,1,0]
	v_exp_f32_e32 v59, v59
	v_pk_fma_f32 v[24:25], v[16:17], v[24:25], s[96:97] op_sel_hi:[1,1,0]
	v_exp_f32_e32 v56, v56
	v_exp_f32_e32 v57, v57
	v_pk_fma_f32 v[68:69], v[54:55], v[68:69], s[48:49] op_sel_hi:[1,1,0]
	v_pk_fma_f32 v[24:25], v[16:17], v[24:25], s[48:49] op_sel_hi:[1,1,0]
	v_pk_fma_f32 v[68:69], v[54:55], v[68:69], s[50:51] op_sel_hi:[1,1,0]
	v_pk_fma_f32 v[24:25], v[16:17], v[24:25], s[50:51] op_sel_hi:[1,1,0]
	v_pk_mul_f32 v[54:55], v[54:55], v[68:69]
	v_pk_mul_f32 v[16:17], v[16:17], v[24:25]
	v_pk_mul_f32 v[50:51], v[30:31], v[18:19]
	v_pk_fma_f32 v[52:53], v[30:31], v[18:19], v[30:31] neg_lo:[1,0,0] neg_hi:[1,0,0]
	v_pk_mul_f32 v[18:19], v[58:59], v[54:55]
	v_pk_mul_f32 v[16:17], v[56:57], v[16:17]
	v_cmp_gt_f32_e32 vcc, 0, v28
	v_pk_mul_f32 v[54:55], v[20:21], v[18:19]
	v_pk_fma_f32 v[18:19], v[20:21], v[18:19], v[20:21] neg_lo:[1,0,0] neg_hi:[1,0,0]
	v_pk_mul_f32 v[56:57], v[22:23], v[16:17]
; DI unsigned pk2(float a, float b) { f32x2 v = {a, b}; hbf16x2 r = __builtin_convertvector(v, hbf16x2); return __builtin_bit_cast(unsigned, r); }
;     DI void operator()(const f32x4 (&acc)[2][2][4][2], const Unit& u, int wr, int wc, int fr, int fq) const {
;     ...
;                 for (int bj = 0; bj < 2; ++bj) { const f32x4 a0 = acc[ai][bj][m][0] * rs, a1 = acc[ai][bj][m][1] * rs;
;                     const f32x2 g0 = gelu_pk((f32x2){a0[0], a0[1]}), g1 = gelu_pk((f32x2){a0[2], a0[3]}), g2 = gelu_pk((f32x2){a1[0], a1[1]}), g3 = gelu_pk((f32x2){a1[2], a1[3]});
;                     s += ((g0.x + g0.y) + (g1.x + g1.y)) + ((g2.x + g2.y) + (g3.x + g3.y));
;                     q += ((g0.x * g0.x + g0.y * g0.y) + (g1.x * g1.x + g1.y * g1.y)) + ((g2.x * g2.x + g2.y * g2.y) + (g3.x * g3.x + g3.y * g3.y));
;                     u32x4 w; w.x = pk2(g0.x, g0.y); w.y = pk2(g1.x, g1.y); w.z = pk2(g2.x, g2.y); w.w = pk2(g3.x, g3.y);
;                     *(u32x4*)(base + (size_t)r * 2048 + colt + bj * HALF) = w; }
;                 if (isv) { s += __shfl_xor(s, 16); s += __shfl_xor(s, 32); q += __shfl_xor(q, 16); q += __shfl_xor(q, 32);
;                     if (fq == 0) *(f32x2*)(STATS + ((size_t)r * 32 + (pn - 8) * 4 + wc) * 2) = (f32x2){s, q}; }
	v_pk_fma_f32 v[58:59], v[22:23], v[16:17], v[22:23] neg_lo:[1,0,0] neg_hi:[1,0,0]
	v_cndmask_b32_e32 v16, v48, v46, vcc
	v_cmp_gt_f32_e32 vcc, 0, v20
	v_pk_mul_f32 v[64:65], v[26:27], v[38:39]
	v_pk_fma_f32 v[38:39], v[26:27], v[38:39], v[26:27] neg_lo:[1,0,0] neg_hi:[1,0,0]
	v_cndmask_b32_e32 v17, v18, v54, vcc
	v_cmp_gt_f32_e32 vcc, 0, v29
	v_and_b32_e32 v48, 0x7fffffff, v42
	s_nop 0
	v_cndmask_b32_e32 v24, v49, v47, vcc
	v_cmp_gt_f32_e32 vcc, 0, v30
	v_and_b32_e32 v49, 0x7fffffff, v43
	v_pk_fma_f32 v[48:49], v[48:49], s[76:77], 1.0 op_sel_hi:[1,0,0]
	v_cndmask_b32_e32 v18, v52, v50, vcc
	v_cmp_gt_f32_e32 vcc, 0, v21
	v_rcp_f32_e32 v48, v48
	v_rcp_f32_e32 v49, v49
	v_cndmask_b32_e32 v19, v19, v55, vcc
	v_cmp_gt_f32_e32 vcc, 0, v31
	s_nop 1
	v_cndmask_b32_e32 v28, v53, v51, vcc
	v_cmp_gt_f32_e32 vcc, 0, v40
	v_and_b32_e32 v40, 0x7fffffff, v44
	s_nop 0
	v_cndmask_b32_e32 v20, v62, v60, vcc
	v_cmp_gt_f32_e32 vcc, 0, v22
	s_nop 1
	v_cndmask_b32_e32 v21, v58, v56, vcc
	v_cmp_gt_f32_e32 vcc, 0, v41
	v_and_b32_e32 v41, 0x7fffffff, v45
	v_pk_fma_f32 v[40:41], v[40:41], s[76:77], 1.0 op_sel_hi:[1,0,0]
	v_cndmask_b32_e32 v30, v63, v61, vcc
	v_cmp_gt_f32_e32 vcc, 0, v26
	v_rcp_f32_e32 v46, v40
	v_rcp_f32_e32 v47, v41
	v_cndmask_b32_e32 v22, v38, v64, vcc
	v_cmp_gt_f32_e32 vcc, 0, v23
	v_cvt_pk_bf16_f32 v38, v16, v24
	v_cvt_pk_bf16_f32 v40, v20, v30
	v_cndmask_b32_e32 v23, v59, v57, vcc
	v_cmp_gt_f32_e32 vcc, 0, v27
	s_nop 1
	v_cndmask_b32_e32 v26, v39, v65, vcc
	v_cvt_pk_bf16_f32 v39, v18, v28
	v_cvt_pk_bf16_f32 v41, v22, v26
	global_store_dwordx4 v[34:35], v[38:41], off sc1
	v_cmp_gt_f32_e32 vcc, 0, v42
	s_nop 0
	v_pk_fma_f32 v[38:39], v[46:47], s[78:79], v[36:37] op_sel_hi:[1,0,0]
	v_pk_mul_f32 v[40:41], v[42:43], v[42:43]
	v_pk_fma_f32 v[38:39], v[46:47], v[38:39], s[96:97] op_sel_hi:[1,1,0]
	v_pk_fma_f32 v[36:37], v[48:49], s[78:79], v[36:37] op_sel_hi:[1,0,0]
	v_pk_fma_f32 v[38:39], v[46:47], v[38:39], s[48:49] op_sel_hi:[1,1,0]
	v_pk_fma_f32 v[36:37], v[48:49], v[36:37], s[96:97] op_sel_hi:[1,1,0]
	v_pk_fma_f32 v[38:39], v[46:47], v[38:39], s[50:51] op_sel_hi:[1,1,0]
	v_pk_fma_f32 v[36:37], v[48:49], v[36:37], s[48:49] op_sel_hi:[1,1,0]
	v_pk_mul_f32 v[38:39], v[46:47], v[38:39]
	v_pk_mul_f32 v[46:47], v[44:45], v[44:45]
	v_pk_fma_f32 v[36:37], v[48:49], v[36:37], s[50:51] op_sel_hi:[1,1,0]
	v_pk_mul_f32 v[46:47], v[46:47], s[52:53] op_sel_hi:[1,0]
	v_pk_mul_f32 v[36:37], v[48:49], v[36:37]
	v_exp_f32_e32 v46, v46
	v_exp_f32_e32 v47, v47
	s_nop 0
	v_pk_mul_f32 v[38:39], v[46:47], v[38:39]
	s_nop 0
	v_pk_mul_f32 v[46:47], v[44:45], v[38:39]
	v_pk_fma_f32 v[50:51], v[44:45], v[38:39], v[44:45] neg_lo:[1,0,0] neg_hi:[1,0,0]
	v_pk_mul_f32 v[38:39], v[40:41], s[52:53] op_sel_hi:[1,0]
	s_nop 0
	v_exp_f32_e32 v38, v38
	v_exp_f32_e32 v39, v39
	s_nop 0
	v_pk_mul_f32 v[36:37], v[38:39], v[36:37]
	s_nop 0
	v_pk_mul_f32 v[38:39], v[42:43], v[36:37]
	v_pk_fma_f32 v[40:41], v[42:43], v[36:37], v[42:43] neg_lo:[1,0,0] neg_hi:[1,0,0]
	s_nop 0
	v_cndmask_b32_e32 v37, v40, v38, vcc
	v_cmp_gt_f32_e32 vcc, 0, v44
	v_cvt_pk_bf16_f32 v40, v17, v19
	s_nop 0
	v_cndmask_b32_e32 v36, v50, v46, vcc
	v_cmp_gt_f32_e32 vcc, 0, v43
	s_nop 1
	v_cndmask_b32_e32 v39, v41, v39, vcc
	v_cmp_gt_f32_e32 vcc, 0, v45
	v_cvt_pk_bf16_f32 v41, v21, v23
	v_cvt_pk_bf16_f32 v43, v37, v39
	v_cndmask_b32_e32 v38, v51, v47, vcc
	v_cvt_pk_bf16_f32 v42, v36, v38
	s_and_b64 vcc, exec, s[4:5]
	global_store_dwordx4 v[34:35], v[40:43], off offset:256 sc1
	s_cbranch_vccnz .LBB0_252
	v_mov_b32_e32 v25, v17
	v_mov_b32_e32 v29, v19
	v_pk_mul_f32 v[40:41], v[24:25], v[24:25]
	v_pk_add_f32 v[54:55], v[16:17], v[24:25]
	v_pk_mul_f32 v[24:25], v[16:17], v[24:25]
	v_mov_b32_e32 v31, v21
	v_pk_mul_f32 v[34:35], v[16:17], v[16:17]
	v_pk_mul_f32 v[44:45], v[28:29], v[28:29]
	v_mov_b32_e32 v55, v25
	v_pk_add_f32 v[24:25], v[18:19], v[28:29]
	v_pk_mul_f32 v[28:29], v[18:19], v[28:29]
	v_mov_b32_e32 v27, v23
	v_pk_mul_f32 v[42:43], v[18:19], v[18:19]
	v_pk_mul_f32 v[48:49], v[30:31], v[30:31]
	v_mov_b32_e32 v25, v29
	v_pk_add_f32 v[28:29], v[20:21], v[30:31]
	v_pk_mul_f32 v[30:31], v[20:21], v[30:31]
	v_pk_mov_b32 v[16:17], v[16:17], v[34:35] op_sel:[1,0]
	v_pk_mov_b32 v[18:19], v[18:19], v[40:41] op_sel:[1,0]
	v_pk_mul_f32 v[46:47], v[20:21], v[20:21]
	v_pk_mul_f32 v[52:53], v[26:27], v[26:27]
	v_mov_b32_e32 v29, v31
	v_pk_add_f32 v[30:31], v[22:23], v[26:27]
	v_pk_mul_f32 v[26:27], v[22:23], v[26:27]
	v_pk_add_f32 v[16:17], v[16:17], v[18:19]
	v_pk_mov_b32 v[18:19], v[20:21], v[42:43] op_sel:[1,0]
	v_pk_mov_b32 v[20:21], v[22:23], v[44:45] op_sel:[1,0]
	v_mov_b32_e32 v31, v27
	v_pk_mul_f32 v[26:27], v[38:39], v[38:39]
	v_pk_add_f32 v[18:19], v[18:19], v[20:21]
	v_pk_mul_f32 v[50:51], v[22:23], v[22:23]
	v_pk_fma_f32 v[26:27], v[36:37], v[36:37], v[26:27]
	v_pk_add_f32 v[16:17], v[16:17], v[18:19]
	v_mov_b32_e32 v18, v36
	v_mov_b32_e32 v19, v46
	v_mov_b32_e32 v20, v38
	v_mov_b32_e32 v21, v48
	v_pk_add_f32 v[26:27], v[26:27], v[26:27] op_sel_hi:[0,1]
	v_cmp_lt_i32_e32 vcc, v248, v243
	v_pk_add_f32 v[18:19], v[18:19], v[20:21]
	v_pk_mov_b32 v[20:21], v[36:37], v[50:51] op_sel:[1,0]
	v_pk_mov_b32 v[22:23], v[38:39], v[52:53] op_sel:[1,0]
	v_cndmask_b32_e32 v26, v241, v248, vcc
	v_pk_add_f32 v[24:25], v[54:55], v[24:25]
	v_pk_add_f32 v[28:29], v[28:29], v[30:31]
	v_pk_add_f32 v[20:21], v[20:21], v[22:23]
	v_lshlrev_b32_e32 v47, 2, v26
	v_pk_add_f32 v[24:25], v[24:25], v[28:29]
	v_mov_b32_e32 v26, v153
	v_pk_add_f32 v[18:19], v[18:19], v[20:21]
	v_pk_add_f32 v[24:25], v[24:25], v[26:27]
	v_pk_add_f32 v[16:17], v[16:17], v[18:19]
	v_cmp_lt_i32_e32 vcc, v249, v243
	v_pk_add_f32 v[16:17], v[16:17], v[24:25]
	ds_bpermute_b32 v18, v47, v16
	ds_bpermute_b32 v19, v47, v17
	v_cndmask_b32_e32 v20, v241, v249, vcc
	v_lshlrev_b32_e32 v20, 2, v20
	s_waitcnt lgkmcnt(0)
	v_pk_add_f32 v[16:17], v[16:17], v[18:19]
	ds_bpermute_b32 v18, v20, v16
	ds_bpermute_b32 v19, v20, v17
	s_and_saveexec_b64 s[28:29], s[0:1]
	s_cbranch_execz .LBB0_251
	v_lshlrev_b64 v[20:21], 8, v[32:33]
	s_waitcnt lgkmcnt(0)
	v_pk_add_f32 v[16:17], v[16:17], v[18:19]
	v_lshl_add_u64 v[18:19], s[18:19], 0, v[20:21]
	v_lshl_add_u64 v[18:19], s[72:73], 3, v[18:19]
	global_store_dwordx2 v[18:19], v[16:17], off

; __device__ __forceinline__ f32x2 gelu_pk(f32x2 v) {
;     const f32x2 av = __builtin_elementwise_abs(v), d = av * 0.2316418882f + 1.0f;
;     f32x2 t; t.x = __builtin_amdgcn_rcpf(d.x); t.y = __builtin_amdgcn_rcpf(d.y);
;     f32x2 q = t * 0.5307027145f + (-0.7265760135f); q = q * t + 0.7107068705f; q = q * t + (-0.142248368f); q = q * t + 0.127414796f; q = q * t;
;     const f32x2 s = (v * v) * (-0.72134752044f);
;     f32x2 e; e.x = __builtin_amdgcn_exp2f(s.x); e.y = __builtin_amdgcn_exp2f(s.y);
;     const f32x2 m = v * (q * e), r = v - m;
;     f32x2 o; o.x = v.x < 0.f ? m.x : r.x; o.y = v.y < 0.f ? m.y : r.y; return o;
;     DI void operator()(const f32x4 (&acc)[2][2][4][2], const Unit& u, int wr, int wc, int fr, int fq) const {
;     ...
;                 const int r = u.pm * BM + ai * HALF + wr * 64 + m * 16 + fr; float s = 0.f, q = 0.f; const float rs = RS[r];
; #pragma unroll
;                 for (int bj = 0; bj < 2; ++bj) { const f32x4 a0 = acc[ai][bj][m][0] * rs, a1 = acc[ai][bj][m][1] * rs;
;                     const f32x2 g0 = gelu_pk((f32x2){a0[0], a0[1]}), g1 = gelu_pk((f32x2){a0[2], a0[3]}), g2 = gelu_pk((f32x2){a1[0], a1[1]}), g3 = gelu_pk((f32x2){a1[2], a1[3]});
.LBB0_252:
	v_add_u32_e32 v16, 0xb0, v138
	v_ashrrev_i32_e32 v17, 31, v16
	s_waitcnt lgkmcnt(0)
	v_lshl_add_u64 v[18:19], v[16:17], 2, s[14:15]
	global_load_dword v22, v[18:19], off
	v_mov_b64_e32 v[20:21], s[80:81]
	v_lshlrev_b64 v[18:19], 12, v[16:17]
	v_lshl_add_u64 v[18:19], v[140:141], 0, v[18:19]
	s_waitcnt vmcnt(0)
	v_pk_mul_f32 v[12:13], v[12:13], v[22:23] op_sel_hi:[1,0]
	v_pk_mul_f32 v[14:15], v[14:15], v[22:23] op_sel_hi:[1,0]
	v_pk_mul_f32 v[10:11], v[10:11], v[22:23] op_sel_hi:[1,0]
	v_pk_mul_f32 v[24:25], v[8:9], v[22:23] op_sel_hi:[1,0]
	v_pk_mul_f32 v[28:29], v[0:1], v[22:23] op_sel_hi:[1,0]
	v_and_b32_e32 v1, 0x7fffffff, v13
	v_and_b32_e32 v0, 0x7fffffff, v12
	v_pk_mul_f32 v[6:7], v[6:7], v[22:23] op_sel_hi:[1,0]
	v_pk_mul_f32 v[4:5], v[4:5], v[22:23] op_sel_hi:[1,0]
	v_pk_mul_f32 v[26:27], v[2:3], v[22:23] op_sel_hi:[1,0]
	v_and_b32_e32 v23, 0x7fffffff, v15
	v_and_b32_e32 v22, 0x7fffffff, v14
	v_and_b32_e32 v31, 0x7fffffff, v25
	v_and_b32_e32 v30, 0x7fffffff, v24
	v_and_b32_e32 v37, 0x7fffffff, v11
	v_and_b32_e32 v36, 0x7fffffff, v10
	v_pk_fma_f32 v[0:1], v[0:1], s[76:77], 1.0 op_sel_hi:[1,0,0]
	v_pk_fma_f32 v[22:23], v[22:23], s[76:77], 1.0 op_sel_hi:[1,0,0]
	v_pk_fma_f32 v[30:31], v[30:31], s[76:77], 1.0 op_sel_hi:[1,0,0]
	v_pk_fma_f32 v[36:37], v[36:37], s[76:77], 1.0 op_sel_hi:[1,0,0]
	v_rcp_f32_e32 v0, v0
	v_rcp_f32_e32 v1, v1
	v_rcp_f32_e32 v22, v22
	v_rcp_f32_e32 v23, v23
	v_rcp_f32_e32 v30, v30
	v_rcp_f32_e32 v31, v31
	v_rcp_f32_e32 v36, v36
	v_rcp_f32_e32 v37, v37
	v_pk_mul_f32 v[8:9], v[12:13], v[12:13]
	v_pk_mul_f32 v[2:3], v[14:15], v[14:15]
	v_pk_mul_f32 v[32:33], v[10:11], v[10:11]
	v_pk_mul_f32 v[34:35], v[24:25], v[24:25]
	v_pk_mul_f32 v[8:9], v[8:9], s[52:53] op_sel_hi:[1,0]
	v_pk_fma_f32 v[44:45], v[0:1], s[78:79], v[20:21] op_sel_hi:[1,0,0]
	v_pk_mul_f32 v[2:3], v[2:3], s[52:53] op_sel_hi:[1,0]
	v_pk_mul_f32 v[34:35], v[34:35], s[52:53] op_sel_hi:[1,0]
	v_pk_mul_f32 v[32:33], v[32:33], s[52:53] op_sel_hi:[1,0]
	v_exp_f32_e32 v8, v8
	v_exp_f32_e32 v9, v9
	v_pk_fma_f32 v[46:47], v[22:23], s[78:79], v[20:21] op_sel_hi:[1,0,0]
	v_pk_fma_f32 v[48:49], v[30:31], s[78:79], v[20:21] op_sel_hi:[1,0,0]
	v_pk_fma_f32 v[50:51], v[36:37], s[78:79], v[20:21] op_sel_hi:[1,0,0]
	v_pk_fma_f32 v[44:45], v[0:1], v[44:45], s[96:97] op_sel_hi:[1,1,0]
	v_exp_f32_e32 v2, v2
	v_exp_f32_e32 v3, v3
	v_exp_f32_e32 v34, v34
	v_exp_f32_e32 v35, v35
	v_exp_f32_e32 v32, v32
	v_exp_f32_e32 v33, v33
	v_pk_fma_f32 v[46:47], v[22:23], v[46:47], s[96:97] op_sel_hi:[1,1,0]
	v_pk_fma_f32 v[48:49], v[30:31], v[48:49], s[96:97] op_sel_hi:[1,1,0]
	v_pk_fma_f32 v[50:51], v[36:37], v[50:51], s[96:97] op_sel_hi:[1,1,0]
	v_pk_fma_f32 v[44:45], v[0:1], v[44:45], s[48:49] op_sel_hi:[1,1,0]
	v_pk_fma_f32 v[46:47], v[22:23], v[46:47], s[48:49] op_sel_hi:[1,1,0]
	v_pk_fma_f32 v[48:49], v[30:31], v[48:49], s[48:49] op_sel_hi:[1,1,0]
	v_pk_fma_f32 v[50:51], v[36:37], v[50:51], s[48:49] op_sel_hi:[1,1,0]
	v_pk_fma_f32 v[44:45], v[0:1], v[44:45], s[50:51] op_sel_hi:[1,1,0]
	v_pk_fma_f32 v[46:47], v[22:23], v[46:47], s[50:51] op_sel_hi:[1,1,0]
	v_pk_fma_f32 v[48:49], v[30:31], v[48:49], s[50:51] op_sel_hi:[1,1,0]
	v_pk_fma_f32 v[50:51], v[36:37], v[50:51], s[50:51] op_sel_hi:[1,1,0]
	v_pk_mul_f32 v[0:1], v[0:1], v[44:45]
	v_pk_mul_f32 v[22:23], v[22:23], v[46:47]
	v_pk_mul_f32 v[30:31], v[30:31], v[48:49]
	v_pk_mul_f32 v[36:37], v[36:37], v[50:51]
	v_pk_mul_f32 v[0:1], v[8:9], v[0:1]
	v_and_b32_e32 v39, 0x7fffffff, v5
	v_and_b32_e32 v38, 0x7fffffff, v4
	v_pk_mul_f32 v[2:3], v[2:3], v[22:23]
	v_pk_mul_f32 v[8:9], v[34:35], v[30:31]
	v_pk_mul_f32 v[22:23], v[32:33], v[36:37]
	v_pk_mul_f32 v[30:31], v[12:13], v[0:1]
	v_pk_fma_f32 v[32:33], v[12:13], v[0:1], v[12:13] neg_lo:[1,0,0] neg_hi:[1,0,0]
	v_and_b32_e32 v1, 0x7fffffff, v7
	v_and_b32_e32 v0, 0x7fffffff, v6
	v_pk_fma_f32 v[38:39], v[38:39], s[76:77], 1.0 op_sel_hi:[1,0,0]
	v_pk_fma_f32 v[0:1], v[0:1], s[76:77], 1.0 op_sel_hi:[1,0,0]
	v_rcp_f32_e32 v38, v38
	v_rcp_f32_e32 v39, v39
	v_rcp_f32_e32 v0, v0
	v_rcp_f32_e32 v1, v1
	v_pk_mul_f32 v[40:41], v[6:7], v[6:7]
	v_pk_mul_f32 v[42:43], v[4:5], v[4:5]
	v_pk_fma_f32 v[52:53], v[38:39], s[78:79], v[20:21] op_sel_hi:[1,0,0]
	v_pk_mul_f32 v[42:43], v[42:43], s[52:53] op_sel_hi:[1,0]
	v_pk_mul_f32 v[44:45], v[24:25], v[8:9]
	v_pk_fma_f32 v[46:47], v[24:25], v[8:9], v[24:25] neg_lo:[1,0,0] neg_hi:[1,0,0]
	v_pk_fma_f32 v[8:9], v[0:1], s[78:79], v[20:21] op_sel_hi:[1,0,0]
	v_pk_mul_f32 v[40:41], v[40:41], s[52:53] op_sel_hi:[1,0]
	v_exp_f32_e32 v42, v42
	v_pk_fma_f32 v[52:53], v[38:39], v[52:53], s[96:97] op_sel_hi:[1,1,0]
	v_exp_f32_e32 v43, v43
	v_pk_fma_f32 v[8:9], v[0:1], v[8:9], s[96:97] op_sel_hi:[1,1,0]
	v_exp_f32_e32 v40, v40
	v_exp_f32_e32 v41, v41
	v_pk_fma_f32 v[52:53], v[38:39], v[52:53], s[48:49] op_sel_hi:[1,1,0]
	v_pk_fma_f32 v[8:9], v[0:1], v[8:9], s[48:49] op_sel_hi:[1,1,0]
	v_pk_fma_f32 v[52:53], v[38:39], v[52:53], s[50:51] op_sel_hi:[1,1,0]
	v_pk_fma_f32 v[8:9], v[0:1], v[8:9], s[50:51] op_sel_hi:[1,1,0]
	v_pk_mul_f32 v[38:39], v[38:39], v[52:53]
	v_pk_mul_f32 v[0:1], v[0:1], v[8:9]
	v_pk_mul_f32 v[34:35], v[14:15], v[2:3]
	v_pk_fma_f32 v[36:37], v[14:15], v[2:3], v[14:15] neg_lo:[1,0,0] neg_hi:[1,0,0]
	v_pk_mul_f32 v[2:3], v[42:43], v[38:39]
	v_pk_mul_f32 v[0:1], v[40:41], v[0:1]
	v_cmp_gt_f32_e32 vcc, 0, v12
	v_pk_mul_f32 v[38:39], v[4:5], v[2:3]
	v_pk_fma_f32 v[2:3], v[4:5], v[2:3], v[4:5] neg_lo:[1,0,0] neg_hi:[1,0,0]
	v_pk_mul_f32 v[40:41], v[6:7], v[0:1]
	v_pk_fma_f32 v[42:43], v[6:7], v[0:1], v[6:7] neg_lo:[1,0,0] neg_hi:[1,0,0]
	v_cndmask_b32_e32 v0, v32, v30, vcc
	v_cmp_gt_f32_e32 vcc, 0, v4
	v_pk_mul_f32 v[48:49], v[10:11], v[22:23]
; DI unsigned pk2(float a, float b) { f32x2 v = {a, b}; hbf16x2 r = __builtin_convertvector(v, hbf16x2); return __builtin_bit_cast(unsigned, r); }
;     DI void operator()(const f32x4 (&acc)[2][2][4][2], const Unit& u, int wr, int wc, int fr, int fq) const {
;     ...
;                     const f32x2 g0 = gelu_pk((f32x2){a0[0], a0[1]}), g1 = gelu_pk((f32x2){a0[2], a0[3]}), g2 = gelu_pk((f32x2){a1[0], a1[1]}), g3 = gelu_pk((f32x2){a1[2], a1[3]});
;                     s += ((g0.x + g0.y) + (g1.x + g1.y)) + ((g2.x + g2.y) + (g3.x + g3.y));
;                     q += ((g0.x * g0.x + g0.y * g0.y) + (g1.x * g1.x + g1.y * g1.y)) + ((g2.x * g2.x + g2.y * g2.y) + (g3.x * g3.x + g3.y * g3.y));
;                     u32x4 w; w.x = pk2(g0.x, g0.y); w.y = pk2(g1.x, g1.y); w.z = pk2(g2.x, g2.y); w.w = pk2(g3.x, g3.y);
;                     *(u32x4*)(base + (size_t)r * 2048 + colt + bj * HALF) = w; }
;                 if (isv) { s += __shfl_xor(s, 16); s += __shfl_xor(s, 32); q += __shfl_xor(q, 16); q += __shfl_xor(q, 32);
;                     if (fq == 0) *(f32x2*)(STATS + ((size_t)r * 32 + (pn - 8) * 4 + wc) * 2) = (f32x2){s, q}; }
	v_pk_fma_f32 v[22:23], v[10:11], v[22:23], v[10:11] neg_lo:[1,0,0] neg_hi:[1,0,0]
	v_cndmask_b32_e32 v1, v2, v38, vcc
	v_cmp_gt_f32_e32 vcc, 0, v13
	v_and_b32_e32 v32, 0x7fffffff, v26
	s_nop 0
	v_cndmask_b32_e32 v8, v33, v31, vcc
	v_cmp_gt_f32_e32 vcc, 0, v14
	v_and_b32_e32 v33, 0x7fffffff, v27
	v_pk_fma_f32 v[32:33], v[32:33], s[76:77], 1.0 op_sel_hi:[1,0,0]
	v_cndmask_b32_e32 v2, v36, v34, vcc
	v_cmp_gt_f32_e32 vcc, 0, v5
	v_rcp_f32_e32 v32, v32
	v_rcp_f32_e32 v33, v33
	v_cndmask_b32_e32 v3, v3, v39, vcc
	v_cmp_gt_f32_e32 vcc, 0, v15
	s_nop 1
	v_cndmask_b32_e32 v12, v37, v35, vcc
	v_cmp_gt_f32_e32 vcc, 0, v24
	v_and_b32_e32 v24, 0x7fffffff, v28
	s_nop 0
	v_cndmask_b32_e32 v4, v46, v44, vcc
	v_cmp_gt_f32_e32 vcc, 0, v6
	s_nop 1
	v_cndmask_b32_e32 v5, v42, v40, vcc
	v_cmp_gt_f32_e32 vcc, 0, v25
	v_and_b32_e32 v25, 0x7fffffff, v29
	v_pk_fma_f32 v[24:25], v[24:25], s[76:77], 1.0 op_sel_hi:[1,0,0]
	v_cndmask_b32_e32 v14, v47, v45, vcc
	v_cmp_gt_f32_e32 vcc, 0, v10
	v_rcp_f32_e32 v30, v24
	v_rcp_f32_e32 v31, v25
	v_cndmask_b32_e32 v6, v22, v48, vcc
	v_cmp_gt_f32_e32 vcc, 0, v7
	v_cvt_pk_bf16_f32 v22, v0, v8
	v_cvt_pk_bf16_f32 v24, v4, v14
	v_cndmask_b32_e32 v7, v43, v41, vcc
	v_cmp_gt_f32_e32 vcc, 0, v11
	s_nop 1
	v_cndmask_b32_e32 v10, v23, v49, vcc
	v_cvt_pk_bf16_f32 v23, v2, v12
	v_cvt_pk_bf16_f32 v25, v6, v10
	global_store_dwordx4 v[18:19], v[22:25], off sc1
	v_cmp_gt_f32_e32 vcc, 0, v26
	s_nop 0
	v_pk_fma_f32 v[22:23], v[30:31], s[78:79], v[20:21] op_sel_hi:[1,0,0]
	v_pk_mul_f32 v[24:25], v[26:27], v[26:27]
	v_pk_fma_f32 v[22:23], v[30:31], v[22:23], s[96:97] op_sel_hi:[1,1,0]
	v_pk_fma_f32 v[20:21], v[32:33], s[78:79], v[20:21] op_sel_hi:[1,0,0]
	v_pk_fma_f32 v[22:23], v[30:31], v[22:23], s[48:49] op_sel_hi:[1,1,0]
	v_pk_fma_f32 v[20:21], v[32:33], v[20:21], s[96:97] op_sel_hi:[1,1,0]
	v_pk_fma_f32 v[22:23], v[30:31], v[22:23], s[50:51] op_sel_hi:[1,1,0]
	v_pk_fma_f32 v[20:21], v[32:33], v[20:21], s[48:49] op_sel_hi:[1,1,0]
	v_pk_mul_f32 v[22:23], v[30:31], v[22:23]
	v_pk_mul_f32 v[30:31], v[28:29], v[28:29]
	v_pk_fma_f32 v[20:21], v[32:33], v[20:21], s[50:51] op_sel_hi:[1,1,0]
	v_pk_mul_f32 v[30:31], v[30:31], s[52:53] op_sel_hi:[1,0]
	v_pk_mul_f32 v[20:21], v[32:33], v[20:21]
	v_exp_f32_e32 v30, v30
	v_exp_f32_e32 v31, v31
	s_nop 0
	v_pk_mul_f32 v[22:23], v[30:31], v[22:23]
	s_nop 0
	v_pk_mul_f32 v[30:31], v[28:29], v[22:23]
	v_pk_fma_f32 v[34:35], v[28:29], v[22:23], v[28:29] neg_lo:[1,0,0] neg_hi:[1,0,0]
	v_pk_mul_f32 v[22:23], v[24:25], s[52:53] op_sel_hi:[1,0]
	s_nop 0
	v_exp_f32_e32 v22, v22
	v_exp_f32_e32 v23, v23
	s_nop 0
	v_pk_mul_f32 v[20:21], v[22:23], v[20:21]
	s_nop 0
	v_pk_mul_f32 v[22:23], v[26:27], v[20:21]
	v_pk_fma_f32 v[24:25], v[26:27], v[20:21], v[26:27] neg_lo:[1,0,0] neg_hi:[1,0,0]
	s_nop 0
	v_cndmask_b32_e32 v21, v24, v22, vcc
	v_cmp_gt_f32_e32 vcc, 0, v28
	v_cvt_pk_bf16_f32 v24, v1, v3
	s_nop 0
	v_cndmask_b32_e32 v20, v34, v30, vcc
	v_cmp_gt_f32_e32 vcc, 0, v27
	s_nop 1
	v_cndmask_b32_e32 v23, v25, v23, vcc
	v_cmp_gt_f32_e32 vcc, 0, v29
	v_cvt_pk_bf16_f32 v25, v5, v7
	v_cvt_pk_bf16_f32 v27, v21, v23
	v_cndmask_b32_e32 v22, v35, v31, vcc
	v_cvt_pk_bf16_f32 v26, v20, v22
	s_and_b64 vcc, exec, s[4:5]
	global_store_dwordx4 v[18:19], v[24:27], off offset:256 sc1
	s_cbranch_vccnz .LBB0_256
	v_mov_b32_e32 v9, v1
	v_mov_b32_e32 v13, v3
	v_pk_mul_f32 v[24:25], v[8:9], v[8:9]
	v_pk_add_f32 v[38:39], v[0:1], v[8:9]
	v_pk_mul_f32 v[8:9], v[0:1], v[8:9]
	v_mov_b32_e32 v15, v5
	v_pk_mul_f32 v[18:19], v[0:1], v[0:1]
	v_pk_mul_f32 v[28:29], v[12:13], v[12:13]
	v_mov_b32_e32 v39, v9
	v_pk_add_f32 v[8:9], v[2:3], v[12:13]
	v_pk_mul_f32 v[12:13], v[2:3], v[12:13]
	v_mov_b32_e32 v11, v7
	v_pk_mul_f32 v[26:27], v[2:3], v[2:3]
	v_pk_mul_f32 v[32:33], v[14:15], v[14:15]
	v_mov_b32_e32 v9, v13
	v_pk_add_f32 v[12:13], v[4:5], v[14:15]
	v_pk_mul_f32 v[14:15], v[4:5], v[14:15]
	v_pk_mov_b32 v[0:1], v[0:1], v[18:19] op_sel:[1,0]
	v_pk_mov_b32 v[2:3], v[2:3], v[24:25] op_sel:[1,0]
	v_pk_mul_f32 v[30:31], v[4:5], v[4:5]
	v_pk_mul_f32 v[36:37], v[10:11], v[10:11]
	v_mov_b32_e32 v13, v15
	v_pk_add_f32 v[14:15], v[6:7], v[10:11]
	v_pk_mul_f32 v[10:11], v[6:7], v[10:11]
	v_pk_add_f32 v[0:1], v[0:1], v[2:3]
	v_pk_mov_b32 v[2:3], v[4:5], v[26:27] op_sel:[1,0]
	v_pk_mov_b32 v[4:5], v[6:7], v[28:29] op_sel:[1,0]
	v_mov_b32_e32 v15, v11
	v_pk_mul_f32 v[10:11], v[22:23], v[22:23]
	v_pk_add_f32 v[2:3], v[2:3], v[4:5]
	v_pk_mul_f32 v[34:35], v[6:7], v[6:7]
	v_pk_fma_f32 v[10:11], v[20:21], v[20:21], v[10:11]
	v_pk_add_f32 v[0:1], v[0:1], v[2:3]
	v_mov_b32_e32 v2, v20
	v_mov_b32_e32 v3, v30
	v_mov_b32_e32 v4, v22
	v_mov_b32_e32 v5, v32
	v_pk_add_f32 v[10:11], v[10:11], v[10:11] op_sel_hi:[0,1]
	v_cmp_lt_i32_e32 vcc, v248, v243
	v_pk_add_f32 v[2:3], v[2:3], v[4:5]
	v_pk_mov_b32 v[4:5], v[20:21], v[34:35] op_sel:[1,0]
	v_pk_mov_b32 v[6:7], v[22:23], v[36:37] op_sel:[1,0]
	v_cndmask_b32_e32 v10, v241, v248, vcc
	v_pk_add_f32 v[8:9], v[38:39], v[8:9]
	v_pk_add_f32 v[12:13], v[12:13], v[14:15]
	v_pk_add_f32 v[4:5], v[4:5], v[6:7]
	v_lshlrev_b32_e32 v31, 2, v10
	v_pk_add_f32 v[8:9], v[8:9], v[12:13]
	v_mov_b32_e32 v10, v153
	v_pk_add_f32 v[2:3], v[2:3], v[4:5]
	v_pk_add_f32 v[8:9], v[8:9], v[10:11]
	v_pk_add_f32 v[0:1], v[0:1], v[2:3]
	v_cmp_lt_i32_e32 vcc, v249, v243
	v_pk_add_f32 v[0:1], v[0:1], v[8:9]
	ds_bpermute_b32 v2, v31, v0
	ds_bpermute_b32 v3, v31, v1
	v_cndmask_b32_e32 v4, v241, v249, vcc
	v_lshlrev_b32_e32 v4, 2, v4
	s_waitcnt lgkmcnt(0)
	v_pk_add_f32 v[0:1], v[0:1], v[2:3]
	ds_bpermute_b32 v2, v4, v0
	ds_bpermute_b32 v3, v4, v1
	s_and_saveexec_b64 s[4:5], s[0:1]
	s_cbranch_execz .LBB0_255
	v_lshlrev_b64 v[4:5], 8, v[16:17]
	s_waitcnt lgkmcnt(0)
	v_pk_add_f32 v[0:1], v[0:1], v[2:3]
	v_lshl_add_u64 v[2:3], s[18:19], 0, v[4:5]
	v_lshl_add_u64 v[2:3], s[72:73], 3, v[2:3]
	global_store_dwordx2 v[2:3], v[0:1], off

; #define LAS __attribute__((address_space(3)))
; DI float bflo(unsigned w) { return __uint_as_float(w << 16); }
; DI float bfhi(unsigned w) { return __uint_as_float(w & 0xffff0000u); }
; DI u32x4 pk8(f32x4 a, f32x4 b) { u32x4 w; w.x = pk2(a[0], a[1]); w.y = pk2(a[2], a[3]); w.z = pk2(b[0], b[1]); w.w = pk2(b[2], b[3]); return w; }
; DI void spatial_cu(LAS unsigned char* lds, int cidx, const bf16* U, const bf16* VB, const float* STATS, const float* lng, const float* lnb,
;                    const float* wsp, const bf16* dummy, const float* bsp, bf16* CAT, float* outV, int tid, int wid, int lane) {
;     ...
;                 for (int e = 0; e < 4; ++e) { w0[e] = (s0 + e > t) ? 0.f : w0[e]; w1[e] = (s0 + 4 + e > t) ? 0.f : w1[e]; }
;                 wfr[ks] = __builtin_bit_cast(bf16x8, pk8(w0, w1));
;             }
;         }
;         u32x4 ug[4];
; #pragma unroll
;         for (int c4 = 0; c4 < 4; ++c4) { const int task = tid + 512 * c4, s = task >> 4, dc = task & 15; ug[c4] = *(const u32x4*)(U + (size_t)(r0 + s) * 2048 + g * 128 + 8 * dc); }
;         const float bias = bsp[g * 128 + t];
; #pragma unroll
;         for (int c4 = 0; c4 < 4; ++c4) {
;             const int task = tid + 512 * c4, s = task >> 4, dc = task & 15;
;             const float mean = st[2 * s], rstd = st[2 * s + 1];
;             const f32x4 ga = *(const f32x4*)(lng + g * 128 + 8 * dc), gb = *(const f32x4*)(lng + g * 128 + 8 * dc + 4), ba = *(const f32x4*)(lnb + g * 128 + 8 * dc), bb = *(const f32x4*)(lnb + g * 128 + 8 * dc + 4);
;             f32x4 va, vb;
; #pragma unroll
;             for (int e = 0; e < 4; ++e) { const unsigned w0 = raw[c4][e >> 1], w1 = raw[c4][2 + (e >> 1)];
;                 va[e] = (((e & 1) ? bfhi(w0) : bflo(w0)) - mean) * rstd * ga[e] + ba[e]; vb[e] = (((e & 1) ? bfhi(w1) : bflo(w1)) - mean) * rstd * gb[e] + bb[e]; }
;             if (n == 15) { float* o = outV + ((size_t)(b * 128 + s)) * 2048 + g * 128 + 8 * dc; *(f32x4*)o = va; *(f32x4*)(o + 4) = vb; }
;             *(LAS u32x4*)(vs + s * VS + 8 * dc) = pk8(va, vb);
;         }
;         {   const int gn = (it < 3) ? g + 1 : g;
; #pragma unroll
;             for (int c4 = 0; c4 < 4; ++c4) { const int task = tid + 512 * c4, s = task >> 4, dc = task & 15; raw[c4] = *(const u32x4*)(VB + (size_t)(r0 + s) * 2048 + gn * 128 + 8 * dc); }
;         }
;         __syncthreads();
.LBB0_349:
	v_readlane_b32 s44, v254, 50
	v_readlane_b32 s45, v254, 51
	s_cmpk_lg_i32 s48, 0x600
	v_cndmask_b32_e64 v4, v4, 0, s[26:27]
	v_cndmask_b32_e64 v32, v92, 0, s[44:45]
	v_readlane_b32 s44, v254, 52
	v_readlane_b32 s45, v254, 53
	v_cndmask_b32_e64 v0, v0, 0, s[28:29]
	v_cndmask_b32_e64 v5, v5, 0, s[30:31]
	v_cndmask_b32_e64 v33, v88, 0, s[44:45]
	v_readlane_b32 s44, v254, 34
	v_readlane_b32 s45, v254, 35
	v_cndmask_b32_e64 v1, v1, 0, s[34:35]
	v_cndmask_b32_e64 v2, v2, 0, s[38:39]
	v_cndmask_b32_e64 v34, 0, v93, s[44:45]
	v_readlane_b32 s44, v254, 42
	v_readlane_b32 s45, v254, 43
	v_cvt_pk_bf16_f32 v88, v32, v34
	v_cndmask_b32_e64 v3, v3, 0, s[42:43]
	v_cndmask_b32_e64 v35, v89, 0, s[44:45]
	v_readlane_b32 s44, v254, 44
	v_readlane_b32 s45, v254, 45
	v_cvt_pk_bf16_f32 v92, v4, v5
	v_add_u32_e32 v4, v139, v200
	v_cndmask_b32_e64 v44, v94, 0, s[44:45]
	v_readlane_b32 s44, v255, 11
	v_readlane_b32 s45, v255, 12
	v_cvt_pk_bf16_f32 v94, v0, v1
	v_cvt_pk_bf16_f32 v0, v36, v37
	v_cndmask_b32_e64 v45, v90, 0, s[44:45]
	v_readlane_b32 s44, v255, 13
	v_readlane_b32 s45, v255, 14
	v_cvt_pk_bf16_f32 v90, v33, v35
	v_cvt_pk_bf16_f32 v1, v38, v39
	v_cndmask_b32_e64 v46, v95, 0, s[44:45]
	v_readlane_b32 s44, v255, 15
	v_readlane_b32 s45, v255, 16
	v_cvt_pk_bf16_f32 v89, v44, v46
	v_cvt_pk_bf16_f32 v95, v2, v3
	v_cndmask_b32_e64 v47, v91, 0, s[44:45]
	v_readlane_b32 s44, v255, 17
	v_readlane_b32 s45, v255, 18
	v_cvt_pk_bf16_f32 v91, v45, v47
	v_cvt_pk_bf16_f32 v2, v40, v41
	v_cndmask_b32_e64 v32, v84, 0, s[44:45]
	v_readlane_b32 s44, v255, 19
	v_readlane_b32 s45, v255, 20
	v_cvt_pk_bf16_f32 v3, v42, v43
	ds_write_b128 v4, v[0:3]
	v_cndmask_b32_e64 v33, v80, 0, s[44:45]
	v_readlane_b32 s44, v255, 21
	v_readlane_b32 s45, v255, 22
	v_cndmask_b32_e64 v6, v6, 0, s[36:37]
	v_cndmask_b32_e64 v7, v7, 0, s[40:41]
	v_cndmask_b32_e64 v34, v85, 0, s[44:45]
	v_readlane_b32 s44, v255, 23
	v_readlane_b32 s45, v255, 24
	v_cvt_pk_bf16_f32 v80, v32, v34
	v_cndmask_b32_e64 v28, v28, 0, s[76:77]
	v_cndmask_b32_e64 v35, v81, 0, s[44:45]
	v_readlane_b32 s44, v255, 25
	v_readlane_b32 s45, v255, 26
	v_cndmask_b32_e64 v24, v24, 0, s[78:79]
	v_cndmask_b32_e64 v29, v29, 0, s[80:81]
	v_cndmask_b32_e64 v44, v86, 0, s[44:45]
	v_readlane_b32 s44, v255, 27
	v_readlane_b32 s45, v255, 28
	v_cndmask_b32_e64 v25, v25, 0, s[82:83]
	v_cndmask_b32_e64 v30, v30, 0, s[84:85]
	v_cndmask_b32_e64 v45, v82, 0, s[44:45]
	v_readlane_b32 s44, v255, 29
	v_readlane_b32 s45, v255, 30
	v_cvt_pk_bf16_f32 v82, v33, v35
	v_cndmask_b32_e64 v26, v26, 0, s[86:87]
	v_cndmask_b32_e64 v46, v87, 0, s[44:45]
	v_readlane_b32 s44, v255, 31
	v_readlane_b32 s45, v255, 32
	v_cvt_pk_bf16_f32 v81, v44, v46
	v_cndmask_b32_e64 v31, v31, 0, s[88:89]
	v_cndmask_b32_e64 v47, v83, 0, s[44:45]
	v_readlane_b32 s44, v255, 33
	v_readlane_b32 s45, v255, 34
	v_cvt_pk_bf16_f32 v83, v45, v47
	v_cndmask_b32_e64 v27, v27, 0, s[90:91]
	v_cndmask_b32_e64 v32, v76, 0, s[44:45]
	v_readlane_b32 s44, v255, 35
	v_readlane_b32 s45, v255, 36
	v_cndmask_b32_e64 v20, v20, 0, s[92:93]
	v_cndmask_b32_e64 v16, v16, 0, s[94:95]
	v_cndmask_b32_e64 v33, v72, 0, s[44:45]
	v_readlane_b32 s44, v255, 37
	v_readlane_b32 s45, v255, 38
	v_cndmask_b32_e64 v21, v21, 0, s[96:97]
	v_cndmask_b32_e64 v17, v17, 0, s[4:5]
	v_cndmask_b32_e64 v34, v77, 0, s[44:45]
	v_readlane_b32 s44, v255, 39
	v_readlane_b32 s45, v255, 40
	v_cvt_pk_bf16_f32 v72, v32, v34
	v_cndmask_b32_e64 v32, v68, 0, s[54:55]
	v_cndmask_b32_e64 v35, v73, 0, s[44:45]
	v_readlane_b32 s44, v255, 41
	v_readlane_b32 s45, v255, 42
	v_cndmask_b32_e64 v34, v69, 0, s[64:65]
	v_cndmask_b32_e64 v22, v22, 0, s[46:47]
	v_cndmask_b32_e64 v44, v78, 0, s[44:45]
	v_readlane_b32 s44, v255, 43
	v_readlane_b32 s45, v255, 44
	v_cndmask_b32_e64 v18, v18, 0, s[6:7]
	v_cndmask_b32_e64 v23, v23, 0, s[0:1]
	v_cndmask_b32_e64 v45, v74, 0, s[44:45]
	v_readlane_b32 s44, v255, 45
	v_readlane_b32 s45, v255, 46
	v_cvt_pk_bf16_f32 v74, v33, v35
	v_cndmask_b32_e64 v35, v65, 0, s[66:67]
	v_cndmask_b32_e64 v46, v79, 0, s[44:45]
	v_readlane_b32 s44, v255, 47
	v_readlane_b32 s45, v255, 48
	v_cvt_pk_bf16_f32 v73, v44, v46
	v_cndmask_b32_e64 v44, v70, 0, s[68:69]
	v_cndmask_b32_e64 v47, v75, 0, s[44:45]
	v_readlane_b32 s44, v255, 49
	v_readlane_b32 s45, v255, 50
	v_cvt_pk_bf16_f32 v75, v45, v47
	v_cndmask_b32_e64 v45, v66, 0, s[52:53]
	v_cndmask_b32_e64 v33, v64, 0, s[44:45]
	s_cselect_b64 s[44:45], -1, 0
	s_cmp_lg_u64 s[44:45], 0
	s_addc_u32 s44, s33, s50
	s_mov_b32 s45, s71
	s_lshl_b32 s44, s44, 8
	v_lshl_add_u64 v[0:1], v[118:119], 0, s[44:45]
	v_cndmask_b32_e64 v46, v71, 0, s[72:73]
	v_cndmask_b32_e64 v47, v67, 0, s[74:75]
	v_lshl_add_u64 v[2:3], v[0:1], 0, v[130:131]
	v_cvt_pk_bf16_f32 v65, v44, v46
	v_cvt_pk_bf16_f32 v67, v45, v47
	global_load_dwordx4 v[44:47], v[2:3], off
	v_lshl_add_u64 v[2:3], v[0:1], 0, v[132:133]
	global_load_dwordx4 v[40:43], v[2:3], off
	v_lshl_add_u64 v[2:3], v[0:1], 0, v[134:135]
	v_lshl_add_u64 v[0:1], v[0:1], 0, v[136:137]
	v_cvt_pk_bf16_f32 v64, v32, v34
	v_cvt_pk_bf16_f32 v66, v33, v35
	v_cndmask_b32_e64 v19, v19, 0, s[8:9]
	v_cndmask_b32_e64 v12, v12, 0, s[10:11]
	v_cndmask_b32_e64 v8, v8, 0, s[12:13]
	v_cndmask_b32_e64 v13, v13, 0, s[14:15]
	v_cndmask_b32_e64 v9, v9, 0, s[16:17]
	v_cndmask_b32_e64 v14, v14, 0, s[18:19]
	v_cndmask_b32_e64 v10, v10, 0, s[20:21]
	v_cndmask_b32_e64 v15, v15, 0, s[22:23]
	v_cndmask_b32_e64 v11, v11, 0, s[24:25]
	v_cvt_pk_bf16_f32 v93, v6, v7
	global_load_dwordx4 v[36:39], v[2:3], off
	global_load_dwordx4 v[32:35], v[0:1], off
	s_waitcnt lgkmcnt(0)
	s_barrier
; #define LAS __attribute__((address_space(3)))
; #define MFMA32(a, b, c) __builtin_amdgcn_mfma_f32_32x32x16_bf16((a), (b), (c), 0, 0, 0)
; DI unsigned pk2(float a, float b) { f32x2 v = {a, b}; hbf16x2 r = __builtin_convertvector(v, hbf16x2); return __builtin_bit_cast(unsigned, r); }
; DI void spatial_cu(LAS unsigned char* lds, int cidx, const bf16* U, const bf16* VB, const float* STATS, const float* lng, const float* lnb,
;                    const float* wsp, const bf16* dummy, const float* bsp, bf16* CAT, float* outV, int tid, int wid, int lane) {
;     ...
;         f32x16 acc0, acc1;
; #pragma unroll
;         for (int i = 0; i < 16; ++i) { acc0[i] = 0.f; acc1[i] = 0.f; }
;         const unsigned tra = (unsigned)(__UINTPTR_TYPE__)vs + (unsigned)(((8 * h + ((lane & 15) >> 2)) * VS + 16 * ((lane >> 4) & 1) + 4 * (lane & 3) + 32 * dd0) * 2);
; #pragma unroll
;         for (int ks = 0; ks < 8; ++ks) {
;             u32x2 a0l, a0h, a1l, a1h;
;             asm volatile("ds_read_b64_tr_b16 %0, %4 offset:%5\n\tds_read_b64_tr_b16 %1, %4 offset:%6\n\tds_read_b64_tr_b16 %2, %4 offset:%7\n\tds_read_b64_tr_b16 %3, %4 offset:%8\n\ts_waitcnt lgkmcnt(0)"
;                          : "=&v"(a0l), "=&v"(a0h), "=&v"(a1l), "=&v"(a1h)
;                          : "v"(tra), "i"(ks * 16 * VS * 2), "i"(ks * 16 * VS * 2 + 4 * VS * 2), "i"(ks * 16 * VS * 2 + 64), "i"(ks * 16 * VS * 2 + 4 * VS * 2 + 64) : "memory");
;             const u32x4 a0w = {a0l.x, a0l.y, a0h.x, a0h.y}, a1w = {a1l.x, a1l.y, a1h.x, a1h.y};
;             acc0 = MFMA32(__builtin_bit_cast(bf16x8, a0w), wfr[ks], acc0); acc1 = MFMA32(__builtin_bit_cast(bf16x8, a1w), wfr[ks], acc1);
;         }
; #pragma unroll
;         for (int gg = 0; gg < 4; ++gg) {
;             const int d0 = 32 * dd0 + 8 * gg + 4 * h;
;             u32x2 oa, ob; oa.x = pk2(acc0[4 * gg] + bias, acc0[4 * gg + 1] + bias); oa.y = pk2(acc0[4 * gg + 2] + bias, acc0[4 * gg + 3] + bias);
;             ob.x = pk2(acc1[4 * gg] + bias, acc1[4 * gg + 1] + bias); ob.y = pk2(acc1[4 * gg + 2] + bias, acc1[4 * gg + 3] + bias);
;             *(LAS u32x2*)(ot + t * VS + d0) = oa; *(LAS u32x2*)(ot + t * VS + d0 + 32) = ob;
;         }
;         __syncthreads();
	v_add_u32_e32 v100, s51, v195
	ds_read_b64_tr_b16 v[4:5], v100 offset:0
	ds_read_b64_tr_b16 v[6:7], v100 offset:0x500
	ds_read_b64_tr_b16 v[0:1], v100 offset:64
	ds_read_b64_tr_b16 v[2:3], v100 offset:0x540
	s_waitcnt lgkmcnt(0)
	v_cvt_pk_bf16_f32 v68, v28, v29
	v_cvt_pk_bf16_f32 v69, v30, v31
	v_cvt_pk_bf16_f32 v70, v24, v25
	v_cvt_pk_bf16_f32 v71, v26, v27
	v_cvt_pk_bf16_f32 v76, v20, v21
	v_cvt_pk_bf16_f32 v77, v22, v23
	v_cvt_pk_bf16_f32 v78, v16, v17
	v_cvt_pk_bf16_f32 v79, v18, v19
	v_cvt_pk_bf16_f32 v84, v12, v13
	v_cvt_pk_bf16_f32 v85, v14, v15
	v_cvt_pk_bf16_f32 v86, v8, v9
	v_cvt_pk_bf16_f32 v87, v10, v11
	v_mfma_f32_32x32x16_bf16 v[16:31], v[4:7], v[88:91], 0
	s_mov_b32 s44, 0x18500000
	s_add_i32 s50, s50, 1
	s_add_u32 s48, s48, 0x200
	s_addc_u32 s49, s49, 0
	v_add_u32_e32 v138, 0x80, v138
	s_cmpk_lg_i32 s48, 0x800
	v_mfma_f32_32x32x16_bf16 v[0:15], v[0:3], v[88:91], 0
	ds_read_b64_tr_b16 v[96:97], v100 offset:0x1400
	ds_read_b64_tr_b16 v[98:99], v100 offset:0x1900
	ds_read_b64_tr_b16 v[88:89], v100 offset:0x1440
	ds_read_b64_tr_b16 v[90:91], v100 offset:0x1940
	s_waitcnt lgkmcnt(0)
	s_nop 0
	v_mfma_f32_32x32x16_bf16 v[16:31], v[96:99], v[80:83], v[16:31]
	v_mfma_f32_32x32x16_bf16 v[0:15], v[88:91], v[80:83], v[0:15]
	ds_read_b64_tr_b16 v[88:89], v100 offset:0x2800
	ds_read_b64_tr_b16 v[90:91], v100 offset:0x2d00
	ds_read_b64_tr_b16 v[80:81], v100 offset:0x2840
	ds_read_b64_tr_b16 v[82:83], v100 offset:0x2d40
	s_waitcnt lgkmcnt(0)
	s_nop 0
	v_mfma_f32_32x32x16_bf16 v[16:31], v[88:91], v[72:75], v[16:31]
	v_mfma_f32_32x32x16_bf16 v[0:15], v[80:83], v[72:75], v[0:15]
	ds_read_b64_tr_b16 v[80:81], v100 offset:0x3c00
	ds_read_b64_tr_b16 v[82:83], v100 offset:0x4100
	ds_read_b64_tr_b16 v[72:73], v100 offset:0x3c40
	ds_read_b64_tr_b16 v[74:75], v100 offset:0x4140
	s_waitcnt lgkmcnt(0)
	s_nop 0
	v_mfma_f32_32x32x16_bf16 v[16:31], v[80:83], v[64:67], v[16:31]
	v_mfma_f32_32x32x16_bf16 v[0:15], v[72:75], v[64:67], v[0:15]
	ds_read_b64_tr_b16 v[72:73], v100 offset:0x5000
	ds_read_b64_tr_b16 v[74:75], v100 offset:0x5500
	ds_read_b64_tr_b16 v[64:65], v100 offset:0x5040
	ds_read_b64_tr_b16 v[66:67], v100 offset:0x5540
	s_waitcnt lgkmcnt(0)
	s_nop 0
	v_mfma_f32_32x32x16_bf16 v[16:31], v[72:75], v[68:71], v[16:31]
	v_mfma_f32_32x32x16_bf16 v[0:15], v[64:67], v[68:71], v[0:15]
	ds_read_b64_tr_b16 v[68:69], v100 offset:0x6400
	ds_read_b64_tr_b16 v[70:71], v100 offset:0x6900
	ds_read_b64_tr_b16 v[64:65], v100 offset:0x6440
	ds_read_b64_tr_b16 v[66:67], v100 offset:0x6940
	s_waitcnt lgkmcnt(0)
	s_nop 0
	v_mfma_f32_32x32x16_bf16 v[16:31], v[68:71], v[76:79], v[16:31]
	v_mfma_f32_32x32x16_bf16 v[0:15], v[64:67], v[76:79], v[0:15]
	ds_read_b64_tr_b16 v[68:69], v100 offset:0x7800
	ds_read_b64_tr_b16 v[70:71], v100 offset:0x7d00
	ds_read_b64_tr_b16 v[64:65], v100 offset:0x7840
	ds_read_b64_tr_b16 v[66:67], v100 offset:0x7d40
	s_waitcnt lgkmcnt(0)
	s_nop 0
	v_mfma_f32_32x32x16_bf16 v[16:31], v[68:71], v[84:87], v[16:31]
	v_mfma_f32_32x32x16_bf16 v[0:15], v[64:67], v[84:87], v[0:15]
	ds_read_b64_tr_b16 v[68:69], v100 offset:0x8c00
	ds_read_b64_tr_b16 v[70:71], v100 offset:0x9100
	ds_read_b64_tr_b16 v[64:65], v100 offset:0x8c40
	ds_read_b64_tr_b16 v[66:67], v100 offset:0x9140
	s_waitcnt lgkmcnt(0)
	s_nop 0
	v_mfma_f32_32x32x16_bf16 v[16:31], v[68:71], v[92:95], v[16:31]
	v_mfma_f32_32x32x16_bf16 v[0:15], v[64:67], v[92:95], v[0:15]
	s_nop 10
	v_add_f32_e64 v16, v182, v16
	v_add_f32_e64 v17, v182, v17
	v_add_f32_e64 v18, v182, v18
	v_add_f32_e64 v19, v182, v19
	v_cvt_pk_bf16_f32 v16, v16, v17
	v_cvt_pk_bf16_f32 v17, v18, v19
	v_pk_add_f32 v[18:19], v[182:183], v[22:23] op_sel_hi:[0,1]
	v_pk_add_f32 v[0:1], v[182:183], v[0:1] op_sel_hi:[0,1]
	v_pk_add_f32 v[2:3], v[182:183], v[2:3] op_sel_hi:[0,1]
	v_cvt_pk_bf16_f32 v0, v0, v1
	v_cvt_pk_bf16_f32 v1, v2, v3
	v_pk_add_f32 v[2:3], v[182:183], v[20:21] op_sel_hi:[0,1]
	v_cvt_pk_bf16_f32 v2, v2, v3
	v_cvt_pk_bf16_f32 v3, v18, v19
	v_pk_add_f32 v[4:5], v[182:183], v[4:5] op_sel_hi:[0,1]
	v_pk_add_f32 v[6:7], v[182:183], v[6:7] op_sel_hi:[0,1]
	v_cvt_pk_bf16_f32 v4, v4, v5
	v_cvt_pk_bf16_f32 v5, v6, v7
	ds_write2_b64 v207, v[16:17], v[2:3] offset1:2
	ds_write2_b64 v207, v[0:1], v[4:5] offset0:8 offset1:10
	v_pk_add_f32 v[0:1], v[182:183], v[24:25] op_sel_hi:[0,1]
	v_pk_add_f32 v[2:3], v[182:183], v[26:27] op_sel_hi:[0,1]
	v_cvt_pk_bf16_f32 v0, v0, v1
	v_cvt_pk_bf16_f32 v1, v2, v3
	v_pk_add_f32 v[2:3], v[182:183], v[8:9] op_sel_hi:[0,1]
	v_pk_add_f32 v[4:5], v[182:183], v[10:11] op_sel_hi:[0,1]
	v_cvt_pk_bf16_f32 v2, v2, v3
	v_cvt_pk_bf16_f32 v3, v4, v5
	v_pk_add_f32 v[4:5], v[182:183], v[28:29] op_sel_hi:[0,1]
	v_pk_add_f32 v[6:7], v[182:183], v[30:31] op_sel_hi:[0,1]
	v_cvt_pk_bf16_f32 v4, v4, v5
	v_cvt_pk_bf16_f32 v5, v6, v7
	v_pk_add_f32 v[6:7], v[182:183], v[12:13] op_sel_hi:[0,1]
	v_pk_add_f32 v[8:9], v[182:183], v[14:15] op_sel_hi:[0,1]
	v_cvt_pk_bf16_f32 v6, v6, v7
	v_cvt_pk_bf16_f32 v7, v8, v9
	ds_write2_b64 v207, v[0:1], v[4:5] offset0:4 offset1:6
	ds_write2_b64 v207, v[2:3], v[6:7] offset0:12 offset1:14
	v_add_u32_e32 v0, v196, v197
	s_waitcnt lgkmcnt(0)
	s_barrier
; #define LAS __attribute__((address_space(3)))
; DI unsigned pk2(float a, float b) { f32x2 v = {a, b}; hbf16x2 r = __builtin_convertvector(v, hbf16x2); return __builtin_bit_cast(unsigned, r); }
; DI float bflo(unsigned w) { return __uint_as_float(w << 16); }
; DI float bfhi(unsigned w) { return __uint_as_float(w & 0xffff0000u); }
; DI void spatial_cu(LAS unsigned char* lds, int cidx, const bf16* U, const bf16* VB, const float* STATS, const float* lng, const float* lnb,
;                    const float* wsp, const bf16* dummy, const float* bsp, bf16* CAT, float* outV, int tid, int wid, int lane) {
;     ...
; #pragma unroll
;         for (int c4 = 0; c4 < 4; ++c4) {
;             const int task = tid + 512 * c4, s = task >> 4, dc = task & 15;
;             const u32x4 mx = *(const LAS u32x4*)(ot + s * VS + 8 * dc), uu = ug[c4];
;             u32x4 o;
; #pragma unroll
;             for (int e = 0; e < 4; ++e) o[e] = pk2(bflo(uu[e]) * bflo(mx[e]), bfhi(uu[e]) * bfhi(mx[e]));
;             *(u32x4*)(CAT + (size_t)(r0 + s) * 2048 + g * 128 + 8 * dc) = o;
;         }
	ds_read_b128 v[0:3], v0
	v_lshlrev_b32_e32 v4, 16, v60
	v_and_b32_e32 v5, 0xffff0000, v60
	s_waitcnt lgkmcnt(0)
	v_lshlrev_b32_e32 v6, 16, v0
	v_and_b32_e32 v7, 0xffff0000, v0
	v_pk_mul_f32 v[4:5], v[4:5], v[6:7]
	v_lshlrev_b32_e32 v6, 16, v1
	v_cvt_pk_bf16_f32 v0, v4, v5
	v_lshlrev_b32_e32 v4, 16, v61
	v_and_b32_e32 v5, 0xffff0000, v61
	v_and_b32_e32 v7, 0xffff0000, v1
	v_pk_mul_f32 v[4:5], v[4:5], v[6:7]
	v_lshlrev_b32_e32 v6, 16, v2
	v_cvt_pk_bf16_f32 v1, v4, v5
	v_lshlrev_b32_e32 v4, 16, v62
	v_and_b32_e32 v5, 0xffff0000, v62
	v_and_b32_e32 v7, 0xffff0000, v2
	v_pk_mul_f32 v[4:5], v[4:5], v[6:7]
	v_lshlrev_b32_e32 v6, 16, v3
	v_cvt_pk_bf16_f32 v2, v4, v5
	v_lshlrev_b32_e32 v4, 16, v63
	v_and_b32_e32 v5, 0xffff0000, v63
	v_and_b32_e32 v7, 0xffff0000, v3
	v_pk_mul_f32 v[4:5], v[4:5], v[6:7]
	s_nop 0
	v_cvt_pk_bf16_f32 v3, v4, v5
	v_add_co_u32_e32 v4, vcc, s44, v180
	s_nop 1
	v_addc_co_u32_e32 v5, vcc, 0, v181, vcc
	global_store_dwordx4 v[4:5], v[0:3], off sc1
	v_lshlrev_b32_e32 v4, 16, v56
	v_and_b32_e32 v5, 0xffff0000, v56
	v_add_u32_e32 v0, v196, v198
	ds_read_b128 v[0:3], v0
	s_waitcnt lgkmcnt(0)
	v_lshlrev_b32_e32 v6, 16, v0
	v_and_b32_e32 v7, 0xffff0000, v0
	v_pk_mul_f32 v[4:5], v[4:5], v[6:7]
	v_lshlrev_b32_e32 v6, 16, v1
	v_cvt_pk_bf16_f32 v0, v4, v5
	v_lshlrev_b32_e32 v4, 16, v57
	v_and_b32_e32 v5, 0xffff0000, v57
	v_and_b32_e32 v7, 0xffff0000, v1
	v_pk_mul_f32 v[4:5], v[4:5], v[6:7]
	v_lshlrev_b32_e32 v6, 16, v2
	v_cvt_pk_bf16_f32 v1, v4, v5
	v_lshlrev_b32_e32 v4, 16, v58
	v_and_b32_e32 v5, 0xffff0000, v58
	v_and_b32_e32 v7, 0xffff0000, v2
	v_pk_mul_f32 v[4:5], v[4:5], v[6:7]
	v_lshlrev_b32_e32 v6, 16, v3
	v_cvt_pk_bf16_f32 v2, v4, v5
	v_lshlrev_b32_e32 v4, 16, v59
	v_and_b32_e32 v5, 0xffff0000, v59
	v_and_b32_e32 v7, 0xffff0000, v3
	v_pk_mul_f32 v[4:5], v[4:5], v[6:7]
	s_nop 0
	v_cvt_pk_bf16_f32 v3, v4, v5
	v_add_co_u32_e32 v4, vcc, s44, v178
	s_nop 1
	v_addc_co_u32_e32 v5, vcc, 0, v179, vcc
	global_store_dwordx4 v[4:5], v[0:3], off sc1
	v_lshlrev_b32_e32 v4, 16, v52
	v_and_b32_e32 v5, 0xffff0000, v52
	v_add_u32_e32 v0, v196, v199
	ds_read_b128 v[0:3], v0
	s_waitcnt lgkmcnt(0)
	v_lshlrev_b32_e32 v6, 16, v0
	v_and_b32_e32 v7, 0xffff0000, v0
	v_pk_mul_f32 v[4:5], v[4:5], v[6:7]
	v_lshlrev_b32_e32 v6, 16, v1
	v_cvt_pk_bf16_f32 v0, v4, v5
	v_lshlrev_b32_e32 v4, 16, v53
	v_and_b32_e32 v5, 0xffff0000, v53
	v_and_b32_e32 v7, 0xffff0000, v1
	v_pk_mul_f32 v[4:5], v[4:5], v[6:7]
	v_lshlrev_b32_e32 v6, 16, v2
	v_cvt_pk_bf16_f32 v1, v4, v5
	v_lshlrev_b32_e32 v4, 16, v54
	v_and_b32_e32 v5, 0xffff0000, v54
	v_and_b32_e32 v7, 0xffff0000, v2
	v_pk_mul_f32 v[4:5], v[4:5], v[6:7]
	v_lshlrev_b32_e32 v6, 16, v3
	v_cvt_pk_bf16_f32 v2, v4, v5
	v_lshlrev_b32_e32 v4, 16, v55
	v_and_b32_e32 v5, 0xffff0000, v55
	v_and_b32_e32 v7, 0xffff0000, v3
	v_pk_mul_f32 v[4:5], v[4:5], v[6:7]
	s_nop 0
	v_cvt_pk_bf16_f32 v3, v4, v5
	v_add_co_u32_e32 v4, vcc, s44, v176
	s_nop 1
	v_addc_co_u32_e32 v5, vcc, 0, v177, vcc
	global_store_dwordx4 v[4:5], v[0:3], off sc1
	v_lshlrev_b32_e32 v4, 16, v48
	v_and_b32_e32 v5, 0xffff0000, v48
	v_add_u32_e32 v0, v196, v200
	ds_read_b128 v[0:3], v0
	s_waitcnt lgkmcnt(0)
	v_lshlrev_b32_e32 v6, 16, v0
	v_and_b32_e32 v7, 0xffff0000, v0
	v_pk_mul_f32 v[4:5], v[4:5], v[6:7]
	v_lshlrev_b32_e32 v6, 16, v1
	v_cvt_pk_bf16_f32 v0, v4, v5
	v_lshlrev_b32_e32 v4, 16, v49
	v_and_b32_e32 v5, 0xffff0000, v49
	v_and_b32_e32 v7, 0xffff0000, v1
	v_pk_mul_f32 v[4:5], v[4:5], v[6:7]
	v_lshlrev_b32_e32 v6, 16, v2
	v_cvt_pk_bf16_f32 v1, v4, v5
	v_lshlrev_b32_e32 v4, 16, v50
	v_and_b32_e32 v5, 0xffff0000, v50
	v_and_b32_e32 v7, 0xffff0000, v2
	v_pk_mul_f32 v[4:5], v[4:5], v[6:7]
	v_lshlrev_b32_e32 v6, 16, v3
	v_cvt_pk_bf16_f32 v2, v4, v5
	v_lshlrev_b32_e32 v4, 16, v51
	v_and_b32_e32 v5, 0xffff0000, v51
	v_and_b32_e32 v7, 0xffff0000, v3
	v_pk_mul_f32 v[4:5], v[4:5], v[6:7]
	s_nop 0
	v_cvt_pk_bf16_f32 v3, v4, v5
	v_add_co_u32_e32 v4, vcc, s44, v174
	s_mov_b64 s[44:45], 0x100
	v_lshl_add_u64 v[146:147], v[146:147], 0, s[44:45]
	v_lshl_add_u64 v[148:149], v[148:149], 0, s[44:45]
	v_lshl_add_u64 v[150:151], v[150:151], 0, s[44:45]
	v_lshl_add_u64 v[164:165], v[164:165], 0, s[44:45]
	s_mov_b64 s[44:45], 0x10000
	v_addc_co_u32_e32 v5, vcc, 0, v175, vcc
	v_lshl_add_u64 v[140:141], v[140:141], 0, s[44:45]
	global_store_dwordx4 v[4:5], v[0:3], off sc1
	s_cbranch_scc0 .LBB0_345
; #define LAS __attribute__((address_space(3)))
; DI float bflo(unsigned w) { return __uint_as_float(w << 16); }
; DI float bfhi(unsigned w) { return __uint_as_float(w & 0xffff0000u); }
; DI void spatial_cu(LAS unsigned char* lds, int cidx, const bf16* U, const bf16* VB, const float* STATS, const float* lng, const float* lnb,
;                    const float* wsp, const bf16* dummy, const float* bsp, bf16* CAT, float* outV, int tid, int wid, int lane) {
;     ...
;     for (int it = 0; it < 4; ++it) {
;         const int g = 4 * gq + it;
;         LAS bf16* vs = (LAS bf16*)(lds + (it & 1) * VTB);
;         bf16x8 wfr[8];
;         {   const float* wrow = wsp + ((size_t)g * 128 + t) * 128;
; #pragma unroll
;             for (int ks = 0; ks < 8; ++ks) {
;                 const int s0 = 16 * ks + 8 * h;
;                 f32x4 w0 = *(const f32x4*)(wrow + s0), w1 = *(const f32x4*)(wrow + s0 + 4);
; #pragma unroll
;                 for (int e = 0; e < 4; ++e) { w0[e] = (s0 + e > t) ? 0.f : w0[e]; w1[e] = (s0 + 4 + e > t) ? 0.f : w1[e]; }
;                 wfr[ks] = __builtin_bit_cast(bf16x8, pk8(w0, w1));
;             }
;         }
;         u32x4 ug[4];
; #pragma unroll
;         for (int c4 = 0; c4 < 4; ++c4) { const int task = tid + 512 * c4, s = task >> 4, dc = task & 15; ug[c4] = *(const u32x4*)(U + (size_t)(r0 + s) * 2048 + g * 128 + 8 * dc); }
;         const float bias = bsp[g * 128 + t];
; #pragma unroll
;         for (int c4 = 0; c4 < 4; ++c4) {
;             const int task = tid + 512 * c4, s = task >> 4, dc = task & 15;
;             const float mean = st[2 * s], rstd = st[2 * s + 1];
;             const f32x4 ga = *(const f32x4*)(lng + g * 128 + 8 * dc), gb = *(const f32x4*)(lng + g * 128 + 8 * dc + 4), ba = *(const f32x4*)(lnb + g * 128 + 8 * dc), bb = *(const f32x4*)(lnb + g * 128 + 8 * dc + 4);
;             f32x4 va, vb;
; #pragma unroll
;             for (int e = 0; e < 4; ++e) { const unsigned w0 = raw[c4][e >> 1], w1 = raw[c4][2 + (e >> 1)];
;                 va[e] = (((e & 1) ? bfhi(w0) : bflo(w0)) - mean) * rstd * ga[e] + ba[e]; vb[e] = (((e & 1) ? bfhi(w1) : bflo(w1)) - mean) * rstd * gb[e] + bb[e]; }
;             if (n == 15) { float* o = outV + ((size_t)(b * 128 + s)) * 2048 + g * 128 + 8 * dc; *(f32x4*)o = va; *(f32x4*)(o + 4) = vb; }
.LBB0_350:
	global_load_dwordx4 v[88:91], v[140:141], off offset:-240
	global_load_dwordx4 v[92:95], v[140:141], off offset:-256
	global_load_dwordx4 v[80:83], v[140:141], off offset:-176
	global_load_dwordx4 v[84:87], v[140:141], off offset:-192
	global_load_dwordx4 v[72:75], v[140:141], off offset:-112
	global_load_dwordx4 v[76:79], v[140:141], off offset:-128
	global_load_dwordx4 v[64:67], v[140:141], off offset:-48
	global_load_dwordx4 v[68:71], v[140:141], off offset:-64
	global_load_dwordx4 v[24:27], v[140:141], off offset:16
	global_load_dwordx4 v[28:31], v[140:141], off
	global_load_dwordx4 v[16:19], v[140:141], off offset:80
	global_load_dwordx4 v[20:23], v[140:141], off offset:64
	global_load_dwordx4 v[8:11], v[140:141], off offset:144
	global_load_dwordx4 v[12:15], v[140:141], off offset:128
	global_load_dwordx4 v[0:3], v[140:141], off offset:208
	global_load_dwordx4 v[4:7], v[140:141], off offset:192
	v_lshl_add_u64 v[180:181], v[146:147], 0, v[152:153]
	s_mov_b32 s44, 0x1de00000
	v_add_co_u32_e32 v48, vcc, s44, v180
	v_lshl_add_u64 v[178:179], v[148:149], 0, v[152:153]
	s_nop 0
	v_addc_co_u32_e32 v49, vcc, 0, v181, vcc
	global_load_dwordx4 v[60:63], v[48:49], off
	v_add_co_u32_e32 v48, vcc, s44, v178
	v_lshl_add_u64 v[176:177], v[150:151], 0, v[152:153]
	s_nop 0
	v_addc_co_u32_e32 v49, vcc, 0, v179, vcc
	global_load_dwordx4 v[56:59], v[48:49], off
	v_add_co_u32_e32 v48, vcc, s44, v176
	v_lshl_add_u64 v[174:175], v[164:165], 0, v[152:153]
	s_nop 0
	v_addc_co_u32_e32 v49, vcc, 0, v177, vcc
	global_load_dwordx4 v[52:55], v[48:49], off
	v_add_co_u32_e32 v48, vcc, s44, v174
	v_readlane_b32 s44, v254, 48
	v_ashrrev_i32_e32 v139, 31, v138
	v_readlane_b32 s45, v254, 49
	v_addc_co_u32_e32 v49, vcc, 0, v175, vcc
	v_lshl_add_u64 v[186:187], v[142:143], 0, s[48:49]
	v_lshl_add_u64 v[112:113], v[138:139], 2, s[44:45]
	v_lshl_add_u64 v[184:185], v[144:145], 0, s[48:49]
	global_load_dwordx4 v[96:99], v[186:187], off
	global_load_dwordx4 v[100:103], v[186:187], off offset:-16
	global_load_dwordx4 v[104:107], v[184:185], off
	global_load_dwordx4 v[108:111], v[184:185], off offset:-16
	s_nop 0
	global_load_dwordx4 v[48:51], v[48:49], off
	s_waitcnt vmcnt(27)
	v_lshlrev_b32_e32 v114, 16, v44
	global_load_dword v182, v[112:113], off
	ds_read_b64 v[112:113], v203
	v_and_b32_e32 v115, 0xffff0000, v44
	v_lshlrev_b32_e32 v208, 16, v46
	v_and_b32_e32 v209, 0xffff0000, v46
	v_lshlrev_b32_e32 v44, 16, v45
	v_and_b32_e32 v45, 0xffff0000, v45
	v_lshlrev_b32_e32 v46, 16, v47
	v_and_b32_e32 v47, 0xffff0000, v47
	s_waitcnt lgkmcnt(0)
	v_pk_add_f32 v[114:115], v[114:115], v[112:113] op_sel_hi:[1,0] neg_lo:[0,1] neg_hi:[0,1]
	v_pk_add_f32 v[208:209], v[208:209], v[112:113] op_sel_hi:[1,0] neg_lo:[0,1] neg_hi:[0,1]
	v_pk_add_f32 v[44:45], v[44:45], v[112:113] op_sel_hi:[1,0] neg_lo:[0,1] neg_hi:[0,1]
	v_pk_add_f32 v[46:47], v[46:47], v[112:113] op_sel_hi:[1,0] neg_lo:[0,1] neg_hi:[0,1]
	v_cndmask_b32_e64 v139, 0, 1, s[2:3]
	v_pk_mul_f32 v[114:115], v[112:113], v[114:115] op_sel:[1,0]
	v_pk_mul_f32 v[208:209], v[112:113], v[208:209] op_sel:[1,0]
	v_pk_mul_f32 v[210:211], v[112:113], v[44:45] op_sel:[1,0]
	v_pk_mul_f32 v[46:47], v[112:113], v[46:47] op_sel:[1,0]
	v_cmp_ne_u32_e64 s[44:45], 1, v139
	s_andn2_b64 vcc, exec, s[2:3]
	s_waitcnt vmcnt(3)
	v_pk_fma_f32 v[44:45], v[208:209], v[96:97], v[104:105]
	s_waitcnt vmcnt(2)
	v_pk_fma_f32 v[112:113], v[114:115], v[100:101], v[108:109]
	v_pk_fma_f32 v[114:115], v[210:211], v[102:103], v[110:111]
	v_pk_fma_f32 v[46:47], v[46:47], v[98:99], v[106:107]
	s_cbranch_vccnz .LBB0_352
	v_lshl_add_u64 v[96:97], v[166:167], 0, s[48:49]
	v_add_co_u32_e32 v96, vcc, 0x4250000, v96
	s_nop 1
	v_addc_co_u32_e32 v97, vcc, 0, v97, vcc
	global_store_dwordx4 v[96:97], v[112:115], off sc1
	global_store_dwordx4 v[96:97], v[44:47], off offset:16 sc1
	global_load_dwordx4 v[96:99], v[186:187], off
	s_nop 0
	global_load_dwordx4 v[100:103], v[186:187], off offset:-16
	global_load_dwordx4 v[104:107], v[184:185], off
	global_load_dwordx4 v[108:111], v[184:185], off offset:-16
; #define LAS __attribute__((address_space(3)))
; DI float bflo(unsigned w) { return __uint_as_float(w << 16); }
; DI float bfhi(unsigned w) { return __uint_as_float(w & 0xffff0000u); }
; DI u32x4 pk8(f32x4 a, f32x4 b) { u32x4 w; w.x = pk2(a[0], a[1]); w.y = pk2(a[2], a[3]); w.z = pk2(b[0], b[1]); w.w = pk2(b[2], b[3]); return w; }
; DI void spatial_cu(LAS unsigned char* lds, int cidx, const bf16* U, const bf16* VB, const float* STATS, const float* lng, const float* lnb,
;                    const float* wsp, const bf16* dummy, const float* bsp, bf16* CAT, float* outV, int tid, int wid, int lane) {
;     ...
; #pragma unroll
;         for (int c4 = 0; c4 < 4; ++c4) {
;             const int task = tid + 512 * c4, s = task >> 4, dc = task & 15;
;             const float mean = st[2 * s], rstd = st[2 * s + 1];
;             const f32x4 ga = *(const f32x4*)(lng + g * 128 + 8 * dc), gb = *(const f32x4*)(lng + g * 128 + 8 * dc + 4), ba = *(const f32x4*)(lnb + g * 128 + 8 * dc), bb = *(const f32x4*)(lnb + g * 128 + 8 * dc + 4);
;             f32x4 va, vb;
; #pragma unroll
;             for (int e = 0; e < 4; ++e) { const unsigned w0 = raw[c4][e >> 1], w1 = raw[c4][2 + (e >> 1)];
;                 va[e] = (((e & 1) ? bfhi(w0) : bflo(w0)) - mean) * rstd * ga[e] + ba[e]; vb[e] = (((e & 1) ? bfhi(w1) : bflo(w1)) - mean) * rstd * gb[e] + bb[e]; }
;             if (n == 15) { float* o = outV + ((size_t)(b * 128 + s)) * 2048 + g * 128 + 8 * dc; *(f32x4*)o = va; *(f32x4*)(o + 4) = vb; }
;             *(LAS u32x4*)(vs + s * VS + 8 * dc) = pk8(va, vb);
.LBB0_352:
	s_bitcmp1_b32 s50, 0
	s_cselect_b32 s51, 0xa000, 0
	s_add_i32 s51, s51, 0
	v_lshl_add_u32 v139, v190, 1, s51
	v_cvt_pk_bf16_f32 v112, v112, v113
	v_cvt_pk_bf16_f32 v113, v114, v115
	v_cvt_pk_bf16_f32 v114, v44, v45
	v_cvt_pk_bf16_f32 v115, v46, v47
	v_add_u32_e32 v44, v139, v197
	ds_write_b128 v44, v[112:115]
	ds_read_b64 v[114:115], v204
	v_lshlrev_b32_e32 v44, 16, v40
	v_and_b32_e32 v45, 0xffff0000, v40
	v_lshlrev_b32_e32 v46, 16, v42
	v_and_b32_e32 v47, 0xffff0000, v42
	v_lshlrev_b32_e32 v40, 16, v41
	v_and_b32_e32 v41, 0xffff0000, v41
	s_waitcnt lgkmcnt(0)
	v_pk_add_f32 v[46:47], v[46:47], v[114:115] op_sel_hi:[1,0] neg_lo:[0,1] neg_hi:[0,1]
	v_pk_add_f32 v[40:41], v[40:41], v[114:115] op_sel_hi:[1,0] neg_lo:[0,1] neg_hi:[0,1]
	v_pk_mul_f32 v[46:47], v[114:115], v[46:47] op_sel:[1,0]
	v_pk_mul_f32 v[40:41], v[114:115], v[40:41] op_sel:[1,0]
	s_waitcnt vmcnt(1)
	v_pk_fma_f32 v[112:113], v[46:47], v[96:97], v[104:105]
	s_waitcnt vmcnt(0)
	v_pk_fma_f32 v[46:47], v[40:41], v[102:103], v[110:111]
	v_lshlrev_b32_e32 v40, 16, v43
	v_and_b32_e32 v41, 0xffff0000, v43
	v_pk_add_f32 v[44:45], v[44:45], v[114:115] op_sel_hi:[1,0] neg_lo:[0,1] neg_hi:[0,1]
	v_pk_add_f32 v[40:41], v[40:41], v[114:115] op_sel_hi:[1,0] neg_lo:[0,1] neg_hi:[0,1]
	v_pk_mul_f32 v[44:45], v[114:115], v[44:45] op_sel:[1,0]
	v_pk_mul_f32 v[40:41], v[114:115], v[40:41] op_sel:[1,0]
	v_pk_fma_f32 v[44:45], v[44:45], v[100:101], v[108:109]
	s_and_b64 vcc, exec, s[44:45]
	v_pk_fma_f32 v[114:115], v[40:41], v[98:99], v[106:107]
	s_cbranch_vccnz .LBB0_354
	v_lshl_add_u64 v[40:41], v[168:169], 0, s[48:49]
	v_add_co_u32_e32 v40, vcc, 0x4250000, v40
	s_nop 1
	v_addc_co_u32_e32 v41, vcc, 0, v41, vcc
	global_store_dwordx4 v[40:41], v[44:47], off sc1
	global_store_dwordx4 v[40:41], v[112:115], off offset:16 sc1
	global_load_dwordx4 v[96:99], v[186:187], off
	global_load_dwordx4 v[100:103], v[186:187], off offset:-16
	global_load_dwordx4 v[104:107], v[184:185], off
	global_load_dwordx4 v[108:111], v[184:185], off offset:-16
.LBB0_354:
	v_cvt_pk_bf16_f32 v40, v44, v45
	v_cvt_pk_bf16_f32 v41, v46, v47
	v_cvt_pk_bf16_f32 v42, v112, v113
	v_cvt_pk_bf16_f32 v43, v114, v115
	v_add_u32_e32 v44, v139, v198
	ds_write_b128 v44, v[40:43]
	ds_read_b64 v[46:47], v205
	v_lshlrev_b32_e32 v40, 16, v36
	v_and_b32_e32 v41, 0xffff0000, v36
	v_lshlrev_b32_e32 v42, 16, v38
	v_and_b32_e32 v43, 0xffff0000, v38
	v_lshlrev_b32_e32 v36, 16, v37
	v_and_b32_e32 v37, 0xffff0000, v37
	s_waitcnt lgkmcnt(0)
	v_pk_add_f32 v[42:43], v[42:43], v[46:47] op_sel_hi:[1,0] neg_lo:[0,1] neg_hi:[0,1]
	v_pk_add_f32 v[36:37], v[36:37], v[46:47] op_sel_hi:[1,0] neg_lo:[0,1] neg_hi:[0,1]
	v_pk_mul_f32 v[42:43], v[46:47], v[42:43] op_sel:[1,0]
	v_pk_mul_f32 v[36:37], v[46:47], v[36:37] op_sel:[1,0]
	s_waitcnt vmcnt(1)
	v_pk_fma_f32 v[44:45], v[42:43], v[96:97], v[104:105]
	s_waitcnt vmcnt(0)
	v_pk_fma_f32 v[42:43], v[36:37], v[102:103], v[110:111]
	v_lshlrev_b32_e32 v36, 16, v39
	v_and_b32_e32 v37, 0xffff0000, v39
	v_pk_add_f32 v[40:41], v[40:41], v[46:47] op_sel_hi:[1,0] neg_lo:[0,1] neg_hi:[0,1]
	v_pk_add_f32 v[36:37], v[36:37], v[46:47] op_sel_hi:[1,0] neg_lo:[0,1] neg_hi:[0,1]
	v_pk_mul_f32 v[40:41], v[46:47], v[40:41] op_sel:[1,0]
	v_pk_mul_f32 v[36:37], v[46:47], v[36:37] op_sel:[1,0]
	v_pk_fma_f32 v[40:41], v[40:41], v[100:101], v[108:109]
	s_and_b64 vcc, exec, s[44:45]
	v_pk_fma_f32 v[46:47], v[36:37], v[98:99], v[106:107]
	s_cbranch_vccnz .LBB0_356
	v_lshl_add_u64 v[36:37], v[170:171], 0, s[48:49]
	v_add_co_u32_e32 v36, vcc, 0x4250000, v36
	s_nop 1
	v_addc_co_u32_e32 v37, vcc, 0, v37, vcc
	global_store_dwordx4 v[36:37], v[40:43], off sc1
	global_store_dwordx4 v[36:37], v[44:47], off offset:16 sc1
	global_load_dwordx4 v[96:99], v[186:187], off
	global_load_dwordx4 v[100:103], v[186:187], off offset:-16
	global_load_dwordx4 v[104:107], v[184:185], off
	global_load_dwordx4 v[108:111], v[184:185], off offset:-16
.LBB0_356:
	v_cvt_pk_bf16_f32 v36, v40, v41
	v_cvt_pk_bf16_f32 v37, v42, v43
	v_cvt_pk_bf16_f32 v38, v44, v45
	v_cvt_pk_bf16_f32 v39, v46, v47
	v_add_u32_e32 v40, v139, v199
	ds_write_b128 v40, v[36:39]
	ds_read_b64 v[42:43], v206
	v_lshlrev_b32_e32 v36, 16, v32
	v_and_b32_e32 v37, 0xffff0000, v32
	v_lshlrev_b32_e32 v38, 16, v34
	v_and_b32_e32 v39, 0xffff0000, v34
	v_lshlrev_b32_e32 v32, 16, v33
	v_and_b32_e32 v33, 0xffff0000, v33
	s_waitcnt lgkmcnt(0)
	v_pk_add_f32 v[38:39], v[38:39], v[42:43] op_sel_hi:[1,0] neg_lo:[0,1] neg_hi:[0,1]
	v_pk_add_f32 v[32:33], v[32:33], v[42:43] op_sel_hi:[1,0] neg_lo:[0,1] neg_hi:[0,1]
	v_pk_mul_f32 v[38:39], v[42:43], v[38:39] op_sel:[1,0]
	v_pk_mul_f32 v[32:33], v[42:43], v[32:33] op_sel:[1,0]
	s_waitcnt vmcnt(1)
	v_pk_fma_f32 v[40:41], v[38:39], v[96:97], v[104:105]
	s_waitcnt vmcnt(0)
	v_pk_fma_f32 v[38:39], v[32:33], v[102:103], v[110:111]
	v_lshlrev_b32_e32 v32, 16, v35
	v_and_b32_e32 v33, 0xffff0000, v35
	v_pk_add_f32 v[36:37], v[36:37], v[42:43] op_sel_hi:[1,0] neg_lo:[0,1] neg_hi:[0,1]
	v_pk_add_f32 v[32:33], v[32:33], v[42:43] op_sel_hi:[1,0] neg_lo:[0,1] neg_hi:[0,1]
	v_pk_mul_f32 v[36:37], v[42:43], v[36:37] op_sel:[1,0]
	v_pk_mul_f32 v[32:33], v[42:43], v[32:33] op_sel:[1,0]
	v_pk_fma_f32 v[36:37], v[36:37], v[100:101], v[108:109]
	s_and_b64 vcc, exec, s[44:45]
	v_pk_fma_f32 v[42:43], v[32:33], v[98:99], v[106:107]
	s_cbranch_vccnz .LBB0_349
	v_lshl_add_u64 v[32:33], v[172:173], 0, s[48:49]
	v_add_co_u32_e32 v32, vcc, 0x4250000, v32
	s_nop 1
	v_addc_co_u32_e32 v33, vcc, 0, v33, vcc
	global_store_dwordx4 v[32:33], v[36:39], off sc1
	global_store_dwordx4 v[32:33], v[40:43], off offset:16 sc1
	s_branch .LBB0_349

; DI float gelu_erf(float x) { const f32x2 r = gelu_pk((f32x2){x, x}); return r.x; }
; __device__ __forceinline__ f32x2 gelu_pk(f32x2 v) {
;     const f32x2 av = __builtin_elementwise_abs(v), d = av * 0.2316418882f + 1.0f;
;     f32x2 t; t.x = __builtin_amdgcn_rcpf(d.x); t.y = __builtin_amdgcn_rcpf(d.y);
;     f32x2 q = t * 0.5307027145f + (-0.7265760135f); q = q * t + 0.7107068705f; q = q * t + (-0.142248368f); q = q * t + 0.127414796f; q = q * t;
;     const f32x2 s = (v * v) * (-0.72134752044f);
;     f32x2 e; e.x = __builtin_amdgcn_exp2f(s.x); e.y = __builtin_amdgcn_exp2f(s.y);
;     const f32x2 m = v * (q * e), r = v - m;
;     f32x2 o; o.x = v.x < 0.f ? m.x : r.x; o.y = v.y < 0.f ? m.y : r.y; return o;
; }
; DI void sample_cmlp(int b, const float* PS, const float* lng, const float* lnb, const float* wsp, const float* bsp, bf16* CAT, float* outVs, int lane) {
;     ...
;     for (int j = 0; j < 8; ++j) { const f32x4 raw = ((const f32x4*)(ps + 2048))[lane + 64 * j];
; #pragma unroll
;         for (int e = 0; e < 4; ++e) { v[j][e] = gelu_erf(raw[e]); s += v[j][e]; } }
.LBB0_360:
	v_lshl_add_u64 v[136:137], s[6:7], 0, v[152:153]
	v_add_co_u32_e32 v8, vcc, 0x2e202000, v136
	v_mov_b64_e32 v[94:95], s[80:81]
	s_nop 0
	v_addc_co_u32_e32 v9, vcc, 0, v137, vcc
	global_load_dwordx4 v[12:15], v[8:9], off
	s_mov_b32 s0, 0x2e203000
	v_add_co_u32_e32 v28, vcc, s0, v136
	s_add_i32 s0, s4, 0x2000
	s_nop 0
	v_addc_co_u32_e32 v29, vcc, 0, v137, vcc
	s_ashr_i32 s1, s0, 31
	s_lshl_b64 s[2:3], s[0:1], 12
	s_mov_b32 s0, 0x2e200000
	v_add_co_u32_e32 v174, vcc, s0, v136
	s_mov_b32 s0, 0x2e201000
	s_nop 0
	v_addc_co_u32_e32 v175, vcc, 0, v137, vcc
	v_add_co_u32_e32 v136, vcc, s0, v136
	s_add_i32 s4, s4, s10
	s_nop 0
	v_addc_co_u32_e32 v137, vcc, 0, v137, vcc
	s_add_u32 s6, s6, s12
	s_addc_u32 s7, s7, s13
	s_waitcnt vmcnt(0)
	v_and_b32_e32 v0, 0x7fffffff, v12
	v_pk_fma_f32 v[0:1], v[0:1], s[76:77], 1.0 op_sel_hi:[0,0,0]
	v_rcp_f32_e32 v0, v0
	v_rcp_f32_e32 v1, v1
	v_cmp_gt_f32_e32 vcc, 0, v14
	v_cmp_gt_f32_e64 s[0:1], 0, v15
	v_pk_fma_f32 v[2:3], v[0:1], s[78:79], v[94:95] op_sel_hi:[1,0,0]
	s_nop 0
	v_pk_fma_f32 v[2:3], v[0:1], v[2:3], s[96:97] op_sel_hi:[1,1,0]
	s_nop 0
	v_pk_fma_f32 v[2:3], v[0:1], v[2:3], s[16:17] op_sel_hi:[1,1,0]
	s_nop 0
	v_pk_fma_f32 v[2:3], v[0:1], v[2:3], s[18:19] op_sel_hi:[1,1,0]
	s_nop 0
	v_pk_mul_f32 v[0:1], v[0:1], v[2:3]
	v_mul_f32_e32 v2, v12, v12
	v_mul_f32_e32 v2, 0xbf38aa3b, v2
	v_exp_f32_e32 v2, v2
	s_nop 0
	v_pk_mul_f32 v[0:1], v[2:3], v[0:1]
	s_nop 0
	v_pk_mul_f32 v[126:127], v[12:13], v[0:1]
	v_and_b32_e32 v0, 0x7fffffff, v13
	v_pk_fma_f32 v[0:1], v[0:1], s[76:77], 1.0 op_sel_hi:[0,0,0]
	v_rcp_f32_e32 v0, v0
	v_rcp_f32_e32 v1, v1
	s_nop 0
	v_pk_fma_f32 v[2:3], v[0:1], s[78:79], v[94:95] op_sel_hi:[1,0,0]
	s_nop 0
	v_pk_fma_f32 v[2:3], v[0:1], v[2:3], s[96:97] op_sel_hi:[1,1,0]
	s_nop 0
	v_pk_fma_f32 v[2:3], v[0:1], v[2:3], s[16:17] op_sel_hi:[1,1,0]
	s_nop 0
	v_pk_fma_f32 v[2:3], v[0:1], v[2:3], s[18:19] op_sel_hi:[1,1,0]
	s_nop 0
	v_pk_mul_f32 v[0:1], v[0:1], v[2:3]
	v_mul_f32_e32 v2, v13, v13
	v_mul_f32_e32 v2, 0xbf38aa3b, v2
	v_exp_f32_e32 v2, v2
	s_nop 0
	v_pk_mul_f32 v[0:1], v[2:3], v[0:1]
	s_nop 0
	v_pk_mul_f32 v[130:131], v[12:13], v[0:1] op_sel:[1,0]
	v_and_b32_e32 v0, 0x7fffffff, v14
	v_pk_fma_f32 v[0:1], v[0:1], s[76:77], 1.0 op_sel_hi:[0,0,0]
	v_rcp_f32_e32 v0, v0
	v_rcp_f32_e32 v1, v1
	v_mov_b32_e32 v127, v130
	v_pk_fma_f32 v[2:3], v[0:1], s[78:79], v[94:95] op_sel_hi:[1,0,0]
	s_nop 0
	v_pk_fma_f32 v[2:3], v[0:1], v[2:3], s[96:97] op_sel_hi:[1,1,0]
	s_nop 0
	v_pk_fma_f32 v[2:3], v[0:1], v[2:3], s[16:17] op_sel_hi:[1,1,0]
	s_nop 0
	v_pk_fma_f32 v[2:3], v[0:1], v[2:3], s[18:19] op_sel_hi:[1,1,0]
	s_nop 0
	v_pk_mul_f32 v[0:1], v[0:1], v[2:3]
	v_mul_f32_e32 v2, v14, v14
	v_mul_f32_e32 v2, 0xbf38aa3b, v2
	v_exp_f32_e32 v2, v2
	s_nop 0
	v_pk_mul_f32 v[0:1], v[2:3], v[0:1]
	v_and_b32_e32 v2, 0x7fffffff, v15
	v_pk_fma_f32 v[2:3], v[2:3], s[76:77], 1.0 op_sel_hi:[0,0,0]
	v_rcp_f32_e32 v2, v2
	v_rcp_f32_e32 v3, v3
	v_pk_mul_f32 v[138:139], v[14:15], v[0:1]
	v_mul_f32_e32 v1, v15, v15
	v_mul_f32_e32 v1, 0xbf38aa3b, v1
	v_pk_fma_f32 v[4:5], v[2:3], s[78:79], v[94:95] op_sel_hi:[1,0,0]
	v_mov_b32_e32 v0, v15
	v_pk_fma_f32 v[4:5], v[2:3], v[4:5], s[96:97] op_sel_hi:[1,1,0]
	s_nop 0
	v_pk_fma_f32 v[4:5], v[2:3], v[4:5], s[16:17] op_sel_hi:[1,1,0]
	s_nop 0
	v_pk_fma_f32 v[4:5], v[2:3], v[4:5], s[18:19] op_sel_hi:[1,1,0]
	s_nop 0
	v_pk_mul_f32 v[2:3], v[2:3], v[4:5]
	v_exp_f32_e32 v4, v1
	s_nop 0
	v_pk_mul_f32 v[2:3], v[4:5], v[2:3]
	s_nop 0
	v_pk_mul_f32 v[144:145], v[0:1], v[2:3] op_sel_hi:[0,1]
	global_load_dwordx4 v[0:3], v[8:9], off offset:1024
	v_mov_b32_e32 v139, v144
	v_pk_add_f32 v[14:15], v[14:15], v[138:139] neg_lo:[0,1] neg_hi:[0,1]
	s_waitcnt vmcnt(0)
	v_and_b32_e32 v4, 0x7fffffff, v0
	v_pk_fma_f32 v[4:5], v[4:5], s[76:77], 1.0 op_sel_hi:[0,0,0]
	v_rcp_f32_e32 v4, v4
	v_rcp_f32_e32 v5, v5
	v_cndmask_b32_e64 v15, v15, v144, s[0:1]
	v_cndmask_b32_e32 v14, v14, v138, vcc
	v_cmp_gt_f32_e32 vcc, 0, v12
	v_pk_fma_f32 v[6:7], v[4:5], s[78:79], v[94:95] op_sel_hi:[1,0,0]
	v_cmp_gt_f32_e64 s[0:1], 0, v13
	v_pk_fma_f32 v[6:7], v[4:5], v[6:7], s[96:97] op_sel_hi:[1,1,0]
	v_pk_add_f32 v[12:13], v[12:13], v[126:127] neg_lo:[0,1] neg_hi:[0,1]
	v_pk_fma_f32 v[6:7], v[4:5], v[6:7], s[16:17] op_sel_hi:[1,1,0]
	v_cndmask_b32_e32 v138, v12, v126, vcc
	v_pk_fma_f32 v[6:7], v[4:5], v[6:7], s[18:19] op_sel_hi:[1,1,0]
	v_cndmask_b32_e64 v139, v13, v130, s[0:1]
	v_pk_mul_f32 v[4:5], v[4:5], v[6:7]
	v_mul_f32_e32 v6, v0, v0
	v_mul_f32_e32 v6, 0xbf38aa3b, v6
	v_exp_f32_e32 v6, v6
	v_add_f32_e32 v12, 0, v138
	v_lshl_add_u64 v[144:145], s[8:9], 0, v[152:153]
	s_add_u32 s8, s8, s14
	v_pk_mul_f32 v[4:5], v[6:7], v[4:5]
	s_addc_u32 s9, s9, s15
	v_pk_mul_f32 v[96:97], v[0:1], v[4:5]
	v_and_b32_e32 v4, 0x7fffffff, v1
	v_pk_fma_f32 v[4:5], v[4:5], s[76:77], 1.0 op_sel_hi:[0,0,0]
	v_rcp_f32_e32 v4, v4
	v_rcp_f32_e32 v5, v5
	s_cmp_gt_i32 s4, 31
	v_pk_fma_f32 v[6:7], v[4:5], s[78:79], v[94:95] op_sel_hi:[1,0,0]
	s_nop 0
	v_pk_fma_f32 v[6:7], v[4:5], v[6:7], s[96:97] op_sel_hi:[1,1,0]
	s_nop 0
	v_pk_fma_f32 v[6:7], v[4:5], v[6:7], s[16:17] op_sel_hi:[1,1,0]
	s_nop 0
	v_pk_fma_f32 v[6:7], v[4:5], v[6:7], s[18:19] op_sel_hi:[1,1,0]
	s_nop 0
	v_pk_mul_f32 v[4:5], v[4:5], v[6:7]
	v_mul_f32_e32 v6, v1, v1
	v_mul_f32_e32 v6, 0xbf38aa3b, v6
	v_exp_f32_e32 v6, v6
	s_nop 0
	v_pk_mul_f32 v[4:5], v[6:7], v[4:5]
	s_nop 0
	v_pk_mul_f32 v[98:99], v[0:1], v[4:5] op_sel:[1,0]
	v_and_b32_e32 v4, 0x7fffffff, v2
	v_pk_fma_f32 v[4:5], v[4:5], s[76:77], 1.0 op_sel_hi:[0,0,0]
	v_rcp_f32_e32 v4, v4
	v_rcp_f32_e32 v5, v5
	s_nop 0
	v_pk_fma_f32 v[6:7], v[4:5], s[78:79], v[94:95] op_sel_hi:[1,0,0]
	s_nop 0
	v_pk_fma_f32 v[6:7], v[4:5], v[6:7], s[96:97] op_sel_hi:[1,1,0]
	s_nop 0
	v_pk_fma_f32 v[6:7], v[4:5], v[6:7], s[16:17] op_sel_hi:[1,1,0]
	s_nop 0
	v_pk_fma_f32 v[6:7], v[4:5], v[6:7], s[18:19] op_sel_hi:[1,1,0]
	s_nop 0
	v_pk_mul_f32 v[4:5], v[4:5], v[6:7]
	v_mul_f32_e32 v6, v2, v2
	v_mul_f32_e32 v6, 0xbf38aa3b, v6
	v_exp_f32_e32 v6, v6
	s_nop 0
	v_pk_mul_f32 v[4:5], v[6:7], v[4:5]
	v_and_b32_e32 v6, 0x7fffffff, v3
	v_pk_fma_f32 v[6:7], v[6:7], s[76:77], 1.0 op_sel_hi:[0,0,0]
	v_rcp_f32_e32 v6, v6
	v_rcp_f32_e32 v7, v7
	v_pk_mul_f32 v[100:101], v[2:3], v[4:5]
	v_mul_f32_e32 v5, v3, v3
	v_mul_f32_e32 v5, 0xbf38aa3b, v5
	v_pk_fma_f32 v[10:11], v[6:7], s[78:79], v[94:95] op_sel_hi:[1,0,0]
	v_mov_b32_e32 v4, v3
	v_pk_fma_f32 v[10:11], v[6:7], v[10:11], s[96:97] op_sel_hi:[1,1,0]
	s_nop 0
	v_pk_fma_f32 v[10:11], v[6:7], v[10:11], s[16:17] op_sel_hi:[1,1,0]
	s_nop 0
	v_pk_fma_f32 v[10:11], v[6:7], v[10:11], s[18:19] op_sel_hi:[1,1,0]
	s_nop 0
	v_pk_mul_f32 v[6:7], v[6:7], v[10:11]
	v_exp_f32_e32 v10, v5
	s_nop 0
	v_pk_mul_f32 v[6:7], v[10:11], v[6:7]
	s_nop 0
	v_pk_mul_f32 v[104:105], v[4:5], v[6:7] op_sel_hi:[0,1]
	global_load_dwordx4 v[4:7], v[8:9], off offset:2048
	v_mov_b32_e32 v101, v104
	s_waitcnt vmcnt(0)
; DI float gelu_erf(float x) { const f32x2 r = gelu_pk((f32x2){x, x}); return r.x; }
; __device__ __forceinline__ f32x2 gelu_pk(f32x2 v) {
;     const f32x2 av = __builtin_elementwise_abs(v), d = av * 0.2316418882f + 1.0f;
;     f32x2 t; t.x = __builtin_amdgcn_rcpf(d.x); t.y = __builtin_amdgcn_rcpf(d.y);
;     f32x2 q = t * 0.5307027145f + (-0.7265760135f); q = q * t + 0.7107068705f; q = q * t + (-0.142248368f); q = q * t + 0.127414796f; q = q * t;
;     const f32x2 s = (v * v) * (-0.72134752044f);
;     f32x2 e; e.x = __builtin_amdgcn_exp2f(s.x); e.y = __builtin_amdgcn_exp2f(s.y);
;     const f32x2 m = v * (q * e), r = v - m;
;     f32x2 o; o.x = v.x < 0.f ? m.x : r.x; o.y = v.y < 0.f ? m.y : r.y; return o;
; }
; DI void sample_cmlp(int b, const float* PS, const float* lng, const float* lnb, const float* wsp, const float* bsp, bf16* CAT, float* outVs, int lane) {
;     ...
;     for (int j = 0; j < 8; ++j) { const f32x4 raw = ((const f32x4*)(ps + 2048))[lane + 64 * j];
; #pragma unroll
;         for (int e = 0; e < 4; ++e) { v[j][e] = gelu_erf(raw[e]); s += v[j][e]; } }
	v_and_b32_e32 v10, 0x7fffffff, v4
	v_pk_fma_f32 v[10:11], v[10:11], s[76:77], 1.0 op_sel_hi:[0,0,0]
	v_rcp_f32_e32 v10, v10
	v_rcp_f32_e32 v11, v11
	s_nop 0
	v_pk_fma_f32 v[16:17], v[10:11], s[78:79], v[94:95] op_sel_hi:[1,0,0]
	s_nop 0
	v_pk_fma_f32 v[16:17], v[10:11], v[16:17], s[96:97] op_sel_hi:[1,1,0]
	s_nop 0
	v_pk_fma_f32 v[16:17], v[10:11], v[16:17], s[16:17] op_sel_hi:[1,1,0]
	s_nop 0
	v_pk_fma_f32 v[16:17], v[10:11], v[16:17], s[18:19] op_sel_hi:[1,1,0]
	s_nop 0
	v_pk_mul_f32 v[10:11], v[10:11], v[16:17]
	v_mul_f32_e32 v16, v4, v4
	v_mul_f32_e32 v16, 0xbf38aa3b, v16
	v_exp_f32_e32 v16, v16
	s_nop 0
	v_pk_mul_f32 v[10:11], v[16:17], v[10:11]
	s_nop 0
	v_pk_mul_f32 v[102:103], v[4:5], v[10:11]
	v_and_b32_e32 v10, 0x7fffffff, v5
	v_pk_fma_f32 v[10:11], v[10:11], s[76:77], 1.0 op_sel_hi:[0,0,0]
	v_rcp_f32_e32 v10, v10
	v_rcp_f32_e32 v11, v11
	s_nop 0
	v_pk_fma_f32 v[16:17], v[10:11], s[78:79], v[94:95] op_sel_hi:[1,0,0]
	s_nop 0
	v_pk_fma_f32 v[16:17], v[10:11], v[16:17], s[96:97] op_sel_hi:[1,1,0]
	s_nop 0
	v_pk_fma_f32 v[16:17], v[10:11], v[16:17], s[16:17] op_sel_hi:[1,1,0]
	s_nop 0
	v_pk_fma_f32 v[16:17], v[10:11], v[16:17], s[18:19] op_sel_hi:[1,1,0]
	s_nop 0
	v_pk_mul_f32 v[10:11], v[10:11], v[16:17]
	v_mul_f32_e32 v16, v5, v5
	v_mul_f32_e32 v16, 0xbf38aa3b, v16
	v_exp_f32_e32 v16, v16
	s_nop 0
	v_pk_mul_f32 v[10:11], v[16:17], v[10:11]
	s_nop 0
	v_pk_mul_f32 v[106:107], v[4:5], v[10:11] op_sel:[1,0]
	v_and_b32_e32 v10, 0x7fffffff, v6
	v_pk_fma_f32 v[10:11], v[10:11], s[76:77], 1.0 op_sel_hi:[0,0,0]
	v_rcp_f32_e32 v10, v10
	v_rcp_f32_e32 v11, v11
	v_mov_b32_e32 v103, v106
	v_pk_fma_f32 v[16:17], v[10:11], s[78:79], v[94:95] op_sel_hi:[1,0,0]
	s_nop 0
	v_pk_fma_f32 v[16:17], v[10:11], v[16:17], s[96:97] op_sel_hi:[1,1,0]
	s_nop 0
	v_pk_fma_f32 v[16:17], v[10:11], v[16:17], s[16:17] op_sel_hi:[1,1,0]
	s_nop 0
	v_pk_fma_f32 v[16:17], v[10:11], v[16:17], s[18:19] op_sel_hi:[1,1,0]
	s_nop 0
	v_pk_mul_f32 v[10:11], v[10:11], v[16:17]
	v_mul_f32_e32 v16, v6, v6
	v_mul_f32_e32 v16, 0xbf38aa3b, v16
	v_exp_f32_e32 v16, v16
	s_nop 0
	v_pk_mul_f32 v[10:11], v[16:17], v[10:11]
	v_and_b32_e32 v16, 0x7fffffff, v7
	v_pk_fma_f32 v[16:17], v[16:17], s[76:77], 1.0 op_sel_hi:[0,0,0]
	v_rcp_f32_e32 v16, v16
	v_rcp_f32_e32 v17, v17
	v_pk_mul_f32 v[108:109], v[6:7], v[10:11]
	v_mul_f32_e32 v11, v7, v7
	v_mul_f32_e32 v11, 0xbf38aa3b, v11
	v_pk_fma_f32 v[18:19], v[16:17], s[78:79], v[94:95] op_sel_hi:[1,0,0]
	v_mov_b32_e32 v10, v7
	v_pk_fma_f32 v[18:19], v[16:17], v[18:19], s[96:97] op_sel_hi:[1,1,0]
	s_nop 0
	v_pk_fma_f32 v[18:19], v[16:17], v[18:19], s[16:17] op_sel_hi:[1,1,0]
	s_nop 0
	v_pk_fma_f32 v[18:19], v[16:17], v[18:19], s[18:19] op_sel_hi:[1,1,0]
	s_nop 0
	v_pk_mul_f32 v[16:17], v[16:17], v[18:19]
	v_exp_f32_e32 v18, v11
	s_nop 0
	v_pk_mul_f32 v[16:17], v[18:19], v[16:17]
	s_nop 0
	v_pk_mul_f32 v[112:113], v[10:11], v[16:17] op_sel_hi:[0,1]
	global_load_dwordx4 v[8:11], v[8:9], off offset:3072
	v_mov_b32_e32 v109, v112
	s_waitcnt vmcnt(0)
	v_and_b32_e32 v16, 0x7fffffff, v8
	v_pk_fma_f32 v[16:17], v[16:17], s[76:77], 1.0 op_sel_hi:[0,0,0]
	v_rcp_f32_e32 v16, v16
	v_rcp_f32_e32 v17, v17
	s_nop 0
	v_pk_fma_f32 v[18:19], v[16:17], s[78:79], v[94:95] op_sel_hi:[1,0,0]
	s_nop 0
	v_pk_fma_f32 v[18:19], v[16:17], v[18:19], s[96:97] op_sel_hi:[1,1,0]
	s_nop 0
	v_pk_fma_f32 v[18:19], v[16:17], v[18:19], s[16:17] op_sel_hi:[1,1,0]
	s_nop 0
	v_pk_fma_f32 v[18:19], v[16:17], v[18:19], s[18:19] op_sel_hi:[1,1,0]
	s_nop 0
	v_pk_mul_f32 v[16:17], v[16:17], v[18:19]
	v_mul_f32_e32 v18, v8, v8
	v_mul_f32_e32 v18, 0xbf38aa3b, v18
	v_exp_f32_e32 v18, v18
	s_nop 0
	v_pk_mul_f32 v[16:17], v[18:19], v[16:17]
	s_nop 0
	v_pk_mul_f32 v[110:111], v[8:9], v[16:17]
	v_and_b32_e32 v16, 0x7fffffff, v9
	v_pk_fma_f32 v[16:17], v[16:17], s[76:77], 1.0 op_sel_hi:[0,0,0]
	v_rcp_f32_e32 v16, v16
	v_rcp_f32_e32 v17, v17
	s_nop 0
	v_pk_fma_f32 v[18:19], v[16:17], s[78:79], v[94:95] op_sel_hi:[1,0,0]
	s_nop 0
	v_pk_fma_f32 v[18:19], v[16:17], v[18:19], s[96:97] op_sel_hi:[1,1,0]
	s_nop 0
	v_pk_fma_f32 v[18:19], v[16:17], v[18:19], s[16:17] op_sel_hi:[1,1,0]
	s_nop 0
	v_pk_fma_f32 v[18:19], v[16:17], v[18:19], s[18:19] op_sel_hi:[1,1,0]
	s_nop 0
	v_pk_mul_f32 v[16:17], v[16:17], v[18:19]
	v_mul_f32_e32 v18, v9, v9
	v_mul_f32_e32 v18, 0xbf38aa3b, v18
	v_exp_f32_e32 v18, v18
	s_nop 0
	v_pk_mul_f32 v[16:17], v[18:19], v[16:17]
	s_nop 0
	v_pk_mul_f32 v[114:115], v[8:9], v[16:17] op_sel:[1,0]
	v_and_b32_e32 v16, 0x7fffffff, v10
	v_pk_fma_f32 v[16:17], v[16:17], s[76:77], 1.0 op_sel_hi:[0,0,0]
	v_rcp_f32_e32 v16, v16
	v_rcp_f32_e32 v17, v17
	v_mov_b32_e32 v111, v114
	v_pk_fma_f32 v[18:19], v[16:17], s[78:79], v[94:95] op_sel_hi:[1,0,0]
	s_nop 0
	v_pk_fma_f32 v[18:19], v[16:17], v[18:19], s[96:97] op_sel_hi:[1,1,0]
	s_nop 0
	v_pk_fma_f32 v[18:19], v[16:17], v[18:19], s[16:17] op_sel_hi:[1,1,0]
	s_nop 0
	v_pk_fma_f32 v[18:19], v[16:17], v[18:19], s[18:19] op_sel_hi:[1,1,0]
	s_nop 0
	v_pk_mul_f32 v[16:17], v[16:17], v[18:19]
	v_mul_f32_e32 v18, v10, v10
	v_mul_f32_e32 v18, 0xbf38aa3b, v18
	v_exp_f32_e32 v18, v18
	s_nop 0
	v_pk_mul_f32 v[16:17], v[18:19], v[16:17]
	v_and_b32_e32 v18, 0x7fffffff, v11
	v_pk_fma_f32 v[18:19], v[18:19], s[76:77], 1.0 op_sel_hi:[0,0,0]
	v_rcp_f32_e32 v18, v18
	v_rcp_f32_e32 v19, v19
	v_pk_mul_f32 v[116:117], v[10:11], v[16:17]
	v_mul_f32_e32 v17, v11, v11
	v_mul_f32_e32 v17, 0xbf38aa3b, v17
	v_pk_fma_f32 v[20:21], v[18:19], s[78:79], v[94:95] op_sel_hi:[1,0,0]
	v_mov_b32_e32 v16, v11
	v_pk_fma_f32 v[20:21], v[18:19], v[20:21], s[96:97] op_sel_hi:[1,1,0]
	s_nop 0
	v_pk_fma_f32 v[20:21], v[18:19], v[20:21], s[16:17] op_sel_hi:[1,1,0]
	s_nop 0
	v_pk_fma_f32 v[20:21], v[18:19], v[20:21], s[18:19] op_sel_hi:[1,1,0]
	s_nop 0
	v_pk_mul_f32 v[18:19], v[18:19], v[20:21]
	v_exp_f32_e32 v20, v17
	s_nop 0
	v_pk_mul_f32 v[18:19], v[20:21], v[18:19]
	s_nop 0
	v_pk_mul_f32 v[118:119], v[16:17], v[18:19] op_sel_hi:[0,1]
	global_load_dwordx4 v[16:19], v[28:29], off
	v_mov_b32_e32 v117, v118
	s_waitcnt vmcnt(0)
; DI float gelu_erf(float x) { const f32x2 r = gelu_pk((f32x2){x, x}); return r.x; }
; __device__ __forceinline__ f32x2 gelu_pk(f32x2 v) {
;     const f32x2 av = __builtin_elementwise_abs(v), d = av * 0.2316418882f + 1.0f;
;     f32x2 t; t.x = __builtin_amdgcn_rcpf(d.x); t.y = __builtin_amdgcn_rcpf(d.y);
;     f32x2 q = t * 0.5307027145f + (-0.7265760135f); q = q * t + 0.7107068705f; q = q * t + (-0.142248368f); q = q * t + 0.127414796f; q = q * t;
;     const f32x2 s = (v * v) * (-0.72134752044f);
;     f32x2 e; e.x = __builtin_amdgcn_exp2f(s.x); e.y = __builtin_amdgcn_exp2f(s.y);
;     const f32x2 m = v * (q * e), r = v - m;
;     f32x2 o; o.x = v.x < 0.f ? m.x : r.x; o.y = v.y < 0.f ? m.y : r.y; return o;
; }
; DI void sample_cmlp(int b, const float* PS, const float* lng, const float* lnb, const float* wsp, const float* bsp, bf16* CAT, float* outVs, int lane) {
;     ...
;     for (int j = 0; j < 8; ++j) { const f32x4 raw = ((const f32x4*)(ps + 2048))[lane + 64 * j];
; #pragma unroll
;         for (int e = 0; e < 4; ++e) { v[j][e] = gelu_erf(raw[e]); s += v[j][e]; } }
	v_and_b32_e32 v20, 0x7fffffff, v16
	v_pk_fma_f32 v[20:21], v[20:21], s[76:77], 1.0 op_sel_hi:[0,0,0]
	v_rcp_f32_e32 v20, v20
	v_rcp_f32_e32 v21, v21
	s_nop 0
	v_pk_fma_f32 v[22:23], v[20:21], s[78:79], v[94:95] op_sel_hi:[1,0,0]
	s_nop 0
	v_pk_fma_f32 v[22:23], v[20:21], v[22:23], s[96:97] op_sel_hi:[1,1,0]
	s_nop 0
	v_pk_fma_f32 v[22:23], v[20:21], v[22:23], s[16:17] op_sel_hi:[1,1,0]
	s_nop 0
	v_pk_fma_f32 v[22:23], v[20:21], v[22:23], s[18:19] op_sel_hi:[1,1,0]
	s_nop 0
	v_pk_mul_f32 v[20:21], v[20:21], v[22:23]
	v_mul_f32_e32 v22, v16, v16
	v_mul_f32_e32 v22, 0xbf38aa3b, v22
	v_exp_f32_e32 v22, v22
	s_nop 0
	v_pk_mul_f32 v[20:21], v[22:23], v[20:21]
	s_nop 0
	v_pk_mul_f32 v[120:121], v[16:17], v[20:21]
	v_and_b32_e32 v20, 0x7fffffff, v17
	v_pk_fma_f32 v[20:21], v[20:21], s[76:77], 1.0 op_sel_hi:[0,0,0]
	v_rcp_f32_e32 v20, v20
	v_rcp_f32_e32 v21, v21
	s_nop 0
	v_pk_fma_f32 v[22:23], v[20:21], s[78:79], v[94:95] op_sel_hi:[1,0,0]
	s_nop 0
	v_pk_fma_f32 v[22:23], v[20:21], v[22:23], s[96:97] op_sel_hi:[1,1,0]
	s_nop 0
	v_pk_fma_f32 v[22:23], v[20:21], v[22:23], s[16:17] op_sel_hi:[1,1,0]
	s_nop 0
	v_pk_fma_f32 v[22:23], v[20:21], v[22:23], s[18:19] op_sel_hi:[1,1,0]
	s_nop 0
	v_pk_mul_f32 v[20:21], v[20:21], v[22:23]
	v_mul_f32_e32 v22, v17, v17
	v_mul_f32_e32 v22, 0xbf38aa3b, v22
	v_exp_f32_e32 v22, v22
	s_nop 0
	v_pk_mul_f32 v[20:21], v[22:23], v[20:21]
	s_nop 0
	v_pk_mul_f32 v[122:123], v[16:17], v[20:21] op_sel:[1,0]
	v_and_b32_e32 v20, 0x7fffffff, v18
	v_pk_fma_f32 v[20:21], v[20:21], s[76:77], 1.0 op_sel_hi:[0,0,0]
	v_rcp_f32_e32 v20, v20
	v_rcp_f32_e32 v21, v21
	v_mov_b32_e32 v121, v122
	v_pk_fma_f32 v[22:23], v[20:21], s[78:79], v[94:95] op_sel_hi:[1,0,0]
	s_nop 0
	v_pk_fma_f32 v[22:23], v[20:21], v[22:23], s[96:97] op_sel_hi:[1,1,0]
	s_nop 0
	v_pk_fma_f32 v[22:23], v[20:21], v[22:23], s[16:17] op_sel_hi:[1,1,0]
	s_nop 0
	v_pk_fma_f32 v[22:23], v[20:21], v[22:23], s[18:19] op_sel_hi:[1,1,0]
	s_nop 0
	v_pk_mul_f32 v[20:21], v[20:21], v[22:23]
	v_mul_f32_e32 v22, v18, v18
	v_mul_f32_e32 v22, 0xbf38aa3b, v22
	v_exp_f32_e32 v22, v22
	s_nop 0
	v_pk_mul_f32 v[20:21], v[22:23], v[20:21]
	v_and_b32_e32 v22, 0x7fffffff, v19
	v_pk_fma_f32 v[22:23], v[22:23], s[76:77], 1.0 op_sel_hi:[0,0,0]
	v_rcp_f32_e32 v22, v22
	v_rcp_f32_e32 v23, v23
	v_pk_mul_f32 v[124:125], v[18:19], v[20:21]
	v_mul_f32_e32 v21, v19, v19
	v_mul_f32_e32 v21, 0xbf38aa3b, v21
	v_pk_fma_f32 v[24:25], v[22:23], s[78:79], v[94:95] op_sel_hi:[1,0,0]
	v_mov_b32_e32 v20, v19
	v_pk_fma_f32 v[24:25], v[22:23], v[24:25], s[96:97] op_sel_hi:[1,1,0]
	s_nop 0
	v_pk_fma_f32 v[24:25], v[22:23], v[24:25], s[16:17] op_sel_hi:[1,1,0]
	s_nop 0
	v_pk_fma_f32 v[24:25], v[22:23], v[24:25], s[18:19] op_sel_hi:[1,1,0]
	s_nop 0
	v_pk_mul_f32 v[22:23], v[22:23], v[24:25]
	v_exp_f32_e32 v24, v21
	s_nop 0
	v_pk_mul_f32 v[22:23], v[24:25], v[22:23]
	s_nop 0
	v_pk_mul_f32 v[132:133], v[20:21], v[22:23] op_sel_hi:[0,1]
	global_load_dwordx4 v[20:23], v[28:29], off offset:1024
	v_mov_b32_e32 v125, v132
	s_waitcnt vmcnt(0)
	v_and_b32_e32 v24, 0x7fffffff, v20
	v_pk_fma_f32 v[24:25], v[24:25], s[76:77], 1.0 op_sel_hi:[0,0,0]
	v_rcp_f32_e32 v24, v24
	v_rcp_f32_e32 v25, v25
	s_nop 0
	v_pk_fma_f32 v[26:27], v[24:25], s[78:79], v[94:95] op_sel_hi:[1,0,0]
	s_nop 0
	v_pk_fma_f32 v[26:27], v[24:25], v[26:27], s[96:97] op_sel_hi:[1,1,0]
	s_nop 0
	v_pk_fma_f32 v[26:27], v[24:25], v[26:27], s[16:17] op_sel_hi:[1,1,0]
	s_nop 0
	v_pk_fma_f32 v[26:27], v[24:25], v[26:27], s[18:19] op_sel_hi:[1,1,0]
	s_nop 0
	v_pk_mul_f32 v[24:25], v[24:25], v[26:27]
	v_mul_f32_e32 v26, v20, v20
	v_mul_f32_e32 v26, 0xbf38aa3b, v26
	v_exp_f32_e32 v26, v26
	s_nop 0
	v_pk_mul_f32 v[24:25], v[26:27], v[24:25]
	s_nop 0
	v_pk_mul_f32 v[128:129], v[20:21], v[24:25]
	v_and_b32_e32 v24, 0x7fffffff, v21
	v_pk_fma_f32 v[24:25], v[24:25], s[76:77], 1.0 op_sel_hi:[0,0,0]
	v_rcp_f32_e32 v24, v24
	v_rcp_f32_e32 v25, v25
	s_nop 0
	v_pk_fma_f32 v[26:27], v[24:25], s[78:79], v[94:95] op_sel_hi:[1,0,0]
	s_nop 0
	v_pk_fma_f32 v[26:27], v[24:25], v[26:27], s[96:97] op_sel_hi:[1,1,0]
	s_nop 0
	v_pk_fma_f32 v[26:27], v[24:25], v[26:27], s[16:17] op_sel_hi:[1,1,0]
	s_nop 0
	v_pk_fma_f32 v[26:27], v[24:25], v[26:27], s[18:19] op_sel_hi:[1,1,0]
	s_nop 0
	v_pk_mul_f32 v[24:25], v[24:25], v[26:27]
	v_mul_f32_e32 v26, v21, v21
	v_mul_f32_e32 v26, 0xbf38aa3b, v26
	v_exp_f32_e32 v26, v26
	s_nop 0
	v_pk_mul_f32 v[24:25], v[26:27], v[24:25]
	s_nop 0
	v_pk_mul_f32 v[134:135], v[20:21], v[24:25] op_sel:[1,0]
	v_and_b32_e32 v24, 0x7fffffff, v22
	v_pk_fma_f32 v[24:25], v[24:25], s[76:77], 1.0 op_sel_hi:[0,0,0]
	v_rcp_f32_e32 v24, v24
	v_rcp_f32_e32 v25, v25
	v_mov_b32_e32 v129, v134
	v_pk_fma_f32 v[26:27], v[24:25], s[78:79], v[94:95] op_sel_hi:[1,0,0]
	s_nop 0
	v_pk_fma_f32 v[26:27], v[24:25], v[26:27], s[96:97] op_sel_hi:[1,1,0]
	s_nop 0
	v_pk_fma_f32 v[26:27], v[24:25], v[26:27], s[16:17] op_sel_hi:[1,1,0]
	s_nop 0
	v_pk_fma_f32 v[26:27], v[24:25], v[26:27], s[18:19] op_sel_hi:[1,1,0]
	s_nop 0
	v_pk_mul_f32 v[24:25], v[24:25], v[26:27]
	v_mul_f32_e32 v26, v22, v22
	v_mul_f32_e32 v26, 0xbf38aa3b, v26
	v_exp_f32_e32 v26, v26
	s_nop 0
	v_pk_mul_f32 v[24:25], v[26:27], v[24:25]
	v_and_b32_e32 v26, 0x7fffffff, v23
	v_pk_fma_f32 v[26:27], v[26:27], s[76:77], 1.0 op_sel_hi:[0,0,0]
	v_rcp_f32_e32 v26, v26
	v_rcp_f32_e32 v27, v27
	v_pk_mul_f32 v[140:141], v[22:23], v[24:25]
	v_mul_f32_e32 v25, v23, v23
	v_mul_f32_e32 v25, 0xbf38aa3b, v25
	v_pk_fma_f32 v[30:31], v[26:27], s[78:79], v[94:95] op_sel_hi:[1,0,0]
	v_mov_b32_e32 v24, v23
	v_pk_fma_f32 v[30:31], v[26:27], v[30:31], s[96:97] op_sel_hi:[1,1,0]
	s_nop 0
	v_pk_fma_f32 v[30:31], v[26:27], v[30:31], s[16:17] op_sel_hi:[1,1,0]
	s_nop 0
	v_pk_fma_f32 v[30:31], v[26:27], v[30:31], s[18:19] op_sel_hi:[1,1,0]
	s_nop 0
	v_pk_mul_f32 v[26:27], v[26:27], v[30:31]
	v_exp_f32_e32 v30, v25
	s_nop 0
	v_pk_mul_f32 v[26:27], v[30:31], v[26:27]
	s_nop 0
	v_pk_mul_f32 v[146:147], v[24:25], v[26:27] op_sel_hi:[0,1]
	global_load_dwordx4 v[24:27], v[28:29], off offset:2048
	v_mov_b32_e32 v141, v146
	s_waitcnt vmcnt(0)
; DI float gelu_erf(float x) { const f32x2 r = gelu_pk((f32x2){x, x}); return r.x; }
; DI void sample_cmlp(int b, const float* PS, const float* lng, const float* lnb, const float* wsp, const float* bsp, bf16* CAT, float* outVs, int lane) {
;     ...
;     for (int j = 0; j < 8; ++j) { const f32x4 raw = ((const f32x4*)(ps + 2048))[lane + 64 * j];
; #pragma unroll
;         for (int e = 0; e < 4; ++e) { v[j][e] = gelu_erf(raw[e]); s += v[j][e]; } }
;     const float mean = wave_sum(s) * (1.0f / 2048.0f); float q = 0.f;
; #pragma unroll
;     for (int j = 0; j < 8; ++j)
; #pragma unroll
;         for (int e = 0; e < 4; ++e) { const float d = v[j][e] - mean; q += d * d; }
;     const float rstd = 1.0f / sqrtf(wave_sum(q) * (1.0f / 2048.0f) + EPSN);
; #pragma unroll
;     for (int j = 0; j < 8; ++j) { const int col = 4 * (lane + 64 * j), g = col >> 7;
;         const f32x4 ga = *(const f32x4*)(lng + col), ba = *(const f32x4*)(lnb + col), ur = *(const f32x4*)(ps + col);
;         const float w00 = wsp[(size_t)g * 16384], b0 = bsp[g * 128];
	v_and_b32_e32 v30, 0x7fffffff, v24
	v_pk_fma_f32 v[30:31], v[30:31], s[76:77], 1.0 op_sel_hi:[0,0,0]
	v_rcp_f32_e32 v30, v30
	v_rcp_f32_e32 v31, v31
	s_nop 0
	v_pk_fma_f32 v[32:33], v[30:31], s[78:79], v[94:95] op_sel_hi:[1,0,0]
	s_nop 0
	v_pk_fma_f32 v[32:33], v[30:31], v[32:33], s[96:97] op_sel_hi:[1,1,0]
	s_nop 0
	v_pk_fma_f32 v[32:33], v[30:31], v[32:33], s[16:17] op_sel_hi:[1,1,0]
	s_nop 0
	v_pk_fma_f32 v[32:33], v[30:31], v[32:33], s[18:19] op_sel_hi:[1,1,0]
	s_nop 0
	v_pk_mul_f32 v[30:31], v[30:31], v[32:33]
	v_mul_f32_e32 v32, v24, v24
	v_mul_f32_e32 v32, 0xbf38aa3b, v32
	v_exp_f32_e32 v32, v32
	s_nop 0
	v_pk_mul_f32 v[30:31], v[32:33], v[30:31]
	s_nop 0
	v_pk_mul_f32 v[142:143], v[24:25], v[30:31]
	v_and_b32_e32 v30, 0x7fffffff, v25
	v_pk_fma_f32 v[30:31], v[30:31], s[76:77], 1.0 op_sel_hi:[0,0,0]
	v_rcp_f32_e32 v30, v30
	v_rcp_f32_e32 v31, v31
	s_nop 0
	v_pk_fma_f32 v[32:33], v[30:31], s[78:79], v[94:95] op_sel_hi:[1,0,0]
	s_nop 0
	v_pk_fma_f32 v[32:33], v[30:31], v[32:33], s[96:97] op_sel_hi:[1,1,0]
	s_nop 0
	v_pk_fma_f32 v[32:33], v[30:31], v[32:33], s[16:17] op_sel_hi:[1,1,0]
	s_nop 0
	v_pk_fma_f32 v[32:33], v[30:31], v[32:33], s[18:19] op_sel_hi:[1,1,0]
	s_nop 0
	v_pk_mul_f32 v[30:31], v[30:31], v[32:33]
	v_mul_f32_e32 v32, v25, v25
	v_mul_f32_e32 v32, 0xbf38aa3b, v32
	v_exp_f32_e32 v32, v32
	s_nop 0
	v_pk_mul_f32 v[30:31], v[32:33], v[30:31]
	s_nop 0
	v_pk_mul_f32 v[148:149], v[24:25], v[30:31] op_sel:[1,0]
	v_and_b32_e32 v30, 0x7fffffff, v26
	v_pk_fma_f32 v[30:31], v[30:31], s[76:77], 1.0 op_sel_hi:[0,0,0]
	v_rcp_f32_e32 v30, v30
	v_rcp_f32_e32 v31, v31
	v_mov_b32_e32 v143, v148
	v_pk_fma_f32 v[32:33], v[30:31], s[78:79], v[94:95] op_sel_hi:[1,0,0]
	s_nop 0
	v_pk_fma_f32 v[32:33], v[30:31], v[32:33], s[96:97] op_sel_hi:[1,1,0]
	s_nop 0
	v_pk_fma_f32 v[32:33], v[30:31], v[32:33], s[16:17] op_sel_hi:[1,1,0]
	s_nop 0
	v_pk_fma_f32 v[32:33], v[30:31], v[32:33], s[18:19] op_sel_hi:[1,1,0]
	s_nop 0
	v_pk_mul_f32 v[30:31], v[30:31], v[32:33]
	v_mul_f32_e32 v32, v26, v26
	v_mul_f32_e32 v32, 0xbf38aa3b, v32
	v_exp_f32_e32 v32, v32
	s_nop 0
	v_pk_mul_f32 v[30:31], v[32:33], v[30:31]
	v_and_b32_e32 v32, 0x7fffffff, v27
	v_pk_fma_f32 v[32:33], v[32:33], s[76:77], 1.0 op_sel_hi:[0,0,0]
	v_rcp_f32_e32 v32, v32
	v_rcp_f32_e32 v33, v33
	v_pk_mul_f32 v[150:151], v[26:27], v[30:31]
	v_mul_f32_e32 v31, v27, v27
	v_mul_f32_e32 v31, 0xbf38aa3b, v31
	v_pk_fma_f32 v[34:35], v[32:33], s[78:79], v[94:95] op_sel_hi:[1,0,0]
	v_mov_b32_e32 v30, v27
	v_pk_fma_f32 v[34:35], v[32:33], v[34:35], s[96:97] op_sel_hi:[1,1,0]
	s_nop 0
	v_pk_fma_f32 v[34:35], v[32:33], v[34:35], s[16:17] op_sel_hi:[1,1,0]
	s_nop 0
	v_pk_fma_f32 v[34:35], v[32:33], v[34:35], s[18:19] op_sel_hi:[1,1,0]
	s_nop 0
	v_pk_mul_f32 v[32:33], v[32:33], v[34:35]
	v_exp_f32_e32 v34, v31
	s_nop 0
	v_pk_mul_f32 v[32:33], v[34:35], v[32:33]
	s_nop 0
	v_pk_mul_f32 v[166:167], v[30:31], v[32:33] op_sel_hi:[0,1]
	global_load_dwordx4 v[28:31], v[28:29], off offset:3072
	v_mov_b32_e32 v151, v166
	s_waitcnt vmcnt(0)
	v_and_b32_e32 v32, 0x7fffffff, v28
	v_pk_fma_f32 v[32:33], v[32:33], s[76:77], 1.0 op_sel_hi:[0,0,0]
	v_rcp_f32_e32 v32, v32
	v_rcp_f32_e32 v33, v33
	s_nop 0
	v_pk_fma_f32 v[34:35], v[32:33], s[78:79], v[94:95] op_sel_hi:[1,0,0]
	s_nop 0
	v_pk_fma_f32 v[34:35], v[32:33], v[34:35], s[96:97] op_sel_hi:[1,1,0]
	s_nop 0
	v_pk_fma_f32 v[34:35], v[32:33], v[34:35], s[16:17] op_sel_hi:[1,1,0]
	s_nop 0
	v_pk_fma_f32 v[34:35], v[32:33], v[34:35], s[18:19] op_sel_hi:[1,1,0]
	s_nop 0
	v_pk_mul_f32 v[32:33], v[32:33], v[34:35]
	v_mul_f32_e32 v34, v28, v28
	v_mul_f32_e32 v34, 0xbf38aa3b, v34
	v_exp_f32_e32 v34, v34
	s_nop 0
	v_pk_mul_f32 v[32:33], v[34:35], v[32:33]
	s_nop 0
	v_pk_mul_f32 v[164:165], v[28:29], v[32:33]
	v_and_b32_e32 v32, 0x7fffffff, v29
	v_pk_fma_f32 v[32:33], v[32:33], s[76:77], 1.0 op_sel_hi:[0,0,0]
	v_rcp_f32_e32 v32, v32
	v_rcp_f32_e32 v33, v33
	s_nop 0
	v_pk_fma_f32 v[34:35], v[32:33], s[78:79], v[94:95] op_sel_hi:[1,0,0]
	s_nop 0
	v_pk_fma_f32 v[34:35], v[32:33], v[34:35], s[96:97] op_sel_hi:[1,1,0]
	s_nop 0
	v_pk_fma_f32 v[34:35], v[32:33], v[34:35], s[16:17] op_sel_hi:[1,1,0]
	s_nop 0
	v_pk_fma_f32 v[34:35], v[32:33], v[34:35], s[18:19] op_sel_hi:[1,1,0]
	s_nop 0
	v_pk_mul_f32 v[32:33], v[32:33], v[34:35]
	v_mul_f32_e32 v34, v29, v29
	v_mul_f32_e32 v34, 0xbf38aa3b, v34
	v_exp_f32_e32 v34, v34
	s_nop 0
	v_pk_mul_f32 v[32:33], v[34:35], v[32:33]
	s_nop 0
	v_pk_mul_f32 v[168:169], v[28:29], v[32:33] op_sel:[1,0]
	v_and_b32_e32 v32, 0x7fffffff, v30
	v_pk_fma_f32 v[32:33], v[32:33], s[76:77], 1.0 op_sel_hi:[0,0,0]
	v_rcp_f32_e32 v32, v32
	v_rcp_f32_e32 v33, v33
	v_mov_b32_e32 v165, v168
	v_pk_fma_f32 v[34:35], v[32:33], s[78:79], v[94:95] op_sel_hi:[1,0,0]
	s_nop 0
	v_pk_fma_f32 v[34:35], v[32:33], v[34:35], s[96:97] op_sel_hi:[1,1,0]
	s_nop 0
	v_pk_fma_f32 v[34:35], v[32:33], v[34:35], s[16:17] op_sel_hi:[1,1,0]
	s_nop 0
	v_pk_fma_f32 v[34:35], v[32:33], v[34:35], s[18:19] op_sel_hi:[1,1,0]
	s_nop 0
	v_pk_mul_f32 v[32:33], v[32:33], v[34:35]
	v_mul_f32_e32 v34, v30, v30
	v_mul_f32_e32 v34, 0xbf38aa3b, v34
	v_exp_f32_e32 v34, v34
	s_nop 0
	v_pk_mul_f32 v[32:33], v[34:35], v[32:33]
	v_and_b32_e32 v34, 0x7fffffff, v31
	v_pk_fma_f32 v[34:35], v[34:35], s[76:77], 1.0 op_sel_hi:[0,0,0]
	v_rcp_f32_e32 v34, v34
	v_rcp_f32_e32 v35, v35
	v_pk_mul_f32 v[170:171], v[30:31], v[32:33]
	v_mul_f32_e32 v33, v31, v31
	v_mul_f32_e32 v33, 0xbf38aa3b, v33
	v_pk_fma_f32 v[36:37], v[34:35], s[78:79], v[94:95] op_sel_hi:[1,0,0]
	v_mov_b32_e32 v32, v31
	v_pk_fma_f32 v[36:37], v[34:35], v[36:37], s[96:97] op_sel_hi:[1,1,0]
	s_nop 0
	v_pk_fma_f32 v[36:37], v[34:35], v[36:37], s[16:17] op_sel_hi:[1,1,0]
	s_nop 0
	v_pk_fma_f32 v[36:37], v[34:35], v[36:37], s[18:19] op_sel_hi:[1,1,0]
	s_nop 0
	v_pk_mul_f32 v[34:35], v[34:35], v[36:37]
	v_exp_f32_e32 v36, v33
	s_nop 0
	v_pk_mul_f32 v[34:35], v[36:37], v[34:35]
	s_nop 0
	v_pk_mul_f32 v[172:173], v[32:33], v[34:35] op_sel_hi:[0,1]
	global_load_dwordx4 v[32:35], v[40:41], off
	global_load_dwordx4 v[36:39], v[42:43], off
	global_load_dwordx4 v[184:187], v[136:137], off offset:-4096
	global_load_dword v176, v[44:45], off
	global_load_dword v178, v[46:47], off
	v_mov_b32_e32 v171, v172
	s_waitcnt vmcnt(2)
; DI float gelu_erf(float x) { const f32x2 r = gelu_pk((f32x2){x, x}); return r.x; }
; DI void sample_cmlp(int b, const float* PS, const float* lng, const float* lnb, const float* wsp, const float* bsp, bf16* CAT, float* outVs, int lane) {
;     ...
;     for (int j = 0; j < 8; ++j) { const f32x4 raw = ((const f32x4*)(ps + 2048))[lane + 64 * j];
; #pragma unroll
;         for (int e = 0; e < 4; ++e) { v[j][e] = gelu_erf(raw[e]); s += v[j][e]; } }
;     const float mean = wave_sum(s) * (1.0f / 2048.0f); float q = 0.f;
; #pragma unroll
;     for (int j = 0; j < 8; ++j)
; #pragma unroll
;         for (int e = 0; e < 4; ++e) { const float d = v[j][e] - mean; q += d * d; }
;     const float rstd = 1.0f / sqrtf(wave_sum(q) * (1.0f / 2048.0f) + EPSN);
; #pragma unroll
;     for (int j = 0; j < 8; ++j) { const int col = 4 * (lane + 64 * j), g = col >> 7;
;         const f32x4 ga = *(const f32x4*)(lng + col), ba = *(const f32x4*)(lnb + col), ur = *(const f32x4*)(ps + col);
;         const float w00 = wsp[(size_t)g * 16384], b0 = bsp[g * 128];
;         f32x4 vn, o;
; #pragma unroll
;         for (int e = 0; e < 4; ++e) { vn[e] = (v[j][e] - mean) * rstd * ga[e] + ba[e]; o[e] = gelu_erf(ur[e]) * (w00 * vn[e] + b0); }
	v_and_b32_e32 v188, 0x7fffffff, v184
	v_pk_fma_f32 v[188:189], v[188:189], s[76:77], 1.0 op_sel_hi:[0,0,0]
	v_rcp_f32_e32 v188, v188
	v_rcp_f32_e32 v189, v189
	v_mul_f32_e32 v97, v184, v184
	v_mul_f32_e32 v97, 0xbf38aa3b, v97
	v_and_b32_e32 v196, 0x7fffffff, v187
	v_pk_fma_f32 v[190:191], v[188:189], s[78:79], v[94:95] op_sel_hi:[1,0,0]
	v_pk_fma_f32 v[196:197], v[196:197], s[76:77], 1.0 op_sel_hi:[0,0,0]
	v_pk_fma_f32 v[190:191], v[188:189], v[190:191], s[96:97] op_sel_hi:[1,1,0]
	v_rcp_f32_e32 v196, v196
	v_pk_fma_f32 v[190:191], v[188:189], v[190:191], s[16:17] op_sel_hi:[1,1,0]
	v_rcp_f32_e32 v197, v197
	v_pk_fma_f32 v[190:191], v[188:189], v[190:191], s[18:19] op_sel_hi:[1,1,0]
	v_cmp_gt_f32_e32 vcc, 0, v184
	v_pk_mul_f32 v[188:189], v[188:189], v[190:191]
	v_exp_f32_e32 v190, v97
	v_mul_f32_e32 v97, v185, v185
	v_mul_f32_e32 v97, 0xbf38aa3b, v97
	v_pk_fma_f32 v[198:199], v[196:197], s[78:79], v[94:95] op_sel_hi:[1,0,0]
	v_pk_mul_f32 v[188:189], v[190:191], v[188:189]
	v_and_b32_e32 v190, 0x7fffffff, v185
	v_pk_fma_f32 v[190:191], v[190:191], s[76:77], 1.0 op_sel_hi:[0,0,0]
	v_rcp_f32_e32 v190, v190
	v_rcp_f32_e32 v191, v191
	v_pk_fma_f32 v[198:199], v[196:197], v[198:199], s[96:97] op_sel_hi:[1,1,0]
	v_pk_mul_f32 v[188:189], v[184:185], v[188:189]
	v_pk_fma_f32 v[198:199], v[196:197], v[198:199], s[16:17] op_sel_hi:[1,1,0]
	v_pk_fma_f32 v[192:193], v[190:191], s[78:79], v[94:95] op_sel_hi:[1,0,0]
	v_pk_fma_f32 v[198:199], v[196:197], v[198:199], s[18:19] op_sel_hi:[1,1,0]
	v_pk_fma_f32 v[192:193], v[190:191], v[192:193], s[96:97] op_sel_hi:[1,1,0]
	v_pk_mul_f32 v[196:197], v[196:197], v[198:199]
	v_pk_fma_f32 v[192:193], v[190:191], v[192:193], s[16:17] op_sel_hi:[1,1,0]
	v_cmp_gt_f32_e64 s[0:1], 0, v185
	v_pk_fma_f32 v[192:193], v[190:191], v[192:193], s[18:19] op_sel_hi:[1,1,0]
	s_nop 0
	v_pk_mul_f32 v[190:191], v[190:191], v[192:193]
	v_exp_f32_e32 v192, v97
	v_mul_f32_e32 v97, v186, v186
	v_mul_f32_e32 v97, 0xbf38aa3b, v97
	v_pk_mul_f32 v[190:191], v[192:193], v[190:191]
	v_and_b32_e32 v192, 0x7fffffff, v186
	v_pk_fma_f32 v[192:193], v[192:193], s[76:77], 1.0 op_sel_hi:[0,0,0]
	v_rcp_f32_e32 v192, v192
	v_rcp_f32_e32 v193, v193
	v_pk_mul_f32 v[190:191], v[184:185], v[190:191] op_sel:[1,0]
	v_pk_fma_f32 v[194:195], v[192:193], s[78:79], v[94:95] op_sel_hi:[1,0,0]
	s_nop 0
	v_pk_fma_f32 v[194:195], v[192:193], v[194:195], s[96:97] op_sel_hi:[1,1,0]
	v_mov_b32_e32 v189, v190
	v_pk_fma_f32 v[194:195], v[192:193], v[194:195], s[16:17] op_sel_hi:[1,1,0]
	s_nop 0
	v_pk_fma_f32 v[194:195], v[192:193], v[194:195], s[18:19] op_sel_hi:[1,1,0]
	s_nop 0
	v_pk_mul_f32 v[192:193], v[192:193], v[194:195]
	v_exp_f32_e32 v194, v97
	v_mul_f32_e32 v97, v187, v187
	v_mul_f32_e32 v97, 0xbf38aa3b, v97
	v_exp_f32_e32 v198, v97
	v_pk_mul_f32 v[192:193], v[194:195], v[192:193]
	v_mov_b32_e32 v194, v187
	v_add_f32_e32 v97, v139, v12
	v_pk_mul_f32 v[196:197], v[198:199], v[196:197]
	v_pk_add_f32 v[12:13], v[184:185], v[188:189] neg_lo:[0,1] neg_hi:[0,1]
	v_pk_mul_f32 v[192:193], v[186:187], v[192:193]
	v_pk_mul_f32 v[194:195], v[194:195], v[196:197] op_sel_hi:[0,1]
	v_cndmask_b32_e32 v126, v12, v188, vcc
	v_add_f32_e32 v12, v14, v97
	v_cndmask_b32_e64 v127, v13, v190, s[0:1]
	v_add_f32_e32 v99, v15, v12
	v_cmp_gt_f32_e32 vcc, 0, v30
	v_cmp_gt_f32_e64 s[0:1], 0, v31
	v_pk_add_f32 v[12:13], v[30:31], v[170:171] neg_lo:[0,1] neg_hi:[0,1]
	v_mov_b32_e32 v193, v194
	v_cndmask_b32_e64 v131, v13, v172, s[0:1]
	v_cndmask_b32_e32 v130, v12, v170, vcc
	v_cmp_gt_f32_e32 vcc, 0, v186
	v_cmp_gt_f32_e64 s[0:1], 0, v187
	v_pk_add_f32 v[12:13], v[186:187], v[192:193] neg_lo:[0,1] neg_hi:[0,1]
	v_mov_b32_e32 v97, v98
	v_cndmask_b32_e64 v31, v13, v194, s[0:1]
	v_cndmask_b32_e32 v30, v12, v192, vcc
	v_cmp_gt_f32_e32 vcc, 0, v2
	v_cmp_gt_f32_e64 s[0:1], 0, v3
	v_pk_add_f32 v[2:3], v[2:3], v[100:101] neg_lo:[0,1] neg_hi:[0,1]
	v_lshl_add_u64 v[12:13], v[92:93], 0, s[2:3]
	v_cndmask_b32_e64 v3, v3, v104, s[0:1]
	v_cndmask_b32_e32 v2, v2, v100, vcc
	v_cmp_gt_f32_e32 vcc, 0, v0
	v_cmp_gt_f32_e64 s[0:1], 0, v1
	v_pk_add_f32 v[0:1], v[0:1], v[96:97] neg_lo:[0,1] neg_hi:[0,1]
	s_nop 0
	v_cndmask_b32_e32 v0, v0, v96, vcc
	v_cndmask_b32_e64 v1, v1, v98, s[0:1]
	v_add_f32_e32 v96, v0, v99
	v_add_f32_e32 v96, v1, v96
	v_cmp_gt_f32_e32 vcc, 0, v6
	v_cmp_gt_f32_e64 s[0:1], 0, v7
	v_pk_add_f32 v[6:7], v[6:7], v[108:109] neg_lo:[0,1] neg_hi:[0,1]
	v_add_f32_e32 v96, v2, v96
	v_cndmask_b32_e64 v7, v7, v112, s[0:1]
	v_cndmask_b32_e32 v6, v6, v108, vcc
	v_cmp_gt_f32_e32 vcc, 0, v4
	v_cmp_gt_f32_e64 s[0:1], 0, v5
	v_pk_add_f32 v[4:5], v[4:5], v[102:103] neg_lo:[0,1] neg_hi:[0,1]
	v_add_f32_e32 v96, v3, v96
	v_cndmask_b32_e32 v4, v4, v102, vcc
	v_cndmask_b32_e64 v5, v5, v106, s[0:1]
	v_add_f32_e32 v96, v4, v96
	v_add_f32_e32 v96, v5, v96
	v_cmp_gt_f32_e32 vcc, 0, v10
	v_cmp_gt_f32_e64 s[0:1], 0, v11
	v_pk_add_f32 v[10:11], v[10:11], v[116:117] neg_lo:[0,1] neg_hi:[0,1]
	v_add_f32_e32 v96, v6, v96
	v_cndmask_b32_e64 v11, v11, v118, s[0:1]
	v_cndmask_b32_e32 v10, v10, v116, vcc
	v_cmp_gt_f32_e32 vcc, 0, v8
	v_cmp_gt_f32_e64 s[0:1], 0, v9
	v_pk_add_f32 v[8:9], v[8:9], v[110:111] neg_lo:[0,1] neg_hi:[0,1]
	v_add_f32_e32 v96, v7, v96
	v_cndmask_b32_e32 v8, v8, v110, vcc
	v_cndmask_b32_e64 v9, v9, v114, s[0:1]
	v_add_f32_e32 v96, v8, v96
	v_add_f32_e32 v96, v9, v96
	v_cmp_gt_f32_e32 vcc, 0, v18
	v_cmp_gt_f32_e64 s[0:1], 0, v19
	v_pk_add_f32 v[18:19], v[18:19], v[124:125] neg_lo:[0,1] neg_hi:[0,1]
	v_add_f32_e32 v96, v10, v96
	v_cndmask_b32_e64 v19, v19, v132, s[0:1]
	v_cndmask_b32_e32 v18, v18, v124, vcc
	v_cmp_gt_f32_e32 vcc, 0, v16
	v_cmp_gt_f32_e64 s[0:1], 0, v17
; DI void sample_cmlp(int b, const float* PS, const float* lng, const float* lnb, const float* wsp, const float* bsp, bf16* CAT, float* outVs, int lane) {
;     ...
;     const float mean = wave_sum(s) * (1.0f / 2048.0f); float q = 0.f;
; #pragma unroll
;     for (int j = 0; j < 8; ++j)
; #pragma unroll
;         for (int e = 0; e < 4; ++e) { const float d = v[j][e] - mean; q += d * d; }
;     const float rstd = 1.0f / sqrtf(wave_sum(q) * (1.0f / 2048.0f) + EPSN);
	v_pk_add_f32 v[16:17], v[16:17], v[120:121] neg_lo:[0,1] neg_hi:[0,1]
	v_add_f32_e32 v96, v11, v96
	v_cndmask_b32_e32 v16, v16, v120, vcc
	v_cndmask_b32_e64 v17, v17, v122, s[0:1]
	v_add_f32_e32 v96, v16, v96
	v_add_f32_e32 v96, v17, v96
	v_cmp_gt_f32_e32 vcc, 0, v22
	v_cmp_gt_f32_e64 s[0:1], 0, v23
	v_pk_add_f32 v[22:23], v[22:23], v[140:141] neg_lo:[0,1] neg_hi:[0,1]
	v_add_f32_e32 v96, v18, v96
	v_cndmask_b32_e64 v101, v23, v146, s[0:1]
	v_cndmask_b32_e32 v100, v22, v140, vcc
	v_cmp_gt_f32_e32 vcc, 0, v20
	v_cmp_gt_f32_e64 s[0:1], 0, v21
	v_pk_add_f32 v[20:21], v[20:21], v[128:129] neg_lo:[0,1] neg_hi:[0,1]
	v_add_f32_e32 v96, v19, v96
	v_cndmask_b32_e32 v102, v20, v128, vcc
	v_cndmask_b32_e64 v103, v21, v134, s[0:1]
	v_add_f32_e32 v20, v102, v96
	v_add_f32_e32 v20, v103, v20
	v_add_f32_e32 v20, v100, v20
	v_add_f32_e32 v22, v101, v20
	v_cmp_gt_f32_e32 vcc, 0, v26
	v_cmp_gt_f32_e64 s[0:1], 0, v27
	v_pk_add_f32 v[20:21], v[26:27], v[150:151] neg_lo:[0,1] neg_hi:[0,1]
	s_nop 0
	v_cndmask_b32_e64 v105, v21, v166, s[0:1]
	v_cndmask_b32_e32 v104, v20, v150, vcc
	v_cmp_gt_f32_e32 vcc, 0, v24
	v_pk_add_f32 v[20:21], v[24:25], v[142:143] neg_lo:[0,1] neg_hi:[0,1]
	v_cmp_gt_f32_e64 s[0:1], 0, v25
	v_cndmask_b32_e32 v106, v20, v142, vcc
	v_add_f32_e32 v20, v106, v22
	v_cndmask_b32_e64 v107, v21, v148, s[0:1]
	v_add_f32_e32 v20, v107, v20
	v_add_f32_e32 v20, v104, v20
	v_add_f32_e32 v22, v105, v20
	v_cmp_gt_f32_e32 vcc, 0, v28
	v_pk_add_f32 v[20:21], v[28:29], v[164:165] neg_lo:[0,1] neg_hi:[0,1]
	v_cmp_gt_f32_e64 s[0:1], 0, v29
	v_cndmask_b32_e32 v108, v20, v164, vcc
	v_add_f32_e32 v20, v108, v22
	v_cndmask_b32_e64 v109, v21, v168, s[0:1]
	v_add_f32_e32 v20, v109, v20
	v_add_f32_e32 v20, v130, v20
	v_add_f32_e32 v20, v131, v20
	ds_bpermute_b32 v21, v177, v20
	s_waitcnt lgkmcnt(0)
	v_add_f32_e32 v20, v20, v21
	ds_bpermute_b32 v21, v179, v20
	s_waitcnt lgkmcnt(0)
	v_add_f32_e32 v20, v20, v21
	ds_bpermute_b32 v21, v180, v20
	s_waitcnt lgkmcnt(0)
	v_add_f32_e32 v20, v20, v21
	ds_bpermute_b32 v21, v181, v20
	s_waitcnt lgkmcnt(0)
	v_add_f32_e32 v20, v20, v21
	ds_bpermute_b32 v21, v182, v20
	s_waitcnt lgkmcnt(0)
	v_add_f32_e32 v20, v20, v21
	ds_bpermute_b32 v21, v183, v20
	s_waitcnt lgkmcnt(0)
	v_add_f32_e32 v20, v20, v21
	v_mul_f32_e32 v110, 0x3a000000, v20
	v_pk_add_f32 v[112:113], v[138:139], v[110:111] op_sel_hi:[1,0] neg_lo:[0,1] neg_hi:[0,1]
	v_pk_add_f32 v[116:117], v[14:15], v[110:111] op_sel_hi:[1,0] neg_lo:[0,1] neg_hi:[0,1]
	v_pk_mul_f32 v[114:115], v[112:113], v[112:113]
	v_pk_mul_f32 v[118:119], v[116:117], v[116:117]
	v_add_f32_e32 v114, v114, v115
	v_pk_add_f32 v[98:99], v[0:1], v[110:111] op_sel_hi:[1,0] neg_lo:[0,1] neg_hi:[0,1]
	v_add_f32_e32 v114, v118, v114
	v_pk_mul_f32 v[120:121], v[98:99], v[98:99]
	v_add_f32_e32 v114, v119, v114
	v_pk_add_f32 v[96:97], v[2:3], v[110:111] op_sel_hi:[1,0] neg_lo:[0,1] neg_hi:[0,1]
	v_add_f32_e32 v114, v120, v114
	v_pk_mul_f32 v[122:123], v[96:97], v[96:97]
	v_add_f32_e32 v114, v121, v114
	v_pk_add_f32 v[28:29], v[4:5], v[110:111] op_sel_hi:[1,0] neg_lo:[0,1] neg_hi:[0,1]
	v_add_f32_e32 v114, v122, v114
	v_pk_mul_f32 v[4:5], v[28:29], v[28:29]
	v_add_f32_e32 v114, v123, v114
	v_pk_add_f32 v[26:27], v[6:7], v[110:111] op_sel_hi:[1,0] neg_lo:[0,1] neg_hi:[0,1]
	v_add_f32_e32 v4, v4, v114
	v_pk_mul_f32 v[124:125], v[26:27], v[26:27]
	v_add_f32_e32 v4, v5, v4
	v_pk_add_f32 v[24:25], v[8:9], v[110:111] op_sel_hi:[1,0] neg_lo:[0,1] neg_hi:[0,1]
	v_add_f32_e32 v4, v124, v4
	v_pk_mul_f32 v[128:129], v[24:25], v[24:25]
	v_add_f32_e32 v4, v125, v4
	v_pk_add_f32 v[22:23], v[10:11], v[110:111] op_sel_hi:[1,0] neg_lo:[0,1] neg_hi:[0,1]
	v_add_f32_e32 v4, v128, v4
	v_pk_mul_f32 v[132:133], v[22:23], v[22:23]
	v_add_f32_e32 v4, v129, v4
	v_pk_add_f32 v[20:21], v[16:17], v[110:111] op_sel_hi:[1,0] neg_lo:[0,1] neg_hi:[0,1]
	v_add_f32_e32 v4, v132, v4
	v_pk_mul_f32 v[134:135], v[20:21], v[20:21]
	v_add_f32_e32 v4, v133, v4
	v_pk_add_f32 v[16:17], v[18:19], v[110:111] op_sel_hi:[1,0] neg_lo:[0,1] neg_hi:[0,1]
	v_add_f32_e32 v4, v134, v4
	v_pk_mul_f32 v[18:19], v[16:17], v[16:17]
	v_add_f32_e32 v4, v135, v4
	v_pk_add_f32 v[14:15], v[102:103], v[110:111] op_sel_hi:[1,0] neg_lo:[0,1] neg_hi:[0,1]
	v_add_f32_e32 v4, v18, v4
	v_pk_mul_f32 v[102:103], v[14:15], v[14:15]
	v_add_f32_e32 v4, v19, v4
	v_pk_add_f32 v[10:11], v[100:101], v[110:111] op_sel_hi:[1,0] neg_lo:[0,1] neg_hi:[0,1]
	v_add_f32_e32 v4, v102, v4
	v_pk_mul_f32 v[100:101], v[10:11], v[10:11]
	v_add_f32_e32 v4, v103, v4
	v_pk_add_f32 v[8:9], v[106:107], v[110:111] op_sel_hi:[1,0] neg_lo:[0,1] neg_hi:[0,1]
	v_add_f32_e32 v4, v100, v4
	v_pk_mul_f32 v[106:107], v[8:9], v[8:9]
	v_add_f32_e32 v4, v101, v4
	v_pk_add_f32 v[6:7], v[104:105], v[110:111] op_sel_hi:[1,0] neg_lo:[0,1] neg_hi:[0,1]
	v_add_f32_e32 v4, v106, v4
	v_pk_mul_f32 v[104:105], v[6:7], v[6:7]
	v_add_f32_e32 v4, v107, v4
	v_pk_add_f32 v[2:3], v[108:109], v[110:111] op_sel_hi:[1,0] neg_lo:[0,1] neg_hi:[0,1]
	v_add_f32_e32 v4, v104, v4
	v_pk_mul_f32 v[108:109], v[2:3], v[2:3]
	v_add_f32_e32 v4, v105, v4
	v_pk_add_f32 v[0:1], v[130:131], v[110:111] op_sel_hi:[1,0] neg_lo:[0,1] neg_hi:[0,1]
	v_add_f32_e32 v4, v108, v4
	v_pk_mul_f32 v[110:111], v[0:1], v[0:1]
	v_add_f32_e32 v4, v109, v4
	v_add_f32_e32 v4, v110, v4
	v_add_f32_e32 v4, v111, v4
	ds_bpermute_b32 v5, v177, v4
	s_waitcnt lgkmcnt(0)
	v_add_f32_e32 v4, v4, v5
	ds_bpermute_b32 v5, v179, v4
	s_waitcnt lgkmcnt(0)
	v_add_f32_e32 v4, v4, v5
	ds_bpermute_b32 v5, v180, v4
	s_waitcnt lgkmcnt(0)
	v_add_f32_e32 v4, v4, v5
	ds_bpermute_b32 v5, v181, v4
	s_waitcnt lgkmcnt(0)
	v_add_f32_e32 v4, v4, v5
	ds_bpermute_b32 v5, v182, v4
	s_waitcnt lgkmcnt(0)
; DI unsigned pk2(float a, float b) { f32x2 v = {a, b}; hbf16x2 r = __builtin_convertvector(v, hbf16x2); return __builtin_bit_cast(unsigned, r); }
; DI float gelu_erf(float x) { const f32x2 r = gelu_pk((f32x2){x, x}); return r.x; }
; DI void sample_cmlp(int b, const float* PS, const float* lng, const float* lnb, const float* wsp, const float* bsp, bf16* CAT, float* outVs, int lane) {
;     ...
;     const float rstd = 1.0f / sqrtf(wave_sum(q) * (1.0f / 2048.0f) + EPSN);
; #pragma unroll
;     for (int j = 0; j < 8; ++j) { const int col = 4 * (lane + 64 * j), g = col >> 7;
;         const f32x4 ga = *(const f32x4*)(lng + col), ba = *(const f32x4*)(lnb + col), ur = *(const f32x4*)(ps + col);
;         const float w00 = wsp[(size_t)g * 16384], b0 = bsp[g * 128];
;         f32x4 vn, o;
; #pragma unroll
;         for (int e = 0; e < 4; ++e) { vn[e] = (v[j][e] - mean) * rstd * ga[e] + ba[e]; o[e] = gelu_erf(ur[e]) * (w00 * vn[e] + b0); }
;         *(f32x4*)(outVs + (size_t)b * 2048 + col) = vn;
;         u32x2 w; w.x = pk2(o[0], o[1]); w.y = pk2(o[2], o[3]);
;         *(u32x2*)(CAT + (size_t)(MP + b) * DM + col) = w; }
	v_add_f32_e32 v4, v4, v5
	ds_bpermute_b32 v5, v183, v4
	s_waitcnt lgkmcnt(0)
	v_add_f32_e32 v4, v4, v5
	v_fmamk_f32 v4, v4, 0x3a000000, v235
	v_cmp_gt_f32_e32 vcc, s66, v4
	v_mul_f32_e32 v5, 0x4f800000, v4
	s_nop 0
	v_cndmask_b32_e32 v4, v4, v5, vcc
	v_sqrt_f32_e32 v5, v4
	s_nop 0
	v_add_u32_e32 v18, -1, v5
	v_fma_f32 v19, -v18, v5, v4
	v_cmp_ge_f32_e64 s[0:1], 0, v19
	v_add_u32_e32 v19, 1, v5
	s_nop 0
	v_cndmask_b32_e64 v18, v5, v18, s[0:1]
	v_fma_f32 v5, -v19, v5, v4
	v_cmp_lt_f32_e64 s[0:1], 0, v5
	s_nop 1
	v_cndmask_b32_e64 v5, v18, v19, s[0:1]
	v_mul_f32_e32 v18, 0x37800000, v5
	v_cndmask_b32_e32 v5, v5, v18, vcc
	v_cmp_class_f32_e32 vcc, v4, v236
	s_nop 1
	v_cndmask_b32_e32 v4, v5, v4, vcc
	v_div_scale_f32 v5, s[0:1], v4, v4, 1.0
	v_rcp_f32_e32 v18, v5
	s_mov_b32 s0, 0x5ad0000
	v_fma_f32 v19, -v5, v18, 1.0
	v_fmac_f32_e32 v18, v19, v18
	v_div_scale_f32 v19, vcc, 1.0, v4, 1.0
	v_mul_f32_e32 v100, v19, v18
	v_fma_f32 v101, -v5, v100, v19
	v_fmac_f32_e32 v100, v101, v18
	v_fma_f32 v5, -v5, v100, v19
	v_div_fmas_f32 v5, v5, v18, v100
	v_div_fixup_f32 v4, v5, v4, 1.0
	v_pk_mul_f32 v[18:19], v[112:113], v[4:5] op_sel_hi:[1,0]
	v_pk_mul_f32 v[98:99], v[98:99], v[4:5] op_sel_hi:[1,0]
	v_pk_fma_f32 v[32:33], v[32:33], v[18:19], v[36:37]
	s_waitcnt vmcnt(0)
	v_pk_fma_f32 v[18:19], v[176:177], v[32:33], v[178:179] op_sel_hi:[0,1,0]
	v_pk_mul_f32 v[36:37], v[126:127], v[18:19]
	v_pk_mul_f32 v[18:19], v[116:117], v[4:5] op_sel_hi:[1,0]
	s_nop 0
	v_pk_fma_f32 v[34:35], v[34:35], v[18:19], v[38:39]
	s_nop 0
	v_pk_fma_f32 v[18:19], v[176:177], v[34:35], v[178:179] op_sel_hi:[0,1,0]
	v_pk_mul_f32 v[38:39], v[30:31], v[18:19]
	v_add_co_u32_e32 v30, vcc, s0, v144
	s_mov_b32 s0, 0x5ad1000
	s_nop 0
	v_addc_co_u32_e32 v31, vcc, 0, v145, vcc
	v_add_co_u32_e32 v18, vcc, s0, v144
	s_nop 1
	v_addc_co_u32_e32 v19, vcc, 0, v145, vcc
	global_store_dwordx4 v[18:19], v[32:35], off offset:-4096 sc1
	s_nop 1
	v_cvt_pk_bf16_f32 v32, v36, v37
	v_cvt_pk_bf16_f32 v33, v38, v39
	global_store_dwordx2 v[12:13], v[32:33], off
	global_load_dwordx4 v[32:35], v[40:41], off offset:1024
	s_nop 0
	global_load_dwordx4 v[36:39], v[42:43], off offset:1024
	global_load_dwordx4 v[100:103], v[174:175], off offset:1024
	global_load_dword v104, v[48:49], off
	global_load_dword v106, v[50:51], off
	s_waitcnt vmcnt(3)
	v_pk_fma_f32 v[32:33], v[32:33], v[98:99], v[36:37]
	s_waitcnt vmcnt(2)
	v_and_b32_e32 v36, 0x7fffffff, v100
	v_pk_fma_f32 v[36:37], v[36:37], s[76:77], 1.0 op_sel_hi:[0,0,0]
	v_rcp_f32_e32 v36, v36
	v_rcp_f32_e32 v37, v37
	v_mul_f32_e32 v5, v100, v100
	v_mul_f32_e32 v5, 0xbf38aa3b, v5
	v_cmp_gt_f32_e32 vcc, 0, v100
	v_pk_fma_f32 v[98:99], v[36:37], s[78:79], v[94:95] op_sel_hi:[1,0,0]
	v_cmp_gt_f32_e64 s[0:1], 0, v101
	v_pk_fma_f32 v[98:99], v[36:37], v[98:99], s[96:97] op_sel_hi:[1,1,0]
	s_nop 0
	v_pk_fma_f32 v[98:99], v[36:37], v[98:99], s[16:17] op_sel_hi:[1,1,0]
	s_nop 0
	v_pk_fma_f32 v[98:99], v[36:37], v[98:99], s[18:19] op_sel_hi:[1,1,0]
	s_nop 0
	v_pk_mul_f32 v[36:37], v[36:37], v[98:99]
	v_exp_f32_e32 v98, v5
	v_mul_f32_e32 v5, v101, v101
	v_mul_f32_e32 v5, 0xbf38aa3b, v5
	v_pk_mul_f32 v[96:97], v[96:97], v[4:5] op_sel_hi:[1,0]
	v_pk_mul_f32 v[36:37], v[98:99], v[36:37]
	v_and_b32_e32 v98, 0x7fffffff, v101
	v_pk_fma_f32 v[98:99], v[98:99], s[76:77], 1.0 op_sel_hi:[0,0,0]
	v_rcp_f32_e32 v98, v98
	v_rcp_f32_e32 v99, v99
	v_pk_mul_f32 v[36:37], v[100:101], v[36:37]
	v_pk_fma_f32 v[34:35], v[34:35], v[96:97], v[38:39]
	v_and_b32_e32 v38, 0x7fffffff, v102
	v_pk_fma_f32 v[108:109], v[98:99], s[78:79], v[94:95] op_sel_hi:[1,0,0]
	v_pk_fma_f32 v[38:39], v[38:39], s[76:77], 1.0 op_sel_hi:[0,0,0]
	v_pk_fma_f32 v[108:109], v[98:99], v[108:109], s[96:97] op_sel_hi:[1,1,0]
	v_rcp_f32_e32 v38, v38
	v_pk_fma_f32 v[108:109], v[98:99], v[108:109], s[16:17] op_sel_hi:[1,1,0]
	v_rcp_f32_e32 v39, v39
	v_pk_fma_f32 v[108:109], v[98:99], v[108:109], s[18:19] op_sel_hi:[1,1,0]
	global_store_dwordx4 v[30:31], v[32:35], off offset:1024 sc1
	v_pk_mul_f32 v[98:99], v[98:99], v[108:109]
	v_exp_f32_e32 v108, v5
	v_pk_fma_f32 v[96:97], v[38:39], s[78:79], v[94:95] op_sel_hi:[1,0,0]
	v_mul_f32_e32 v5, v102, v102
	v_pk_fma_f32 v[96:97], v[38:39], v[96:97], s[96:97] op_sel_hi:[1,1,0]
	v_pk_mul_f32 v[98:99], v[108:109], v[98:99]
	v_pk_fma_f32 v[96:97], v[38:39], v[96:97], s[16:17] op_sel_hi:[1,1,0]
	v_pk_mul_f32 v[98:99], v[100:101], v[98:99] op_sel:[1,0]
	v_pk_fma_f32 v[96:97], v[38:39], v[96:97], s[18:19] op_sel_hi:[1,1,0]
	v_mov_b32_e32 v37, v98
	v_pk_add_f32 v[100:101], v[100:101], v[36:37] neg_lo:[0,1] neg_hi:[0,1]
	v_mul_f32_e32 v5, 0xbf38aa3b, v5
	v_cndmask_b32_e64 v37, v101, v98, s[0:1]
	v_cndmask_b32_e32 v36, v100, v36, vcc
	s_waitcnt vmcnt(1)
	v_pk_fma_f32 v[98:99], v[104:105], v[32:33], v[106:107] op_sel_hi:[0,1,0]
	v_pk_mul_f32 v[36:37], v[36:37], v[98:99]
	v_and_b32_e32 v98, 0x7fffffff, v103
	v_pk_fma_f32 v[98:99], v[98:99], s[76:77], 1.0 op_sel_hi:[0,0,0]
	v_rcp_f32_e32 v98, v98
	v_rcp_f32_e32 v99, v99
	v_pk_mul_f32 v[38:39], v[38:39], v[96:97]
	v_exp_f32_e32 v96, v5
	v_mul_f32_e32 v5, v103, v103
	v_pk_fma_f32 v[100:101], v[98:99], s[78:79], v[94:95] op_sel_hi:[1,0,0]
	v_mul_f32_e32 v5, 0xbf38aa3b, v5
	v_pk_fma_f32 v[100:101], v[98:99], v[100:101], s[96:97] op_sel_hi:[1,1,0]
	v_pk_mul_f32 v[38:39], v[96:97], v[38:39]
	v_pk_fma_f32 v[100:101], v[98:99], v[100:101], s[16:17] op_sel_hi:[1,1,0]
	v_mov_b32_e32 v96, v103
	v_pk_fma_f32 v[100:101], v[98:99], v[100:101], s[18:19] op_sel_hi:[1,1,0]
	v_pk_mul_f32 v[38:39], v[102:103], v[38:39]
	v_pk_mul_f32 v[98:99], v[98:99], v[100:101]
	v_exp_f32_e32 v100, v5
	v_cmp_gt_f32_e32 vcc, 0, v102
	v_cmp_gt_f32_e64 s[0:1], 0, v103
	v_cvt_pk_bf16_f32 v32, v36, v37
	v_pk_mul_f32 v[98:99], v[100:101], v[98:99]
	v_pk_mul_f32 v[28:29], v[28:29], v[4:5] op_sel_hi:[1,0]
	v_pk_mul_f32 v[96:97], v[96:97], v[98:99] op_sel_hi:[0,1]
	v_mov_b32_e32 v39, v96
	v_pk_add_f32 v[98:99], v[102:103], v[38:39] neg_lo:[0,1] neg_hi:[0,1]
	s_nop 0
	v_cndmask_b32_e64 v39, v99, v96, s[0:1]
	v_cndmask_b32_e32 v38, v98, v38, vcc
	v_pk_fma_f32 v[96:97], v[104:105], v[34:35], v[106:107] op_sel_hi:[0,1,0]
	v_pk_mul_f32 v[38:39], v[38:39], v[96:97]
	s_nop 0
	v_cvt_pk_bf16_f32 v33, v38, v39
	global_store_dwordx2 v[12:13], v[32:33], off offset:512
	global_load_dwordx4 v[32:35], v[40:41], off offset:2048
	s_nop 0
	global_load_dwordx4 v[36:39], v[42:43], off offset:2048
	global_load_dwordx4 v[96:99], v[174:175], off offset:2048
	global_load_dword v100, v[52:53], off
	global_load_dword v102, v[54:55], off
	s_waitcnt vmcnt(3)
; DI unsigned pk2(float a, float b) { f32x2 v = {a, b}; hbf16x2 r = __builtin_convertvector(v, hbf16x2); return __builtin_bit_cast(unsigned, r); }
; DI float gelu_erf(float x) { const f32x2 r = gelu_pk((f32x2){x, x}); return r.x; }
; DI void sample_cmlp(int b, const float* PS, const float* lng, const float* lnb, const float* wsp, const float* bsp, bf16* CAT, float* outVs, int lane) {
;     ...
;     for (int j = 0; j < 8; ++j) { const int col = 4 * (lane + 64 * j), g = col >> 7;
;         const f32x4 ga = *(const f32x4*)(lng + col), ba = *(const f32x4*)(lnb + col), ur = *(const f32x4*)(ps + col);
;         const float w00 = wsp[(size_t)g * 16384], b0 = bsp[g * 128];
;         f32x4 vn, o;
; #pragma unroll
;         for (int e = 0; e < 4; ++e) { vn[e] = (v[j][e] - mean) * rstd * ga[e] + ba[e]; o[e] = gelu_erf(ur[e]) * (w00 * vn[e] + b0); }
;         *(f32x4*)(outVs + (size_t)b * 2048 + col) = vn;
;         u32x2 w; w.x = pk2(o[0], o[1]); w.y = pk2(o[2], o[3]);
;         *(u32x2*)(CAT + (size_t)(MP + b) * DM + col) = w; }
	v_pk_fma_f32 v[32:33], v[32:33], v[28:29], v[36:37]
	s_waitcnt vmcnt(2)
	v_and_b32_e32 v28, 0x7fffffff, v96
	v_pk_fma_f32 v[28:29], v[28:29], s[76:77], 1.0 op_sel_hi:[0,0,0]
	v_rcp_f32_e32 v28, v28
	v_rcp_f32_e32 v29, v29
	v_mul_f32_e32 v5, v96, v96
	v_mul_f32_e32 v5, 0xbf38aa3b, v5
	v_cmp_gt_f32_e32 vcc, 0, v96
	v_pk_fma_f32 v[36:37], v[28:29], s[78:79], v[94:95] op_sel_hi:[1,0,0]
	v_cmp_gt_f32_e64 s[0:1], 0, v97
	v_pk_fma_f32 v[36:37], v[28:29], v[36:37], s[96:97] op_sel_hi:[1,1,0]
	s_nop 0
	v_pk_fma_f32 v[36:37], v[28:29], v[36:37], s[16:17] op_sel_hi:[1,1,0]
	s_nop 0
	v_pk_fma_f32 v[36:37], v[28:29], v[36:37], s[18:19] op_sel_hi:[1,1,0]
	s_nop 0
	v_pk_mul_f32 v[28:29], v[28:29], v[36:37]
	v_exp_f32_e32 v36, v5
	v_mul_f32_e32 v5, v97, v97
	v_mul_f32_e32 v5, 0xbf38aa3b, v5
	v_pk_mul_f32 v[26:27], v[26:27], v[4:5] op_sel_hi:[1,0]
	v_pk_mul_f32 v[28:29], v[36:37], v[28:29]
	v_and_b32_e32 v36, 0x7fffffff, v97
	v_pk_fma_f32 v[36:37], v[36:37], s[76:77], 1.0 op_sel_hi:[0,0,0]
	v_rcp_f32_e32 v36, v36
	v_rcp_f32_e32 v37, v37
	v_pk_fma_f32 v[34:35], v[34:35], v[26:27], v[38:39]
	v_and_b32_e32 v26, 0x7fffffff, v98
	v_pk_fma_f32 v[26:27], v[26:27], s[76:77], 1.0 op_sel_hi:[0,0,0]
	v_pk_fma_f32 v[104:105], v[36:37], s[78:79], v[94:95] op_sel_hi:[1,0,0]
	v_pk_mul_f32 v[28:29], v[96:97], v[28:29]
	v_pk_fma_f32 v[104:105], v[36:37], v[104:105], s[96:97] op_sel_hi:[1,1,0]
	v_rcp_f32_e32 v26, v26
	v_pk_fma_f32 v[104:105], v[36:37], v[104:105], s[16:17] op_sel_hi:[1,1,0]
	v_rcp_f32_e32 v27, v27
	v_pk_fma_f32 v[104:105], v[36:37], v[104:105], s[18:19] op_sel_hi:[1,1,0]
	v_and_b32_e32 v38, 0x7fffffff, v99
	v_pk_mul_f32 v[36:37], v[36:37], v[104:105]
	v_exp_f32_e32 v104, v5
	v_pk_fma_f32 v[38:39], v[38:39], s[76:77], 1.0 op_sel_hi:[0,0,0]
	v_rcp_f32_e32 v38, v38
	v_rcp_f32_e32 v39, v39
	v_pk_mul_f32 v[36:37], v[104:105], v[36:37]
	v_mul_f32_e32 v5, v98, v98
	v_pk_mul_f32 v[36:37], v[96:97], v[36:37] op_sel:[1,0]
	v_mul_f32_e32 v5, 0xbf38aa3b, v5
	v_mov_b32_e32 v29, v36
	v_pk_add_f32 v[96:97], v[96:97], v[28:29] neg_lo:[0,1] neg_hi:[0,1]
	global_store_dwordx4 v[30:31], v[32:35], off offset:2048 sc1
	v_cndmask_b32_e64 v29, v97, v36, s[0:1]
	v_cndmask_b32_e32 v28, v96, v28, vcc
	s_waitcnt vmcnt(1)
	v_pk_fma_f32 v[36:37], v[100:101], v[32:33], v[102:103] op_sel_hi:[0,1,0]
	v_pk_mul_f32 v[28:29], v[28:29], v[36:37]
	v_pk_fma_f32 v[36:37], v[26:27], s[78:79], v[94:95] op_sel_hi:[1,0,0]
	v_pk_fma_f32 v[96:97], v[38:39], s[78:79], v[94:95] op_sel_hi:[1,0,0]
	v_pk_fma_f32 v[36:37], v[26:27], v[36:37], s[96:97] op_sel_hi:[1,1,0]
	v_pk_fma_f32 v[96:97], v[38:39], v[96:97], s[96:97] op_sel_hi:[1,1,0]
	v_pk_fma_f32 v[36:37], v[26:27], v[36:37], s[16:17] op_sel_hi:[1,1,0]
	v_pk_fma_f32 v[96:97], v[38:39], v[96:97], s[16:17] op_sel_hi:[1,1,0]
	v_pk_fma_f32 v[36:37], v[26:27], v[36:37], s[18:19] op_sel_hi:[1,1,0]
	v_pk_fma_f32 v[96:97], v[38:39], v[96:97], s[18:19] op_sel_hi:[1,1,0]
	v_pk_mul_f32 v[26:27], v[26:27], v[36:37]
	v_exp_f32_e32 v36, v5
	v_mul_f32_e32 v5, v99, v99
	v_mul_f32_e32 v5, 0xbf38aa3b, v5
	v_pk_mul_f32 v[38:39], v[38:39], v[96:97]
	v_exp_f32_e32 v96, v5
	v_pk_mul_f32 v[26:27], v[36:37], v[26:27]
	v_mov_b32_e32 v36, v99
	v_pk_mul_f32 v[26:27], v[98:99], v[26:27]
	v_pk_mul_f32 v[38:39], v[96:97], v[38:39]
	v_cmp_gt_f32_e32 vcc, 0, v98
	v_pk_mul_f32 v[36:37], v[36:37], v[38:39] op_sel_hi:[0,1]
	v_mov_b32_e32 v27, v36
	v_cmp_gt_f32_e64 s[0:1], 0, v99
	v_pk_add_f32 v[38:39], v[98:99], v[26:27] neg_lo:[0,1] neg_hi:[0,1]
	v_cvt_pk_bf16_f32 v28, v28, v29
	v_cndmask_b32_e64 v27, v39, v36, s[0:1]
	v_cndmask_b32_e32 v26, v38, v26, vcc
	v_pk_fma_f32 v[36:37], v[100:101], v[34:35], v[102:103] op_sel_hi:[0,1,0]
	v_pk_mul_f32 v[26:27], v[26:27], v[36:37]
	v_pk_mul_f32 v[24:25], v[24:25], v[4:5] op_sel_hi:[1,0]
	v_cvt_pk_bf16_f32 v29, v26, v27
	global_store_dwordx2 v[12:13], v[28:29], off offset:1024
	global_load_dwordx4 v[26:29], v[40:41], off offset:3072
	s_nop 0
	global_load_dwordx4 v[32:35], v[42:43], off offset:3072
	global_load_dwordx4 v[36:39], v[174:175], off offset:3072
	global_load_dword v96, v[56:57], off
	global_load_dword v98, v[58:59], off
	s_waitcnt vmcnt(3)
	v_pk_fma_f32 v[24:25], v[26:27], v[24:25], v[32:33]
	s_waitcnt vmcnt(2)
	v_and_b32_e32 v26, 0x7fffffff, v36
	v_pk_fma_f32 v[26:27], v[26:27], s[76:77], 1.0 op_sel_hi:[0,0,0]
	v_rcp_f32_e32 v26, v26
	v_rcp_f32_e32 v27, v27
	v_mul_f32_e32 v5, v36, v36
	v_mul_f32_e32 v5, 0xbf38aa3b, v5
	v_cmp_gt_f32_e32 vcc, 0, v36
	v_pk_fma_f32 v[32:33], v[26:27], s[78:79], v[94:95] op_sel_hi:[1,0,0]
	v_cmp_gt_f32_e64 s[0:1], 0, v37
	v_pk_fma_f32 v[32:33], v[26:27], v[32:33], s[96:97] op_sel_hi:[1,1,0]
	s_nop 0
	v_pk_fma_f32 v[32:33], v[26:27], v[32:33], s[16:17] op_sel_hi:[1,1,0]
	s_nop 0
	v_pk_fma_f32 v[32:33], v[26:27], v[32:33], s[18:19] op_sel_hi:[1,1,0]
	s_nop 0
	v_pk_mul_f32 v[26:27], v[26:27], v[32:33]
	v_exp_f32_e32 v32, v5
	v_mul_f32_e32 v5, v37, v37
	v_mul_f32_e32 v5, 0xbf38aa3b, v5
	v_pk_mul_f32 v[22:23], v[22:23], v[4:5] op_sel_hi:[1,0]
	v_pk_mul_f32 v[26:27], v[32:33], v[26:27]
	v_and_b32_e32 v32, 0x7fffffff, v37
	v_pk_fma_f32 v[32:33], v[32:33], s[76:77], 1.0 op_sel_hi:[0,0,0]
	v_rcp_f32_e32 v32, v32
	v_rcp_f32_e32 v33, v33
	v_pk_mul_f32 v[26:27], v[36:37], v[26:27]
	v_pk_fma_f32 v[100:101], v[32:33], s[78:79], v[94:95] op_sel_hi:[1,0,0]
	s_nop 0
	v_pk_fma_f32 v[100:101], v[32:33], v[100:101], s[96:97] op_sel_hi:[1,1,0]
	s_nop 0
	v_pk_fma_f32 v[100:101], v[32:33], v[100:101], s[16:17] op_sel_hi:[1,1,0]
	s_nop 0
	v_pk_fma_f32 v[100:101], v[32:33], v[100:101], s[18:19] op_sel_hi:[1,1,0]
	s_nop 0
	v_pk_mul_f32 v[32:33], v[32:33], v[100:101]
	v_exp_f32_e32 v100, v5
	v_mul_f32_e32 v5, v38, v38
	v_mul_f32_e32 v5, 0xbf38aa3b, v5
	v_pk_mul_f32 v[32:33], v[100:101], v[32:33]
	s_nop 0
	v_pk_mul_f32 v[32:33], v[36:37], v[32:33] op_sel:[1,0]
	s_nop 0
	v_mov_b32_e32 v27, v32
	v_pk_add_f32 v[36:37], v[36:37], v[26:27] neg_lo:[0,1] neg_hi:[0,1]
	s_nop 0
	v_cndmask_b32_e64 v27, v37, v32, s[0:1]
	v_cndmask_b32_e32 v26, v36, v26, vcc
	s_waitcnt vmcnt(0)
; DI unsigned pk2(float a, float b) { f32x2 v = {a, b}; hbf16x2 r = __builtin_convertvector(v, hbf16x2); return __builtin_bit_cast(unsigned, r); }
; DI float gelu_erf(float x) { const f32x2 r = gelu_pk((f32x2){x, x}); return r.x; }
; DI void sample_cmlp(int b, const float* PS, const float* lng, const float* lnb, const float* wsp, const float* bsp, bf16* CAT, float* outVs, int lane) {
;     ...
;     for (int j = 0; j < 8; ++j) { const int col = 4 * (lane + 64 * j), g = col >> 7;
;         const f32x4 ga = *(const f32x4*)(lng + col), ba = *(const f32x4*)(lnb + col), ur = *(const f32x4*)(ps + col);
;         const float w00 = wsp[(size_t)g * 16384], b0 = bsp[g * 128];
;         f32x4 vn, o;
; #pragma unroll
;         for (int e = 0; e < 4; ++e) { vn[e] = (v[j][e] - mean) * rstd * ga[e] + ba[e]; o[e] = gelu_erf(ur[e]) * (w00 * vn[e] + b0); }
;         *(f32x4*)(outVs + (size_t)b * 2048 + col) = vn;
;         u32x2 w; w.x = pk2(o[0], o[1]); w.y = pk2(o[2], o[3]);
;         *(u32x2*)(CAT + (size_t)(MP + b) * DM + col) = w; }
	v_pk_fma_f32 v[32:33], v[96:97], v[24:25], v[98:99] op_sel_hi:[0,1,0]
	v_pk_mul_f32 v[32:33], v[26:27], v[32:33]
	v_pk_fma_f32 v[26:27], v[28:29], v[22:23], v[34:35]
	v_and_b32_e32 v22, 0x7fffffff, v38
	v_pk_fma_f32 v[22:23], v[22:23], s[76:77], 1.0 op_sel_hi:[0,0,0]
	v_rcp_f32_e32 v22, v22
	v_rcp_f32_e32 v23, v23
	v_and_b32_e32 v34, 0x7fffffff, v39
	v_pk_fma_f32 v[34:35], v[34:35], s[76:77], 1.0 op_sel_hi:[0,0,0]
	v_rcp_f32_e32 v34, v34
	v_rcp_f32_e32 v35, v35
	v_pk_fma_f32 v[28:29], v[22:23], s[78:79], v[94:95] op_sel_hi:[1,0,0]
	v_cmp_gt_f32_e32 vcc, 0, v38
	v_pk_fma_f32 v[28:29], v[22:23], v[28:29], s[96:97] op_sel_hi:[1,1,0]
	v_pk_fma_f32 v[36:37], v[34:35], s[78:79], v[94:95] op_sel_hi:[1,0,0]
	v_pk_fma_f32 v[28:29], v[22:23], v[28:29], s[16:17] op_sel_hi:[1,1,0]
	v_pk_fma_f32 v[36:37], v[34:35], v[36:37], s[96:97] op_sel_hi:[1,1,0]
	v_pk_fma_f32 v[28:29], v[22:23], v[28:29], s[18:19] op_sel_hi:[1,1,0]
	v_pk_fma_f32 v[36:37], v[34:35], v[36:37], s[16:17] op_sel_hi:[1,1,0]
	v_pk_mul_f32 v[22:23], v[22:23], v[28:29]
	v_exp_f32_e32 v28, v5
	v_mul_f32_e32 v5, v39, v39
	v_pk_fma_f32 v[36:37], v[34:35], v[36:37], s[18:19] op_sel_hi:[1,1,0]
	v_mul_f32_e32 v5, 0xbf38aa3b, v5
	v_pk_mul_f32 v[34:35], v[34:35], v[36:37]
	v_exp_f32_e32 v36, v5
	v_pk_mul_f32 v[22:23], v[28:29], v[22:23]
	v_mov_b32_e32 v28, v39
	v_pk_mul_f32 v[22:23], v[38:39], v[22:23]
	v_pk_mul_f32 v[34:35], v[36:37], v[34:35]
	v_cmp_gt_f32_e64 s[0:1], 0, v39
	v_pk_mul_f32 v[28:29], v[28:29], v[34:35] op_sel_hi:[0,1]
	v_mov_b32_e32 v23, v28
	v_pk_add_f32 v[34:35], v[38:39], v[22:23] neg_lo:[0,1] neg_hi:[0,1]
	global_store_dwordx4 v[30:31], v[24:27], off offset:3072 sc1
	v_cndmask_b32_e64 v23, v35, v28, s[0:1]
	v_cndmask_b32_e32 v22, v34, v22, vcc
	v_pk_fma_f32 v[28:29], v[96:97], v[26:27], v[98:99] op_sel_hi:[0,1,0]
	v_pk_mul_f32 v[22:23], v[22:23], v[28:29]
	v_cvt_pk_bf16_f32 v24, v32, v33
	v_cvt_pk_bf16_f32 v25, v22, v23
	global_store_dwordx2 v[12:13], v[24:25], off offset:1536
	global_load_dwordx4 v[22:25], v[60:61], off
	s_nop 0
	global_load_dwordx4 v[26:29], v[62:63], off
	global_load_dwordx4 v[30:33], v[136:137], off
	global_load_dword v34, v[64:65], off
	global_load_dword v36, v[66:67], off
	v_pk_mul_f32 v[20:21], v[20:21], v[4:5] op_sel_hi:[1,0]
	s_waitcnt vmcnt(2)
	v_mul_f32_e32 v5, v30, v30
	v_pk_fma_f32 v[20:21], v[22:23], v[20:21], v[26:27]
	v_and_b32_e32 v22, 0x7fffffff, v30
	v_pk_fma_f32 v[22:23], v[22:23], s[76:77], 1.0 op_sel_hi:[0,0,0]
	v_rcp_f32_e32 v22, v22
	v_rcp_f32_e32 v23, v23
	v_mul_f32_e32 v5, 0xbf38aa3b, v5
	v_cmp_gt_f32_e32 vcc, 0, v30
	v_cmp_gt_f32_e64 s[0:1], 0, v31
	v_pk_fma_f32 v[26:27], v[22:23], s[78:79], v[94:95] op_sel_hi:[1,0,0]
	s_nop 0
	v_pk_fma_f32 v[26:27], v[22:23], v[26:27], s[96:97] op_sel_hi:[1,1,0]
	s_nop 0
	v_pk_fma_f32 v[26:27], v[22:23], v[26:27], s[16:17] op_sel_hi:[1,1,0]
	s_nop 0
	v_pk_fma_f32 v[26:27], v[22:23], v[26:27], s[18:19] op_sel_hi:[1,1,0]
	s_nop 0
	v_pk_mul_f32 v[22:23], v[22:23], v[26:27]
	v_exp_f32_e32 v26, v5
	v_mul_f32_e32 v5, v31, v31
	v_mul_f32_e32 v5, 0xbf38aa3b, v5
	v_pk_mul_f32 v[16:17], v[16:17], v[4:5] op_sel_hi:[1,0]
	v_pk_mul_f32 v[22:23], v[26:27], v[22:23]
	v_and_b32_e32 v26, 0x7fffffff, v31
	v_pk_fma_f32 v[26:27], v[26:27], s[76:77], 1.0 op_sel_hi:[0,0,0]
	v_rcp_f32_e32 v26, v26
	v_rcp_f32_e32 v27, v27
	v_pk_mul_f32 v[22:23], v[30:31], v[22:23]
	v_pk_fma_f32 v[38:39], v[26:27], s[78:79], v[94:95] op_sel_hi:[1,0,0]
	s_nop 0
	v_pk_fma_f32 v[38:39], v[26:27], v[38:39], s[96:97] op_sel_hi:[1,1,0]
	s_nop 0
	v_pk_fma_f32 v[38:39], v[26:27], v[38:39], s[16:17] op_sel_hi:[1,1,0]
	s_nop 0
	v_pk_fma_f32 v[38:39], v[26:27], v[38:39], s[18:19] op_sel_hi:[1,1,0]
	s_nop 0
	v_pk_mul_f32 v[26:27], v[26:27], v[38:39]
	v_exp_f32_e32 v38, v5
	v_mul_f32_e32 v5, v32, v32
	v_mul_f32_e32 v5, 0xbf38aa3b, v5
	v_pk_mul_f32 v[26:27], v[38:39], v[26:27]
	s_nop 0
	v_pk_mul_f32 v[26:27], v[30:31], v[26:27] op_sel:[1,0]
	s_nop 0
	v_mov_b32_e32 v23, v26
	v_pk_add_f32 v[30:31], v[30:31], v[22:23] neg_lo:[0,1] neg_hi:[0,1]
	s_nop 0
	v_cndmask_b32_e64 v23, v31, v26, s[0:1]
	v_cndmask_b32_e32 v22, v30, v22, vcc
	s_waitcnt vmcnt(0)
	v_pk_fma_f32 v[26:27], v[34:35], v[20:21], v[36:37] op_sel_hi:[0,1,0]
	v_pk_mul_f32 v[26:27], v[22:23], v[26:27]
	v_pk_fma_f32 v[22:23], v[24:25], v[16:17], v[28:29]
	v_and_b32_e32 v16, 0x7fffffff, v32
	v_pk_fma_f32 v[16:17], v[16:17], s[76:77], 1.0 op_sel_hi:[0,0,0]
	v_rcp_f32_e32 v16, v16
	v_rcp_f32_e32 v17, v17
	v_and_b32_e32 v28, 0x7fffffff, v33
	v_pk_fma_f32 v[28:29], v[28:29], s[76:77], 1.0 op_sel_hi:[0,0,0]
	v_rcp_f32_e32 v28, v28
	v_rcp_f32_e32 v29, v29
	v_pk_fma_f32 v[24:25], v[16:17], s[78:79], v[94:95] op_sel_hi:[1,0,0]
	v_cmp_gt_f32_e32 vcc, 0, v32
	v_pk_fma_f32 v[24:25], v[16:17], v[24:25], s[96:97] op_sel_hi:[1,1,0]
	v_pk_fma_f32 v[30:31], v[28:29], s[78:79], v[94:95] op_sel_hi:[1,0,0]
	v_pk_fma_f32 v[24:25], v[16:17], v[24:25], s[16:17] op_sel_hi:[1,1,0]
	v_pk_fma_f32 v[30:31], v[28:29], v[30:31], s[96:97] op_sel_hi:[1,1,0]
	v_pk_fma_f32 v[24:25], v[16:17], v[24:25], s[18:19] op_sel_hi:[1,1,0]
	v_pk_fma_f32 v[30:31], v[28:29], v[30:31], s[16:17] op_sel_hi:[1,1,0]
	v_pk_mul_f32 v[16:17], v[16:17], v[24:25]
	v_exp_f32_e32 v24, v5
	v_mul_f32_e32 v5, v33, v33
	v_pk_fma_f32 v[30:31], v[28:29], v[30:31], s[18:19] op_sel_hi:[1,1,0]
	v_mul_f32_e32 v5, 0xbf38aa3b, v5
	v_pk_mul_f32 v[28:29], v[28:29], v[30:31]
	v_exp_f32_e32 v30, v5
	v_pk_mul_f32 v[16:17], v[24:25], v[16:17]
	v_mov_b32_e32 v24, v33
	v_pk_mul_f32 v[16:17], v[32:33], v[16:17]
	v_pk_mul_f32 v[28:29], v[30:31], v[28:29]
	v_cmp_gt_f32_e64 s[0:1], 0, v33
	v_pk_mul_f32 v[24:25], v[24:25], v[28:29] op_sel_hi:[0,1]
	v_mov_b32_e32 v17, v24
	v_pk_add_f32 v[28:29], v[32:33], v[16:17] neg_lo:[0,1] neg_hi:[0,1]
	global_store_dwordx4 v[18:19], v[20:23], off sc1
	v_cndmask_b32_e64 v17, v29, v24, s[0:1]
	v_cndmask_b32_e32 v16, v28, v16, vcc
	v_pk_fma_f32 v[24:25], v[34:35], v[22:23], v[36:37] op_sel_hi:[0,1,0]
	v_pk_mul_f32 v[16:17], v[16:17], v[24:25]
	v_cvt_pk_bf16_f32 v20, v26, v27
	v_cvt_pk_bf16_f32 v21, v16, v17
	global_store_dwordx2 v[12:13], v[20:21], off offset:2048
	global_load_dwordx4 v[20:23], v[68:69], off
	s_nop 0
	global_load_dwordx4 v[24:27], v[70:71], off
	global_load_dwordx4 v[28:31], v[136:137], off offset:1024
	global_load_dword v32, v[72:73], off
	global_load_dword v34, v[74:75], off
	v_pk_mul_f32 v[14:15], v[14:15], v[4:5] op_sel_hi:[1,0]
	s_waitcnt vmcnt(2)
; DI unsigned pk2(float a, float b) { f32x2 v = {a, b}; hbf16x2 r = __builtin_convertvector(v, hbf16x2); return __builtin_bit_cast(unsigned, r); }
; DI float gelu_erf(float x) { const f32x2 r = gelu_pk((f32x2){x, x}); return r.x; }
; DI void sample_cmlp(int b, const float* PS, const float* lng, const float* lnb, const float* wsp, const float* bsp, bf16* CAT, float* outVs, int lane) {
;     ...
;     for (int j = 0; j < 8; ++j) { const int col = 4 * (lane + 64 * j), g = col >> 7;
;         const f32x4 ga = *(const f32x4*)(lng + col), ba = *(const f32x4*)(lnb + col), ur = *(const f32x4*)(ps + col);
;         const float w00 = wsp[(size_t)g * 16384], b0 = bsp[g * 128];
;         f32x4 vn, o;
; #pragma unroll
;         for (int e = 0; e < 4; ++e) { vn[e] = (v[j][e] - mean) * rstd * ga[e] + ba[e]; o[e] = gelu_erf(ur[e]) * (w00 * vn[e] + b0); }
;         *(f32x4*)(outVs + (size_t)b * 2048 + col) = vn;
;         u32x2 w; w.x = pk2(o[0], o[1]); w.y = pk2(o[2], o[3]);
;         *(u32x2*)(CAT + (size_t)(MP + b) * DM + col) = w; }
	v_and_b32_e32 v16, 0x7fffffff, v28
	v_pk_fma_f32 v[16:17], v[16:17], s[76:77], 1.0 op_sel_hi:[0,0,0]
	v_rcp_f32_e32 v16, v16
	v_rcp_f32_e32 v17, v17
	v_pk_fma_f32 v[14:15], v[20:21], v[14:15], v[24:25]
	v_mul_f32_e32 v5, v28, v28
	v_mul_f32_e32 v5, 0xbf38aa3b, v5
	v_pk_fma_f32 v[20:21], v[16:17], s[78:79], v[94:95] op_sel_hi:[1,0,0]
	v_cmp_gt_f32_e32 vcc, 0, v28
	v_pk_fma_f32 v[20:21], v[16:17], v[20:21], s[96:97] op_sel_hi:[1,1,0]
	v_cmp_gt_f32_e64 s[0:1], 0, v29
	v_pk_fma_f32 v[20:21], v[16:17], v[20:21], s[16:17] op_sel_hi:[1,1,0]
	s_nop 0
	v_pk_fma_f32 v[20:21], v[16:17], v[20:21], s[18:19] op_sel_hi:[1,1,0]
	s_nop 0
	v_pk_mul_f32 v[16:17], v[16:17], v[20:21]
	v_exp_f32_e32 v20, v5
	v_mul_f32_e32 v5, v29, v29
	v_mul_f32_e32 v5, 0xbf38aa3b, v5
	v_pk_mul_f32 v[10:11], v[10:11], v[4:5] op_sel_hi:[1,0]
	v_pk_mul_f32 v[16:17], v[20:21], v[16:17]
	v_and_b32_e32 v20, 0x7fffffff, v29
	v_pk_fma_f32 v[20:21], v[20:21], s[76:77], 1.0 op_sel_hi:[0,0,0]
	v_rcp_f32_e32 v20, v20
	v_rcp_f32_e32 v21, v21
	v_pk_mul_f32 v[16:17], v[28:29], v[16:17]
	v_pk_fma_f32 v[24:25], v[20:21], s[78:79], v[94:95] op_sel_hi:[1,0,0]
	s_nop 0
	v_pk_fma_f32 v[24:25], v[20:21], v[24:25], s[96:97] op_sel_hi:[1,1,0]
	s_nop 0
	v_pk_fma_f32 v[24:25], v[20:21], v[24:25], s[16:17] op_sel_hi:[1,1,0]
	s_nop 0
	v_pk_fma_f32 v[24:25], v[20:21], v[24:25], s[18:19] op_sel_hi:[1,1,0]
	s_nop 0
	v_pk_mul_f32 v[20:21], v[20:21], v[24:25]
	v_exp_f32_e32 v24, v5
	v_mul_f32_e32 v5, v30, v30
	v_mul_f32_e32 v5, 0xbf38aa3b, v5
	v_pk_mul_f32 v[20:21], v[24:25], v[20:21]
	s_nop 0
	v_pk_mul_f32 v[20:21], v[28:29], v[20:21] op_sel:[1,0]
	s_nop 0
	v_mov_b32_e32 v17, v20
	v_pk_add_f32 v[24:25], v[28:29], v[16:17] neg_lo:[0,1] neg_hi:[0,1]
	s_nop 0
	v_cndmask_b32_e64 v17, v25, v20, s[0:1]
	v_cndmask_b32_e32 v16, v24, v16, vcc
	s_waitcnt vmcnt(0)
	v_pk_fma_f32 v[20:21], v[32:33], v[14:15], v[34:35] op_sel_hi:[0,1,0]
	v_pk_mul_f32 v[20:21], v[16:17], v[20:21]
	v_pk_fma_f32 v[16:17], v[22:23], v[10:11], v[26:27]
	v_and_b32_e32 v10, 0x7fffffff, v30
	v_pk_fma_f32 v[10:11], v[10:11], s[76:77], 1.0 op_sel_hi:[0,0,0]
	v_rcp_f32_e32 v10, v10
	v_rcp_f32_e32 v11, v11
	v_and_b32_e32 v24, 0x7fffffff, v31
	v_pk_fma_f32 v[24:25], v[24:25], s[76:77], 1.0 op_sel_hi:[0,0,0]
	v_rcp_f32_e32 v24, v24
	v_rcp_f32_e32 v25, v25
	v_pk_fma_f32 v[22:23], v[10:11], s[78:79], v[94:95] op_sel_hi:[1,0,0]
	v_cmp_gt_f32_e32 vcc, 0, v30
	v_pk_fma_f32 v[22:23], v[10:11], v[22:23], s[96:97] op_sel_hi:[1,1,0]
	v_pk_fma_f32 v[26:27], v[24:25], s[78:79], v[94:95] op_sel_hi:[1,0,0]
	v_pk_fma_f32 v[22:23], v[10:11], v[22:23], s[16:17] op_sel_hi:[1,1,0]
	v_pk_fma_f32 v[26:27], v[24:25], v[26:27], s[96:97] op_sel_hi:[1,1,0]
	v_pk_fma_f32 v[22:23], v[10:11], v[22:23], s[18:19] op_sel_hi:[1,1,0]
	v_pk_fma_f32 v[26:27], v[24:25], v[26:27], s[16:17] op_sel_hi:[1,1,0]
	v_pk_mul_f32 v[10:11], v[10:11], v[22:23]
	v_exp_f32_e32 v22, v5
	v_mul_f32_e32 v5, v31, v31
	v_pk_fma_f32 v[26:27], v[24:25], v[26:27], s[18:19] op_sel_hi:[1,1,0]
	v_mul_f32_e32 v5, 0xbf38aa3b, v5
	v_pk_mul_f32 v[24:25], v[24:25], v[26:27]
	v_exp_f32_e32 v26, v5
	v_pk_mul_f32 v[10:11], v[22:23], v[10:11]
	v_mov_b32_e32 v22, v31
	v_pk_mul_f32 v[10:11], v[30:31], v[10:11]
	v_pk_mul_f32 v[24:25], v[26:27], v[24:25]
	v_cmp_gt_f32_e64 s[0:1], 0, v31
	v_pk_mul_f32 v[22:23], v[22:23], v[24:25] op_sel_hi:[0,1]
	v_mov_b32_e32 v11, v22
	v_pk_add_f32 v[24:25], v[30:31], v[10:11] neg_lo:[0,1] neg_hi:[0,1]
	global_store_dwordx4 v[18:19], v[14:17], off offset:1024 sc1
	v_cndmask_b32_e64 v11, v25, v22, s[0:1]
	v_cndmask_b32_e32 v10, v24, v10, vcc
	v_pk_fma_f32 v[22:23], v[32:33], v[16:17], v[34:35] op_sel_hi:[0,1,0]
	v_pk_mul_f32 v[10:11], v[10:11], v[22:23]
	v_cvt_pk_bf16_f32 v14, v20, v21
	v_cvt_pk_bf16_f32 v15, v10, v11
	global_store_dwordx2 v[12:13], v[14:15], off offset:2560
	global_load_dwordx4 v[14:17], v[76:77], off
	s_nop 0
	global_load_dwordx4 v[20:23], v[78:79], off
	global_load_dwordx4 v[24:27], v[136:137], off offset:2048
	global_load_dword v28, v[80:81], off
	global_load_dword v30, v[82:83], off
	v_pk_mul_f32 v[8:9], v[8:9], v[4:5] op_sel_hi:[1,0]
	s_waitcnt vmcnt(2)
	v_and_b32_e32 v10, 0x7fffffff, v24
	v_pk_fma_f32 v[10:11], v[10:11], s[76:77], 1.0 op_sel_hi:[0,0,0]
	v_rcp_f32_e32 v10, v10
	v_rcp_f32_e32 v11, v11
	v_pk_fma_f32 v[8:9], v[14:15], v[8:9], v[20:21]
	v_mul_f32_e32 v5, v24, v24
	v_mul_f32_e32 v5, 0xbf38aa3b, v5
	v_pk_fma_f32 v[14:15], v[10:11], s[78:79], v[94:95] op_sel_hi:[1,0,0]
	v_cmp_gt_f32_e32 vcc, 0, v24
	v_pk_fma_f32 v[14:15], v[10:11], v[14:15], s[96:97] op_sel_hi:[1,1,0]
	v_cmp_gt_f32_e64 s[0:1], 0, v25
	v_pk_fma_f32 v[14:15], v[10:11], v[14:15], s[16:17] op_sel_hi:[1,1,0]
	s_nop 0
	v_pk_fma_f32 v[14:15], v[10:11], v[14:15], s[18:19] op_sel_hi:[1,1,0]
	s_nop 0
	v_pk_mul_f32 v[10:11], v[10:11], v[14:15]
	v_exp_f32_e32 v14, v5
	v_mul_f32_e32 v5, v25, v25
	v_mul_f32_e32 v5, 0xbf38aa3b, v5
	v_pk_mul_f32 v[6:7], v[6:7], v[4:5] op_sel_hi:[1,0]
	v_pk_mul_f32 v[10:11], v[14:15], v[10:11]
	v_and_b32_e32 v14, 0x7fffffff, v25
	v_pk_fma_f32 v[14:15], v[14:15], s[76:77], 1.0 op_sel_hi:[0,0,0]
	v_rcp_f32_e32 v14, v14
	v_rcp_f32_e32 v15, v15
	v_pk_mul_f32 v[10:11], v[24:25], v[10:11]
	v_pk_fma_f32 v[20:21], v[14:15], s[78:79], v[94:95] op_sel_hi:[1,0,0]
	s_nop 0
	v_pk_fma_f32 v[20:21], v[14:15], v[20:21], s[96:97] op_sel_hi:[1,1,0]
	s_nop 0
	v_pk_fma_f32 v[20:21], v[14:15], v[20:21], s[16:17] op_sel_hi:[1,1,0]
	s_nop 0
	v_pk_fma_f32 v[20:21], v[14:15], v[20:21], s[18:19] op_sel_hi:[1,1,0]
	s_nop 0
	v_pk_mul_f32 v[14:15], v[14:15], v[20:21]
	v_exp_f32_e32 v20, v5
	v_mul_f32_e32 v5, v26, v26
	v_mul_f32_e32 v5, 0xbf38aa3b, v5
	v_pk_mul_f32 v[14:15], v[20:21], v[14:15]
	s_nop 0
	v_pk_mul_f32 v[14:15], v[24:25], v[14:15] op_sel:[1,0]
	s_nop 0
	v_mov_b32_e32 v11, v14
	v_pk_add_f32 v[20:21], v[24:25], v[10:11] neg_lo:[0,1] neg_hi:[0,1]
	s_nop 0
	v_cndmask_b32_e64 v11, v21, v14, s[0:1]
	v_cndmask_b32_e32 v10, v20, v10, vcc
	s_waitcnt vmcnt(0)
; DI unsigned pk2(float a, float b) { f32x2 v = {a, b}; hbf16x2 r = __builtin_convertvector(v, hbf16x2); return __builtin_bit_cast(unsigned, r); }
; DI float gelu_erf(float x) { const f32x2 r = gelu_pk((f32x2){x, x}); return r.x; }
; DI void sample_cmlp(int b, const float* PS, const float* lng, const float* lnb, const float* wsp, const float* bsp, bf16* CAT, float* outVs, int lane) {
;     ...
;     for (int j = 0; j < 8; ++j) { const int col = 4 * (lane + 64 * j), g = col >> 7;
;         const f32x4 ga = *(const f32x4*)(lng + col), ba = *(const f32x4*)(lnb + col), ur = *(const f32x4*)(ps + col);
;         const float w00 = wsp[(size_t)g * 16384], b0 = bsp[g * 128];
;         f32x4 vn, o;
; #pragma unroll
;         for (int e = 0; e < 4; ++e) { vn[e] = (v[j][e] - mean) * rstd * ga[e] + ba[e]; o[e] = gelu_erf(ur[e]) * (w00 * vn[e] + b0); }
;         *(f32x4*)(outVs + (size_t)b * 2048 + col) = vn;
;         u32x2 w; w.x = pk2(o[0], o[1]); w.y = pk2(o[2], o[3]);
;         *(u32x2*)(CAT + (size_t)(MP + b) * DM + col) = w; }
	v_pk_fma_f32 v[14:15], v[28:29], v[8:9], v[30:31] op_sel_hi:[0,1,0]
	v_pk_mul_f32 v[14:15], v[10:11], v[14:15]
	v_pk_fma_f32 v[10:11], v[16:17], v[6:7], v[22:23]
	v_and_b32_e32 v6, 0x7fffffff, v26
	v_pk_fma_f32 v[6:7], v[6:7], s[76:77], 1.0 op_sel_hi:[0,0,0]
	v_rcp_f32_e32 v6, v6
	v_rcp_f32_e32 v7, v7
	v_and_b32_e32 v20, 0x7fffffff, v27
	v_pk_fma_f32 v[20:21], v[20:21], s[76:77], 1.0 op_sel_hi:[0,0,0]
	v_rcp_f32_e32 v20, v20
	v_rcp_f32_e32 v21, v21
	v_pk_fma_f32 v[16:17], v[6:7], s[78:79], v[94:95] op_sel_hi:[1,0,0]
	v_cmp_gt_f32_e32 vcc, 0, v26
	v_pk_fma_f32 v[16:17], v[6:7], v[16:17], s[96:97] op_sel_hi:[1,1,0]
	v_pk_fma_f32 v[22:23], v[20:21], s[78:79], v[94:95] op_sel_hi:[1,0,0]
	v_pk_fma_f32 v[16:17], v[6:7], v[16:17], s[16:17] op_sel_hi:[1,1,0]
	v_pk_fma_f32 v[22:23], v[20:21], v[22:23], s[96:97] op_sel_hi:[1,1,0]
	v_pk_fma_f32 v[16:17], v[6:7], v[16:17], s[18:19] op_sel_hi:[1,1,0]
	v_pk_fma_f32 v[22:23], v[20:21], v[22:23], s[16:17] op_sel_hi:[1,1,0]
	v_pk_mul_f32 v[6:7], v[6:7], v[16:17]
	v_exp_f32_e32 v16, v5
	v_mul_f32_e32 v5, v27, v27
	v_pk_fma_f32 v[22:23], v[20:21], v[22:23], s[18:19] op_sel_hi:[1,1,0]
	v_mul_f32_e32 v5, 0xbf38aa3b, v5
	v_pk_mul_f32 v[20:21], v[20:21], v[22:23]
	v_exp_f32_e32 v22, v5
	v_pk_mul_f32 v[6:7], v[16:17], v[6:7]
	v_mov_b32_e32 v16, v27
	v_pk_mul_f32 v[6:7], v[26:27], v[6:7]
	v_pk_mul_f32 v[20:21], v[22:23], v[20:21]
	v_cmp_gt_f32_e64 s[0:1], 0, v27
	v_pk_mul_f32 v[16:17], v[16:17], v[20:21] op_sel_hi:[0,1]
	v_mov_b32_e32 v7, v16
	v_pk_add_f32 v[20:21], v[26:27], v[6:7] neg_lo:[0,1] neg_hi:[0,1]
	global_store_dwordx4 v[18:19], v[8:11], off offset:2048 sc1
	v_cndmask_b32_e64 v7, v21, v16, s[0:1]
	v_cndmask_b32_e32 v6, v20, v6, vcc
	v_pk_fma_f32 v[16:17], v[28:29], v[10:11], v[30:31] op_sel_hi:[0,1,0]
	v_pk_mul_f32 v[6:7], v[6:7], v[16:17]
	v_cvt_pk_bf16_f32 v8, v14, v15
	v_cvt_pk_bf16_f32 v9, v6, v7
	global_store_dwordx2 v[12:13], v[8:9], off offset:3072
	global_load_dwordx4 v[6:9], v[84:85], off
	s_nop 0
	global_load_dwordx4 v[14:17], v[86:87], off
	global_load_dwordx4 v[20:23], v[136:137], off offset:3072
	global_load_dword v10, v[88:89], off
	global_load_dword v24, v[90:91], off
	v_pk_mul_f32 v[2:3], v[2:3], v[4:5] op_sel_hi:[1,0]
	s_waitcnt vmcnt(2)
	v_mul_f32_e32 v5, v20, v20
	v_pk_fma_f32 v[2:3], v[6:7], v[2:3], v[14:15]
	v_and_b32_e32 v6, 0x7fffffff, v20
	v_pk_fma_f32 v[6:7], v[6:7], s[76:77], 1.0 op_sel_hi:[0,0,0]
	v_rcp_f32_e32 v6, v6
	v_rcp_f32_e32 v7, v7
	v_mul_f32_e32 v5, 0xbf38aa3b, v5
	v_cmp_gt_f32_e32 vcc, 0, v20
	v_cmp_gt_f32_e64 s[0:1], 0, v21
	v_pk_fma_f32 v[14:15], v[6:7], s[78:79], v[94:95] op_sel_hi:[1,0,0]
	s_nop 0
	v_pk_fma_f32 v[14:15], v[6:7], v[14:15], s[96:97] op_sel_hi:[1,1,0]
	s_nop 0
	v_pk_fma_f32 v[14:15], v[6:7], v[14:15], s[16:17] op_sel_hi:[1,1,0]
	s_nop 0
	v_pk_fma_f32 v[14:15], v[6:7], v[14:15], s[18:19] op_sel_hi:[1,1,0]
	s_nop 0
	v_pk_mul_f32 v[6:7], v[6:7], v[14:15]
	v_exp_f32_e32 v14, v5
	v_mul_f32_e32 v5, v21, v21
	v_mul_f32_e32 v5, 0xbf38aa3b, v5
	v_pk_mul_f32 v[6:7], v[14:15], v[6:7]
	v_and_b32_e32 v14, 0x7fffffff, v21
	v_pk_fma_f32 v[14:15], v[14:15], s[76:77], 1.0 op_sel_hi:[0,0,0]
	v_rcp_f32_e32 v14, v14
	v_rcp_f32_e32 v15, v15
	v_pk_mul_f32 v[6:7], v[20:21], v[6:7]
	v_pk_fma_f32 v[26:27], v[14:15], s[78:79], v[94:95] op_sel_hi:[1,0,0]
	s_nop 0
	v_pk_fma_f32 v[26:27], v[14:15], v[26:27], s[96:97] op_sel_hi:[1,1,0]
	s_nop 0
	v_pk_fma_f32 v[26:27], v[14:15], v[26:27], s[16:17] op_sel_hi:[1,1,0]
	s_nop 0
	v_pk_fma_f32 v[26:27], v[14:15], v[26:27], s[18:19] op_sel_hi:[1,1,0]
	s_nop 0
	v_pk_mul_f32 v[14:15], v[14:15], v[26:27]
	v_exp_f32_e32 v26, v5
	v_mul_f32_e32 v5, v22, v22
	v_mul_f32_e32 v5, 0xbf38aa3b, v5
	v_pk_mul_f32 v[14:15], v[26:27], v[14:15]
	s_nop 0
	v_pk_mul_f32 v[14:15], v[20:21], v[14:15] op_sel:[1,0]
	v_and_b32_e32 v26, 0x7fffffff, v23
	v_mov_b32_e32 v7, v14
	v_pk_add_f32 v[20:21], v[20:21], v[6:7] neg_lo:[0,1] neg_hi:[0,1]
	v_pk_fma_f32 v[26:27], v[26:27], s[76:77], 1.0 op_sel_hi:[0,0,0]
	v_cndmask_b32_e64 v7, v21, v14, s[0:1]
	v_cndmask_b32_e32 v6, v20, v6, vcc
	s_waitcnt vmcnt(0)
	v_pk_fma_f32 v[14:15], v[10:11], v[2:3], v[24:25] op_sel_hi:[0,1,0]
	v_pk_mul_f32 v[6:7], v[6:7], v[14:15]
	v_and_b32_e32 v14, 0x7fffffff, v22
	v_pk_fma_f32 v[14:15], v[14:15], s[76:77], 1.0 op_sel_hi:[0,0,0]
	v_rcp_f32_e32 v14, v14
	v_rcp_f32_e32 v15, v15
	v_rcp_f32_e32 v26, v26
	v_rcp_f32_e32 v27, v27
	v_cmp_gt_f32_e32 vcc, 0, v22
	v_pk_fma_f32 v[20:21], v[14:15], s[78:79], v[94:95] op_sel_hi:[1,0,0]
	v_cmp_gt_f32_e64 s[0:1], 0, v23
	v_pk_fma_f32 v[20:21], v[14:15], v[20:21], s[96:97] op_sel_hi:[1,1,0]
	v_pk_fma_f32 v[28:29], v[26:27], s[78:79], v[94:95] op_sel_hi:[1,0,0]
	v_pk_fma_f32 v[20:21], v[14:15], v[20:21], s[16:17] op_sel_hi:[1,1,0]
	v_pk_fma_f32 v[28:29], v[26:27], v[28:29], s[96:97] op_sel_hi:[1,1,0]
	v_pk_fma_f32 v[20:21], v[14:15], v[20:21], s[18:19] op_sel_hi:[1,1,0]
	v_pk_fma_f32 v[28:29], v[26:27], v[28:29], s[16:17] op_sel_hi:[1,1,0]
	v_pk_mul_f32 v[14:15], v[14:15], v[20:21]
	v_exp_f32_e32 v20, v5
	v_mul_f32_e32 v5, v23, v23
	v_pk_fma_f32 v[28:29], v[26:27], v[28:29], s[18:19] op_sel_hi:[1,1,0]
	v_mul_f32_e32 v5, 0xbf38aa3b, v5
	v_pk_mul_f32 v[26:27], v[26:27], v[28:29]
	v_exp_f32_e32 v28, v5
	v_pk_mul_f32 v[14:15], v[20:21], v[14:15]
	v_mov_b32_e32 v20, v23
	v_pk_mul_f32 v[14:15], v[22:23], v[14:15]
	v_pk_mul_f32 v[26:27], v[28:29], v[26:27]
	v_pk_mul_f32 v[0:1], v[0:1], v[4:5] op_sel_hi:[1,0]
	v_pk_mul_f32 v[20:21], v[20:21], v[26:27] op_sel_hi:[0,1]
	v_mov_b32_e32 v15, v20
	v_pk_fma_f32 v[4:5], v[8:9], v[0:1], v[16:17]
	v_pk_add_f32 v[0:1], v[22:23], v[14:15] neg_lo:[0,1] neg_hi:[0,1]
	v_pk_fma_f32 v[8:9], v[10:11], v[4:5], v[24:25] op_sel_hi:[0,1,0]
	v_cndmask_b32_e64 v1, v1, v20, s[0:1]
	v_cndmask_b32_e32 v0, v0, v14, vcc
	v_pk_mul_f32 v[0:1], v[0:1], v[8:9]
	global_store_dwordx4 v[18:19], v[2:5], off offset:3072 sc1
	s_nop 1
	v_cvt_pk_bf16_f32 v2, v6, v7
	v_cvt_pk_bf16_f32 v3, v0, v1
	global_store_dwordx2 v[12:13], v[2:3], off offset:3584
	s_cbranch_scc0 .LBB0_360

;     DI void operator()(const f32x4 (&acc)[2][2][4][2], const Unit& u, int wr, int wc, int fr, int fq) const {
;     ...
;                 const int r = u.pm * BM + ai * HALF + wr * 64 + m * 16 + fr, pos = r & (SEQL - 1), b = r >> 11;
;                 const float rs = RS[r];
;                 const f32x4 A00 = acc[ai][0][m][0] * rs, A01 = acc[ai][0][m][1] * rs, A10 = acc[ai][1][m][0] * rs, A11 = acc[ai][1][m][1] * rs;
;                 if (pn < 5) {
;                     const f32x4* cp = (const f32x4*)(cosT + pos * 32 + 8 * fq); const f32x4* sp = (const f32x4*)(sinT + pos * 32 + 8 * fq);
;                     const f32x4 c0 = cp[0], c1 = cp[1], s0 = sp[0], s1 = sp[1];
;                     const f32x4 x1a = A00, x1b = A01, x2a = A10, x2b = A11;
;                     f32x4 o1a = x1a * c0 - x2a * s0, o1b = x1b * c1 - x2b * s1, o2a = x2a * c0 + x1a * s0, o2b = x2b * c1 + x1b * s1;
;                     if (pn < 4) {
;                         bf16* qp = Q + (size_t)r * 1024 + (4 * pn + wc) * 64 + 8 * fq;
;                         *(u32x4*)qp = pk8(o1a * QSC, o1b * QSC); *(u32x4*)(qp + 32) = pk8(o2a * QSC, o2b * QSC);
;                     } else {
;                         bf16* kp = Kb + (size_t)r * 256 + wc * 64 + 8 * fq;
;                         *(u32x4*)kp = pk8(o1a, o1b); *(u32x4*)(kp + 32) = pk8(o2a, o2b);
;                         if (pos >= SEQL - 128) { float* o = outK + ((size_t)(b * 128 + pos - (SEQL - 128))) * 256 + wc * 64 + 8 * fq;
;                             *(f32x4*)o = o1a; *(f32x4*)(o + 4) = o1b; *(f32x4*)(o + 32) = o2a; *(f32x4*)(o + 36) = o2b; }
;                     }
;                 } else if (pn == 5) {
; #pragma unroll
;                     for (int bj = 0; bj < 2; ++bj) { const int c = 128 * bj + 32 * wc + 8 * fq; const f32x4 va = bj ? A10 : A00, vb = bj ? A11 : A01;
;                         *(u32x4*)(Vb + (size_t)r * 256 + c) = pk8(va, vb);
;                         if (pos >= SEQL - 128) { float* o = outV + ((size_t)(b * 128 + pos - (SEQL - 128))) * 256 + c; *(f32x4*)o = va; *(f32x4*)(o + 4) = vb; } }
;                 } else if (pn < 10) {
; #pragma unroll
;                     for (int bj = 0; bj < 2; ++bj) { const int c = (pn - 6) * 256 + 128 * bj + 32 * wc + 8 * fq;
;                         *(u32x4*)(GB + (size_t)r * 1024 + c) = pk8(bj ? A10 : A00, bj ? A11 : A01); }
;                 } else {
.LBB0_450:
	v_mov_b32_e32 v194, v190
	v_mov_b32_e32 v195, v191
	s_cmp_eq_u32 s2, 32
	s_mov_b64 s[0:1], -1
	s_cbranch_scc1 .LBB0_636
	s_cmp_gt_i32 s54, 4
	s_cselect_b64 s[58:59], -1, 0
	s_cmp_lg_u32 s54, 5
	s_cselect_b64 s[4:5], -1, 0
	s_cmp_gt_u32 s54, 9
	s_cselect_b64 s[56:57], -1, 0
	s_lshl_b32 s0, s54, 7
	s_lshl_b32 s33, s54, 8
	s_add_i32 s3, s0, s74
	s_add_i32 s47, s75, s33
	s_cmp_lg_u32 s54, 4
	s_cselect_b64 s[0:1], -1, 0
	s_lshl_b32 s2, s2, 8
	s_add_i32 s2, s2, s70
	v_add_u32_e32 v186, s2, v194
	v_ashrrev_i32_e32 v187, 31, v186
	v_lshl_add_u64 v[128:129], v[186:187], 2, s[28:29]
	global_load_dword v128, v[128:129], off
	v_lshlrev_b32_e32 v176, 3, v195
	v_add_u32_e32 v182, s3, v176
	s_mov_b64 s[8:9], -1
	v_add_u32_e32 v178, s71, v176
	v_add_u32_e32 v180, s47, v176
	v_ashrrev_i32_e32 v183, 31, v182
	s_and_b64 vcc, exec, s[58:59]
	v_and_b32_e32 v188, 0x7ff, v186
	v_ashrrev_i32_e32 v189, 11, v186
	s_waitcnt vmcnt(0)
	v_pk_mul_f32 v[142:143], v[30:31], v[128:129] op_sel_hi:[1,0]
	v_pk_mul_f32 v[140:141], v[28:29], v[128:129] op_sel_hi:[1,0]
	v_pk_mul_f32 v[138:139], v[26:27], v[128:129] op_sel_hi:[1,0]
	v_pk_mul_f32 v[136:137], v[24:25], v[128:129] op_sel_hi:[1,0]
	v_pk_mul_f32 v[134:135], v[22:23], v[128:129] op_sel_hi:[1,0]
	v_pk_mul_f32 v[132:133], v[20:21], v[128:129] op_sel_hi:[1,0]
	v_pk_mul_f32 v[130:131], v[18:19], v[128:129] op_sel_hi:[1,0]
	v_pk_mul_f32 v[128:129], v[16:17], v[128:129] op_sel_hi:[1,0]
	s_cbranch_vccz .LBB0_467
	s_mov_b64 s[2:3], -1
	s_and_b64 vcc, exec, s[4:5]
	s_cbranch_vccz .LBB0_460
	s_and_b64 vcc, exec, s[56:57]
	s_cbranch_vccz .LBB0_457
	v_lshlrev_b64 v[184:185], 11, v[186:187]
	v_pk_mul_f32 v[146:147], v[142:143], v[134:135]
	v_pk_mul_f32 v[144:145], v[140:141], v[132:133]
	v_pk_mul_f32 v[150:151], v[138:139], v[130:131]
	v_pk_mul_f32 v[148:149], v[136:137], v[128:129]
	v_lshl_add_u64 v[184:185], s[24:25], 0, v[184:185]
	s_movk_i32 s2, 0x7fd
	v_cvt_pk_bf16_f32 v196, v144, v145
	v_cvt_pk_bf16_f32 v197, v146, v147
	v_cvt_pk_bf16_f32 v198, v148, v149
	v_cvt_pk_bf16_f32 v199, v150, v151
	v_lshl_add_u64 v[184:185], v[182:183], 1, v[184:185]
	v_cmp_lt_u32_e32 vcc, s2, v188
	global_store_dwordx4 v[184:185], v[196:199], off sc1
	s_and_saveexec_b64 s[2:3], vcc
	s_cbranch_execz .LBB0_456
	v_lshlrev_b32_e32 v152, 1, v189
	s_movk_i32 s8, 0xf802
	v_add3_u32 v184, v188, v152, s8
	v_ashrrev_i32_e32 v185, 31, v184
	v_lshlrev_b64 v[184:185], 12, v[184:185]
	v_lshl_add_u64 v[184:185], s[38:39], 0, v[184:185]
	v_lshl_add_u64 v[184:185], v[182:183], 2, v[184:185]
	global_store_dwordx4 v[184:185], v[144:147], off sc1
	global_store_dwordx4 v[184:185], v[148:151], off offset:16 sc1

; DI u32x4 pk8(f32x4 a, f32x4 b) { u32x4 w; w.x = pk2(a[0], a[1]); w.y = pk2(a[2], a[3]); w.z = pk2(b[0], b[1]); w.w = pk2(b[2], b[3]); return w; }
;     DI void operator()(const f32x4 (&acc)[2][2][4][2], const Unit& u, int wr, int wc, int fr, int fq) const {
;     ...
;                 } else if (pn < 10) {
; #pragma unroll
;                     for (int bj = 0; bj < 2; ++bj) { const int c = (pn - 6) * 256 + 128 * bj + 32 * wc + 8 * fq;
;                         *(u32x4*)(GB + (size_t)r * 1024 + c) = pk8(bj ? A10 : A00, bj ? A11 : A01); }
.LBB0_457:
	s_andn2_b64 vcc, exec, s[2:3]
	s_cbranch_vccnz .LBB0_459
	v_lshlrev_b64 v[148:149], 11, v[186:187]
	v_lshl_add_u64 v[148:149], s[22:23], 0, v[148:149]
	v_ashrrev_i32_e32 v181, 31, v180
	v_cvt_pk_bf16_f32 v144, v140, v141
	v_cvt_pk_bf16_f32 v145, v142, v143
	v_cvt_pk_bf16_f32 v146, v136, v137
	v_cvt_pk_bf16_f32 v147, v138, v139
	v_lshl_add_u64 v[148:149], v[180:181], 1, v[148:149]
	global_store_dwordx4 v[148:149], v[144:147], off sc1
	s_nop 1
	v_cvt_pk_bf16_f32 v144, v132, v133
	v_cvt_pk_bf16_f32 v145, v134, v135
	v_cvt_pk_bf16_f32 v146, v128, v129
	v_cvt_pk_bf16_f32 v147, v130, v131
	global_store_dwordx4 v[148:149], v[144:147], off offset:256 sc1

; DI u32x4 pk8(f32x4 a, f32x4 b) { u32x4 w; w.x = pk2(a[0], a[1]); w.y = pk2(a[2], a[3]); w.z = pk2(b[0], b[1]); w.w = pk2(b[2], b[3]); return w; }
;     DI void operator()(const f32x4 (&acc)[2][2][4][2], const Unit& u, int wr, int wc, int fr, int fq) const {
;     ...
;                 } else if (pn == 5) {
; #pragma unroll
;                     for (int bj = 0; bj < 2; ++bj) { const int c = 128 * bj + 32 * wc + 8 * fq; const f32x4 va = bj ? A10 : A00, vb = bj ? A11 : A01;
;                         *(u32x4*)(Vb + (size_t)r * 256 + c) = pk8(va, vb);
;                         if (pos >= SEQL - 128) { float* o = outV + ((size_t)(b * 128 + pos - (SEQL - 128))) * 256 + c; *(f32x4*)o = va; *(f32x4*)(o + 4) = vb; } }
.LBB0_460:
	s_andn2_b64 vcc, exec, s[2:3]
	s_cbranch_vccnz .LBB0_466
	s_movk_i32 s2, 0x77f
	v_cmp_lt_u32_e32 vcc, s2, v188
	v_lshlrev_b32_e32 v146, 7, v189
	s_movk_i32 s2, 0xf880
	v_add3_u32 v146, v188, v146, s2
	v_lshlrev_b64 v[144:145], 9, v[186:187]
	v_ashrrev_i32_e32 v147, 31, v146
	v_lshlrev_b64 v[184:185], 10, v[146:147]
	v_lshl_add_u64 v[144:145], s[20:21], 0, v[144:145]
	v_ashrrev_i32_e32 v179, 31, v178
	v_lshl_add_u64 v[146:147], v[178:179], 1, v[144:145]
	v_lshl_add_u64 v[144:145], s[36:37], 0, v[184:185]
	v_cvt_pk_bf16_f32 v148, v140, v141
	v_cvt_pk_bf16_f32 v149, v142, v143
	v_cvt_pk_bf16_f32 v150, v136, v137
	v_cvt_pk_bf16_f32 v151, v138, v139
	v_lshl_add_u64 v[144:145], v[178:179], 2, v[144:145]
	global_store_dwordx4 v[146:147], v[148:151], off sc1
	s_and_saveexec_b64 s[2:3], vcc
	s_cbranch_execz .LBB0_463
	global_store_dwordx4 v[144:145], v[140:143], off sc1
	global_store_dwordx4 v[144:145], v[136:139], off offset:16 sc1
.LBB0_463:
	s_or_b64 exec, exec, s[2:3]
	v_cvt_pk_bf16_f32 v148, v132, v133
	v_cvt_pk_bf16_f32 v149, v134, v135
	v_cvt_pk_bf16_f32 v150, v128, v129
	v_cvt_pk_bf16_f32 v151, v130, v131
	global_store_dwordx4 v[146:147], v[148:151], off offset:256 sc1
	s_and_saveexec_b64 s[2:3], vcc
	s_cbranch_execz .LBB0_465
	global_store_dwordx4 v[144:145], v[132:135], off offset:512 sc1
	global_store_dwordx4 v[144:145], v[128:131], off offset:528 sc1

; DI u32x4 pk8(f32x4 a, f32x4 b) { u32x4 w; w.x = pk2(a[0], a[1]); w.y = pk2(a[2], a[3]); w.z = pk2(b[0], b[1]); w.w = pk2(b[2], b[3]); return w; }
;     DI void operator()(const f32x4 (&acc)[2][2][4][2], const Unit& u, int wr, int wc, int fr, int fq) const {
;     ...
;                 if (pn < 5) {
;                     const f32x4* cp = (const f32x4*)(cosT + pos * 32 + 8 * fq); const f32x4* sp = (const f32x4*)(sinT + pos * 32 + 8 * fq);
;                     const f32x4 c0 = cp[0], c1 = cp[1], s0 = sp[0], s1 = sp[1];
;                     const f32x4 x1a = A00, x1b = A01, x2a = A10, x2b = A11;
;                     f32x4 o1a = x1a * c0 - x2a * s0, o1b = x1b * c1 - x2b * s1, o2a = x2a * c0 + x1a * s0, o2b = x2b * c1 + x1b * s1;
;                     if (pn < 4) {
;                         bf16* qp = Q + (size_t)r * 1024 + (4 * pn + wc) * 64 + 8 * fq;
;                         *(u32x4*)qp = pk8(o1a * QSC, o1b * QSC); *(u32x4*)(qp + 32) = pk8(o2a * QSC, o2b * QSC);
;                     } else {
;                         bf16* kp = Kb + (size_t)r * 256 + wc * 64 + 8 * fq;
;                         *(u32x4*)kp = pk8(o1a, o1b); *(u32x4*)(kp + 32) = pk8(o2a, o2b);
;                         if (pos >= SEQL - 128) { float* o = outK + ((size_t)(b * 128 + pos - (SEQL - 128))) * 256 + wc * 64 + 8 * fq;
;                             *(f32x4*)o = o1a; *(f32x4*)(o + 4) = o1b; *(f32x4*)(o + 32) = o2a; *(f32x4*)(o + 36) = o2b; }
;                     }
.LBB0_467:
	v_ashrrev_i32_e32 v177, 31, v176
	s_or_b32 s2, s33, s76
	v_cndmask_b32_e64 v144, 0, 1, s[0:1]
	s_ashr_i32 s3, s2, 31
	s_andn2_b64 vcc, exec, s[8:9]
	v_lshlrev_b64 v[184:185], 2, v[176:177]
	v_cmp_ne_u32_e64 s[0:1], 1, v144
	s_cbranch_vccnz .LBB0_474
	v_lshlrev_b32_e32 v152, 7, v188
	v_lshl_add_u64 v[144:145], s[34:35], 0, v[152:153]
	v_lshl_add_u64 v[148:149], v[144:145], 0, v[184:185]
	v_lshl_add_u64 v[196:197], s[30:31], 0, v[152:153]
	global_load_dwordx4 v[144:147], v[148:149], off
	s_nop 0
	global_load_dwordx4 v[148:151], v[148:149], off offset:16
	v_lshl_add_u64 v[200:201], v[196:197], 0, v[184:185]
	global_load_dwordx4 v[196:199], v[200:201], off
	s_nop 0
	global_load_dwordx4 v[200:203], v[200:201], off offset:16
	s_and_b64 vcc, exec, s[0:1]
	s_mov_b64 s[8:9], -1
	s_waitcnt vmcnt(3)
	v_pk_mul_f32 v[204:205], v[134:135], v[146:147]
	v_pk_mul_f32 v[206:207], v[132:133], v[144:145]
	s_waitcnt vmcnt(2)
	v_pk_mul_f32 v[208:209], v[130:131], v[150:151]
	v_pk_mul_f32 v[210:211], v[128:129], v[148:149]
	v_pk_mul_f32 v[146:147], v[142:143], v[146:147]
	v_pk_mul_f32 v[144:145], v[140:141], v[144:145]
	v_pk_mul_f32 v[150:151], v[138:139], v[150:151]
	v_pk_mul_f32 v[148:149], v[136:137], v[148:149]
	s_waitcnt vmcnt(1)
	v_pk_fma_f32 v[142:143], v[142:143], v[198:199], v[204:205] neg_lo:[0,0,1] neg_hi:[0,0,1]
	v_pk_fma_f32 v[140:141], v[140:141], v[196:197], v[206:207] neg_lo:[0,0,1] neg_hi:[0,0,1]
	s_waitcnt vmcnt(0)
	v_pk_fma_f32 v[138:139], v[138:139], v[202:203], v[208:209] neg_lo:[0,0,1] neg_hi:[0,0,1]
	v_pk_fma_f32 v[136:137], v[136:137], v[200:201], v[210:211] neg_lo:[0,0,1] neg_hi:[0,0,1]
	v_pk_fma_f32 v[134:135], v[134:135], v[198:199], v[146:147]
	v_pk_fma_f32 v[132:133], v[132:133], v[196:197], v[144:145]
	v_pk_fma_f32 v[130:131], v[130:131], v[202:203], v[150:151]
	v_pk_fma_f32 v[128:129], v[128:129], v[200:201], v[148:149]
	s_cbranch_vccnz .LBB0_470
	v_lshlrev_b64 v[144:145], 11, v[186:187]
	v_lshl_add_u64 v[144:145], s[18:19], 0, v[144:145]
	v_lshl_add_u64 v[144:145], s[2:3], 1, v[144:145]
	s_mov_b32 s8, 0x3e38aa3b
	v_lshl_add_u64 v[148:149], v[176:177], 1, v[144:145]
	v_pk_mul_f32 v[146:147], v[142:143], s[8:9] op_sel_hi:[1,0]
	v_pk_mul_f32 v[144:145], v[140:141], s[8:9] op_sel_hi:[1,0]
	v_pk_mul_f32 v[150:151], v[138:139], s[8:9] op_sel_hi:[1,0]
	v_pk_mul_f32 v[196:197], v[136:137], s[8:9] op_sel_hi:[1,0]
	v_cvt_pk_bf16_f32 v144, v144, v145
	v_cvt_pk_bf16_f32 v145, v146, v147
	v_cvt_pk_bf16_f32 v146, v196, v197
	v_cvt_pk_bf16_f32 v147, v150, v151
	global_store_dwordx4 v[148:149], v[144:147], off sc1
	v_pk_mul_f32 v[150:151], v[130:131], s[8:9] op_sel_hi:[1,0]
	v_pk_mul_f32 v[196:197], v[128:129], s[8:9] op_sel_hi:[1,0]
	v_pk_mul_f32 v[146:147], v[134:135], s[8:9] op_sel_hi:[1,0]
	v_pk_mul_f32 v[144:145], v[132:133], s[8:9] op_sel_hi:[1,0]
	s_mov_b64 s[8:9], 0
	v_cvt_pk_bf16_f32 v144, v144, v145
	v_cvt_pk_bf16_f32 v145, v146, v147
	v_cvt_pk_bf16_f32 v146, v196, v197
	v_cvt_pk_bf16_f32 v147, v150, v151
	global_store_dwordx4 v[148:149], v[144:147], off offset:64 sc1
.LBB0_470:
	s_andn2_b64 vcc, exec, s[8:9]
	s_cbranch_vccnz .LBB0_474
	v_lshlrev_b64 v[144:145], 9, v[186:187]
	v_lshl_add_u64 v[144:145], s[42:43], 0, v[144:145]
	v_lshl_add_u64 v[148:149], v[176:177], 1, v[144:145]
	v_cvt_pk_bf16_f32 v144, v140, v141
	v_cvt_pk_bf16_f32 v145, v142, v143
	v_cvt_pk_bf16_f32 v146, v136, v137
	v_cvt_pk_bf16_f32 v147, v138, v139
	s_movk_i32 s8, 0x77f
	global_store_dwordx4 v[148:149], v[144:147], off sc1
	v_cmp_lt_u32_e32 vcc, s8, v188
	s_nop 0
	v_cvt_pk_bf16_f32 v144, v132, v133
	v_cvt_pk_bf16_f32 v145, v134, v135
	v_cvt_pk_bf16_f32 v146, v128, v129
	v_cvt_pk_bf16_f32 v147, v130, v131
	global_store_dwordx4 v[148:149], v[144:147], off offset:64 sc1
	s_and_saveexec_b64 s[8:9], vcc
	s_cbranch_execz .LBB0_473
	v_lshlrev_b32_e32 v144, 7, v189
	s_movk_i32 s33, 0xf880
	v_add3_u32 v144, v188, v144, s33
	v_ashrrev_i32_e32 v145, 31, v144
	v_lshlrev_b64 v[144:145], 10, v[144:145]
	v_lshl_add_u64 v[144:145], s[44:45], 0, v[144:145]
	v_lshl_add_u64 v[144:145], v[176:177], 2, v[144:145]
	global_store_dwordx4 v[144:145], v[140:143], off sc1
	global_store_dwordx4 v[144:145], v[136:139], off offset:16 sc1
	global_store_dwordx4 v[144:145], v[132:135], off offset:128 sc1
	global_store_dwordx4 v[144:145], v[128:131], off offset:144 sc1

; DI u32x4 pk8(f32x4 a, f32x4 b) { u32x4 w; w.x = pk2(a[0], a[1]); w.y = pk2(a[2], a[3]); w.z = pk2(b[0], b[1]); w.w = pk2(b[2], b[3]); return w; }
;     DI void operator()(const f32x4 (&acc)[2][2][4][2], const Unit& u, int wr, int wc, int fr, int fq) const {
;     ...
;                 const int r = u.pm * BM + ai * HALF + wr * 64 + m * 16 + fr, pos = r & (SEQL - 1), b = r >> 11;
;                 const float rs = RS[r];
;                 const f32x4 A00 = acc[ai][0][m][0] * rs, A01 = acc[ai][0][m][1] * rs, A10 = acc[ai][1][m][0] * rs, A11 = acc[ai][1][m][1] * rs;
;     ...
;                 } else {
;                     const int c = 128 * (pn - 10) + 32 * wc + 8 * fq;
;                     const f32x4 za = A00 * A10, zb = A01 * A11;
;                     *(u32x4*)(Z + (size_t)r * 1024 + c) = pk8(za, zb);
;                     if (pos >= SEQL - 2) { float* o = outC + ((size_t)(b * 2 + pos - (SEQL - 2))) * 1024 + c; *(f32x4*)o = za; *(f32x4*)(o + 4) = zb; }
.LBB0_474:
	v_add_u32_e32 v188, 16, v186
	v_ashrrev_i32_e32 v189, 31, v188
	v_lshl_add_u64 v[128:129], v[188:189], 2, s[28:29]
	global_load_dword v128, v[128:129], off
	v_cndmask_b32_e64 v144, 0, 1, s[58:59]
	v_cmp_ne_u32_e64 s[8:9], 1, v144
	v_cndmask_b32_e64 v144, 0, 1, s[4:5]
	v_and_b32_e32 v187, 0x7ff, v188
	v_ashrrev_i32_e32 v196, 11, v188
	s_mov_b64 s[60:61], -1
	s_andn2_b64 vcc, exec, s[58:59]
	v_cmp_ne_u32_e64 s[4:5], 1, v144
	s_waitcnt vmcnt(0)
	v_pk_mul_f32 v[142:143], v[14:15], v[128:129] op_sel_hi:[1,0]
	v_pk_mul_f32 v[140:141], v[12:13], v[128:129] op_sel_hi:[1,0]
	v_pk_mul_f32 v[138:139], v[10:11], v[128:129] op_sel_hi:[1,0]
	v_pk_mul_f32 v[136:137], v[8:9], v[128:129] op_sel_hi:[1,0]
	v_pk_mul_f32 v[134:135], v[6:7], v[128:129] op_sel_hi:[1,0]
	v_pk_mul_f32 v[132:133], v[4:5], v[128:129] op_sel_hi:[1,0]
	v_pk_mul_f32 v[130:131], v[2:3], v[128:129] op_sel_hi:[1,0]
	v_pk_mul_f32 v[128:129], v[0:1], v[128:129] op_sel_hi:[1,0]
	s_cbranch_vccnz .LBB0_490
	s_and_b64 vcc, exec, s[4:5]
	s_mov_b64 s[58:59], -1
	s_cbranch_vccnz .LBB0_483
	s_andn2_b64 vcc, exec, s[56:57]
	s_cbranch_vccnz .LBB0_480
	v_lshlrev_b64 v[202:203], 11, v[188:189]
	v_pk_mul_f32 v[146:147], v[142:143], v[134:135]
	v_pk_mul_f32 v[144:145], v[140:141], v[132:133]
	v_pk_mul_f32 v[150:151], v[138:139], v[130:131]
	v_pk_mul_f32 v[148:149], v[136:137], v[128:129]
	v_lshl_add_u64 v[202:203], s[24:25], 0, v[202:203]
	s_movk_i32 s33, 0x7fd
	v_cvt_pk_bf16_f32 v198, v144, v145
	v_cvt_pk_bf16_f32 v199, v146, v147
	v_cvt_pk_bf16_f32 v200, v148, v149
	v_cvt_pk_bf16_f32 v201, v150, v151
	v_lshl_add_u64 v[202:203], v[182:183], 1, v[202:203]
	v_cmp_lt_u32_e32 vcc, s33, v187
	global_store_dwordx4 v[202:203], v[198:201], off sc1
	s_and_saveexec_b64 s[58:59], vcc
	s_cbranch_execz .LBB0_479
	v_lshlrev_b32_e32 v152, 1, v196
	s_movk_i32 s33, 0xf802
	v_add3_u32 v198, v187, v152, s33
	v_ashrrev_i32_e32 v199, 31, v198
	v_lshlrev_b64 v[198:199], 12, v[198:199]
	v_lshl_add_u64 v[198:199], s[38:39], 0, v[198:199]
	v_lshl_add_u64 v[198:199], v[182:183], 2, v[198:199]
	global_store_dwordx4 v[198:199], v[144:147], off sc1
	global_store_dwordx4 v[198:199], v[148:151], off offset:16 sc1

; DI u32x4 pk8(f32x4 a, f32x4 b) { u32x4 w; w.x = pk2(a[0], a[1]); w.y = pk2(a[2], a[3]); w.z = pk2(b[0], b[1]); w.w = pk2(b[2], b[3]); return w; }
;     DI void operator()(const f32x4 (&acc)[2][2][4][2], const Unit& u, int wr, int wc, int fr, int fq) const {
;     ...
;                 } else if (pn < 10) {
; #pragma unroll
;                     for (int bj = 0; bj < 2; ++bj) { const int c = (pn - 6) * 256 + 128 * bj + 32 * wc + 8 * fq;
;                         *(u32x4*)(GB + (size_t)r * 1024 + c) = pk8(bj ? A10 : A00, bj ? A11 : A01); }
.LBB0_480:
	s_andn2_b64 vcc, exec, s[58:59]
	s_cbranch_vccnz .LBB0_482
	v_lshlrev_b64 v[148:149], 11, v[188:189]
	v_lshl_add_u64 v[148:149], s[22:23], 0, v[148:149]
	v_ashrrev_i32_e32 v181, 31, v180
	v_cvt_pk_bf16_f32 v144, v140, v141
	v_cvt_pk_bf16_f32 v145, v142, v143
	v_cvt_pk_bf16_f32 v146, v136, v137
	v_cvt_pk_bf16_f32 v147, v138, v139
	v_lshl_add_u64 v[148:149], v[180:181], 1, v[148:149]
	global_store_dwordx4 v[148:149], v[144:147], off sc1
	s_nop 1
	v_cvt_pk_bf16_f32 v144, v132, v133
	v_cvt_pk_bf16_f32 v145, v134, v135
	v_cvt_pk_bf16_f32 v146, v128, v129
	v_cvt_pk_bf16_f32 v147, v130, v131
	global_store_dwordx4 v[148:149], v[144:147], off offset:256 sc1

; DI u32x4 pk8(f32x4 a, f32x4 b) { u32x4 w; w.x = pk2(a[0], a[1]); w.y = pk2(a[2], a[3]); w.z = pk2(b[0], b[1]); w.w = pk2(b[2], b[3]); return w; }
;     DI void operator()(const f32x4 (&acc)[2][2][4][2], const Unit& u, int wr, int wc, int fr, int fq) const {
;     ...
;                 } else if (pn == 5) {
; #pragma unroll
;                     for (int bj = 0; bj < 2; ++bj) { const int c = 128 * bj + 32 * wc + 8 * fq; const f32x4 va = bj ? A10 : A00, vb = bj ? A11 : A01;
;                         *(u32x4*)(Vb + (size_t)r * 256 + c) = pk8(va, vb);
;                         if (pos >= SEQL - 128) { float* o = outV + ((size_t)(b * 128 + pos - (SEQL - 128))) * 256 + c; *(f32x4*)o = va; *(f32x4*)(o + 4) = vb; } }
.LBB0_483:
	s_andn2_b64 vcc, exec, s[58:59]
	s_cbranch_vccnz .LBB0_489
	s_movk_i32 s33, 0x77f
	v_cmp_lt_u32_e32 vcc, s33, v187
	v_lshlrev_b32_e32 v146, 7, v196
	s_movk_i32 s33, 0xf880
	v_add3_u32 v146, v187, v146, s33
	v_lshlrev_b64 v[144:145], 9, v[188:189]
	v_ashrrev_i32_e32 v147, 31, v146
	v_lshlrev_b64 v[198:199], 10, v[146:147]
	v_lshl_add_u64 v[144:145], s[20:21], 0, v[144:145]
	v_ashrrev_i32_e32 v179, 31, v178
	v_lshl_add_u64 v[146:147], v[178:179], 1, v[144:145]
	v_lshl_add_u64 v[144:145], s[36:37], 0, v[198:199]
	v_cvt_pk_bf16_f32 v148, v140, v141
	v_cvt_pk_bf16_f32 v149, v142, v143
	v_cvt_pk_bf16_f32 v150, v136, v137
	v_cvt_pk_bf16_f32 v151, v138, v139
	v_lshl_add_u64 v[144:145], v[178:179], 2, v[144:145]
	global_store_dwordx4 v[146:147], v[148:151], off sc1
	s_and_saveexec_b64 s[58:59], vcc
	s_cbranch_execz .LBB0_486
	global_store_dwordx4 v[144:145], v[140:143], off sc1
	global_store_dwordx4 v[144:145], v[136:139], off offset:16 sc1
.LBB0_486:
	s_or_b64 exec, exec, s[58:59]
	v_cvt_pk_bf16_f32 v148, v132, v133
	v_cvt_pk_bf16_f32 v149, v134, v135
	v_cvt_pk_bf16_f32 v150, v128, v129
	v_cvt_pk_bf16_f32 v151, v130, v131
	global_store_dwordx4 v[146:147], v[148:151], off offset:256 sc1
	s_and_saveexec_b64 s[58:59], vcc
	s_cbranch_execz .LBB0_488
	global_store_dwordx4 v[144:145], v[132:135], off offset:512 sc1
	global_store_dwordx4 v[144:145], v[128:131], off offset:528 sc1

; DI u32x4 pk8(f32x4 a, f32x4 b) { u32x4 w; w.x = pk2(a[0], a[1]); w.y = pk2(a[2], a[3]); w.z = pk2(b[0], b[1]); w.w = pk2(b[2], b[3]); return w; }
;     DI void operator()(const f32x4 (&acc)[2][2][4][2], const Unit& u, int wr, int wc, int fr, int fq) const {
;     ...
;                 if (pn < 5) {
;                     const f32x4* cp = (const f32x4*)(cosT + pos * 32 + 8 * fq); const f32x4* sp = (const f32x4*)(sinT + pos * 32 + 8 * fq);
;                     const f32x4 c0 = cp[0], c1 = cp[1], s0 = sp[0], s1 = sp[1];
;                     const f32x4 x1a = A00, x1b = A01, x2a = A10, x2b = A11;
;                     f32x4 o1a = x1a * c0 - x2a * s0, o1b = x1b * c1 - x2b * s1, o2a = x2a * c0 + x1a * s0, o2b = x2b * c1 + x1b * s1;
;                     if (pn < 4) {
;                         bf16* qp = Q + (size_t)r * 1024 + (4 * pn + wc) * 64 + 8 * fq;
;                         *(u32x4*)qp = pk8(o1a * QSC, o1b * QSC); *(u32x4*)(qp + 32) = pk8(o2a * QSC, o2b * QSC);
;                     } else {
;                         bf16* kp = Kb + (size_t)r * 256 + wc * 64 + 8 * fq;
;                         *(u32x4*)kp = pk8(o1a, o1b); *(u32x4*)(kp + 32) = pk8(o2a, o2b);
;                         if (pos >= SEQL - 128) { float* o = outK + ((size_t)(b * 128 + pos - (SEQL - 128))) * 256 + wc * 64 + 8 * fq;
;                             *(f32x4*)o = o1a; *(f32x4*)(o + 4) = o1b; *(f32x4*)(o + 32) = o2a; *(f32x4*)(o + 36) = o2b; }
;                     }
.LBB0_490:
	s_andn2_b64 vcc, exec, s[60:61]
	s_cbranch_vccnz .LBB0_497
	v_lshlrev_b32_e32 v152, 7, v187
	v_lshl_add_u64 v[144:145], s[34:35], 0, v[152:153]
	v_lshl_add_u64 v[148:149], v[144:145], 0, v[184:185]
	v_lshl_add_u64 v[198:199], s[30:31], 0, v[152:153]
	global_load_dwordx4 v[144:147], v[148:149], off
	s_nop 0
	global_load_dwordx4 v[148:151], v[148:149], off offset:16
	v_lshl_add_u64 v[202:203], v[198:199], 0, v[184:185]
	global_load_dwordx4 v[198:201], v[202:203], off
	s_nop 0
	global_load_dwordx4 v[202:205], v[202:203], off offset:16
	s_and_b64 vcc, exec, s[0:1]
	s_mov_b64 s[58:59], -1
	s_waitcnt vmcnt(3)
	v_pk_mul_f32 v[206:207], v[134:135], v[146:147]
	v_pk_mul_f32 v[208:209], v[132:133], v[144:145]
	s_waitcnt vmcnt(2)
	v_pk_mul_f32 v[210:211], v[130:131], v[150:151]
	v_pk_mul_f32 v[212:213], v[128:129], v[148:149]
	v_pk_mul_f32 v[146:147], v[142:143], v[146:147]
	v_pk_mul_f32 v[144:145], v[140:141], v[144:145]
	v_pk_mul_f32 v[150:151], v[138:139], v[150:151]
	v_pk_mul_f32 v[148:149], v[136:137], v[148:149]
	s_waitcnt vmcnt(1)
	v_pk_fma_f32 v[142:143], v[142:143], v[200:201], v[206:207] neg_lo:[0,0,1] neg_hi:[0,0,1]
	v_pk_fma_f32 v[140:141], v[140:141], v[198:199], v[208:209] neg_lo:[0,0,1] neg_hi:[0,0,1]
	s_waitcnt vmcnt(0)
	v_pk_fma_f32 v[138:139], v[138:139], v[204:205], v[210:211] neg_lo:[0,0,1] neg_hi:[0,0,1]
	v_pk_fma_f32 v[136:137], v[136:137], v[202:203], v[212:213] neg_lo:[0,0,1] neg_hi:[0,0,1]
	v_pk_fma_f32 v[134:135], v[134:135], v[200:201], v[146:147]
	v_pk_fma_f32 v[132:133], v[132:133], v[198:199], v[144:145]
	v_pk_fma_f32 v[130:131], v[130:131], v[204:205], v[150:151]
	v_pk_fma_f32 v[128:129], v[128:129], v[202:203], v[148:149]
	s_cbranch_vccnz .LBB0_493
	v_lshlrev_b64 v[144:145], 11, v[188:189]
	v_lshl_add_u64 v[144:145], s[18:19], 0, v[144:145]
	v_lshl_add_u64 v[144:145], s[2:3], 1, v[144:145]
	s_mov_b32 s58, 0x3e38aa3b
	v_lshl_add_u64 v[148:149], v[176:177], 1, v[144:145]
	v_pk_mul_f32 v[146:147], v[142:143], s[58:59] op_sel_hi:[1,0]
	v_pk_mul_f32 v[144:145], v[140:141], s[58:59] op_sel_hi:[1,0]
	v_pk_mul_f32 v[150:151], v[138:139], s[58:59] op_sel_hi:[1,0]
	v_pk_mul_f32 v[198:199], v[136:137], s[58:59] op_sel_hi:[1,0]
	v_cvt_pk_bf16_f32 v144, v144, v145
	v_cvt_pk_bf16_f32 v145, v146, v147
	v_cvt_pk_bf16_f32 v146, v198, v199
	v_cvt_pk_bf16_f32 v147, v150, v151
	global_store_dwordx4 v[148:149], v[144:147], off sc1
	v_pk_mul_f32 v[150:151], v[130:131], s[58:59] op_sel_hi:[1,0]
	v_pk_mul_f32 v[198:199], v[128:129], s[58:59] op_sel_hi:[1,0]
	v_pk_mul_f32 v[146:147], v[134:135], s[58:59] op_sel_hi:[1,0]
	v_pk_mul_f32 v[144:145], v[132:133], s[58:59] op_sel_hi:[1,0]
	s_mov_b64 s[58:59], 0
	v_cvt_pk_bf16_f32 v144, v144, v145
	v_cvt_pk_bf16_f32 v145, v146, v147
	v_cvt_pk_bf16_f32 v146, v198, v199
	v_cvt_pk_bf16_f32 v147, v150, v151
	global_store_dwordx4 v[148:149], v[144:147], off offset:64 sc1
.LBB0_493:
	s_andn2_b64 vcc, exec, s[58:59]
	s_cbranch_vccnz .LBB0_497
	v_lshlrev_b64 v[144:145], 9, v[188:189]
	v_lshl_add_u64 v[144:145], s[42:43], 0, v[144:145]
	v_lshl_add_u64 v[148:149], v[176:177], 1, v[144:145]
	v_cvt_pk_bf16_f32 v144, v140, v141
	v_cvt_pk_bf16_f32 v145, v142, v143
	v_cvt_pk_bf16_f32 v146, v136, v137
	v_cvt_pk_bf16_f32 v147, v138, v139
	s_movk_i32 s33, 0x77f
	global_store_dwordx4 v[148:149], v[144:147], off sc1
	v_cmp_lt_u32_e32 vcc, s33, v187
	s_nop 0
	v_cvt_pk_bf16_f32 v144, v132, v133
	v_cvt_pk_bf16_f32 v145, v134, v135
	v_cvt_pk_bf16_f32 v146, v128, v129
	v_cvt_pk_bf16_f32 v147, v130, v131
	global_store_dwordx4 v[148:149], v[144:147], off offset:64 sc1
	s_and_saveexec_b64 s[58:59], vcc
	s_cbranch_execz .LBB0_496
	v_lshlrev_b32_e32 v144, 7, v196
	s_movk_i32 s33, 0xf880
	v_add3_u32 v144, v187, v144, s33
	v_ashrrev_i32_e32 v145, 31, v144
	v_lshlrev_b64 v[144:145], 10, v[144:145]
	v_lshl_add_u64 v[144:145], s[44:45], 0, v[144:145]
	v_lshl_add_u64 v[144:145], v[176:177], 2, v[144:145]
	global_store_dwordx4 v[144:145], v[140:143], off sc1
	global_store_dwordx4 v[144:145], v[136:139], off offset:16 sc1
	global_store_dwordx4 v[144:145], v[132:135], off offset:128 sc1
	global_store_dwordx4 v[144:145], v[128:131], off offset:144 sc1

; DI u32x4 pk8(f32x4 a, f32x4 b) { u32x4 w; w.x = pk2(a[0], a[1]); w.y = pk2(a[2], a[3]); w.z = pk2(b[0], b[1]); w.w = pk2(b[2], b[3]); return w; }
;     DI void operator()(const f32x4 (&acc)[2][2][4][2], const Unit& u, int wr, int wc, int fr, int fq) const {
;     ...
;                 const int r = u.pm * BM + ai * HALF + wr * 64 + m * 16 + fr, pos = r & (SEQL - 1), b = r >> 11;
;                 const float rs = RS[r];
;                 const f32x4 A00 = acc[ai][0][m][0] * rs, A01 = acc[ai][0][m][1] * rs, A10 = acc[ai][1][m][0] * rs, A11 = acc[ai][1][m][1] * rs;
;     ...
;                 } else {
;                     const int c = 128 * (pn - 10) + 32 * wc + 8 * fq;
;                     const f32x4 za = A00 * A10, zb = A01 * A11;
;                     *(u32x4*)(Z + (size_t)r * 1024 + c) = pk8(za, zb);
;                     if (pos >= SEQL - 2) { float* o = outC + ((size_t)(b * 2 + pos - (SEQL - 2))) * 1024 + c; *(f32x4*)o = za; *(f32x4*)(o + 4) = zb; }
;                 }
.LBB0_497:
	v_add_u32_e32 v136, 32, v186
	v_ashrrev_i32_e32 v137, 31, v136
	v_lshl_add_u64 v[128:129], v[136:137], 2, s[28:29]
	global_load_dword v128, v[128:129], off
	s_and_b64 vcc, exec, s[8:9]
	v_and_b32_e32 v138, 0x7ff, v136
	v_ashrrev_i32_e32 v139, 11, v136
	s_mov_b64 s[58:59], -1
	s_waitcnt vmcnt(0)
	v_pk_mul_f32 v[126:127], v[126:127], v[128:129] op_sel_hi:[1,0]
	v_pk_mul_f32 v[124:125], v[124:125], v[128:129] op_sel_hi:[1,0]
	v_pk_mul_f32 v[122:123], v[122:123], v[128:129] op_sel_hi:[1,0]
	v_pk_mul_f32 v[120:121], v[120:121], v[128:129] op_sel_hi:[1,0]
	v_pk_mul_f32 v[118:119], v[118:119], v[128:129] op_sel_hi:[1,0]
	v_pk_mul_f32 v[116:117], v[116:117], v[128:129] op_sel_hi:[1,0]
	v_pk_mul_f32 v[114:115], v[114:115], v[128:129] op_sel_hi:[1,0]
	v_pk_mul_f32 v[112:113], v[112:113], v[128:129] op_sel_hi:[1,0]
	s_cbranch_vccnz .LBB0_513
	s_and_b64 vcc, exec, s[4:5]
	s_cbranch_vccnz .LBB0_506
	s_andn2_b64 vcc, exec, s[56:57]
	s_cbranch_vccnz .LBB0_503
	v_lshlrev_b64 v[144:145], 11, v[136:137]
	v_pk_mul_f32 v[130:131], v[126:127], v[118:119]
	v_pk_mul_f32 v[128:129], v[124:125], v[116:117]
	v_pk_mul_f32 v[134:135], v[122:123], v[114:115]
	v_pk_mul_f32 v[132:133], v[120:121], v[112:113]
	v_lshl_add_u64 v[144:145], s[24:25], 0, v[144:145]
	s_movk_i32 s33, 0x7fd
	v_cvt_pk_bf16_f32 v140, v128, v129
	v_cvt_pk_bf16_f32 v141, v130, v131
	v_cvt_pk_bf16_f32 v142, v132, v133
	v_cvt_pk_bf16_f32 v143, v134, v135
	v_lshl_add_u64 v[144:145], v[182:183], 1, v[144:145]
	v_cmp_lt_u32_e32 vcc, s33, v138
	global_store_dwordx4 v[144:145], v[140:143], off sc1
	s_and_saveexec_b64 s[58:59], vcc
	s_cbranch_execz .LBB0_502
	v_lshlrev_b32_e32 v140, 1, v139
	s_movk_i32 s33, 0xf802
	v_add3_u32 v140, v138, v140, s33
	v_ashrrev_i32_e32 v141, 31, v140
	v_lshlrev_b64 v[140:141], 12, v[140:141]
	v_lshl_add_u64 v[140:141], s[38:39], 0, v[140:141]
	v_lshl_add_u64 v[140:141], v[182:183], 2, v[140:141]
	global_store_dwordx4 v[140:141], v[128:131], off sc1
	global_store_dwordx4 v[140:141], v[132:135], off offset:16 sc1

; DI u32x4 pk8(f32x4 a, f32x4 b) { u32x4 w; w.x = pk2(a[0], a[1]); w.y = pk2(a[2], a[3]); w.z = pk2(b[0], b[1]); w.w = pk2(b[2], b[3]); return w; }
;     DI void operator()(const f32x4 (&acc)[2][2][4][2], const Unit& u, int wr, int wc, int fr, int fq) const {
;     ...
;                 } else if (pn < 10) {
; #pragma unroll
;                     for (int bj = 0; bj < 2; ++bj) { const int c = (pn - 6) * 256 + 128 * bj + 32 * wc + 8 * fq;
;                         *(u32x4*)(GB + (size_t)r * 1024 + c) = pk8(bj ? A10 : A00, bj ? A11 : A01); }
.LBB0_503:
	s_andn2_b64 vcc, exec, s[58:59]
	s_cbranch_vccnz .LBB0_505
	v_lshlrev_b64 v[132:133], 11, v[136:137]
	v_lshl_add_u64 v[132:133], s[22:23], 0, v[132:133]
	v_ashrrev_i32_e32 v181, 31, v180
	v_cvt_pk_bf16_f32 v128, v124, v125
	v_cvt_pk_bf16_f32 v129, v126, v127
	v_cvt_pk_bf16_f32 v130, v120, v121
	v_cvt_pk_bf16_f32 v131, v122, v123
	v_lshl_add_u64 v[132:133], v[180:181], 1, v[132:133]
	global_store_dwordx4 v[132:133], v[128:131], off sc1
	s_nop 1
	v_cvt_pk_bf16_f32 v128, v116, v117
	v_cvt_pk_bf16_f32 v129, v118, v119
	v_cvt_pk_bf16_f32 v130, v112, v113
	v_cvt_pk_bf16_f32 v131, v114, v115
	global_store_dwordx4 v[132:133], v[128:131], off offset:256 sc1

; DI u32x4 pk8(f32x4 a, f32x4 b) { u32x4 w; w.x = pk2(a[0], a[1]); w.y = pk2(a[2], a[3]); w.z = pk2(b[0], b[1]); w.w = pk2(b[2], b[3]); return w; }
;     DI void operator()(const f32x4 (&acc)[2][2][4][2], const Unit& u, int wr, int wc, int fr, int fq) const {
;     ...
;                 } else if (pn == 5) {
; #pragma unroll
;                     for (int bj = 0; bj < 2; ++bj) { const int c = 128 * bj + 32 * wc + 8 * fq; const f32x4 va = bj ? A10 : A00, vb = bj ? A11 : A01;
;                         *(u32x4*)(Vb + (size_t)r * 256 + c) = pk8(va, vb);
;                         if (pos >= SEQL - 128) { float* o = outV + ((size_t)(b * 128 + pos - (SEQL - 128))) * 256 + c; *(f32x4*)o = va; *(f32x4*)(o + 4) = vb; } }
.LBB0_506:
	s_andn2_b64 vcc, exec, s[58:59]
	s_cbranch_vccnz .LBB0_512
	s_movk_i32 s33, 0x77f
	v_cmp_lt_u32_e32 vcc, s33, v138
	v_lshlrev_b32_e32 v130, 7, v139
	s_movk_i32 s33, 0xf880
	v_add3_u32 v130, v138, v130, s33
	v_lshlrev_b64 v[128:129], 9, v[136:137]
	v_ashrrev_i32_e32 v131, 31, v130
	v_lshlrev_b64 v[140:141], 10, v[130:131]
	v_lshl_add_u64 v[128:129], s[20:21], 0, v[128:129]
	v_ashrrev_i32_e32 v179, 31, v178
	v_lshl_add_u64 v[130:131], v[178:179], 1, v[128:129]
	v_lshl_add_u64 v[128:129], s[36:37], 0, v[140:141]
	v_cvt_pk_bf16_f32 v132, v124, v125
	v_cvt_pk_bf16_f32 v133, v126, v127
	v_cvt_pk_bf16_f32 v134, v120, v121
	v_cvt_pk_bf16_f32 v135, v122, v123
	v_lshl_add_u64 v[128:129], v[178:179], 2, v[128:129]
	global_store_dwordx4 v[130:131], v[132:135], off sc1
	s_and_saveexec_b64 s[58:59], vcc
	s_cbranch_execz .LBB0_509
	global_store_dwordx4 v[128:129], v[124:127], off sc1
	global_store_dwordx4 v[128:129], v[120:123], off offset:16 sc1
.LBB0_509:
	s_or_b64 exec, exec, s[58:59]
	v_cvt_pk_bf16_f32 v132, v116, v117
	v_cvt_pk_bf16_f32 v133, v118, v119
	v_cvt_pk_bf16_f32 v134, v112, v113
	v_cvt_pk_bf16_f32 v135, v114, v115
	global_store_dwordx4 v[130:131], v[132:135], off offset:256 sc1
	s_and_saveexec_b64 s[58:59], vcc
	s_cbranch_execz .LBB0_511
	global_store_dwordx4 v[128:129], v[116:119], off offset:512 sc1
	global_store_dwordx4 v[128:129], v[112:115], off offset:528 sc1

; DI u32x4 pk8(f32x4 a, f32x4 b) { u32x4 w; w.x = pk2(a[0], a[1]); w.y = pk2(a[2], a[3]); w.z = pk2(b[0], b[1]); w.w = pk2(b[2], b[3]); return w; }
;     DI void operator()(const f32x4 (&acc)[2][2][4][2], const Unit& u, int wr, int wc, int fr, int fq) const {
;     ...
;                 if (pn < 5) {
;                     const f32x4* cp = (const f32x4*)(cosT + pos * 32 + 8 * fq); const f32x4* sp = (const f32x4*)(sinT + pos * 32 + 8 * fq);
;                     const f32x4 c0 = cp[0], c1 = cp[1], s0 = sp[0], s1 = sp[1];
;                     const f32x4 x1a = A00, x1b = A01, x2a = A10, x2b = A11;
;                     f32x4 o1a = x1a * c0 - x2a * s0, o1b = x1b * c1 - x2b * s1, o2a = x2a * c0 + x1a * s0, o2b = x2b * c1 + x1b * s1;
;                     if (pn < 4) {
;                         bf16* qp = Q + (size_t)r * 1024 + (4 * pn + wc) * 64 + 8 * fq;
;                         *(u32x4*)qp = pk8(o1a * QSC, o1b * QSC); *(u32x4*)(qp + 32) = pk8(o2a * QSC, o2b * QSC);
;                     } else {
;                         bf16* kp = Kb + (size_t)r * 256 + wc * 64 + 8 * fq;
;                         *(u32x4*)kp = pk8(o1a, o1b); *(u32x4*)(kp + 32) = pk8(o2a, o2b);
;                         if (pos >= SEQL - 128) { float* o = outK + ((size_t)(b * 128 + pos - (SEQL - 128))) * 256 + wc * 64 + 8 * fq;
;                             *(f32x4*)o = o1a; *(f32x4*)(o + 4) = o1b; *(f32x4*)(o + 32) = o2a; *(f32x4*)(o + 36) = o2b; }
;                     }
.LBB0_513:
	s_andn2_b64 vcc, exec, s[58:59]
	s_cbranch_vccnz .LBB0_520
	v_lshlrev_b32_e32 v152, 7, v138
	v_lshl_add_u64 v[128:129], s[34:35], 0, v[152:153]
	v_lshl_add_u64 v[132:133], v[128:129], 0, v[184:185]
	v_lshl_add_u64 v[140:141], s[30:31], 0, v[152:153]
	global_load_dwordx4 v[128:131], v[132:133], off
	s_nop 0
	global_load_dwordx4 v[132:135], v[132:133], off offset:16
	v_lshl_add_u64 v[144:145], v[140:141], 0, v[184:185]
	global_load_dwordx4 v[140:143], v[144:145], off
	s_nop 0
	global_load_dwordx4 v[144:147], v[144:145], off offset:16
	s_and_b64 vcc, exec, s[0:1]
	s_mov_b64 s[58:59], -1
	s_waitcnt vmcnt(3)
	v_pk_mul_f32 v[148:149], v[118:119], v[130:131]
	v_pk_mul_f32 v[150:151], v[116:117], v[128:129]
	s_waitcnt vmcnt(2)
	v_pk_mul_f32 v[188:189], v[114:115], v[134:135]
	v_pk_mul_f32 v[196:197], v[112:113], v[132:133]
	v_pk_mul_f32 v[130:131], v[126:127], v[130:131]
	v_pk_mul_f32 v[128:129], v[124:125], v[128:129]
	v_pk_mul_f32 v[134:135], v[122:123], v[134:135]
	v_pk_mul_f32 v[132:133], v[120:121], v[132:133]
	s_waitcnt vmcnt(1)
	v_pk_fma_f32 v[126:127], v[126:127], v[142:143], v[148:149] neg_lo:[0,0,1] neg_hi:[0,0,1]
	v_pk_fma_f32 v[124:125], v[124:125], v[140:141], v[150:151] neg_lo:[0,0,1] neg_hi:[0,0,1]
	s_waitcnt vmcnt(0)
	v_pk_fma_f32 v[122:123], v[122:123], v[146:147], v[188:189] neg_lo:[0,0,1] neg_hi:[0,0,1]
	v_pk_fma_f32 v[120:121], v[120:121], v[144:145], v[196:197] neg_lo:[0,0,1] neg_hi:[0,0,1]
	v_pk_fma_f32 v[118:119], v[118:119], v[142:143], v[130:131]
	v_pk_fma_f32 v[116:117], v[116:117], v[140:141], v[128:129]
	v_pk_fma_f32 v[114:115], v[114:115], v[146:147], v[134:135]
	v_pk_fma_f32 v[112:113], v[112:113], v[144:145], v[132:133]
	s_cbranch_vccnz .LBB0_516
	v_lshlrev_b64 v[128:129], 11, v[136:137]
	v_lshl_add_u64 v[128:129], s[18:19], 0, v[128:129]
	v_lshl_add_u64 v[128:129], s[2:3], 1, v[128:129]
	s_mov_b32 s58, 0x3e38aa3b
	v_lshl_add_u64 v[132:133], v[176:177], 1, v[128:129]
	v_pk_mul_f32 v[130:131], v[126:127], s[58:59] op_sel_hi:[1,0]
	v_pk_mul_f32 v[128:129], v[124:125], s[58:59] op_sel_hi:[1,0]
	v_pk_mul_f32 v[134:135], v[122:123], s[58:59] op_sel_hi:[1,0]
	v_pk_mul_f32 v[140:141], v[120:121], s[58:59] op_sel_hi:[1,0]
	v_cvt_pk_bf16_f32 v128, v128, v129
	v_cvt_pk_bf16_f32 v129, v130, v131
	v_cvt_pk_bf16_f32 v130, v140, v141
	v_cvt_pk_bf16_f32 v131, v134, v135
	global_store_dwordx4 v[132:133], v[128:131], off sc1
	v_pk_mul_f32 v[134:135], v[114:115], s[58:59] op_sel_hi:[1,0]
	v_pk_mul_f32 v[140:141], v[112:113], s[58:59] op_sel_hi:[1,0]
	v_pk_mul_f32 v[130:131], v[118:119], s[58:59] op_sel_hi:[1,0]
	v_pk_mul_f32 v[128:129], v[116:117], s[58:59] op_sel_hi:[1,0]
	s_mov_b64 s[58:59], 0
	v_cvt_pk_bf16_f32 v128, v128, v129
	v_cvt_pk_bf16_f32 v129, v130, v131
	v_cvt_pk_bf16_f32 v130, v140, v141
	v_cvt_pk_bf16_f32 v131, v134, v135
	global_store_dwordx4 v[132:133], v[128:131], off offset:64 sc1
.LBB0_516:
	s_andn2_b64 vcc, exec, s[58:59]
	s_cbranch_vccnz .LBB0_520
	v_lshlrev_b64 v[128:129], 9, v[136:137]
	v_lshl_add_u64 v[128:129], s[42:43], 0, v[128:129]
	v_lshl_add_u64 v[132:133], v[176:177], 1, v[128:129]
	v_cvt_pk_bf16_f32 v128, v124, v125
	v_cvt_pk_bf16_f32 v129, v126, v127
	v_cvt_pk_bf16_f32 v130, v120, v121
	v_cvt_pk_bf16_f32 v131, v122, v123
	s_movk_i32 s33, 0x77f
	global_store_dwordx4 v[132:133], v[128:131], off sc1
	v_cmp_lt_u32_e32 vcc, s33, v138
	s_nop 0
	v_cvt_pk_bf16_f32 v128, v116, v117
	v_cvt_pk_bf16_f32 v129, v118, v119
	v_cvt_pk_bf16_f32 v130, v112, v113
	v_cvt_pk_bf16_f32 v131, v114, v115
	global_store_dwordx4 v[132:133], v[128:131], off offset:64 sc1
	s_and_saveexec_b64 s[58:59], vcc
	s_cbranch_execz .LBB0_519
	v_lshlrev_b32_e32 v128, 7, v139
	s_movk_i32 s33, 0xf880
	v_add3_u32 v128, v138, v128, s33
	v_ashrrev_i32_e32 v129, 31, v128
	v_lshlrev_b64 v[128:129], 10, v[128:129]
	v_lshl_add_u64 v[128:129], s[44:45], 0, v[128:129]
	v_lshl_add_u64 v[128:129], v[176:177], 2, v[128:129]
	global_store_dwordx4 v[128:129], v[124:127], off sc1
	global_store_dwordx4 v[128:129], v[120:123], off offset:16 sc1
	global_store_dwordx4 v[128:129], v[116:119], off offset:128 sc1
	global_store_dwordx4 v[128:129], v[112:115], off offset:144 sc1

; DI u32x4 pk8(f32x4 a, f32x4 b) { u32x4 w; w.x = pk2(a[0], a[1]); w.y = pk2(a[2], a[3]); w.z = pk2(b[0], b[1]); w.w = pk2(b[2], b[3]); return w; }
;     DI void operator()(const f32x4 (&acc)[2][2][4][2], const Unit& u, int wr, int wc, int fr, int fq) const {
;     ...
;                 const int r = u.pm * BM + ai * HALF + wr * 64 + m * 16 + fr, pos = r & (SEQL - 1), b = r >> 11;
;                 const float rs = RS[r];
;                 const f32x4 A00 = acc[ai][0][m][0] * rs, A01 = acc[ai][0][m][1] * rs, A10 = acc[ai][1][m][0] * rs, A11 = acc[ai][1][m][1] * rs;
;     ...
;                 } else {
;                     const int c = 128 * (pn - 10) + 32 * wc + 8 * fq;
;                     const f32x4 za = A00 * A10, zb = A01 * A11;
;                     *(u32x4*)(Z + (size_t)r * 1024 + c) = pk8(za, zb);
;                     if (pos >= SEQL - 2) { float* o = outC + ((size_t)(b * 2 + pos - (SEQL - 2))) * 1024 + c; *(f32x4*)o = za; *(f32x4*)(o + 4) = zb; }
;                 }
.LBB0_520:
	v_add_u32_e32 v120, 48, v186
	v_ashrrev_i32_e32 v121, 31, v120
	v_lshl_add_u64 v[112:113], v[120:121], 2, s[28:29]
	global_load_dword v112, v[112:113], off
	s_and_b64 vcc, exec, s[8:9]
	v_and_b32_e32 v122, 0x7ff, v120
	v_ashrrev_i32_e32 v123, 11, v120
	s_mov_b64 s[58:59], -1
	s_waitcnt vmcnt(0)
	v_pk_mul_f32 v[110:111], v[110:111], v[112:113] op_sel_hi:[1,0]
	v_pk_mul_f32 v[108:109], v[108:109], v[112:113] op_sel_hi:[1,0]
	v_pk_mul_f32 v[106:107], v[106:107], v[112:113] op_sel_hi:[1,0]
	v_pk_mul_f32 v[104:105], v[104:105], v[112:113] op_sel_hi:[1,0]
	v_pk_mul_f32 v[102:103], v[102:103], v[112:113] op_sel_hi:[1,0]
	v_pk_mul_f32 v[100:101], v[100:101], v[112:113] op_sel_hi:[1,0]
	v_pk_mul_f32 v[98:99], v[98:99], v[112:113] op_sel_hi:[1,0]
	v_pk_mul_f32 v[96:97], v[96:97], v[112:113] op_sel_hi:[1,0]
	s_cbranch_vccnz .LBB0_536
	s_and_b64 vcc, exec, s[4:5]
	s_cbranch_vccnz .LBB0_529
	s_andn2_b64 vcc, exec, s[56:57]
	s_cbranch_vccnz .LBB0_526
	v_lshlrev_b64 v[128:129], 11, v[120:121]
	v_pk_mul_f32 v[114:115], v[110:111], v[102:103]
	v_pk_mul_f32 v[112:113], v[108:109], v[100:101]
	v_pk_mul_f32 v[118:119], v[106:107], v[98:99]
	v_pk_mul_f32 v[116:117], v[104:105], v[96:97]
	v_lshl_add_u64 v[128:129], s[24:25], 0, v[128:129]
	s_movk_i32 s33, 0x7fd
	v_cvt_pk_bf16_f32 v124, v112, v113
	v_cvt_pk_bf16_f32 v125, v114, v115
	v_cvt_pk_bf16_f32 v126, v116, v117
	v_cvt_pk_bf16_f32 v127, v118, v119
	v_lshl_add_u64 v[128:129], v[182:183], 1, v[128:129]
	v_cmp_lt_u32_e32 vcc, s33, v122
	global_store_dwordx4 v[128:129], v[124:127], off sc1
	s_and_saveexec_b64 s[58:59], vcc
	s_cbranch_execz .LBB0_525
	v_lshlrev_b32_e32 v124, 1, v123
	s_movk_i32 s33, 0xf802
	v_add3_u32 v124, v122, v124, s33
	v_ashrrev_i32_e32 v125, 31, v124
	v_lshlrev_b64 v[124:125], 12, v[124:125]
	v_lshl_add_u64 v[124:125], s[38:39], 0, v[124:125]
	v_lshl_add_u64 v[124:125], v[182:183], 2, v[124:125]
	global_store_dwordx4 v[124:125], v[112:115], off sc1
	global_store_dwordx4 v[124:125], v[116:119], off offset:16 sc1

; DI u32x4 pk8(f32x4 a, f32x4 b) { u32x4 w; w.x = pk2(a[0], a[1]); w.y = pk2(a[2], a[3]); w.z = pk2(b[0], b[1]); w.w = pk2(b[2], b[3]); return w; }
;     DI void operator()(const f32x4 (&acc)[2][2][4][2], const Unit& u, int wr, int wc, int fr, int fq) const {
;     ...
;                 } else if (pn < 10) {
; #pragma unroll
;                     for (int bj = 0; bj < 2; ++bj) { const int c = (pn - 6) * 256 + 128 * bj + 32 * wc + 8 * fq;
;                         *(u32x4*)(GB + (size_t)r * 1024 + c) = pk8(bj ? A10 : A00, bj ? A11 : A01); }
.LBB0_526:
	s_andn2_b64 vcc, exec, s[58:59]
	s_cbranch_vccnz .LBB0_528
	v_lshlrev_b64 v[116:117], 11, v[120:121]
	v_lshl_add_u64 v[116:117], s[22:23], 0, v[116:117]
	v_ashrrev_i32_e32 v181, 31, v180
	v_cvt_pk_bf16_f32 v112, v108, v109
	v_cvt_pk_bf16_f32 v113, v110, v111
	v_cvt_pk_bf16_f32 v114, v104, v105
	v_cvt_pk_bf16_f32 v115, v106, v107
	v_lshl_add_u64 v[116:117], v[180:181], 1, v[116:117]
	global_store_dwordx4 v[116:117], v[112:115], off sc1
	s_nop 1
	v_cvt_pk_bf16_f32 v112, v100, v101
	v_cvt_pk_bf16_f32 v113, v102, v103
	v_cvt_pk_bf16_f32 v114, v96, v97
	v_cvt_pk_bf16_f32 v115, v98, v99
	global_store_dwordx4 v[116:117], v[112:115], off offset:256 sc1

; DI u32x4 pk8(f32x4 a, f32x4 b) { u32x4 w; w.x = pk2(a[0], a[1]); w.y = pk2(a[2], a[3]); w.z = pk2(b[0], b[1]); w.w = pk2(b[2], b[3]); return w; }
;     DI void operator()(const f32x4 (&acc)[2][2][4][2], const Unit& u, int wr, int wc, int fr, int fq) const {
;     ...
;                 } else if (pn == 5) {
; #pragma unroll
;                     for (int bj = 0; bj < 2; ++bj) { const int c = 128 * bj + 32 * wc + 8 * fq; const f32x4 va = bj ? A10 : A00, vb = bj ? A11 : A01;
;                         *(u32x4*)(Vb + (size_t)r * 256 + c) = pk8(va, vb);
;                         if (pos >= SEQL - 128) { float* o = outV + ((size_t)(b * 128 + pos - (SEQL - 128))) * 256 + c; *(f32x4*)o = va; *(f32x4*)(o + 4) = vb; } }
.LBB0_529:
	s_andn2_b64 vcc, exec, s[58:59]
	s_cbranch_vccnz .LBB0_535
	s_movk_i32 s33, 0x77f
	v_cmp_lt_u32_e32 vcc, s33, v122
	v_lshlrev_b32_e32 v114, 7, v123
	s_movk_i32 s33, 0xf880
	v_add3_u32 v114, v122, v114, s33
	v_lshlrev_b64 v[112:113], 9, v[120:121]
	v_ashrrev_i32_e32 v115, 31, v114
	v_lshlrev_b64 v[124:125], 10, v[114:115]
	v_lshl_add_u64 v[112:113], s[20:21], 0, v[112:113]
	v_ashrrev_i32_e32 v179, 31, v178
	v_lshl_add_u64 v[114:115], v[178:179], 1, v[112:113]
	v_lshl_add_u64 v[112:113], s[36:37], 0, v[124:125]
	v_cvt_pk_bf16_f32 v116, v108, v109
	v_cvt_pk_bf16_f32 v117, v110, v111
	v_cvt_pk_bf16_f32 v118, v104, v105
	v_cvt_pk_bf16_f32 v119, v106, v107
	v_lshl_add_u64 v[112:113], v[178:179], 2, v[112:113]
	global_store_dwordx4 v[114:115], v[116:119], off sc1
	s_and_saveexec_b64 s[58:59], vcc
	s_cbranch_execz .LBB0_532
	global_store_dwordx4 v[112:113], v[108:111], off sc1
	global_store_dwordx4 v[112:113], v[104:107], off offset:16 sc1
.LBB0_532:
	s_or_b64 exec, exec, s[58:59]
	v_cvt_pk_bf16_f32 v116, v100, v101
	v_cvt_pk_bf16_f32 v117, v102, v103
	v_cvt_pk_bf16_f32 v118, v96, v97
	v_cvt_pk_bf16_f32 v119, v98, v99
	global_store_dwordx4 v[114:115], v[116:119], off offset:256 sc1
	s_and_saveexec_b64 s[58:59], vcc
	s_cbranch_execz .LBB0_534
	global_store_dwordx4 v[112:113], v[100:103], off offset:512 sc1
	global_store_dwordx4 v[112:113], v[96:99], off offset:528 sc1

; DI u32x4 pk8(f32x4 a, f32x4 b) { u32x4 w; w.x = pk2(a[0], a[1]); w.y = pk2(a[2], a[3]); w.z = pk2(b[0], b[1]); w.w = pk2(b[2], b[3]); return w; }
;     DI void operator()(const f32x4 (&acc)[2][2][4][2], const Unit& u, int wr, int wc, int fr, int fq) const {
;     ...
;                 if (pn < 5) {
;                     const f32x4* cp = (const f32x4*)(cosT + pos * 32 + 8 * fq); const f32x4* sp = (const f32x4*)(sinT + pos * 32 + 8 * fq);
;                     const f32x4 c0 = cp[0], c1 = cp[1], s0 = sp[0], s1 = sp[1];
;                     const f32x4 x1a = A00, x1b = A01, x2a = A10, x2b = A11;
;                     f32x4 o1a = x1a * c0 - x2a * s0, o1b = x1b * c1 - x2b * s1, o2a = x2a * c0 + x1a * s0, o2b = x2b * c1 + x1b * s1;
;                     if (pn < 4) {
;                         bf16* qp = Q + (size_t)r * 1024 + (4 * pn + wc) * 64 + 8 * fq;
;                         *(u32x4*)qp = pk8(o1a * QSC, o1b * QSC); *(u32x4*)(qp + 32) = pk8(o2a * QSC, o2b * QSC);
;                     } else {
;                         bf16* kp = Kb + (size_t)r * 256 + wc * 64 + 8 * fq;
;                         *(u32x4*)kp = pk8(o1a, o1b); *(u32x4*)(kp + 32) = pk8(o2a, o2b);
;                         if (pos >= SEQL - 128) { float* o = outK + ((size_t)(b * 128 + pos - (SEQL - 128))) * 256 + wc * 64 + 8 * fq;
;                             *(f32x4*)o = o1a; *(f32x4*)(o + 4) = o1b; *(f32x4*)(o + 32) = o2a; *(f32x4*)(o + 36) = o2b; }
;                     }
.LBB0_536:
	s_andn2_b64 vcc, exec, s[58:59]
	s_cbranch_vccnz .LBB0_543
	v_lshlrev_b32_e32 v152, 7, v122
	v_lshl_add_u64 v[112:113], s[34:35], 0, v[152:153]
	v_lshl_add_u64 v[116:117], v[112:113], 0, v[184:185]
	v_lshl_add_u64 v[124:125], s[30:31], 0, v[152:153]
	global_load_dwordx4 v[112:115], v[116:117], off
	s_nop 0
	global_load_dwordx4 v[116:119], v[116:117], off offset:16
	v_lshl_add_u64 v[128:129], v[124:125], 0, v[184:185]
	global_load_dwordx4 v[124:127], v[128:129], off
	s_nop 0
	global_load_dwordx4 v[128:131], v[128:129], off offset:16
	s_and_b64 vcc, exec, s[0:1]
	s_mov_b64 s[58:59], -1
	s_waitcnt vmcnt(3)
	v_pk_mul_f32 v[132:133], v[102:103], v[114:115]
	v_pk_mul_f32 v[134:135], v[100:101], v[112:113]
	s_waitcnt vmcnt(2)
	v_pk_mul_f32 v[136:137], v[98:99], v[118:119]
	v_pk_mul_f32 v[138:139], v[96:97], v[116:117]
	v_pk_mul_f32 v[114:115], v[110:111], v[114:115]
	v_pk_mul_f32 v[112:113], v[108:109], v[112:113]
	v_pk_mul_f32 v[118:119], v[106:107], v[118:119]
	v_pk_mul_f32 v[116:117], v[104:105], v[116:117]
	s_waitcnt vmcnt(1)
	v_pk_fma_f32 v[110:111], v[110:111], v[126:127], v[132:133] neg_lo:[0,0,1] neg_hi:[0,0,1]
	v_pk_fma_f32 v[108:109], v[108:109], v[124:125], v[134:135] neg_lo:[0,0,1] neg_hi:[0,0,1]
	s_waitcnt vmcnt(0)
	v_pk_fma_f32 v[106:107], v[106:107], v[130:131], v[136:137] neg_lo:[0,0,1] neg_hi:[0,0,1]
	v_pk_fma_f32 v[104:105], v[104:105], v[128:129], v[138:139] neg_lo:[0,0,1] neg_hi:[0,0,1]
	v_pk_fma_f32 v[102:103], v[102:103], v[126:127], v[114:115]
	v_pk_fma_f32 v[100:101], v[100:101], v[124:125], v[112:113]
	v_pk_fma_f32 v[98:99], v[98:99], v[130:131], v[118:119]
	v_pk_fma_f32 v[96:97], v[96:97], v[128:129], v[116:117]
	s_cbranch_vccnz .LBB0_539
	v_lshlrev_b64 v[112:113], 11, v[120:121]
	v_lshl_add_u64 v[112:113], s[18:19], 0, v[112:113]
	v_lshl_add_u64 v[112:113], s[2:3], 1, v[112:113]
	s_mov_b32 s58, 0x3e38aa3b
	v_lshl_add_u64 v[116:117], v[176:177], 1, v[112:113]
	v_pk_mul_f32 v[114:115], v[110:111], s[58:59] op_sel_hi:[1,0]
	v_pk_mul_f32 v[112:113], v[108:109], s[58:59] op_sel_hi:[1,0]
	v_pk_mul_f32 v[118:119], v[106:107], s[58:59] op_sel_hi:[1,0]
	v_pk_mul_f32 v[124:125], v[104:105], s[58:59] op_sel_hi:[1,0]
	v_cvt_pk_bf16_f32 v112, v112, v113
	v_cvt_pk_bf16_f32 v113, v114, v115
	v_cvt_pk_bf16_f32 v114, v124, v125
	v_cvt_pk_bf16_f32 v115, v118, v119
	global_store_dwordx4 v[116:117], v[112:115], off sc1
	v_pk_mul_f32 v[118:119], v[98:99], s[58:59] op_sel_hi:[1,0]
	v_pk_mul_f32 v[124:125], v[96:97], s[58:59] op_sel_hi:[1,0]
	v_pk_mul_f32 v[114:115], v[102:103], s[58:59] op_sel_hi:[1,0]
	v_pk_mul_f32 v[112:113], v[100:101], s[58:59] op_sel_hi:[1,0]
	s_mov_b64 s[58:59], 0
	v_cvt_pk_bf16_f32 v112, v112, v113
	v_cvt_pk_bf16_f32 v113, v114, v115
	v_cvt_pk_bf16_f32 v114, v124, v125
	v_cvt_pk_bf16_f32 v115, v118, v119
	global_store_dwordx4 v[116:117], v[112:115], off offset:64 sc1
.LBB0_539:
	s_andn2_b64 vcc, exec, s[58:59]
	s_cbranch_vccnz .LBB0_543
	v_lshlrev_b64 v[112:113], 9, v[120:121]
	v_lshl_add_u64 v[112:113], s[42:43], 0, v[112:113]
	v_lshl_add_u64 v[116:117], v[176:177], 1, v[112:113]
	v_cvt_pk_bf16_f32 v112, v108, v109
	v_cvt_pk_bf16_f32 v113, v110, v111
	v_cvt_pk_bf16_f32 v114, v104, v105
	v_cvt_pk_bf16_f32 v115, v106, v107
	s_movk_i32 s33, 0x77f
	global_store_dwordx4 v[116:117], v[112:115], off sc1
	v_cmp_lt_u32_e32 vcc, s33, v122
	s_nop 0
	v_cvt_pk_bf16_f32 v112, v100, v101
	v_cvt_pk_bf16_f32 v113, v102, v103
	v_cvt_pk_bf16_f32 v114, v96, v97
	v_cvt_pk_bf16_f32 v115, v98, v99
	global_store_dwordx4 v[116:117], v[112:115], off offset:64 sc1
	s_and_saveexec_b64 s[58:59], vcc
	s_cbranch_execz .LBB0_542
	v_lshlrev_b32_e32 v112, 7, v123
	s_movk_i32 s33, 0xf880
	v_add3_u32 v112, v122, v112, s33
	v_ashrrev_i32_e32 v113, 31, v112
	v_lshlrev_b64 v[112:113], 10, v[112:113]
	v_lshl_add_u64 v[112:113], s[44:45], 0, v[112:113]
	v_lshl_add_u64 v[112:113], v[176:177], 2, v[112:113]
	global_store_dwordx4 v[112:113], v[108:111], off sc1
	global_store_dwordx4 v[112:113], v[104:107], off offset:16 sc1
	global_store_dwordx4 v[112:113], v[100:103], off offset:128 sc1
	global_store_dwordx4 v[112:113], v[96:99], off offset:144 sc1

; DI u32x4 pk8(f32x4 a, f32x4 b) { u32x4 w; w.x = pk2(a[0], a[1]); w.y = pk2(a[2], a[3]); w.z = pk2(b[0], b[1]); w.w = pk2(b[2], b[3]); return w; }
;     DI void operator()(const f32x4 (&acc)[2][2][4][2], const Unit& u, int wr, int wc, int fr, int fq) const {
;     ...
;                 const int r = u.pm * BM + ai * HALF + wr * 64 + m * 16 + fr, pos = r & (SEQL - 1), b = r >> 11;
;                 const float rs = RS[r];
;                 const f32x4 A00 = acc[ai][0][m][0] * rs, A01 = acc[ai][0][m][1] * rs, A10 = acc[ai][1][m][0] * rs, A11 = acc[ai][1][m][1] * rs;
;     ...
;                 } else {
;                     const int c = 128 * (pn - 10) + 32 * wc + 8 * fq;
;                     const f32x4 za = A00 * A10, zb = A01 * A11;
;                     *(u32x4*)(Z + (size_t)r * 1024 + c) = pk8(za, zb);
;                     if (pos >= SEQL - 2) { float* o = outC + ((size_t)(b * 2 + pos - (SEQL - 2))) * 1024 + c; *(f32x4*)o = za; *(f32x4*)(o + 4) = zb; }
;                 }
.LBB0_543:
	v_add_u32_e32 v104, 0x80, v186
	v_ashrrev_i32_e32 v105, 31, v104
	v_lshl_add_u64 v[96:97], v[104:105], 2, s[28:29]
	global_load_dword v96, v[96:97], off
	s_and_b64 vcc, exec, s[8:9]
	v_and_b32_e32 v106, 0x7ff, v104
	v_ashrrev_i32_e32 v107, 11, v104
	s_mov_b64 s[58:59], -1
	s_waitcnt vmcnt(0)
	v_pk_mul_f32 v[94:95], v[94:95], v[96:97] op_sel_hi:[1,0]
	v_pk_mul_f32 v[92:93], v[92:93], v[96:97] op_sel_hi:[1,0]
	v_pk_mul_f32 v[90:91], v[90:91], v[96:97] op_sel_hi:[1,0]
	v_pk_mul_f32 v[88:89], v[88:89], v[96:97] op_sel_hi:[1,0]
	v_pk_mul_f32 v[86:87], v[86:87], v[96:97] op_sel_hi:[1,0]
	v_pk_mul_f32 v[84:85], v[84:85], v[96:97] op_sel_hi:[1,0]
	v_pk_mul_f32 v[82:83], v[82:83], v[96:97] op_sel_hi:[1,0]
	v_pk_mul_f32 v[80:81], v[80:81], v[96:97] op_sel_hi:[1,0]
	s_cbranch_vccnz .LBB0_559
	s_and_b64 vcc, exec, s[4:5]
	s_cbranch_vccnz .LBB0_552
	s_andn2_b64 vcc, exec, s[56:57]
	s_cbranch_vccnz .LBB0_549
	v_lshlrev_b64 v[112:113], 11, v[104:105]
	v_pk_mul_f32 v[98:99], v[94:95], v[86:87]
	v_pk_mul_f32 v[96:97], v[92:93], v[84:85]
	v_pk_mul_f32 v[102:103], v[90:91], v[82:83]
	v_pk_mul_f32 v[100:101], v[88:89], v[80:81]
	v_lshl_add_u64 v[112:113], s[24:25], 0, v[112:113]
	s_movk_i32 s33, 0x7fd
	v_cvt_pk_bf16_f32 v108, v96, v97
	v_cvt_pk_bf16_f32 v109, v98, v99
	v_cvt_pk_bf16_f32 v110, v100, v101
	v_cvt_pk_bf16_f32 v111, v102, v103
	v_lshl_add_u64 v[112:113], v[182:183], 1, v[112:113]
	v_cmp_lt_u32_e32 vcc, s33, v106
	global_store_dwordx4 v[112:113], v[108:111], off sc1
	s_and_saveexec_b64 s[58:59], vcc
	s_cbranch_execz .LBB0_548
	v_lshlrev_b32_e32 v108, 1, v107
	s_movk_i32 s33, 0xf802
	v_add3_u32 v108, v106, v108, s33
	v_ashrrev_i32_e32 v109, 31, v108
	v_lshlrev_b64 v[108:109], 12, v[108:109]
	v_lshl_add_u64 v[108:109], s[38:39], 0, v[108:109]
	v_lshl_add_u64 v[108:109], v[182:183], 2, v[108:109]
	global_store_dwordx4 v[108:109], v[96:99], off sc1
	global_store_dwordx4 v[108:109], v[100:103], off offset:16 sc1

; DI u32x4 pk8(f32x4 a, f32x4 b) { u32x4 w; w.x = pk2(a[0], a[1]); w.y = pk2(a[2], a[3]); w.z = pk2(b[0], b[1]); w.w = pk2(b[2], b[3]); return w; }
;     DI void operator()(const f32x4 (&acc)[2][2][4][2], const Unit& u, int wr, int wc, int fr, int fq) const {
;     ...
;                 } else if (pn < 10) {
; #pragma unroll
;                     for (int bj = 0; bj < 2; ++bj) { const int c = (pn - 6) * 256 + 128 * bj + 32 * wc + 8 * fq;
;                         *(u32x4*)(GB + (size_t)r * 1024 + c) = pk8(bj ? A10 : A00, bj ? A11 : A01); }
.LBB0_549:
	s_andn2_b64 vcc, exec, s[58:59]
	s_cbranch_vccnz .LBB0_551
	v_lshlrev_b64 v[100:101], 11, v[104:105]
	v_lshl_add_u64 v[100:101], s[22:23], 0, v[100:101]
	v_ashrrev_i32_e32 v181, 31, v180
	v_cvt_pk_bf16_f32 v96, v92, v93
	v_cvt_pk_bf16_f32 v97, v94, v95
	v_cvt_pk_bf16_f32 v98, v88, v89
	v_cvt_pk_bf16_f32 v99, v90, v91
	v_lshl_add_u64 v[100:101], v[180:181], 1, v[100:101]
	global_store_dwordx4 v[100:101], v[96:99], off sc1
	s_nop 1
	v_cvt_pk_bf16_f32 v96, v84, v85
	v_cvt_pk_bf16_f32 v97, v86, v87
	v_cvt_pk_bf16_f32 v98, v80, v81
	v_cvt_pk_bf16_f32 v99, v82, v83
	global_store_dwordx4 v[100:101], v[96:99], off offset:256 sc1

; DI u32x4 pk8(f32x4 a, f32x4 b) { u32x4 w; w.x = pk2(a[0], a[1]); w.y = pk2(a[2], a[3]); w.z = pk2(b[0], b[1]); w.w = pk2(b[2], b[3]); return w; }
;     DI void operator()(const f32x4 (&acc)[2][2][4][2], const Unit& u, int wr, int wc, int fr, int fq) const {
;     ...
;                 } else if (pn == 5) {
; #pragma unroll
;                     for (int bj = 0; bj < 2; ++bj) { const int c = 128 * bj + 32 * wc + 8 * fq; const f32x4 va = bj ? A10 : A00, vb = bj ? A11 : A01;
;                         *(u32x4*)(Vb + (size_t)r * 256 + c) = pk8(va, vb);
;                         if (pos >= SEQL - 128) { float* o = outV + ((size_t)(b * 128 + pos - (SEQL - 128))) * 256 + c; *(f32x4*)o = va; *(f32x4*)(o + 4) = vb; } }
.LBB0_552:
	s_andn2_b64 vcc, exec, s[58:59]
	s_cbranch_vccnz .LBB0_558
	s_movk_i32 s33, 0x77f
	v_cmp_lt_u32_e32 vcc, s33, v106
	v_lshlrev_b32_e32 v98, 7, v107
	s_movk_i32 s33, 0xf880
	v_add3_u32 v98, v106, v98, s33
	v_lshlrev_b64 v[96:97], 9, v[104:105]
	v_ashrrev_i32_e32 v99, 31, v98
	v_lshlrev_b64 v[108:109], 10, v[98:99]
	v_lshl_add_u64 v[96:97], s[20:21], 0, v[96:97]
	v_ashrrev_i32_e32 v179, 31, v178
	v_lshl_add_u64 v[98:99], v[178:179], 1, v[96:97]
	v_lshl_add_u64 v[96:97], s[36:37], 0, v[108:109]
	v_cvt_pk_bf16_f32 v100, v92, v93
	v_cvt_pk_bf16_f32 v101, v94, v95
	v_cvt_pk_bf16_f32 v102, v88, v89
	v_cvt_pk_bf16_f32 v103, v90, v91
	v_lshl_add_u64 v[96:97], v[178:179], 2, v[96:97]
	global_store_dwordx4 v[98:99], v[100:103], off sc1
	s_and_saveexec_b64 s[58:59], vcc
	s_cbranch_execz .LBB0_555
	global_store_dwordx4 v[96:97], v[92:95], off sc1
	global_store_dwordx4 v[96:97], v[88:91], off offset:16 sc1
.LBB0_555:
	s_or_b64 exec, exec, s[58:59]
	v_cvt_pk_bf16_f32 v100, v84, v85
	v_cvt_pk_bf16_f32 v101, v86, v87
	v_cvt_pk_bf16_f32 v102, v80, v81
	v_cvt_pk_bf16_f32 v103, v82, v83
	global_store_dwordx4 v[98:99], v[100:103], off offset:256 sc1
	s_and_saveexec_b64 s[58:59], vcc
	s_cbranch_execz .LBB0_557
	global_store_dwordx4 v[96:97], v[84:87], off offset:512 sc1
	global_store_dwordx4 v[96:97], v[80:83], off offset:528 sc1

; DI u32x4 pk8(f32x4 a, f32x4 b) { u32x4 w; w.x = pk2(a[0], a[1]); w.y = pk2(a[2], a[3]); w.z = pk2(b[0], b[1]); w.w = pk2(b[2], b[3]); return w; }
;     DI void operator()(const f32x4 (&acc)[2][2][4][2], const Unit& u, int wr, int wc, int fr, int fq) const {
;     ...
;                 if (pn < 5) {
;                     const f32x4* cp = (const f32x4*)(cosT + pos * 32 + 8 * fq); const f32x4* sp = (const f32x4*)(sinT + pos * 32 + 8 * fq);
;                     const f32x4 c0 = cp[0], c1 = cp[1], s0 = sp[0], s1 = sp[1];
;                     const f32x4 x1a = A00, x1b = A01, x2a = A10, x2b = A11;
;                     f32x4 o1a = x1a * c0 - x2a * s0, o1b = x1b * c1 - x2b * s1, o2a = x2a * c0 + x1a * s0, o2b = x2b * c1 + x1b * s1;
;                     if (pn < 4) {
;                         bf16* qp = Q + (size_t)r * 1024 + (4 * pn + wc) * 64 + 8 * fq;
;                         *(u32x4*)qp = pk8(o1a * QSC, o1b * QSC); *(u32x4*)(qp + 32) = pk8(o2a * QSC, o2b * QSC);
;                     } else {
;                         bf16* kp = Kb + (size_t)r * 256 + wc * 64 + 8 * fq;
;                         *(u32x4*)kp = pk8(o1a, o1b); *(u32x4*)(kp + 32) = pk8(o2a, o2b);
;                         if (pos >= SEQL - 128) { float* o = outK + ((size_t)(b * 128 + pos - (SEQL - 128))) * 256 + wc * 64 + 8 * fq;
;                             *(f32x4*)o = o1a; *(f32x4*)(o + 4) = o1b; *(f32x4*)(o + 32) = o2a; *(f32x4*)(o + 36) = o2b; }
;                     }
.LBB0_559:
	s_andn2_b64 vcc, exec, s[58:59]
	s_cbranch_vccnz .LBB0_566
	v_lshlrev_b32_e32 v152, 7, v106
	v_lshl_add_u64 v[96:97], s[34:35], 0, v[152:153]
	v_lshl_add_u64 v[100:101], v[96:97], 0, v[184:185]
	v_lshl_add_u64 v[108:109], s[30:31], 0, v[152:153]
	global_load_dwordx4 v[96:99], v[100:101], off
	s_nop 0
	global_load_dwordx4 v[100:103], v[100:101], off offset:16
	v_lshl_add_u64 v[112:113], v[108:109], 0, v[184:185]
	global_load_dwordx4 v[108:111], v[112:113], off
	s_nop 0
	global_load_dwordx4 v[112:115], v[112:113], off offset:16
	s_and_b64 vcc, exec, s[0:1]
	s_mov_b64 s[58:59], -1
	s_waitcnt vmcnt(3)
	v_pk_mul_f32 v[116:117], v[86:87], v[98:99]
	v_pk_mul_f32 v[118:119], v[84:85], v[96:97]
	s_waitcnt vmcnt(2)
	v_pk_mul_f32 v[120:121], v[82:83], v[102:103]
	v_pk_mul_f32 v[122:123], v[80:81], v[100:101]
	v_pk_mul_f32 v[98:99], v[94:95], v[98:99]
	v_pk_mul_f32 v[96:97], v[92:93], v[96:97]
	v_pk_mul_f32 v[102:103], v[90:91], v[102:103]
	v_pk_mul_f32 v[100:101], v[88:89], v[100:101]
	s_waitcnt vmcnt(1)
	v_pk_fma_f32 v[94:95], v[94:95], v[110:111], v[116:117] neg_lo:[0,0,1] neg_hi:[0,0,1]
	v_pk_fma_f32 v[92:93], v[92:93], v[108:109], v[118:119] neg_lo:[0,0,1] neg_hi:[0,0,1]
	s_waitcnt vmcnt(0)
	v_pk_fma_f32 v[90:91], v[90:91], v[114:115], v[120:121] neg_lo:[0,0,1] neg_hi:[0,0,1]
	v_pk_fma_f32 v[88:89], v[88:89], v[112:113], v[122:123] neg_lo:[0,0,1] neg_hi:[0,0,1]
	v_pk_fma_f32 v[86:87], v[86:87], v[110:111], v[98:99]
	v_pk_fma_f32 v[84:85], v[84:85], v[108:109], v[96:97]
	v_pk_fma_f32 v[82:83], v[82:83], v[114:115], v[102:103]
	v_pk_fma_f32 v[80:81], v[80:81], v[112:113], v[100:101]
	s_cbranch_vccnz .LBB0_562
	v_lshlrev_b64 v[96:97], 11, v[104:105]
	v_lshl_add_u64 v[96:97], s[18:19], 0, v[96:97]
	v_lshl_add_u64 v[96:97], s[2:3], 1, v[96:97]
	s_mov_b32 s58, 0x3e38aa3b
	v_lshl_add_u64 v[100:101], v[176:177], 1, v[96:97]
	v_pk_mul_f32 v[98:99], v[94:95], s[58:59] op_sel_hi:[1,0]
	v_pk_mul_f32 v[96:97], v[92:93], s[58:59] op_sel_hi:[1,0]
	v_pk_mul_f32 v[102:103], v[90:91], s[58:59] op_sel_hi:[1,0]
	v_pk_mul_f32 v[108:109], v[88:89], s[58:59] op_sel_hi:[1,0]
	v_cvt_pk_bf16_f32 v96, v96, v97
	v_cvt_pk_bf16_f32 v97, v98, v99
	v_cvt_pk_bf16_f32 v98, v108, v109
	v_cvt_pk_bf16_f32 v99, v102, v103
	global_store_dwordx4 v[100:101], v[96:99], off sc1
	v_pk_mul_f32 v[102:103], v[82:83], s[58:59] op_sel_hi:[1,0]
	v_pk_mul_f32 v[108:109], v[80:81], s[58:59] op_sel_hi:[1,0]
	v_pk_mul_f32 v[98:99], v[86:87], s[58:59] op_sel_hi:[1,0]
	v_pk_mul_f32 v[96:97], v[84:85], s[58:59] op_sel_hi:[1,0]
	s_mov_b64 s[58:59], 0
	v_cvt_pk_bf16_f32 v96, v96, v97
	v_cvt_pk_bf16_f32 v97, v98, v99
	v_cvt_pk_bf16_f32 v98, v108, v109
	v_cvt_pk_bf16_f32 v99, v102, v103
	global_store_dwordx4 v[100:101], v[96:99], off offset:64 sc1
.LBB0_562:
	s_andn2_b64 vcc, exec, s[58:59]
	s_cbranch_vccnz .LBB0_566
	v_lshlrev_b64 v[96:97], 9, v[104:105]
	v_lshl_add_u64 v[96:97], s[42:43], 0, v[96:97]
	v_lshl_add_u64 v[100:101], v[176:177], 1, v[96:97]
	v_cvt_pk_bf16_f32 v96, v92, v93
	v_cvt_pk_bf16_f32 v97, v94, v95
	v_cvt_pk_bf16_f32 v98, v88, v89
	v_cvt_pk_bf16_f32 v99, v90, v91
	s_movk_i32 s33, 0x77f
	global_store_dwordx4 v[100:101], v[96:99], off sc1
	v_cmp_lt_u32_e32 vcc, s33, v106
	s_nop 0
	v_cvt_pk_bf16_f32 v96, v84, v85
	v_cvt_pk_bf16_f32 v97, v86, v87
	v_cvt_pk_bf16_f32 v98, v80, v81
	v_cvt_pk_bf16_f32 v99, v82, v83
	global_store_dwordx4 v[100:101], v[96:99], off offset:64 sc1
	s_and_saveexec_b64 s[58:59], vcc
	s_cbranch_execz .LBB0_565
	v_lshlrev_b32_e32 v96, 7, v107
	s_movk_i32 s33, 0xf880
	v_add3_u32 v96, v106, v96, s33
	v_ashrrev_i32_e32 v97, 31, v96
	v_lshlrev_b64 v[96:97], 10, v[96:97]
	v_lshl_add_u64 v[96:97], s[44:45], 0, v[96:97]
	v_lshl_add_u64 v[96:97], v[176:177], 2, v[96:97]
	global_store_dwordx4 v[96:97], v[92:95], off sc1
	global_store_dwordx4 v[96:97], v[88:91], off offset:16 sc1
	global_store_dwordx4 v[96:97], v[84:87], off offset:128 sc1
	global_store_dwordx4 v[96:97], v[80:83], off offset:144 sc1

; DI u32x4 pk8(f32x4 a, f32x4 b) { u32x4 w; w.x = pk2(a[0], a[1]); w.y = pk2(a[2], a[3]); w.z = pk2(b[0], b[1]); w.w = pk2(b[2], b[3]); return w; }
;     DI void operator()(const f32x4 (&acc)[2][2][4][2], const Unit& u, int wr, int wc, int fr, int fq) const {
;     ...
;                 const int r = u.pm * BM + ai * HALF + wr * 64 + m * 16 + fr, pos = r & (SEQL - 1), b = r >> 11;
;                 const float rs = RS[r];
;                 const f32x4 A00 = acc[ai][0][m][0] * rs, A01 = acc[ai][0][m][1] * rs, A10 = acc[ai][1][m][0] * rs, A11 = acc[ai][1][m][1] * rs;
;     ...
;                 } else {
;                     const int c = 128 * (pn - 10) + 32 * wc + 8 * fq;
;                     const f32x4 za = A00 * A10, zb = A01 * A11;
;                     *(u32x4*)(Z + (size_t)r * 1024 + c) = pk8(za, zb);
;                     if (pos >= SEQL - 2) { float* o = outC + ((size_t)(b * 2 + pos - (SEQL - 2))) * 1024 + c; *(f32x4*)o = za; *(f32x4*)(o + 4) = zb; }
;                 }
.LBB0_566:
	v_add_u32_e32 v88, 0x90, v186
	v_ashrrev_i32_e32 v89, 31, v88
	v_lshl_add_u64 v[80:81], v[88:89], 2, s[28:29]
	global_load_dword v80, v[80:81], off
	s_and_b64 vcc, exec, s[8:9]
	v_and_b32_e32 v90, 0x7ff, v88
	v_ashrrev_i32_e32 v91, 11, v88
	s_mov_b64 s[58:59], -1
	s_waitcnt vmcnt(0)
	v_pk_mul_f32 v[78:79], v[78:79], v[80:81] op_sel_hi:[1,0]
	v_pk_mul_f32 v[76:77], v[76:77], v[80:81] op_sel_hi:[1,0]
	v_pk_mul_f32 v[74:75], v[74:75], v[80:81] op_sel_hi:[1,0]
	v_pk_mul_f32 v[72:73], v[72:73], v[80:81] op_sel_hi:[1,0]
	v_pk_mul_f32 v[70:71], v[70:71], v[80:81] op_sel_hi:[1,0]
	v_pk_mul_f32 v[68:69], v[68:69], v[80:81] op_sel_hi:[1,0]
	v_pk_mul_f32 v[66:67], v[66:67], v[80:81] op_sel_hi:[1,0]
	v_pk_mul_f32 v[64:65], v[64:65], v[80:81] op_sel_hi:[1,0]
	s_cbranch_vccnz .LBB0_582
	s_and_b64 vcc, exec, s[4:5]
	s_cbranch_vccnz .LBB0_575
	s_andn2_b64 vcc, exec, s[56:57]
	s_cbranch_vccnz .LBB0_572
	v_lshlrev_b64 v[96:97], 11, v[88:89]
	v_pk_mul_f32 v[82:83], v[78:79], v[70:71]
	v_pk_mul_f32 v[80:81], v[76:77], v[68:69]
	v_pk_mul_f32 v[86:87], v[74:75], v[66:67]
	v_pk_mul_f32 v[84:85], v[72:73], v[64:65]
	v_lshl_add_u64 v[96:97], s[24:25], 0, v[96:97]
	s_movk_i32 s33, 0x7fd
	v_cvt_pk_bf16_f32 v92, v80, v81
	v_cvt_pk_bf16_f32 v93, v82, v83
	v_cvt_pk_bf16_f32 v94, v84, v85
	v_cvt_pk_bf16_f32 v95, v86, v87
	v_lshl_add_u64 v[96:97], v[182:183], 1, v[96:97]
	v_cmp_lt_u32_e32 vcc, s33, v90
	global_store_dwordx4 v[96:97], v[92:95], off sc1
	s_and_saveexec_b64 s[58:59], vcc
	s_cbranch_execz .LBB0_571
	v_lshlrev_b32_e32 v92, 1, v91
	s_movk_i32 s33, 0xf802
	v_add3_u32 v92, v90, v92, s33
	v_ashrrev_i32_e32 v93, 31, v92
	v_lshlrev_b64 v[92:93], 12, v[92:93]
	v_lshl_add_u64 v[92:93], s[38:39], 0, v[92:93]
	v_lshl_add_u64 v[92:93], v[182:183], 2, v[92:93]
	global_store_dwordx4 v[92:93], v[80:83], off sc1
	global_store_dwordx4 v[92:93], v[84:87], off offset:16 sc1

; DI u32x4 pk8(f32x4 a, f32x4 b) { u32x4 w; w.x = pk2(a[0], a[1]); w.y = pk2(a[2], a[3]); w.z = pk2(b[0], b[1]); w.w = pk2(b[2], b[3]); return w; }
;     DI void operator()(const f32x4 (&acc)[2][2][4][2], const Unit& u, int wr, int wc, int fr, int fq) const {
;     ...
;                 } else if (pn < 10) {
; #pragma unroll
;                     for (int bj = 0; bj < 2; ++bj) { const int c = (pn - 6) * 256 + 128 * bj + 32 * wc + 8 * fq;
;                         *(u32x4*)(GB + (size_t)r * 1024 + c) = pk8(bj ? A10 : A00, bj ? A11 : A01); }
.LBB0_572:
	s_andn2_b64 vcc, exec, s[58:59]
	s_cbranch_vccnz .LBB0_574
	v_lshlrev_b64 v[84:85], 11, v[88:89]
	v_lshl_add_u64 v[84:85], s[22:23], 0, v[84:85]
	v_ashrrev_i32_e32 v181, 31, v180
	v_cvt_pk_bf16_f32 v80, v76, v77
	v_cvt_pk_bf16_f32 v81, v78, v79
	v_cvt_pk_bf16_f32 v82, v72, v73
	v_cvt_pk_bf16_f32 v83, v74, v75
	v_lshl_add_u64 v[84:85], v[180:181], 1, v[84:85]
	global_store_dwordx4 v[84:85], v[80:83], off sc1
	s_nop 1
	v_cvt_pk_bf16_f32 v80, v68, v69
	v_cvt_pk_bf16_f32 v81, v70, v71
	v_cvt_pk_bf16_f32 v82, v64, v65
	v_cvt_pk_bf16_f32 v83, v66, v67
	global_store_dwordx4 v[84:85], v[80:83], off offset:256 sc1

; DI u32x4 pk8(f32x4 a, f32x4 b) { u32x4 w; w.x = pk2(a[0], a[1]); w.y = pk2(a[2], a[3]); w.z = pk2(b[0], b[1]); w.w = pk2(b[2], b[3]); return w; }
;     DI void operator()(const f32x4 (&acc)[2][2][4][2], const Unit& u, int wr, int wc, int fr, int fq) const {
;     ...
;                 } else if (pn == 5) {
; #pragma unroll
;                     for (int bj = 0; bj < 2; ++bj) { const int c = 128 * bj + 32 * wc + 8 * fq; const f32x4 va = bj ? A10 : A00, vb = bj ? A11 : A01;
;                         *(u32x4*)(Vb + (size_t)r * 256 + c) = pk8(va, vb);
;                         if (pos >= SEQL - 128) { float* o = outV + ((size_t)(b * 128 + pos - (SEQL - 128))) * 256 + c; *(f32x4*)o = va; *(f32x4*)(o + 4) = vb; } }
.LBB0_575:
	s_andn2_b64 vcc, exec, s[58:59]
	s_cbranch_vccnz .LBB0_581
	s_movk_i32 s33, 0x77f
	v_cmp_lt_u32_e32 vcc, s33, v90
	v_lshlrev_b32_e32 v82, 7, v91
	s_movk_i32 s33, 0xf880
	v_add3_u32 v82, v90, v82, s33
	v_lshlrev_b64 v[80:81], 9, v[88:89]
	v_ashrrev_i32_e32 v83, 31, v82
	v_lshlrev_b64 v[92:93], 10, v[82:83]
	v_lshl_add_u64 v[80:81], s[20:21], 0, v[80:81]
	v_ashrrev_i32_e32 v179, 31, v178
	v_lshl_add_u64 v[82:83], v[178:179], 1, v[80:81]
	v_lshl_add_u64 v[80:81], s[36:37], 0, v[92:93]
	v_cvt_pk_bf16_f32 v84, v76, v77
	v_cvt_pk_bf16_f32 v85, v78, v79
	v_cvt_pk_bf16_f32 v86, v72, v73
	v_cvt_pk_bf16_f32 v87, v74, v75
	v_lshl_add_u64 v[80:81], v[178:179], 2, v[80:81]
	global_store_dwordx4 v[82:83], v[84:87], off sc1
	s_and_saveexec_b64 s[58:59], vcc
	s_cbranch_execz .LBB0_578
	global_store_dwordx4 v[80:81], v[76:79], off sc1
	global_store_dwordx4 v[80:81], v[72:75], off offset:16 sc1
.LBB0_578:
	s_or_b64 exec, exec, s[58:59]
	v_cvt_pk_bf16_f32 v84, v68, v69
	v_cvt_pk_bf16_f32 v85, v70, v71
	v_cvt_pk_bf16_f32 v86, v64, v65
	v_cvt_pk_bf16_f32 v87, v66, v67
	global_store_dwordx4 v[82:83], v[84:87], off offset:256 sc1
	s_and_saveexec_b64 s[58:59], vcc
	s_cbranch_execz .LBB0_580
	global_store_dwordx4 v[80:81], v[68:71], off offset:512 sc1
	global_store_dwordx4 v[80:81], v[64:67], off offset:528 sc1

; DI u32x4 pk8(f32x4 a, f32x4 b) { u32x4 w; w.x = pk2(a[0], a[1]); w.y = pk2(a[2], a[3]); w.z = pk2(b[0], b[1]); w.w = pk2(b[2], b[3]); return w; }
;     DI void operator()(const f32x4 (&acc)[2][2][4][2], const Unit& u, int wr, int wc, int fr, int fq) const {
;     ...
;                 if (pn < 5) {
;                     const f32x4* cp = (const f32x4*)(cosT + pos * 32 + 8 * fq); const f32x4* sp = (const f32x4*)(sinT + pos * 32 + 8 * fq);
;                     const f32x4 c0 = cp[0], c1 = cp[1], s0 = sp[0], s1 = sp[1];
;                     const f32x4 x1a = A00, x1b = A01, x2a = A10, x2b = A11;
;                     f32x4 o1a = x1a * c0 - x2a * s0, o1b = x1b * c1 - x2b * s1, o2a = x2a * c0 + x1a * s0, o2b = x2b * c1 + x1b * s1;
;                     if (pn < 4) {
;                         bf16* qp = Q + (size_t)r * 1024 + (4 * pn + wc) * 64 + 8 * fq;
;                         *(u32x4*)qp = pk8(o1a * QSC, o1b * QSC); *(u32x4*)(qp + 32) = pk8(o2a * QSC, o2b * QSC);
;                     } else {
;                         bf16* kp = Kb + (size_t)r * 256 + wc * 64 + 8 * fq;
;                         *(u32x4*)kp = pk8(o1a, o1b); *(u32x4*)(kp + 32) = pk8(o2a, o2b);
;                         if (pos >= SEQL - 128) { float* o = outK + ((size_t)(b * 128 + pos - (SEQL - 128))) * 256 + wc * 64 + 8 * fq;
;                             *(f32x4*)o = o1a; *(f32x4*)(o + 4) = o1b; *(f32x4*)(o + 32) = o2a; *(f32x4*)(o + 36) = o2b; }
;                     }
.LBB0_582:
	s_andn2_b64 vcc, exec, s[58:59]
	s_cbranch_vccnz .LBB0_589
	v_lshlrev_b32_e32 v152, 7, v90
	v_lshl_add_u64 v[80:81], s[34:35], 0, v[152:153]
	v_lshl_add_u64 v[84:85], v[80:81], 0, v[184:185]
	v_lshl_add_u64 v[92:93], s[30:31], 0, v[152:153]
	global_load_dwordx4 v[80:83], v[84:85], off
	s_nop 0
	global_load_dwordx4 v[84:87], v[84:85], off offset:16
	v_lshl_add_u64 v[96:97], v[92:93], 0, v[184:185]
	global_load_dwordx4 v[92:95], v[96:97], off
	s_nop 0
	global_load_dwordx4 v[96:99], v[96:97], off offset:16
	s_and_b64 vcc, exec, s[0:1]
	s_mov_b64 s[58:59], -1
	s_waitcnt vmcnt(3)
	v_pk_mul_f32 v[100:101], v[70:71], v[82:83]
	v_pk_mul_f32 v[102:103], v[68:69], v[80:81]
	s_waitcnt vmcnt(2)
	v_pk_mul_f32 v[104:105], v[66:67], v[86:87]
	v_pk_mul_f32 v[106:107], v[64:65], v[84:85]
	v_pk_mul_f32 v[82:83], v[78:79], v[82:83]
	v_pk_mul_f32 v[80:81], v[76:77], v[80:81]
	v_pk_mul_f32 v[86:87], v[74:75], v[86:87]
	v_pk_mul_f32 v[84:85], v[72:73], v[84:85]
	s_waitcnt vmcnt(1)
	v_pk_fma_f32 v[78:79], v[78:79], v[94:95], v[100:101] neg_lo:[0,0,1] neg_hi:[0,0,1]
	v_pk_fma_f32 v[76:77], v[76:77], v[92:93], v[102:103] neg_lo:[0,0,1] neg_hi:[0,0,1]
	s_waitcnt vmcnt(0)
	v_pk_fma_f32 v[74:75], v[74:75], v[98:99], v[104:105] neg_lo:[0,0,1] neg_hi:[0,0,1]
	v_pk_fma_f32 v[72:73], v[72:73], v[96:97], v[106:107] neg_lo:[0,0,1] neg_hi:[0,0,1]
	v_pk_fma_f32 v[70:71], v[70:71], v[94:95], v[82:83]
	v_pk_fma_f32 v[68:69], v[68:69], v[92:93], v[80:81]
	v_pk_fma_f32 v[66:67], v[66:67], v[98:99], v[86:87]
	v_pk_fma_f32 v[64:65], v[64:65], v[96:97], v[84:85]
	s_cbranch_vccnz .LBB0_585
	v_lshlrev_b64 v[80:81], 11, v[88:89]
	v_lshl_add_u64 v[80:81], s[18:19], 0, v[80:81]
	v_lshl_add_u64 v[80:81], s[2:3], 1, v[80:81]
	s_mov_b32 s58, 0x3e38aa3b
	v_lshl_add_u64 v[84:85], v[176:177], 1, v[80:81]
	v_pk_mul_f32 v[82:83], v[78:79], s[58:59] op_sel_hi:[1,0]
	v_pk_mul_f32 v[80:81], v[76:77], s[58:59] op_sel_hi:[1,0]
	v_pk_mul_f32 v[86:87], v[74:75], s[58:59] op_sel_hi:[1,0]
	v_pk_mul_f32 v[92:93], v[72:73], s[58:59] op_sel_hi:[1,0]
	v_cvt_pk_bf16_f32 v80, v80, v81
	v_cvt_pk_bf16_f32 v81, v82, v83
	v_cvt_pk_bf16_f32 v82, v92, v93
	v_cvt_pk_bf16_f32 v83, v86, v87
	global_store_dwordx4 v[84:85], v[80:83], off sc1
	v_pk_mul_f32 v[86:87], v[66:67], s[58:59] op_sel_hi:[1,0]
	v_pk_mul_f32 v[92:93], v[64:65], s[58:59] op_sel_hi:[1,0]
	v_pk_mul_f32 v[82:83], v[70:71], s[58:59] op_sel_hi:[1,0]
	v_pk_mul_f32 v[80:81], v[68:69], s[58:59] op_sel_hi:[1,0]
	s_mov_b64 s[58:59], 0
	v_cvt_pk_bf16_f32 v80, v80, v81
	v_cvt_pk_bf16_f32 v81, v82, v83
	v_cvt_pk_bf16_f32 v82, v92, v93
	v_cvt_pk_bf16_f32 v83, v86, v87
	global_store_dwordx4 v[84:85], v[80:83], off offset:64 sc1
.LBB0_585:
	s_andn2_b64 vcc, exec, s[58:59]
	s_cbranch_vccnz .LBB0_589
	v_lshlrev_b64 v[80:81], 9, v[88:89]
	v_lshl_add_u64 v[80:81], s[42:43], 0, v[80:81]
	v_lshl_add_u64 v[84:85], v[176:177], 1, v[80:81]
	v_cvt_pk_bf16_f32 v80, v76, v77
	v_cvt_pk_bf16_f32 v81, v78, v79
	v_cvt_pk_bf16_f32 v82, v72, v73
	v_cvt_pk_bf16_f32 v83, v74, v75
	s_movk_i32 s33, 0x77f
	global_store_dwordx4 v[84:85], v[80:83], off sc1
	v_cmp_lt_u32_e32 vcc, s33, v90
	s_nop 0
	v_cvt_pk_bf16_f32 v80, v68, v69
	v_cvt_pk_bf16_f32 v81, v70, v71
	v_cvt_pk_bf16_f32 v82, v64, v65
	v_cvt_pk_bf16_f32 v83, v66, v67
	global_store_dwordx4 v[84:85], v[80:83], off offset:64 sc1
	s_and_saveexec_b64 s[58:59], vcc
	s_cbranch_execz .LBB0_588
	v_lshlrev_b32_e32 v80, 7, v91
	s_movk_i32 s33, 0xf880
	v_add3_u32 v80, v90, v80, s33
	v_ashrrev_i32_e32 v81, 31, v80
	v_lshlrev_b64 v[80:81], 10, v[80:81]
	v_lshl_add_u64 v[80:81], s[44:45], 0, v[80:81]
	v_lshl_add_u64 v[80:81], v[176:177], 2, v[80:81]
	global_store_dwordx4 v[80:81], v[76:79], off sc1
	global_store_dwordx4 v[80:81], v[72:75], off offset:16 sc1
	global_store_dwordx4 v[80:81], v[68:71], off offset:128 sc1
	global_store_dwordx4 v[80:81], v[64:67], off offset:144 sc1

; DI u32x4 pk8(f32x4 a, f32x4 b) { u32x4 w; w.x = pk2(a[0], a[1]); w.y = pk2(a[2], a[3]); w.z = pk2(b[0], b[1]); w.w = pk2(b[2], b[3]); return w; }
;     DI void operator()(const f32x4 (&acc)[2][2][4][2], const Unit& u, int wr, int wc, int fr, int fq) const {
;     ...
;                 const int r = u.pm * BM + ai * HALF + wr * 64 + m * 16 + fr, pos = r & (SEQL - 1), b = r >> 11;
;                 const float rs = RS[r];
;                 const f32x4 A00 = acc[ai][0][m][0] * rs, A01 = acc[ai][0][m][1] * rs, A10 = acc[ai][1][m][0] * rs, A11 = acc[ai][1][m][1] * rs;
;     ...
;                 } else {
;                     const int c = 128 * (pn - 10) + 32 * wc + 8 * fq;
;                     const f32x4 za = A00 * A10, zb = A01 * A11;
;                     *(u32x4*)(Z + (size_t)r * 1024 + c) = pk8(za, zb);
;                     if (pos >= SEQL - 2) { float* o = outC + ((size_t)(b * 2 + pos - (SEQL - 2))) * 1024 + c; *(f32x4*)o = za; *(f32x4*)(o + 4) = zb; }
;                 }
.LBB0_589:
	v_add_u32_e32 v72, 0xa0, v186
	v_ashrrev_i32_e32 v73, 31, v72
	v_lshl_add_u64 v[64:65], v[72:73], 2, s[28:29]
	global_load_dword v64, v[64:65], off
	s_and_b64 vcc, exec, s[8:9]
	v_and_b32_e32 v74, 0x7ff, v72
	v_ashrrev_i32_e32 v75, 11, v72
	s_mov_b64 s[58:59], -1
	s_waitcnt vmcnt(0)
	v_pk_mul_f32 v[62:63], v[62:63], v[64:65] op_sel_hi:[1,0]
	v_pk_mul_f32 v[60:61], v[60:61], v[64:65] op_sel_hi:[1,0]
	v_pk_mul_f32 v[58:59], v[58:59], v[64:65] op_sel_hi:[1,0]
	v_pk_mul_f32 v[56:57], v[56:57], v[64:65] op_sel_hi:[1,0]
	v_pk_mul_f32 v[54:55], v[54:55], v[64:65] op_sel_hi:[1,0]
	v_pk_mul_f32 v[52:53], v[52:53], v[64:65] op_sel_hi:[1,0]
	v_pk_mul_f32 v[50:51], v[50:51], v[64:65] op_sel_hi:[1,0]
	v_pk_mul_f32 v[48:49], v[48:49], v[64:65] op_sel_hi:[1,0]
	s_cbranch_vccnz .LBB0_605
	s_and_b64 vcc, exec, s[4:5]
	s_cbranch_vccnz .LBB0_598
	s_andn2_b64 vcc, exec, s[56:57]
	s_cbranch_vccnz .LBB0_595
	v_lshlrev_b64 v[80:81], 11, v[72:73]
	v_pk_mul_f32 v[66:67], v[62:63], v[54:55]
	v_pk_mul_f32 v[64:65], v[60:61], v[52:53]
	v_pk_mul_f32 v[70:71], v[58:59], v[50:51]
	v_pk_mul_f32 v[68:69], v[56:57], v[48:49]
	v_lshl_add_u64 v[80:81], s[24:25], 0, v[80:81]
	s_movk_i32 s33, 0x7fd
	v_cvt_pk_bf16_f32 v76, v64, v65
	v_cvt_pk_bf16_f32 v77, v66, v67
	v_cvt_pk_bf16_f32 v78, v68, v69
	v_cvt_pk_bf16_f32 v79, v70, v71
	v_lshl_add_u64 v[80:81], v[182:183], 1, v[80:81]
	v_cmp_lt_u32_e32 vcc, s33, v74
	global_store_dwordx4 v[80:81], v[76:79], off sc1
	s_and_saveexec_b64 s[58:59], vcc
	s_cbranch_execz .LBB0_594
	v_lshlrev_b32_e32 v76, 1, v75
	s_movk_i32 s33, 0xf802
	v_add3_u32 v76, v74, v76, s33
	v_ashrrev_i32_e32 v77, 31, v76
	v_lshlrev_b64 v[76:77], 12, v[76:77]
	v_lshl_add_u64 v[76:77], s[38:39], 0, v[76:77]
	v_lshl_add_u64 v[76:77], v[182:183], 2, v[76:77]
	global_store_dwordx4 v[76:77], v[64:67], off sc1
	global_store_dwordx4 v[76:77], v[68:71], off offset:16 sc1

; DI u32x4 pk8(f32x4 a, f32x4 b) { u32x4 w; w.x = pk2(a[0], a[1]); w.y = pk2(a[2], a[3]); w.z = pk2(b[0], b[1]); w.w = pk2(b[2], b[3]); return w; }
;     DI void operator()(const f32x4 (&acc)[2][2][4][2], const Unit& u, int wr, int wc, int fr, int fq) const {
;     ...
;                 } else if (pn < 10) {
; #pragma unroll
;                     for (int bj = 0; bj < 2; ++bj) { const int c = (pn - 6) * 256 + 128 * bj + 32 * wc + 8 * fq;
;                         *(u32x4*)(GB + (size_t)r * 1024 + c) = pk8(bj ? A10 : A00, bj ? A11 : A01); }
.LBB0_595:
	s_andn2_b64 vcc, exec, s[58:59]
	s_cbranch_vccnz .LBB0_597
	v_lshlrev_b64 v[68:69], 11, v[72:73]
	v_lshl_add_u64 v[68:69], s[22:23], 0, v[68:69]
	v_ashrrev_i32_e32 v181, 31, v180
	v_cvt_pk_bf16_f32 v64, v60, v61
	v_cvt_pk_bf16_f32 v65, v62, v63
	v_cvt_pk_bf16_f32 v66, v56, v57
	v_cvt_pk_bf16_f32 v67, v58, v59
	v_lshl_add_u64 v[68:69], v[180:181], 1, v[68:69]
	global_store_dwordx4 v[68:69], v[64:67], off sc1
	s_nop 1
	v_cvt_pk_bf16_f32 v64, v52, v53
	v_cvt_pk_bf16_f32 v65, v54, v55
	v_cvt_pk_bf16_f32 v66, v48, v49
	v_cvt_pk_bf16_f32 v67, v50, v51
	global_store_dwordx4 v[68:69], v[64:67], off offset:256 sc1

; DI u32x4 pk8(f32x4 a, f32x4 b) { u32x4 w; w.x = pk2(a[0], a[1]); w.y = pk2(a[2], a[3]); w.z = pk2(b[0], b[1]); w.w = pk2(b[2], b[3]); return w; }
;     DI void operator()(const f32x4 (&acc)[2][2][4][2], const Unit& u, int wr, int wc, int fr, int fq) const {
;     ...
;                 } else if (pn == 5) {
; #pragma unroll
;                     for (int bj = 0; bj < 2; ++bj) { const int c = 128 * bj + 32 * wc + 8 * fq; const f32x4 va = bj ? A10 : A00, vb = bj ? A11 : A01;
;                         *(u32x4*)(Vb + (size_t)r * 256 + c) = pk8(va, vb);
;                         if (pos >= SEQL - 128) { float* o = outV + ((size_t)(b * 128 + pos - (SEQL - 128))) * 256 + c; *(f32x4*)o = va; *(f32x4*)(o + 4) = vb; } }
.LBB0_598:
	s_andn2_b64 vcc, exec, s[58:59]
	s_cbranch_vccnz .LBB0_604
	s_movk_i32 s33, 0x77f
	v_cmp_lt_u32_e32 vcc, s33, v74
	v_lshlrev_b32_e32 v66, 7, v75
	s_movk_i32 s33, 0xf880
	v_add3_u32 v66, v74, v66, s33
	v_lshlrev_b64 v[64:65], 9, v[72:73]
	v_ashrrev_i32_e32 v67, 31, v66
	v_lshlrev_b64 v[76:77], 10, v[66:67]
	v_lshl_add_u64 v[64:65], s[20:21], 0, v[64:65]
	v_ashrrev_i32_e32 v179, 31, v178
	v_lshl_add_u64 v[66:67], v[178:179], 1, v[64:65]
	v_lshl_add_u64 v[64:65], s[36:37], 0, v[76:77]
	v_cvt_pk_bf16_f32 v68, v60, v61
	v_cvt_pk_bf16_f32 v69, v62, v63
	v_cvt_pk_bf16_f32 v70, v56, v57
	v_cvt_pk_bf16_f32 v71, v58, v59
	v_lshl_add_u64 v[64:65], v[178:179], 2, v[64:65]
	global_store_dwordx4 v[66:67], v[68:71], off sc1
	s_and_saveexec_b64 s[58:59], vcc
	s_cbranch_execz .LBB0_601
	global_store_dwordx4 v[64:65], v[60:63], off sc1
	global_store_dwordx4 v[64:65], v[56:59], off offset:16 sc1
.LBB0_601:
	s_or_b64 exec, exec, s[58:59]
	v_cvt_pk_bf16_f32 v68, v52, v53
	v_cvt_pk_bf16_f32 v69, v54, v55
	v_cvt_pk_bf16_f32 v70, v48, v49
	v_cvt_pk_bf16_f32 v71, v50, v51
	global_store_dwordx4 v[66:67], v[68:71], off offset:256 sc1
	s_and_saveexec_b64 s[58:59], vcc
	s_cbranch_execz .LBB0_603
	global_store_dwordx4 v[64:65], v[52:55], off offset:512 sc1
	global_store_dwordx4 v[64:65], v[48:51], off offset:528 sc1

; DI u32x4 pk8(f32x4 a, f32x4 b) { u32x4 w; w.x = pk2(a[0], a[1]); w.y = pk2(a[2], a[3]); w.z = pk2(b[0], b[1]); w.w = pk2(b[2], b[3]); return w; }
;     DI void operator()(const f32x4 (&acc)[2][2][4][2], const Unit& u, int wr, int wc, int fr, int fq) const {
;     ...
;                 if (pn < 5) {
;                     const f32x4* cp = (const f32x4*)(cosT + pos * 32 + 8 * fq); const f32x4* sp = (const f32x4*)(sinT + pos * 32 + 8 * fq);
;                     const f32x4 c0 = cp[0], c1 = cp[1], s0 = sp[0], s1 = sp[1];
;                     const f32x4 x1a = A00, x1b = A01, x2a = A10, x2b = A11;
;                     f32x4 o1a = x1a * c0 - x2a * s0, o1b = x1b * c1 - x2b * s1, o2a = x2a * c0 + x1a * s0, o2b = x2b * c1 + x1b * s1;
;                     if (pn < 4) {
;                         bf16* qp = Q + (size_t)r * 1024 + (4 * pn + wc) * 64 + 8 * fq;
;                         *(u32x4*)qp = pk8(o1a * QSC, o1b * QSC); *(u32x4*)(qp + 32) = pk8(o2a * QSC, o2b * QSC);
;                     } else {
;                         bf16* kp = Kb + (size_t)r * 256 + wc * 64 + 8 * fq;
;                         *(u32x4*)kp = pk8(o1a, o1b); *(u32x4*)(kp + 32) = pk8(o2a, o2b);
;                         if (pos >= SEQL - 128) { float* o = outK + ((size_t)(b * 128 + pos - (SEQL - 128))) * 256 + wc * 64 + 8 * fq;
;                             *(f32x4*)o = o1a; *(f32x4*)(o + 4) = o1b; *(f32x4*)(o + 32) = o2a; *(f32x4*)(o + 36) = o2b; }
;                     }
.LBB0_605:
	s_andn2_b64 vcc, exec, s[58:59]
	s_cbranch_vccnz .LBB0_612
	v_lshlrev_b32_e32 v152, 7, v74
	v_lshl_add_u64 v[64:65], s[34:35], 0, v[152:153]
	v_lshl_add_u64 v[68:69], v[64:65], 0, v[184:185]
	v_lshl_add_u64 v[76:77], s[30:31], 0, v[152:153]
	global_load_dwordx4 v[64:67], v[68:69], off
	s_nop 0
	global_load_dwordx4 v[68:71], v[68:69], off offset:16
	v_lshl_add_u64 v[80:81], v[76:77], 0, v[184:185]
	global_load_dwordx4 v[76:79], v[80:81], off
	s_nop 0
	global_load_dwordx4 v[80:83], v[80:81], off offset:16
	s_and_b64 vcc, exec, s[0:1]
	s_mov_b64 s[58:59], -1
	s_waitcnt vmcnt(3)
	v_pk_mul_f32 v[84:85], v[54:55], v[66:67]
	v_pk_mul_f32 v[86:87], v[52:53], v[64:65]
	s_waitcnt vmcnt(2)
	v_pk_mul_f32 v[88:89], v[50:51], v[70:71]
	v_pk_mul_f32 v[90:91], v[48:49], v[68:69]
	v_pk_mul_f32 v[66:67], v[62:63], v[66:67]
	v_pk_mul_f32 v[64:65], v[60:61], v[64:65]
	v_pk_mul_f32 v[70:71], v[58:59], v[70:71]
	v_pk_mul_f32 v[68:69], v[56:57], v[68:69]
	s_waitcnt vmcnt(1)
	v_pk_fma_f32 v[62:63], v[62:63], v[78:79], v[84:85] neg_lo:[0,0,1] neg_hi:[0,0,1]
	v_pk_fma_f32 v[60:61], v[60:61], v[76:77], v[86:87] neg_lo:[0,0,1] neg_hi:[0,0,1]
	s_waitcnt vmcnt(0)
	v_pk_fma_f32 v[58:59], v[58:59], v[82:83], v[88:89] neg_lo:[0,0,1] neg_hi:[0,0,1]
	v_pk_fma_f32 v[56:57], v[56:57], v[80:81], v[90:91] neg_lo:[0,0,1] neg_hi:[0,0,1]
	v_pk_fma_f32 v[54:55], v[54:55], v[78:79], v[66:67]
	v_pk_fma_f32 v[52:53], v[52:53], v[76:77], v[64:65]
	v_pk_fma_f32 v[50:51], v[50:51], v[82:83], v[70:71]
	v_pk_fma_f32 v[48:49], v[48:49], v[80:81], v[68:69]
	s_cbranch_vccnz .LBB0_608
	v_lshlrev_b64 v[64:65], 11, v[72:73]
	v_lshl_add_u64 v[64:65], s[18:19], 0, v[64:65]
	v_lshl_add_u64 v[64:65], s[2:3], 1, v[64:65]
	s_mov_b32 s58, 0x3e38aa3b
	v_lshl_add_u64 v[68:69], v[176:177], 1, v[64:65]
	v_pk_mul_f32 v[66:67], v[62:63], s[58:59] op_sel_hi:[1,0]
	v_pk_mul_f32 v[64:65], v[60:61], s[58:59] op_sel_hi:[1,0]
	v_pk_mul_f32 v[70:71], v[58:59], s[58:59] op_sel_hi:[1,0]
	v_pk_mul_f32 v[76:77], v[56:57], s[58:59] op_sel_hi:[1,0]
	v_cvt_pk_bf16_f32 v64, v64, v65
	v_cvt_pk_bf16_f32 v65, v66, v67
	v_cvt_pk_bf16_f32 v66, v76, v77
	v_cvt_pk_bf16_f32 v67, v70, v71
	global_store_dwordx4 v[68:69], v[64:67], off sc1
	v_pk_mul_f32 v[70:71], v[50:51], s[58:59] op_sel_hi:[1,0]
	v_pk_mul_f32 v[76:77], v[48:49], s[58:59] op_sel_hi:[1,0]
	v_pk_mul_f32 v[66:67], v[54:55], s[58:59] op_sel_hi:[1,0]
	v_pk_mul_f32 v[64:65], v[52:53], s[58:59] op_sel_hi:[1,0]
	s_mov_b64 s[58:59], 0
	v_cvt_pk_bf16_f32 v64, v64, v65
	v_cvt_pk_bf16_f32 v65, v66, v67
	v_cvt_pk_bf16_f32 v66, v76, v77
	v_cvt_pk_bf16_f32 v67, v70, v71
	global_store_dwordx4 v[68:69], v[64:67], off offset:64 sc1
.LBB0_608:
	s_andn2_b64 vcc, exec, s[58:59]
	s_cbranch_vccnz .LBB0_612
	v_lshlrev_b64 v[64:65], 9, v[72:73]
	v_lshl_add_u64 v[64:65], s[42:43], 0, v[64:65]
	v_lshl_add_u64 v[68:69], v[176:177], 1, v[64:65]
	v_cvt_pk_bf16_f32 v64, v60, v61
	v_cvt_pk_bf16_f32 v65, v62, v63
	v_cvt_pk_bf16_f32 v66, v56, v57
	v_cvt_pk_bf16_f32 v67, v58, v59
	s_movk_i32 s33, 0x77f
	global_store_dwordx4 v[68:69], v[64:67], off sc1
	v_cmp_lt_u32_e32 vcc, s33, v74
	s_nop 0
	v_cvt_pk_bf16_f32 v64, v52, v53
	v_cvt_pk_bf16_f32 v65, v54, v55
	v_cvt_pk_bf16_f32 v66, v48, v49
	v_cvt_pk_bf16_f32 v67, v50, v51
	global_store_dwordx4 v[68:69], v[64:67], off offset:64 sc1
	s_and_saveexec_b64 s[58:59], vcc
	s_cbranch_execz .LBB0_611
	v_lshlrev_b32_e32 v64, 7, v75
	s_movk_i32 s33, 0xf880
	v_add3_u32 v64, v74, v64, s33
	v_ashrrev_i32_e32 v65, 31, v64
	v_lshlrev_b64 v[64:65], 10, v[64:65]
	v_lshl_add_u64 v[64:65], s[44:45], 0, v[64:65]
	v_lshl_add_u64 v[64:65], v[176:177], 2, v[64:65]
	global_store_dwordx4 v[64:65], v[60:63], off sc1
	global_store_dwordx4 v[64:65], v[56:59], off offset:16 sc1
	global_store_dwordx4 v[64:65], v[52:55], off offset:128 sc1
	global_store_dwordx4 v[64:65], v[48:51], off offset:144 sc1

; DI u32x4 pk8(f32x4 a, f32x4 b) { u32x4 w; w.x = pk2(a[0], a[1]); w.y = pk2(a[2], a[3]); w.z = pk2(b[0], b[1]); w.w = pk2(b[2], b[3]); return w; }
;     DI void operator()(const f32x4 (&acc)[2][2][4][2], const Unit& u, int wr, int wc, int fr, int fq) const {
;     ...
;                 const int r = u.pm * BM + ai * HALF + wr * 64 + m * 16 + fr, pos = r & (SEQL - 1), b = r >> 11;
;                 const float rs = RS[r];
;                 const f32x4 A00 = acc[ai][0][m][0] * rs, A01 = acc[ai][0][m][1] * rs, A10 = acc[ai][1][m][0] * rs, A11 = acc[ai][1][m][1] * rs;
;     ...
;                 } else {
;                     const int c = 128 * (pn - 10) + 32 * wc + 8 * fq;
;                     const f32x4 za = A00 * A10, zb = A01 * A11;
;                     *(u32x4*)(Z + (size_t)r * 1024 + c) = pk8(za, zb);
;                     if (pos >= SEQL - 2) { float* o = outC + ((size_t)(b * 2 + pos - (SEQL - 2))) * 1024 + c; *(f32x4*)o = za; *(f32x4*)(o + 4) = zb; }
;                 }
.LBB0_612:
	v_add_u32_e32 v56, 0xb0, v186
	v_ashrrev_i32_e32 v57, 31, v56
	v_lshl_add_u64 v[48:49], v[56:57], 2, s[28:29]
	global_load_dword v48, v[48:49], off
	s_and_b64 vcc, exec, s[8:9]
	v_and_b32_e32 v58, 0x7ff, v56
	v_ashrrev_i32_e32 v59, 11, v56
	s_mov_b64 s[8:9], -1
	s_waitcnt vmcnt(0)
	v_pk_mul_f32 v[46:47], v[46:47], v[48:49] op_sel_hi:[1,0]
	v_pk_mul_f32 v[44:45], v[44:45], v[48:49] op_sel_hi:[1,0]
	v_pk_mul_f32 v[42:43], v[42:43], v[48:49] op_sel_hi:[1,0]
	v_pk_mul_f32 v[40:41], v[40:41], v[48:49] op_sel_hi:[1,0]
	v_pk_mul_f32 v[38:39], v[38:39], v[48:49] op_sel_hi:[1,0]
	v_pk_mul_f32 v[36:37], v[36:37], v[48:49] op_sel_hi:[1,0]
	v_pk_mul_f32 v[34:35], v[34:35], v[48:49] op_sel_hi:[1,0]
	v_pk_mul_f32 v[32:33], v[32:33], v[48:49] op_sel_hi:[1,0]
	s_cbranch_vccnz .LBB0_628
	s_and_b64 vcc, exec, s[4:5]
	s_mov_b64 s[4:5], -1
	s_cbranch_vccnz .LBB0_621
	s_andn2_b64 vcc, exec, s[56:57]
	s_cbranch_vccnz .LBB0_618
	v_lshlrev_b64 v[64:65], 11, v[56:57]
	v_pk_mul_f32 v[50:51], v[46:47], v[38:39]
	v_pk_mul_f32 v[48:49], v[44:45], v[36:37]
	v_pk_mul_f32 v[54:55], v[42:43], v[34:35]
	v_pk_mul_f32 v[52:53], v[40:41], v[32:33]
	v_lshl_add_u64 v[64:65], s[24:25], 0, v[64:65]
	s_movk_i32 s4, 0x7fd
	v_cvt_pk_bf16_f32 v60, v48, v49
	v_cvt_pk_bf16_f32 v61, v50, v51
	v_cvt_pk_bf16_f32 v62, v52, v53
	v_cvt_pk_bf16_f32 v63, v54, v55
	v_lshl_add_u64 v[64:65], v[182:183], 1, v[64:65]
	v_cmp_lt_u32_e32 vcc, s4, v58
	global_store_dwordx4 v[64:65], v[60:63], off sc1
	s_and_saveexec_b64 s[4:5], vcc
	s_cbranch_execz .LBB0_617
	v_lshlrev_b32_e32 v60, 1, v59
	s_movk_i32 s8, 0xf802
	v_add3_u32 v60, v58, v60, s8
	v_ashrrev_i32_e32 v61, 31, v60
	v_lshlrev_b64 v[60:61], 12, v[60:61]
	v_lshl_add_u64 v[60:61], s[38:39], 0, v[60:61]
	v_lshl_add_u64 v[60:61], v[182:183], 2, v[60:61]
	global_store_dwordx4 v[60:61], v[48:51], off sc1
	global_store_dwordx4 v[60:61], v[52:55], off offset:16 sc1

; DI u32x4 pk8(f32x4 a, f32x4 b) { u32x4 w; w.x = pk2(a[0], a[1]); w.y = pk2(a[2], a[3]); w.z = pk2(b[0], b[1]); w.w = pk2(b[2], b[3]); return w; }
;     DI void operator()(const f32x4 (&acc)[2][2][4][2], const Unit& u, int wr, int wc, int fr, int fq) const {
;     ...
;                 } else if (pn < 10) {
; #pragma unroll
;                     for (int bj = 0; bj < 2; ++bj) { const int c = (pn - 6) * 256 + 128 * bj + 32 * wc + 8 * fq;
;                         *(u32x4*)(GB + (size_t)r * 1024 + c) = pk8(bj ? A10 : A00, bj ? A11 : A01); }
.LBB0_618:
	s_andn2_b64 vcc, exec, s[4:5]
	s_cbranch_vccnz .LBB0_620
	v_lshlrev_b64 v[52:53], 11, v[56:57]
	v_lshl_add_u64 v[52:53], s[22:23], 0, v[52:53]
	v_ashrrev_i32_e32 v181, 31, v180
	v_cvt_pk_bf16_f32 v48, v44, v45
	v_cvt_pk_bf16_f32 v49, v46, v47
	v_cvt_pk_bf16_f32 v50, v40, v41
	v_cvt_pk_bf16_f32 v51, v42, v43
	v_lshl_add_u64 v[52:53], v[180:181], 1, v[52:53]
	global_store_dwordx4 v[52:53], v[48:51], off sc1
	s_nop 1
	v_cvt_pk_bf16_f32 v48, v36, v37
	v_cvt_pk_bf16_f32 v49, v38, v39
	v_cvt_pk_bf16_f32 v50, v32, v33
	v_cvt_pk_bf16_f32 v51, v34, v35
	global_store_dwordx4 v[52:53], v[48:51], off offset:256 sc1

; DI u32x4 pk8(f32x4 a, f32x4 b) { u32x4 w; w.x = pk2(a[0], a[1]); w.y = pk2(a[2], a[3]); w.z = pk2(b[0], b[1]); w.w = pk2(b[2], b[3]); return w; }
;     DI void operator()(const f32x4 (&acc)[2][2][4][2], const Unit& u, int wr, int wc, int fr, int fq) const {
;     ...
;                 } else if (pn == 5) {
; #pragma unroll
;                     for (int bj = 0; bj < 2; ++bj) { const int c = 128 * bj + 32 * wc + 8 * fq; const f32x4 va = bj ? A10 : A00, vb = bj ? A11 : A01;
;                         *(u32x4*)(Vb + (size_t)r * 256 + c) = pk8(va, vb);
;                         if (pos >= SEQL - 128) { float* o = outV + ((size_t)(b * 128 + pos - (SEQL - 128))) * 256 + c; *(f32x4*)o = va; *(f32x4*)(o + 4) = vb; } }
.LBB0_621:
	s_andn2_b64 vcc, exec, s[4:5]
	s_cbranch_vccnz .LBB0_627
	s_movk_i32 s4, 0x77f
	v_cmp_lt_u32_e32 vcc, s4, v58
	v_lshlrev_b32_e32 v50, 7, v59
	s_movk_i32 s4, 0xf880
	v_add3_u32 v50, v58, v50, s4
	v_lshlrev_b64 v[48:49], 9, v[56:57]
	v_ashrrev_i32_e32 v51, 31, v50
	v_lshlrev_b64 v[60:61], 10, v[50:51]
	v_lshl_add_u64 v[48:49], s[20:21], 0, v[48:49]
	v_ashrrev_i32_e32 v179, 31, v178
	v_lshl_add_u64 v[50:51], v[178:179], 1, v[48:49]
	v_lshl_add_u64 v[48:49], s[36:37], 0, v[60:61]
	v_cvt_pk_bf16_f32 v52, v44, v45
	v_cvt_pk_bf16_f32 v53, v46, v47
	v_cvt_pk_bf16_f32 v54, v40, v41
	v_cvt_pk_bf16_f32 v55, v42, v43
	v_lshl_add_u64 v[48:49], v[178:179], 2, v[48:49]
	global_store_dwordx4 v[50:51], v[52:55], off sc1
	s_and_saveexec_b64 s[4:5], vcc
	s_cbranch_execz .LBB0_624
	global_store_dwordx4 v[48:49], v[44:47], off sc1
	global_store_dwordx4 v[48:49], v[40:43], off offset:16 sc1
.LBB0_624:
	s_or_b64 exec, exec, s[4:5]
	v_cvt_pk_bf16_f32 v52, v36, v37
	v_cvt_pk_bf16_f32 v53, v38, v39
	v_cvt_pk_bf16_f32 v54, v32, v33
	v_cvt_pk_bf16_f32 v55, v34, v35
	global_store_dwordx4 v[50:51], v[52:55], off offset:256 sc1
	s_and_saveexec_b64 s[4:5], vcc
	s_cbranch_execz .LBB0_626
	global_store_dwordx4 v[48:49], v[36:39], off offset:512 sc1
	global_store_dwordx4 v[48:49], v[32:35], off offset:528 sc1

; DI u32x4 pk8(f32x4 a, f32x4 b) { u32x4 w; w.x = pk2(a[0], a[1]); w.y = pk2(a[2], a[3]); w.z = pk2(b[0], b[1]); w.w = pk2(b[2], b[3]); return w; }
;     DI void operator()(const f32x4 (&acc)[2][2][4][2], const Unit& u, int wr, int wc, int fr, int fq) const {
;     ...
;                 if (pn < 5) {
;                     const f32x4* cp = (const f32x4*)(cosT + pos * 32 + 8 * fq); const f32x4* sp = (const f32x4*)(sinT + pos * 32 + 8 * fq);
;                     const f32x4 c0 = cp[0], c1 = cp[1], s0 = sp[0], s1 = sp[1];
;                     const f32x4 x1a = A00, x1b = A01, x2a = A10, x2b = A11;
;                     f32x4 o1a = x1a * c0 - x2a * s0, o1b = x1b * c1 - x2b * s1, o2a = x2a * c0 + x1a * s0, o2b = x2b * c1 + x1b * s1;
;                     if (pn < 4) {
;                         bf16* qp = Q + (size_t)r * 1024 + (4 * pn + wc) * 64 + 8 * fq;
;                         *(u32x4*)qp = pk8(o1a * QSC, o1b * QSC); *(u32x4*)(qp + 32) = pk8(o2a * QSC, o2b * QSC);
;                     } else {
;                         bf16* kp = Kb + (size_t)r * 256 + wc * 64 + 8 * fq;
;                         *(u32x4*)kp = pk8(o1a, o1b); *(u32x4*)(kp + 32) = pk8(o2a, o2b);
;                         if (pos >= SEQL - 128) { float* o = outK + ((size_t)(b * 128 + pos - (SEQL - 128))) * 256 + wc * 64 + 8 * fq;
;                             *(f32x4*)o = o1a; *(f32x4*)(o + 4) = o1b; *(f32x4*)(o + 32) = o2a; *(f32x4*)(o + 36) = o2b; }
;                     }
.LBB0_628:
	s_andn2_b64 vcc, exec, s[8:9]
	s_cbranch_vccnz .LBB0_635
	v_lshlrev_b32_e32 v152, 7, v58
	v_lshl_add_u64 v[48:49], s[34:35], 0, v[152:153]
	v_lshl_add_u64 v[52:53], v[48:49], 0, v[184:185]
	v_lshl_add_u64 v[60:61], s[30:31], 0, v[152:153]
	global_load_dwordx4 v[48:51], v[52:53], off
	s_nop 0
	global_load_dwordx4 v[52:55], v[52:53], off offset:16
	v_lshl_add_u64 v[64:65], v[60:61], 0, v[184:185]
	global_load_dwordx4 v[60:63], v[64:65], off
	s_nop 0
	global_load_dwordx4 v[64:67], v[64:65], off offset:16
	s_and_b64 vcc, exec, s[0:1]
	s_mov_b64 s[0:1], -1
	s_waitcnt vmcnt(3)
	v_pk_mul_f32 v[68:69], v[38:39], v[50:51]
	v_pk_mul_f32 v[70:71], v[36:37], v[48:49]
	s_waitcnt vmcnt(2)
	v_pk_mul_f32 v[72:73], v[34:35], v[54:55]
	v_pk_mul_f32 v[74:75], v[32:33], v[52:53]
	v_pk_mul_f32 v[50:51], v[46:47], v[50:51]
	v_pk_mul_f32 v[48:49], v[44:45], v[48:49]
	v_pk_mul_f32 v[54:55], v[42:43], v[54:55]
	v_pk_mul_f32 v[52:53], v[40:41], v[52:53]
	s_waitcnt vmcnt(1)
	v_pk_fma_f32 v[46:47], v[46:47], v[62:63], v[68:69] neg_lo:[0,0,1] neg_hi:[0,0,1]
	v_pk_fma_f32 v[44:45], v[44:45], v[60:61], v[70:71] neg_lo:[0,0,1] neg_hi:[0,0,1]
	s_waitcnt vmcnt(0)
	v_pk_fma_f32 v[42:43], v[42:43], v[66:67], v[72:73] neg_lo:[0,0,1] neg_hi:[0,0,1]
	v_pk_fma_f32 v[40:41], v[40:41], v[64:65], v[74:75] neg_lo:[0,0,1] neg_hi:[0,0,1]
	v_pk_fma_f32 v[38:39], v[38:39], v[62:63], v[50:51]
	v_pk_fma_f32 v[36:37], v[36:37], v[60:61], v[48:49]
	v_pk_fma_f32 v[34:35], v[34:35], v[66:67], v[54:55]
	v_pk_fma_f32 v[32:33], v[32:33], v[64:65], v[52:53]
	s_cbranch_vccnz .LBB0_631
	v_lshlrev_b64 v[48:49], 11, v[56:57]
	v_lshl_add_u64 v[48:49], s[18:19], 0, v[48:49]
	v_lshl_add_u64 v[48:49], s[2:3], 1, v[48:49]
	s_mov_b32 s0, 0x3e38aa3b
	v_lshl_add_u64 v[52:53], v[176:177], 1, v[48:49]
	v_pk_mul_f32 v[50:51], v[46:47], s[0:1] op_sel_hi:[1,0]
	v_pk_mul_f32 v[48:49], v[44:45], s[0:1] op_sel_hi:[1,0]
	v_pk_mul_f32 v[54:55], v[42:43], s[0:1] op_sel_hi:[1,0]
	v_pk_mul_f32 v[60:61], v[40:41], s[0:1] op_sel_hi:[1,0]
	v_cvt_pk_bf16_f32 v48, v48, v49
	v_cvt_pk_bf16_f32 v49, v50, v51
	v_cvt_pk_bf16_f32 v50, v60, v61
	v_cvt_pk_bf16_f32 v51, v54, v55
	global_store_dwordx4 v[52:53], v[48:51], off sc1
	v_pk_mul_f32 v[54:55], v[34:35], s[0:1] op_sel_hi:[1,0]
	v_pk_mul_f32 v[60:61], v[32:33], s[0:1] op_sel_hi:[1,0]
	v_pk_mul_f32 v[50:51], v[38:39], s[0:1] op_sel_hi:[1,0]
	v_pk_mul_f32 v[48:49], v[36:37], s[0:1] op_sel_hi:[1,0]
	s_mov_b64 s[0:1], 0
	v_cvt_pk_bf16_f32 v48, v48, v49
	v_cvt_pk_bf16_f32 v49, v50, v51
	v_cvt_pk_bf16_f32 v50, v60, v61
	v_cvt_pk_bf16_f32 v51, v54, v55
	global_store_dwordx4 v[52:53], v[48:51], off offset:64 sc1
.LBB0_631:
	s_andn2_b64 vcc, exec, s[0:1]
	s_cbranch_vccnz .LBB0_635
	v_lshlrev_b64 v[48:49], 9, v[56:57]
	v_lshl_add_u64 v[48:49], s[42:43], 0, v[48:49]
	v_lshl_add_u64 v[52:53], v[176:177], 1, v[48:49]
	v_cvt_pk_bf16_f32 v48, v44, v45
	v_cvt_pk_bf16_f32 v49, v46, v47
	v_cvt_pk_bf16_f32 v50, v40, v41
	v_cvt_pk_bf16_f32 v51, v42, v43
	s_movk_i32 s0, 0x77f
	global_store_dwordx4 v[52:53], v[48:51], off sc1
	v_cmp_lt_u32_e32 vcc, s0, v58
	s_nop 0
	v_cvt_pk_bf16_f32 v48, v36, v37
	v_cvt_pk_bf16_f32 v49, v38, v39
	v_cvt_pk_bf16_f32 v50, v32, v33
	v_cvt_pk_bf16_f32 v51, v34, v35
	global_store_dwordx4 v[52:53], v[48:51], off offset:64 sc1
	s_and_saveexec_b64 s[0:1], vcc
	s_cbranch_execz .LBB0_634
	v_lshlrev_b32_e32 v48, 7, v59
	s_movk_i32 s2, 0xf880
	v_add3_u32 v48, v58, v48, s2
	v_ashrrev_i32_e32 v49, 31, v48
	v_lshlrev_b64 v[48:49], 10, v[48:49]
	v_lshl_add_u64 v[48:49], s[44:45], 0, v[48:49]
	v_lshl_add_u64 v[48:49], v[176:177], 2, v[48:49]
	global_store_dwordx4 v[48:49], v[44:47], off sc1
	global_store_dwordx4 v[48:49], v[40:43], off offset:16 sc1
	global_store_dwordx4 v[48:49], v[36:39], off offset:128 sc1
	global_store_dwordx4 v[48:49], v[32:35], off offset:144 sc1

;     DI void operator()(const f32x4 (&acc)[2][2][4][2], const Unit& u, int wr, int wc, int fr, int fq) const {
;     ...
;         if (u.pm == MP / BM) {
;             if (wr == 0) {
; #pragma unroll
;                 for (int m = 0; m < 2; ++m) { const float rs = RS[MP + 16 * m + fr];
; #pragma unroll
;                     for (int bj = 0; bj < 2; ++bj) { float* o = PS + (size_t)(16 * m + fr) * EPROJ + even_src32(8 * pn + 4 * bj + wc) + 8 * fq;
;                         *(f32x4*)o = acc[0][bj][m][0] * rs; *(f32x4*)(o + 4) = acc[0][bj][m][1] * rs; } }
;             }
;             return;
;         }
.LBB0_636:
	s_and_b64 vcc, exec, s[0:1]
	s_cbranch_vccz .LBB0_639
	s_andn2_b64 vcc, exec, s[40:41]
	s_cbranch_vccnz .LBB0_639
	v_add_u32_e32 v32, 0x2000, v194
	v_ashrrev_i32_e32 v33, 31, v32
	v_lshl_add_u64 v[32:33], v[32:33], 2, s[28:29]
	global_load_dword v38, v[32:33], off
	s_lshl_b32 s0, s54, 7
	s_lshl_b32 s1, s54, 8
	s_or_b32 s2, s1, s77
	s_or_b32 s1, s1, s71
	s_add_i32 s0, s0, s74
	s_add_i32 s3, s0, 0xa00
	s_or_b32 s4, s1, 0x80
	s_or_b32 s5, s2, 32
	s_addk_i32 s0, 0xe00
	s_cmp_lt_u32 s54, 10
	s_cselect_b32 s3, s1, s3
	s_cselect_b32 s0, s4, s0
	s_cmp_eq_u32 s54, 4
	v_mov_b64_e32 v[34:35], s[26:27]
	s_movk_i32 s8, 0x4800
	s_cselect_b32 s4, s79, s0
	s_cmp_lt_i32 s54, 4
	v_mad_i64_i32 v[40:41], s[0:1], v194, s8, v[34:35]
	s_cselect_b32 s1, s2, s78
	s_cselect_b32 s0, s5, s4
	s_cmp_lt_i32 s54, 5
	s_cselect_b32 s2, s1, s3
	v_lshlrev_b32_e32 v36, 3, v195
	s_ashr_i32 s3, s2, 31
	v_ashrrev_i32_e32 v37, 31, v36
	s_lshl_b64 s[2:3], s[2:3], 2
	v_lshl_add_u64 v[42:43], v[40:41], 0, s[2:3]
	v_lshlrev_b64 v[32:33], 2, v[36:37]
	s_ashr_i32 s1, s0, 31
	v_lshl_add_u64 v[36:37], v[42:43], 0, v[32:33]
	s_lshl_b64 s[0:1], s[0:1], 2
	s_waitcnt vmcnt(0)
	v_pk_mul_f32 v[26:27], v[26:27], v[38:39] op_sel_hi:[1,0]
	v_pk_mul_f32 v[24:25], v[24:25], v[38:39] op_sel_hi:[1,0]
	global_store_dwordx4 v[36:37], v[24:27], off offset:16 sc1
	v_pk_mul_f32 v[30:31], v[30:31], v[38:39] op_sel_hi:[1,0]
	v_pk_mul_f32 v[28:29], v[28:29], v[38:39] op_sel_hi:[1,0]
	v_lshl_add_u64 v[24:25], v[40:41], 0, s[0:1]
	v_lshl_add_u64 v[24:25], v[24:25], 0, v[32:33]
	v_pk_mul_f32 v[18:19], v[18:19], v[38:39] op_sel_hi:[1,0]
	v_pk_mul_f32 v[16:17], v[16:17], v[38:39] op_sel_hi:[1,0]
	global_store_dwordx4 v[36:37], v[28:31], off sc1
	global_store_dwordx4 v[24:25], v[16:19], off offset:16 sc1
	v_pk_mul_f32 v[22:23], v[22:23], v[38:39] op_sel_hi:[1,0]
	v_pk_mul_f32 v[20:21], v[20:21], v[38:39] op_sel_hi:[1,0]
	v_add_u32_e32 v16, 0x2010, v194
	v_ashrrev_i32_e32 v17, 31, v16
	global_store_dwordx4 v[24:25], v[20:23], off sc1
	v_lshl_add_u64 v[16:17], v[16:17], 2, s[28:29]
	global_load_dword v16, v[16:17], off
	v_add_u32_e32 v17, 16, v194
	v_mad_i64_i32 v[18:19], s[4:5], v17, s8, v[34:35]
	v_lshl_add_u64 v[20:21], v[18:19], 0, s[2:3]
	v_lshl_add_u64 v[20:21], v[20:21], 0, v[32:33]
	s_waitcnt vmcnt(0)
	v_pk_mul_f32 v[10:11], v[10:11], v[16:17] op_sel_hi:[1,0]
	v_pk_mul_f32 v[8:9], v[8:9], v[16:17] op_sel_hi:[1,0]
	global_store_dwordx4 v[20:21], v[8:11], off offset:16 sc1
	v_pk_mul_f32 v[14:15], v[14:15], v[16:17] op_sel_hi:[1,0]
	v_pk_mul_f32 v[12:13], v[12:13], v[16:17] op_sel_hi:[1,0]
	v_lshl_add_u64 v[8:9], v[18:19], 0, s[0:1]
	v_lshl_add_u64 v[8:9], v[8:9], 0, v[32:33]
	v_pk_mul_f32 v[6:7], v[6:7], v[16:17] op_sel_hi:[1,0]
	v_pk_mul_f32 v[4:5], v[4:5], v[16:17] op_sel_hi:[1,0]
	v_pk_mul_f32 v[2:3], v[2:3], v[16:17] op_sel_hi:[1,0]
	v_pk_mul_f32 v[0:1], v[0:1], v[16:17] op_sel_hi:[1,0]
	global_store_dwordx4 v[20:21], v[12:15], off sc1
	global_store_dwordx4 v[8:9], v[4:7], off sc1
	global_store_dwordx4 v[8:9], v[0:3], off offset:16 sc1

; DI void sample_cache_shift(const float* ck, const float* cv, float* outKs, float* outVs, int sgtid, int SGT) {
;     for (int it = sgtid; it < 2 * DBS * 127 * 64; it += SGT) {
;         const int which = it >= DBS * 127 * 64, i2 = it - which * (DBS * 127 * 64), b = i2 / (127 * 64), rem = i2 - b * (127 * 64), w = rem >> 6, c4 = rem & 63;
;         const f32x4 v = *(const f32x4*)((which ? cv : ck) + ((size_t)(b * 128 + w + 1)) * 256 + 4 * c4);
;         *(f32x4*)((which ? outVs : outKs) + ((size_t)(b * 128 + w)) * 256 + 4 * c4) = v;
;     }
; }
.LBB0_646:
	s_mov_b32 s17, 0x3f7ff
	v_cmp_lt_i32_e32 vcc, s17, v0
	v_mov_b32_e32 v3, s5
	v_mov_b32_e32 v4, s7
	v_cndmask_b32_e32 v2, 0, v250, vcc
	v_add_u32_e32 v8, v2, v0
	s_mov_b32 s17, 0x81020409
	v_cndmask_b32_e32 v3, v3, v4, vcc
	v_mul_hi_i32 v4, v8, s17
	v_mov_b32_e32 v5, s4
	v_mov_b32_e32 v6, s6
	v_add_u32_e32 v4, v4, v8
	v_cndmask_b32_e32 v2, v5, v6, vcc
	v_lshrrev_b32_e32 v5, 31, v4
	v_ashrrev_i32_e32 v4, 12, v4
	v_add_u32_e32 v4, v4, v5
	s_movk_i32 s17, 0xe040
	v_mad_i32_i24 v5, v4, s17, v8
	v_ashrrev_i32_e32 v5, 6, v5
	v_lshl_add_u32 v4, v4, 7, v5
	v_and_b32_e32 v7, 0xfc, v1
	v_ashrrev_i32_e32 v5, 31, v4
	v_lshlrev_b32_e32 v152, 2, v7
	v_lshl_add_u64 v[2:3], s[2:3], 2, v[2:3]
	v_lshlrev_b64 v[6:7], 10, v[4:5]
	v_lshl_add_u64 v[2:3], v[2:3], 0, v[6:7]
	v_lshl_add_u64 v[2:3], v[2:3], 0, v[152:153]
	global_load_dwordx4 v[2:5], v[2:3], off offset:1024
	v_mov_b32_e32 v9, v153
	v_cndmask_b32_e32 v8, v251, v252, vcc
	v_add_u32_e32 v0, s58, v0
	v_lshl_add_u64 v[8:9], s[8:9], 0, v[8:9]
	s_mov_b32 s17, 0x7efff
	v_cmp_lt_i32_e32 vcc, s17, v0
	v_lshl_add_u64 v[6:7], v[8:9], 0, v[6:7]
	v_add_u32_e32 v1, s62, v1
	s_or_b64 s[12:13], vcc, s[12:13]
	v_lshl_add_u64 v[6:7], v[6:7], 0, v[152:153]
	s_waitcnt vmcnt(0)
	global_store_dwordx4 v[6:7], v[2:5], off sc1
	s_andn2_b64 exec, exec, s[12:13]
	s_cbranch_execnz .LBB0_646

; #define LAS __attribute__((address_space(3)))
; DI unsigned pk2(float a, float b) { f32x2 v = {a, b}; hbf16x2 r = __builtin_convertvector(v, hbf16x2); return __builtin_bit_cast(unsigned, r); }
; DI void ti_load(f32x4 (&v)[8], float (&g)[8], const TItem& ti) {
; #pragma unroll
;     for (int i = 0; i < 8; ++i) v[i] = *(const f32x4*)(ti.src + (size_t)(8 * i) * ti.N);
; #pragma unroll
;     for (int i = 0; i < 8; ++i) g[i] = ti.gp[8 * i];
; }
; DI void ti_finish(const f32x4 (&v)[8], const float (&g)[8], const TItem& ti, LAS float* scr, int lane) {
;     const int q8 = lane & 7, kr = lane >> 3;
; #pragma unroll
;     for (int i = 0; i < 8; ++i) *(LAS f32x4*)(scr + (8 * i + kr) * 36 + 4 * q8) = v[i] * (ti.hasg ? g[i] : 1.0f);
;     asm volatile("s_waitcnt lgkmcnt(0)" ::: "memory");
;     const int n = lane & 31, kc = lane >> 5;
; #pragma unroll
;     for (int p2 = 0; p2 < 4; ++p2) { const int c = 2 * p2 + kc; const LAS float* s = scr + (8 * c) * 36 + n;
;         u32x4 o; o.x = pk2(s[0], s[36]); o.y = pk2(s[72], s[108]); o.z = pk2(s[144], s[180]); o.w = pk2(s[216], s[252]);
;         *(u32x4*)(ti.dst + 16 * p2) = o; }
;     asm volatile("s_waitcnt lgkmcnt(0)" ::: "memory");
; }
.LBB0_662:
	s_lshl_b64 s[22:23], s[22:23], 5
	global_load_dwordx4 v[8:11], v[0:1], off
	v_lshl_add_u64 v[0:1], v[0:1], 0, s[22:23]
	v_lshl_add_u64 v[12:13], v[0:1], 0, s[22:23]
	global_load_dwordx4 v[0:3], v[0:1], off
	s_nop 0
	global_load_dwordx4 v[4:7], v[12:13], off
	v_lshl_add_u64 v[12:13], v[12:13], 0, s[22:23]
	v_lshl_add_u64 v[20:21], v[12:13], 0, s[22:23]
	global_load_dwordx4 v[12:15], v[12:13], off
	s_nop 0
	global_load_dwordx4 v[16:19], v[20:21], off
	v_lshl_add_u64 v[20:21], v[20:21], 0, s[22:23]
	v_lshl_add_u64 v[28:29], v[20:21], 0, s[22:23]
	global_load_dwordx4 v[20:23], v[20:21], off
	s_nop 0
	global_load_dwordx4 v[24:27], v[28:29], off
	v_lshl_add_u64 v[28:29], v[28:29], 0, s[22:23]
	global_load_dwordx4 v[28:31], v[28:29], off
	s_nop 0
	global_load_dword v88, v[68:69], off
	global_load_dword v89, v[68:69], off offset:32
	global_load_dword v90, v[68:69], off offset:64
	global_load_dword v91, v[68:69], off offset:96
	global_load_dword v92, v[68:69], off offset:128
	global_load_dword v93, v[68:69], off offset:160
	global_load_dword v94, v[68:69], off offset:192
	global_load_dword v95, v[68:69], off offset:224
	s_cmp_eq_u32 s31, 0
	s_cselect_b64 s[22:23], -1, 0
	s_waitcnt vmcnt(27)
	v_cndmask_b32_e64 v110, v103, 1.0, s[22:23]
	v_pk_mul_f32 v[58:59], v[58:59], v[110:111] op_sel_hi:[1,0]
	v_pk_mul_f32 v[56:57], v[56:57], v[110:111] op_sel_hi:[1,0]
	ds_write_b128 v86, v[56:59]
	s_waitcnt vmcnt(26)
	v_cndmask_b32_e64 v56, v102, 1.0, s[22:23]
	v_pk_mul_f32 v[58:59], v[62:63], v[56:57] op_sel_hi:[1,0]
	v_pk_mul_f32 v[56:57], v[60:61], v[56:57] op_sel_hi:[1,0]
	ds_write_b128 v86, v[56:59] offset:1152
	s_waitcnt vmcnt(25)
	v_cndmask_b32_e64 v56, v101, 1.0, s[22:23]
	v_pk_mul_f32 v[54:55], v[54:55], v[56:57] op_sel_hi:[1,0]
	v_pk_mul_f32 v[52:53], v[52:53], v[56:57] op_sel_hi:[1,0]
	ds_write_b128 v86, v[52:55] offset:2304
	s_waitcnt vmcnt(24)
	v_cndmask_b32_e64 v52, v100, 1.0, s[22:23]
	v_pk_mul_f32 v[50:51], v[50:51], v[52:53] op_sel_hi:[1,0]
	v_pk_mul_f32 v[48:49], v[48:49], v[52:53] op_sel_hi:[1,0]
	ds_write_b128 v86, v[48:51] offset:3456
	s_waitcnt vmcnt(23)
	v_cndmask_b32_e64 v48, v99, 1.0, s[22:23]
	v_pk_mul_f32 v[46:47], v[46:47], v[48:49] op_sel_hi:[1,0]
	v_pk_mul_f32 v[44:45], v[44:45], v[48:49] op_sel_hi:[1,0]
	ds_write_b128 v86, v[44:47] offset:4608
	s_waitcnt vmcnt(22)
	v_cndmask_b32_e64 v44, v98, 1.0, s[22:23]
	v_pk_mul_f32 v[42:43], v[42:43], v[44:45] op_sel_hi:[1,0]
	v_pk_mul_f32 v[40:41], v[40:41], v[44:45] op_sel_hi:[1,0]
	ds_write_b128 v86, v[40:43] offset:5760
	s_waitcnt vmcnt(21)
	v_cndmask_b32_e64 v40, v97, 1.0, s[22:23]
	v_pk_mul_f32 v[38:39], v[38:39], v[40:41] op_sel_hi:[1,0]
	v_pk_mul_f32 v[36:37], v[36:37], v[40:41] op_sel_hi:[1,0]
	ds_write_b128 v86, v[36:39] offset:6912
	s_waitcnt vmcnt(20)
	v_cndmask_b32_e64 v36, v96, 1.0, s[22:23]
	v_pk_mul_f32 v[34:35], v[34:35], v[36:37] op_sel_hi:[1,0]
	v_pk_mul_f32 v[32:33], v[32:33], v[36:37] op_sel_hi:[1,0]
	ds_write_b128 v86, v[32:35] offset:8064
	s_waitcnt lgkmcnt(0)
	ds_read2_b32 v[32:33], v87 offset1:36
	ds_read2_b32 v[34:35], v87 offset0:72 offset1:108
	ds_read2_b32 v[36:37], v87 offset0:144 offset1:180
	ds_read2_b32 v[38:39], v87 offset0:216 offset1:252
	s_and_b64 s[22:23], s[20:21], exec
	s_waitcnt lgkmcnt(3)
	v_cvt_pk_bf16_f32 v32, v32, v33
	s_waitcnt lgkmcnt(2)
	v_cvt_pk_bf16_f32 v33, v34, v35
	s_waitcnt lgkmcnt(1)
	v_cvt_pk_bf16_f32 v34, v36, v37
	s_waitcnt lgkmcnt(0)
	v_cvt_pk_bf16_f32 v35, v38, v39
	ds_read2_b32 v[36:37], v104 offset0:64 offset1:100
	ds_read2_b32 v[38:39], v104 offset0:136 offset1:172
	ds_read2_b32 v[40:41], v104 offset0:208 offset1:244
	ds_read2_b32 v[42:43], v105 offset0:24 offset1:60
	global_store_dwordx4 v[80:81], v[32:35], off sc1
	s_cselect_b32 s30, s19, s30
	s_waitcnt lgkmcnt(3)
	v_cvt_pk_bf16_f32 v32, v36, v37
	s_waitcnt lgkmcnt(2)
	v_cvt_pk_bf16_f32 v33, v38, v39
	s_waitcnt lgkmcnt(1)
	v_cvt_pk_bf16_f32 v34, v40, v41
	s_waitcnt lgkmcnt(0)
	v_cvt_pk_bf16_f32 v35, v42, v43
	ds_read2_b32 v[36:37], v106 offset0:128 offset1:164
	ds_read2_b32 v[38:39], v106 offset0:200 offset1:236
	ds_read2_b32 v[40:41], v107 offset0:16 offset1:52
	ds_read2_b32 v[42:43], v107 offset0:88 offset1:124
	global_store_dwordx4 v[80:81], v[32:35], off offset:32 sc1
	s_waitcnt lgkmcnt(3)
	s_nop 0
	v_cvt_pk_bf16_f32 v32, v36, v37
	s_waitcnt lgkmcnt(2)
	v_cvt_pk_bf16_f32 v33, v38, v39
	s_waitcnt lgkmcnt(1)
	v_cvt_pk_bf16_f32 v34, v40, v41
	s_waitcnt lgkmcnt(0)
	v_cvt_pk_bf16_f32 v35, v42, v43
	ds_read2_b32 v[36:37], v108 offset0:192 offset1:228
	ds_read2_b32 v[38:39], v109 offset0:8 offset1:44
	ds_read2_b32 v[40:41], v109 offset0:80 offset1:116
	ds_read2_b32 v[42:43], v109 offset0:152 offset1:188
	global_store_dwordx4 v[80:81], v[32:35], off offset:64 sc1
	s_waitcnt lgkmcnt(3)
	s_nop 0
	v_cvt_pk_bf16_f32 v32, v36, v37
	s_waitcnt lgkmcnt(2)
	v_cvt_pk_bf16_f32 v33, v38, v39
	s_waitcnt lgkmcnt(1)
	v_cvt_pk_bf16_f32 v34, v40, v41
	s_waitcnt lgkmcnt(0)
	v_cvt_pk_bf16_f32 v35, v42, v43
	global_store_dwordx4 v[80:81], v[32:35], off offset:96 sc1
	s_waitcnt lgkmcnt(0)

; #define LAS __attribute__((address_space(3)))
; DI unsigned pk2(float a, float b) { f32x2 v = {a, b}; hbf16x2 r = __builtin_convertvector(v, hbf16x2); return __builtin_bit_cast(unsigned, r); }
; template <int NS>
; DI void ti_decode(TItem& ti, int it, const CStack (&st)[NS], int lane) {
;     int base = 0;
; #pragma unroll
;     for (int j = 0; j < NS; ++j) {
;         const int nblk = st[j].N / 32, per = (st[j].K / 64) * nblk, tot = st[j].L * per;
;         if (it >= base && (it < base + tot || j == NS - 1)) {
;             const int K = st[j].K, N = st[j].N, r0 = it - base, l = r0 / per, rem = r0 - l * per, kb = rem / nblk, nb = rem - kb * nblk, k0 = 64 * kb;
;             ti.src = st[j].W + (size_t)l * K * N + (size_t)(k0 + (lane >> 3)) * N + (st[j].perm ? even_src32(nb) : 32 * nb) + 4 * (lane & 7);
;             ti.dst = st[j].WT + (size_t)l * K * N + (size_t)(32 * nb + (lane & 31)) * K + k0 + 8 * (lane >> 5);
;             ti.hasg = st[j].gk != nullptr; ti.gp = ti.hasg ? st[j].gk + (size_t)l * st[j].gstride + k0 + (lane >> 3) : ti.src;
;             ti.N = N;
;         }
; DI void ti_load(f32x4 (&v)[8], float (&g)[8], const TItem& ti) {
; #pragma unroll
;     for (int i = 0; i < 8; ++i) v[i] = *(const f32x4*)(ti.src + (size_t)(8 * i) * ti.N);
; #pragma unroll
;     for (int i = 0; i < 8; ++i) g[i] = ti.gp[8 * i];
; }
; DI void ti_finish(const f32x4 (&v)[8], const float (&g)[8], const TItem& ti, LAS float* scr, int lane) {
;     const int q8 = lane & 7, kr = lane >> 3;
; #pragma unroll
;     for (int i = 0; i < 8; ++i) *(LAS f32x4*)(scr + (8 * i + kr) * 36 + 4 * q8) = v[i] * (ti.hasg ? g[i] : 1.0f);
;     asm volatile("s_waitcnt lgkmcnt(0)" ::: "memory");
;     const int n = lane & 31, kc = lane >> 5;
; #pragma unroll
;     for (int p2 = 0; p2 < 4; ++p2) { const int c = 2 * p2 + kc; const LAS float* s = scr + (8 * c) * 36 + n;
;         u32x4 o; o.x = pk2(s[0], s[36]); o.y = pk2(s[72], s[108]); o.z = pk2(s[144], s[180]); o.w = pk2(s[216], s[252]);
;         *(u32x4*)(ti.dst + 16 * p2) = o; }
;     asm volatile("s_waitcnt lgkmcnt(0)" ::: "memory");
; }
.LBB0_673:
	s_lshl_b64 s[20:21], s[20:21], 5
	v_lshl_add_u64 v[32:33], v[78:79], 0, s[20:21]
	global_load_dwordx4 v[56:59], v[78:79], off
	global_load_dwordx4 v[60:63], v[32:33], off
	v_lshl_add_u64 v[32:33], v[32:33], 0, s[20:21]
	global_load_dwordx4 v[52:55], v[32:33], off
	v_lshl_add_u64 v[32:33], v[32:33], 0, s[20:21]
	global_load_dwordx4 v[48:51], v[32:33], off
	v_lshl_add_u64 v[32:33], v[32:33], 0, s[20:21]
	global_load_dwordx4 v[44:47], v[32:33], off
	v_lshl_add_u64 v[32:33], v[32:33], 0, s[20:21]
	global_load_dwordx4 v[40:43], v[32:33], off
	v_lshl_add_u64 v[32:33], v[32:33], 0, s[20:21]
	global_load_dwordx4 v[36:39], v[32:33], off
	v_lshl_add_u64 v[32:33], v[32:33], 0, s[20:21]
	global_load_dwordx4 v[32:35], v[32:33], off
	s_nop 0
	global_load_dword v103, v[76:77], off
	global_load_dword v102, v[76:77], off offset:32
	global_load_dword v101, v[76:77], off offset:64
	global_load_dword v100, v[76:77], off offset:96
	global_load_dword v99, v[76:77], off offset:128
	global_load_dword v98, v[76:77], off offset:160
	global_load_dword v97, v[76:77], off offset:192
	global_load_dword v96, v[76:77], off offset:224
	s_cmp_eq_u32 s29, 0
	s_cselect_b64 s[20:21], -1, 0
	s_waitcnt vmcnt(23)
	v_cndmask_b32_e64 v104, v88, 1.0, s[20:21]
	v_pk_mul_f32 v[106:107], v[10:11], v[104:105] op_sel_hi:[1,0]
	v_pk_mul_f32 v[104:105], v[8:9], v[104:105] op_sel_hi:[1,0]
	ds_write_b128 v86, v[104:107]
	s_waitcnt vmcnt(22)
	v_cndmask_b32_e64 v104, v89, 1.0, s[20:21]
	v_pk_mul_f32 v[106:107], v[2:3], v[104:105] op_sel_hi:[1,0]
	v_pk_mul_f32 v[104:105], v[0:1], v[104:105] op_sel_hi:[1,0]
	ds_write_b128 v86, v[104:107] offset:1152
	s_waitcnt vmcnt(21)
	v_cndmask_b32_e64 v104, v90, 1.0, s[20:21]
	v_pk_mul_f32 v[106:107], v[6:7], v[104:105] op_sel_hi:[1,0]
	v_pk_mul_f32 v[104:105], v[4:5], v[104:105] op_sel_hi:[1,0]
	ds_write_b128 v86, v[104:107] offset:2304
	s_waitcnt vmcnt(20)
	v_cndmask_b32_e64 v104, v91, 1.0, s[20:21]
	v_pk_mul_f32 v[106:107], v[14:15], v[104:105] op_sel_hi:[1,0]
	v_pk_mul_f32 v[104:105], v[12:13], v[104:105] op_sel_hi:[1,0]
	ds_write_b128 v86, v[104:107] offset:3456
	s_waitcnt vmcnt(19)
	v_cndmask_b32_e64 v104, v92, 1.0, s[20:21]
	v_pk_mul_f32 v[106:107], v[18:19], v[104:105] op_sel_hi:[1,0]
	v_pk_mul_f32 v[104:105], v[16:17], v[104:105] op_sel_hi:[1,0]
	ds_write_b128 v86, v[104:107] offset:4608
	s_waitcnt vmcnt(18)
	v_cndmask_b32_e64 v104, v93, 1.0, s[20:21]
	v_pk_mul_f32 v[106:107], v[22:23], v[104:105] op_sel_hi:[1,0]
	v_pk_mul_f32 v[104:105], v[20:21], v[104:105] op_sel_hi:[1,0]
	ds_write_b128 v86, v[104:107] offset:5760
	s_waitcnt vmcnt(17)
	v_cndmask_b32_e64 v104, v94, 1.0, s[20:21]
	v_pk_mul_f32 v[106:107], v[26:27], v[104:105] op_sel_hi:[1,0]
	v_pk_mul_f32 v[104:105], v[24:25], v[104:105] op_sel_hi:[1,0]
	ds_write_b128 v86, v[104:107] offset:6912
	s_waitcnt vmcnt(16)
	v_cndmask_b32_e64 v104, v95, 1.0, s[20:21]
	v_pk_mul_f32 v[106:107], v[30:31], v[104:105] op_sel_hi:[1,0]
	v_pk_mul_f32 v[104:105], v[28:29], v[104:105] op_sel_hi:[1,0]
	ds_write_b128 v86, v[104:107] offset:8064
	s_waitcnt lgkmcnt(0)
	ds_read2_b32 v[104:105], v87 offset1:36
	ds_read2_b32 v[106:107], v87 offset0:72 offset1:108
	ds_read2_b32 v[108:109], v87 offset0:216 offset1:252
	s_mov_b64 s[20:21], 0
	s_andn2_b64 vcc, exec, s[22:23]
	s_waitcnt lgkmcnt(2)
	v_cvt_pk_bf16_f32 v104, v104, v105
	s_waitcnt lgkmcnt(1)
	v_cvt_pk_bf16_f32 v105, v106, v107
	ds_read2_b32 v[106:107], v87 offset0:144 offset1:180
	s_waitcnt lgkmcnt(0)
	v_cvt_pk_bf16_f32 v106, v106, v107
	v_cvt_pk_bf16_f32 v107, v108, v109
	global_store_dwordx4 v[72:73], v[104:107], off sc1
	s_nop 1
	v_add_u32_e32 v104, 0x800, v87
	ds_read2_b32 v[106:107], v104 offset0:64 offset1:100
	ds_read2_b32 v[108:109], v104 offset0:136 offset1:172
	v_add_u32_e32 v105, 0xc00, v87
	ds_read2_b32 v[110:111], v105 offset0:24 offset1:60
	s_waitcnt lgkmcnt(2)
	v_cvt_pk_bf16_f32 v106, v106, v107
	s_waitcnt lgkmcnt(1)
	v_cvt_pk_bf16_f32 v107, v108, v109
	ds_read2_b32 v[108:109], v104 offset0:208 offset1:244
	s_waitcnt lgkmcnt(0)
	v_cvt_pk_bf16_f32 v108, v108, v109
	v_cvt_pk_bf16_f32 v109, v110, v111
	global_store_dwordx4 v[72:73], v[106:109], off offset:32 sc1
	s_nop 1
	v_add_u32_e32 v106, 0x1000, v87
	ds_read2_b32 v[108:109], v106 offset0:128 offset1:164
	ds_read2_b32 v[110:111], v106 offset0:200 offset1:236
	v_add_u32_e32 v107, 0x1400, v87
	ds_read2_b32 v[112:113], v107 offset0:88 offset1:124
	s_waitcnt lgkmcnt(2)
	v_cvt_pk_bf16_f32 v108, v108, v109
	s_waitcnt lgkmcnt(1)
	v_cvt_pk_bf16_f32 v109, v110, v111
	ds_read2_b32 v[110:111], v107 offset0:16 offset1:52
	s_waitcnt lgkmcnt(0)
	v_cvt_pk_bf16_f32 v110, v110, v111
	v_cvt_pk_bf16_f32 v111, v112, v113
	global_store_dwordx4 v[72:73], v[108:111], off offset:64 sc1
	s_nop 1
	v_add_u32_e32 v108, 0x1800, v87
	v_add_u32_e32 v109, 0x1c00, v87
	ds_read2_b32 v[110:111], v108 offset0:192 offset1:228
	ds_read2_b32 v[112:113], v109 offset0:8 offset1:44
	ds_read2_b32 v[114:115], v109 offset0:152 offset1:188
	s_waitcnt lgkmcnt(2)
	v_cvt_pk_bf16_f32 v110, v110, v111
	s_waitcnt lgkmcnt(1)
	v_cvt_pk_bf16_f32 v111, v112, v113
	ds_read2_b32 v[112:113], v109 offset0:80 offset1:116
	s_waitcnt lgkmcnt(0)
	v_cvt_pk_bf16_f32 v112, v112, v113
	v_cvt_pk_bf16_f32 v113, v114, v115
	global_store_dwordx4 v[72:73], v[110:113], off offset:96 sc1
	s_waitcnt lgkmcnt(0)
	s_cbranch_vccnz .LBB0_663
	s_add_i32 s19, s17, s33
	s_cmpk_lt_i32 s19, 0x3000
	s_cselect_b64 s[20:21], -1, 0
	s_and_b64 s[22:23], s[20:21], exec
	s_cselect_b32 s17, s19, s17
	s_cmpk_gt_u32 s17, 0x1fff
	s_cbranch_scc1 .LBB0_678
	s_lshr_b32 s16, s17, 2
	s_and_b32 s16, s16, 0x7c0
	v_or_b32_e32 v0, s16, v84
	s_lshl_b32 s22, s17, 5
	v_lshlrev_b32_e32 v152, 15, v0
	s_and_b32 s22, s22, 0x1fe0
	v_lshl_add_u64 v[0:1], s[0:1], 0, v[152:153]
	s_lshl_b32 s72, s22, 2
	v_lshl_add_u64 v[0:1], v[0:1], 0, s[72:73]
	v_mov_b32_e32 v65, v153
	v_lshl_add_u64 v[70:71], v[0:1], 0, v[64:65]
	v_or_b32_e32 v0, s22, v85
	v_lshlrev_b32_e32 v152, 12, v0
	v_lshl_add_u64 v[0:1], s[2:3], 0, v[152:153]
	s_lshl_b32 s72, s16, 1
	v_lshl_add_u64 v[0:1], v[0:1], 0, s[72:73]
	v_mov_b32_e32 v67, v153
	s_lshl_b32 s72, s16, 2
	s_mov_b32 s29, 1
	v_lshl_add_u64 v[72:73], v[0:1], 0, v[66:67]
	v_lshl_add_u64 v[68:69], v[74:75], 0, s[72:73]
	s_movk_i32 s16, 0x2000
	s_and_b32 s22, s17, 0xfffff800
	s_cmpk_lg_i32 s22, 0x2000
	s_cbranch_scc0 .LBB0_679

; #define LAS __attribute__((address_space(3)))
; DI unsigned pk2(float a, float b) { f32x2 v = {a, b}; hbf16x2 r = __builtin_convertvector(v, hbf16x2); return __builtin_bit_cast(unsigned, r); }
; DI void ti_load(f32x4 (&v)[8], float (&g)[8], const TItem& ti) {
; #pragma unroll
;     for (int i = 0; i < 8; ++i) v[i] = *(const f32x4*)(ti.src + (size_t)(8 * i) * ti.N);
; #pragma unroll
;     for (int i = 0; i < 8; ++i) g[i] = ti.gp[8 * i];
; }
; DI void ti_finish(const f32x4 (&v)[8], const float (&g)[8], const TItem& ti, LAS float* scr, int lane) {
;     const int q8 = lane & 7, kr = lane >> 3;
; #pragma unroll
;     for (int i = 0; i < 8; ++i) *(LAS f32x4*)(scr + (8 * i + kr) * 36 + 4 * q8) = v[i] * (ti.hasg ? g[i] : 1.0f);
;     asm volatile("s_waitcnt lgkmcnt(0)" ::: "memory");
;     const int n = lane & 31, kc = lane >> 5;
; #pragma unroll
;     for (int p2 = 0; p2 < 4; ++p2) { const int c = 2 * p2 + kc; const LAS float* s = scr + (8 * c) * 36 + n;
;         u32x4 o; o.x = pk2(s[0], s[36]); o.y = pk2(s[72], s[108]); o.z = pk2(s[144], s[180]); o.w = pk2(s[216], s[252]);
;         *(u32x4*)(ti.dst + 16 * p2) = o; }
;     asm volatile("s_waitcnt lgkmcnt(0)" ::: "memory");
; }
.LBB0_691:
	s_lshl_b64 s[12:13], s[12:13], 5
	v_lshl_add_u64 v[0:1], v[82:83], 0, s[12:13]
	v_lshl_add_u64 v[2:3], v[0:1], 0, s[12:13]
	global_load_dwordx4 v[24:27], v[0:1], off
	global_load_dwordx4 v[20:23], v[2:3], off
	v_lshl_add_u64 v[0:1], v[2:3], 0, s[12:13]
	v_lshl_add_u64 v[2:3], v[0:1], 0, s[12:13]
	global_load_dwordx4 v[16:19], v[0:1], off
	global_load_dwordx4 v[12:15], v[2:3], off
	v_lshl_add_u64 v[0:1], v[2:3], 0, s[12:13]
	v_lshl_add_u64 v[8:9], v[0:1], 0, s[12:13]
	global_load_dwordx4 v[4:7], v[0:1], off
	s_nop 0
	global_load_dwordx4 v[0:3], v[8:9], off
	v_lshl_add_u64 v[8:9], v[8:9], 0, s[12:13]
	global_load_dwordx4 v[28:31], v[82:83], off
	s_nop 0
	global_load_dwordx4 v[8:11], v[8:9], off
	s_nop 0
	global_load_dword v99, v[86:87], off
	global_load_dword v98, v[86:87], off offset:32
	global_load_dword v97, v[86:87], off offset:64
	global_load_dword v96, v[86:87], off offset:96
	global_load_dword v95, v[86:87], off offset:128
	global_load_dword v94, v[86:87], off offset:160
	global_load_dword v93, v[86:87], off offset:192
	global_load_dword v92, v[86:87], off offset:224
	s_cmp_eq_u32 s7, 0
	s_cselect_b64 s[12:13], -1, 0
	s_waitcnt vmcnt(27)
	v_cndmask_b32_e64 v76, v107, 1.0, s[12:13]
	v_pk_mul_f32 v[62:63], v[62:63], v[76:77] op_sel_hi:[1,0]
	v_pk_mul_f32 v[60:61], v[60:61], v[76:77] op_sel_hi:[1,0]
	ds_write_b128 v90, v[60:63]
	s_waitcnt vmcnt(26)
	v_cndmask_b32_e64 v60, v106, 1.0, s[12:13]
	v_pk_mul_f32 v[58:59], v[58:59], v[60:61] op_sel_hi:[1,0]
	v_pk_mul_f32 v[56:57], v[56:57], v[60:61] op_sel_hi:[1,0]
	ds_write_b128 v90, v[56:59] offset:1152
	s_waitcnt vmcnt(25)
	v_cndmask_b32_e64 v56, v105, 1.0, s[12:13]
	v_pk_mul_f32 v[54:55], v[54:55], v[56:57] op_sel_hi:[1,0]
	v_pk_mul_f32 v[52:53], v[52:53], v[56:57] op_sel_hi:[1,0]
	ds_write_b128 v90, v[52:55] offset:2304
	s_waitcnt vmcnt(24)
	v_cndmask_b32_e64 v52, v104, 1.0, s[12:13]
	v_pk_mul_f32 v[50:51], v[50:51], v[52:53] op_sel_hi:[1,0]
	v_pk_mul_f32 v[48:49], v[48:49], v[52:53] op_sel_hi:[1,0]
	ds_write_b128 v90, v[48:51] offset:3456
	s_waitcnt vmcnt(23)
	v_cndmask_b32_e64 v48, v103, 1.0, s[12:13]
	v_pk_mul_f32 v[46:47], v[46:47], v[48:49] op_sel_hi:[1,0]
	v_pk_mul_f32 v[44:45], v[44:45], v[48:49] op_sel_hi:[1,0]
	ds_write_b128 v90, v[44:47] offset:4608
	s_waitcnt vmcnt(22)
	v_cndmask_b32_e64 v44, v102, 1.0, s[12:13]
	v_pk_mul_f32 v[42:43], v[42:43], v[44:45] op_sel_hi:[1,0]
	v_pk_mul_f32 v[40:41], v[40:41], v[44:45] op_sel_hi:[1,0]
	ds_write_b128 v90, v[40:43] offset:5760
	s_waitcnt vmcnt(21)
	v_cndmask_b32_e64 v40, v101, 1.0, s[12:13]
	v_pk_mul_f32 v[38:39], v[38:39], v[40:41] op_sel_hi:[1,0]
	v_pk_mul_f32 v[36:37], v[36:37], v[40:41] op_sel_hi:[1,0]
	ds_write_b128 v90, v[36:39] offset:6912
	s_waitcnt vmcnt(20)
	v_cndmask_b32_e64 v36, v100, 1.0, s[12:13]
	v_pk_mul_f32 v[34:35], v[34:35], v[36:37] op_sel_hi:[1,0]
	v_pk_mul_f32 v[32:33], v[32:33], v[36:37] op_sel_hi:[1,0]
	ds_write_b128 v90, v[32:35] offset:8064
	s_waitcnt lgkmcnt(0)
	ds_read2_b32 v[32:33], v91 offset1:36
	ds_read2_b32 v[34:35], v91 offset0:72 offset1:108
	ds_read2_b32 v[36:37], v91 offset0:144 offset1:180
	ds_read2_b32 v[38:39], v91 offset0:216 offset1:252
	v_readlane_b32 s10, v253, 54
	s_waitcnt lgkmcnt(3)
	v_cvt_pk_bf16_f32 v32, v32, v33
	s_waitcnt lgkmcnt(2)
	v_cvt_pk_bf16_f32 v33, v34, v35
	s_waitcnt lgkmcnt(1)
	v_cvt_pk_bf16_f32 v34, v36, v37
	s_waitcnt lgkmcnt(0)
	v_cvt_pk_bf16_f32 v35, v38, v39
	ds_read2_b32 v[36:37], v108 offset0:64 offset1:100
	ds_read2_b32 v[38:39], v108 offset0:136 offset1:172
	ds_read2_b32 v[40:41], v108 offset0:208 offset1:244
	ds_read2_b32 v[42:43], v110 offset0:24 offset1:60
	global_store_dwordx4 v[72:73], v[32:35], off sc1
	s_add_i32 s18, s18, s10
	s_add_i32 s10, s63, s18
	s_waitcnt lgkmcnt(3)
	v_cvt_pk_bf16_f32 v32, v36, v37
	s_waitcnt lgkmcnt(2)
	v_cvt_pk_bf16_f32 v33, v38, v39
	s_waitcnt lgkmcnt(1)
	v_cvt_pk_bf16_f32 v34, v40, v41
	s_waitcnt lgkmcnt(0)
	v_cvt_pk_bf16_f32 v35, v42, v43
	ds_read2_b32 v[36:37], v109 offset0:128 offset1:164
	ds_read2_b32 v[38:39], v109 offset0:200 offset1:236
	ds_read2_b32 v[40:41], v111 offset0:16 offset1:52
	ds_read2_b32 v[42:43], v111 offset0:88 offset1:124
	global_store_dwordx4 v[72:73], v[32:35], off offset:32 sc1
	s_cmpk_gt_i32 s10, 0x2fff
	s_cselect_b64 s[12:13], -1, 0
	s_waitcnt lgkmcnt(3)
	v_cvt_pk_bf16_f32 v32, v36, v37
	s_waitcnt lgkmcnt(2)
	v_cvt_pk_bf16_f32 v33, v38, v39
	s_waitcnt lgkmcnt(1)
	v_cvt_pk_bf16_f32 v34, v40, v41
	s_waitcnt lgkmcnt(0)
	v_cvt_pk_bf16_f32 v35, v42, v43
	ds_read2_b32 v[36:37], v113 offset0:192 offset1:228
	ds_read2_b32 v[38:39], v112 offset0:8 offset1:44
	ds_read2_b32 v[40:41], v112 offset0:80 offset1:116
	ds_read2_b32 v[42:43], v112 offset0:152 offset1:188
	global_store_dwordx4 v[72:73], v[32:35], off offset:64 sc1
	s_mov_b32 s19, s11
	s_mov_b32 s10, s14
	s_waitcnt lgkmcnt(3)
	v_cvt_pk_bf16_f32 v32, v36, v37
	s_waitcnt lgkmcnt(2)
	v_cvt_pk_bf16_f32 v33, v38, v39
	s_waitcnt lgkmcnt(1)
	v_cvt_pk_bf16_f32 v34, v40, v41
	s_waitcnt lgkmcnt(0)
	v_cvt_pk_bf16_f32 v35, v42, v43
	global_store_dwordx4 v[72:73], v[32:35], off offset:96 sc1
	s_waitcnt lgkmcnt(0)
	v_mov_b64_e32 v[80:81], v[86:87]
	v_mov_b64_e32 v[78:79], v[84:85]
	v_mov_b64_e32 v[76:77], v[82:83]

; #define LAS __attribute__((address_space(3)))
; DI unsigned pk2(float a, float b) { f32x2 v = {a, b}; hbf16x2 r = __builtin_convertvector(v, hbf16x2); return __builtin_bit_cast(unsigned, r); }
; template <int NS>
; DI void ti_decode(TItem& ti, int it, const CStack (&st)[NS], int lane) {
;     int base = 0;
; #pragma unroll
;     for (int j = 0; j < NS; ++j) {
;         const int nblk = st[j].N / 32, per = (st[j].K / 64) * nblk, tot = st[j].L * per;
;         if (it >= base && (it < base + tot || j == NS - 1)) {
;             const int K = st[j].K, N = st[j].N, r0 = it - base, l = r0 / per, rem = r0 - l * per, kb = rem / nblk, nb = rem - kb * nblk, k0 = 64 * kb;
;             ti.src = st[j].W + (size_t)l * K * N + (size_t)(k0 + (lane >> 3)) * N + (st[j].perm ? even_src32(nb) : 32 * nb) + 4 * (lane & 7);
;             ti.dst = st[j].WT + (size_t)l * K * N + (size_t)(32 * nb + (lane & 31)) * K + k0 + 8 * (lane >> 5);
;             ti.hasg = st[j].gk != nullptr; ti.gp = ti.hasg ? st[j].gk + (size_t)l * st[j].gstride + k0 + (lane >> 3) : ti.src;
;             ti.N = N;
;         }
; DI void ti_load(f32x4 (&v)[8], float (&g)[8], const TItem& ti) {
; #pragma unroll
;     for (int i = 0; i < 8; ++i) v[i] = *(const f32x4*)(ti.src + (size_t)(8 * i) * ti.N);
; #pragma unroll
;     for (int i = 0; i < 8; ++i) g[i] = ti.gp[8 * i];
; }
; DI void ti_finish(const f32x4 (&v)[8], const float (&g)[8], const TItem& ti, LAS float* scr, int lane) {
;     const int q8 = lane & 7, kr = lane >> 3;
; #pragma unroll
;     for (int i = 0; i < 8; ++i) *(LAS f32x4*)(scr + (8 * i + kr) * 36 + 4 * q8) = v[i] * (ti.hasg ? g[i] : 1.0f);
;     asm volatile("s_waitcnt lgkmcnt(0)" ::: "memory");
;     const int n = lane & 31, kc = lane >> 5;
; #pragma unroll
;     for (int p2 = 0; p2 < 4; ++p2) { const int c = 2 * p2 + kc; const LAS float* s = scr + (8 * c) * 36 + n;
;         u32x4 o; o.x = pk2(s[0], s[36]); o.y = pk2(s[72], s[108]); o.z = pk2(s[144], s[180]); o.w = pk2(s[216], s[252]);
;         *(u32x4*)(ti.dst + 16 * p2) = o; }
;     asm volatile("s_waitcnt lgkmcnt(0)" ::: "memory");
; }
.LBB0_700:
	s_lshl_b64 s[14:15], s[14:15], 5
	v_lshl_add_u64 v[32:33], v[70:71], 0, s[14:15]
	v_lshl_add_u64 v[34:35], v[32:33], 0, s[14:15]
	global_load_dwordx4 v[56:59], v[32:33], off
	global_load_dwordx4 v[52:55], v[34:35], off
	v_lshl_add_u64 v[32:33], v[34:35], 0, s[14:15]
	v_lshl_add_u64 v[34:35], v[32:33], 0, s[14:15]
	global_load_dwordx4 v[48:51], v[32:33], off
	global_load_dwordx4 v[44:47], v[34:35], off
	v_lshl_add_u64 v[32:33], v[34:35], 0, s[14:15]
	v_lshl_add_u64 v[34:35], v[32:33], 0, s[14:15]
	global_load_dwordx4 v[40:43], v[32:33], off
	global_load_dwordx4 v[36:39], v[34:35], off
	v_lshl_add_u64 v[32:33], v[34:35], 0, s[14:15]
	global_load_dwordx4 v[60:63], v[70:71], off
	s_nop 0
	global_load_dwordx4 v[32:35], v[32:33], off
	s_nop 0
	global_load_dword v107, v[74:75], off
	global_load_dword v106, v[74:75], off offset:32
	global_load_dword v105, v[74:75], off offset:64
	global_load_dword v104, v[74:75], off offset:96
	global_load_dword v103, v[74:75], off offset:128
	global_load_dword v102, v[74:75], off offset:160
	global_load_dword v101, v[74:75], off offset:192
	global_load_dword v100, v[74:75], off offset:224
	s_cmp_eq_u32 s19, 0
	s_cselect_b64 s[14:15], -1, 0
	s_waitcnt vmcnt(23)
	v_cndmask_b32_e64 v82, v99, 1.0, s[14:15]
	v_pk_mul_f32 v[30:31], v[30:31], v[82:83] op_sel_hi:[1,0]
	v_pk_mul_f32 v[28:29], v[28:29], v[82:83] op_sel_hi:[1,0]
	ds_write_b128 v90, v[28:31]
	s_waitcnt vmcnt(22)
	v_cndmask_b32_e64 v28, v98, 1.0, s[14:15]
	v_pk_mul_f32 v[26:27], v[26:27], v[28:29] op_sel_hi:[1,0]
	v_pk_mul_f32 v[24:25], v[24:25], v[28:29] op_sel_hi:[1,0]
	ds_write_b128 v90, v[24:27] offset:1152
	s_waitcnt vmcnt(21)
	v_cndmask_b32_e64 v24, v97, 1.0, s[14:15]
	v_pk_mul_f32 v[22:23], v[22:23], v[24:25] op_sel_hi:[1,0]
	v_pk_mul_f32 v[20:21], v[20:21], v[24:25] op_sel_hi:[1,0]
	ds_write_b128 v90, v[20:23] offset:2304
	s_waitcnt vmcnt(20)
	v_cndmask_b32_e64 v20, v96, 1.0, s[14:15]
	v_pk_mul_f32 v[18:19], v[18:19], v[20:21] op_sel_hi:[1,0]
	v_pk_mul_f32 v[16:17], v[16:17], v[20:21] op_sel_hi:[1,0]
	ds_write_b128 v90, v[16:19] offset:3456
	s_waitcnt vmcnt(19)
	v_cndmask_b32_e64 v16, v95, 1.0, s[14:15]
	v_pk_mul_f32 v[14:15], v[14:15], v[16:17] op_sel_hi:[1,0]
	v_pk_mul_f32 v[12:13], v[12:13], v[16:17] op_sel_hi:[1,0]
	ds_write_b128 v90, v[12:15] offset:4608
	s_waitcnt vmcnt(18)
	v_cndmask_b32_e64 v12, v94, 1.0, s[14:15]
	v_pk_mul_f32 v[6:7], v[6:7], v[12:13] op_sel_hi:[1,0]
	v_pk_mul_f32 v[4:5], v[4:5], v[12:13] op_sel_hi:[1,0]
	ds_write_b128 v90, v[4:7] offset:5760
	s_waitcnt vmcnt(17)
	v_cndmask_b32_e64 v4, v93, 1.0, s[14:15]
	v_pk_mul_f32 v[2:3], v[2:3], v[4:5] op_sel_hi:[1,0]
	v_pk_mul_f32 v[0:1], v[0:1], v[4:5] op_sel_hi:[1,0]
	ds_write_b128 v90, v[0:3] offset:6912
	s_waitcnt vmcnt(16)
	v_cndmask_b32_e64 v0, v92, 1.0, s[14:15]
	v_pk_mul_f32 v[2:3], v[10:11], v[0:1] op_sel_hi:[1,0]
	v_pk_mul_f32 v[0:1], v[8:9], v[0:1] op_sel_hi:[1,0]
	ds_write_b128 v90, v[0:3] offset:8064
	s_waitcnt lgkmcnt(0)
	ds_read2_b32 v[0:1], v91 offset1:36
	ds_read2_b32 v[2:3], v91 offset0:72 offset1:108
	ds_read2_b32 v[4:5], v91 offset0:144 offset1:180
	ds_read2_b32 v[6:7], v91 offset0:216 offset1:252
	v_add_u32_e32 v108, 0x800, v91
	v_add_u32_e32 v110, 0xc00, v91
	s_waitcnt lgkmcnt(3)
	v_cvt_pk_bf16_f32 v0, v0, v1
	s_waitcnt lgkmcnt(2)
	v_cvt_pk_bf16_f32 v1, v2, v3
	s_waitcnt lgkmcnt(1)
	v_cvt_pk_bf16_f32 v2, v4, v5
	s_waitcnt lgkmcnt(0)
	v_cvt_pk_bf16_f32 v3, v6, v7
	ds_read2_b32 v[4:5], v108 offset0:64 offset1:100
	ds_read2_b32 v[6:7], v108 offset0:136 offset1:172
	ds_read2_b32 v[8:9], v108 offset0:208 offset1:244
	ds_read2_b32 v[10:11], v110 offset0:24 offset1:60
	global_store_dwordx4 v[78:79], v[0:3], off sc1
	v_add_u32_e32 v109, 0x1000, v91
	v_add_u32_e32 v111, 0x1400, v91
	s_waitcnt lgkmcnt(3)
	v_cvt_pk_bf16_f32 v0, v4, v5
	s_waitcnt lgkmcnt(2)
	v_cvt_pk_bf16_f32 v1, v6, v7
	s_waitcnt lgkmcnt(1)
	v_cvt_pk_bf16_f32 v2, v8, v9
	s_waitcnt lgkmcnt(0)
	v_cvt_pk_bf16_f32 v3, v10, v11
	ds_read2_b32 v[4:5], v109 offset0:128 offset1:164
	ds_read2_b32 v[6:7], v109 offset0:200 offset1:236
	ds_read2_b32 v[8:9], v111 offset0:16 offset1:52
	ds_read2_b32 v[10:11], v111 offset0:88 offset1:124
	global_store_dwordx4 v[78:79], v[0:3], off offset:32 sc1
	v_add_u32_e32 v113, 0x1800, v91
	v_add_u32_e32 v112, 0x1c00, v91
	s_waitcnt lgkmcnt(3)
	v_cvt_pk_bf16_f32 v0, v4, v5
	s_waitcnt lgkmcnt(2)
	v_cvt_pk_bf16_f32 v1, v6, v7
	s_waitcnt lgkmcnt(1)
	v_cvt_pk_bf16_f32 v2, v8, v9
	s_waitcnt lgkmcnt(0)
	v_cvt_pk_bf16_f32 v3, v10, v11
	ds_read2_b32 v[4:5], v113 offset0:192 offset1:228
	ds_read2_b32 v[6:7], v112 offset0:8 offset1:44
	ds_read2_b32 v[8:9], v112 offset0:80 offset1:116
	ds_read2_b32 v[10:11], v112 offset0:152 offset1:188
	global_store_dwordx4 v[78:79], v[0:3], off offset:64 sc1
	s_andn2_b64 vcc, exec, s[12:13]
	s_mov_b64 s[12:13], -1
	s_waitcnt lgkmcnt(3)
	v_cvt_pk_bf16_f32 v0, v4, v5
	s_waitcnt lgkmcnt(2)
	v_cvt_pk_bf16_f32 v1, v6, v7
	s_waitcnt lgkmcnt(1)
	v_cvt_pk_bf16_f32 v2, v8, v9
	s_waitcnt lgkmcnt(0)
	v_cvt_pk_bf16_f32 v3, v10, v11
	global_store_dwordx4 v[78:79], v[0:3], off offset:96 sc1
	s_waitcnt lgkmcnt(0)
	s_cbranch_vccnz .LBB0_692
	v_readlane_b32 s12, v253, 55
	s_add_i32 s12, s12, s18
	s_cmpk_lt_i32 s12, 0x3000
	s_cselect_b32 s11, s12, s11
	s_cmpk_gt_u32 s11, 0x1fff
	s_cbranch_scc1 .LBB0_703
	s_and_b32 s10, s11, 0x1fc0
	v_or_b32_e32 v0, s10, v88
	s_lshl_b32 s12, s11, 5
	v_lshlrev_b32_e32 v152, 13, v0
	s_and_b32 s12, s12, 0x7e0
	v_lshl_add_u64 v[0:1], s[0:1], 0, v[152:153]
	s_lshl_b32 s72, s12, 2
	v_lshl_add_u64 v[0:1], v[0:1], 0, s[72:73]
	v_mov_b32_e32 v65, v153
	v_lshl_add_u64 v[76:77], v[0:1], 0, v[64:65]
	v_or_b32_e32 v0, s12, v89
	v_lshlrev_b32_e32 v152, 14, v0
	v_lshl_add_u64 v[0:1], s[2:3], 0, v[152:153]
	s_lshl_b32 s72, s10, 1
	v_lshl_add_u64 v[0:1], v[0:1], 0, s[72:73]
	v_mov_b32_e32 v67, v153
	v_lshl_add_u64 v[78:79], v[0:1], 0, v[66:67]
	s_mov_b32 s19, 0
	s_movk_i32 s10, 0x800
	v_mov_b64_e32 v[80:81], v[76:77]

; DI void conv_prompt(const bf16* GB, const bf16* Z, const float* cw, bf16* CAT, int gtid, int GT) {
;     for (int it = gtid; it < (MP / 8) * 128; it += GT) {
;         const int c = (it & 127) * 8, r = (it >> 7) * 8, pos = r & (SEQL - 1);
;         u32x4 zr[10], gr[8];
; #pragma unroll
;         for (int k = 0; k < 10; ++k) { const bool ok = (k >= 2 || pos > 0); const unsigned msk = ok ? 0xffffffffu : 0u; zr[k] = *(const u32x4*)(Z + (size_t)(ok ? r - 2 + k : r) * 1024 + c); zr[k] = zr[k] & msk; }
; #pragma unroll
;         for (int k = 0; k < 8; ++k) gr[k] = *(const u32x4*)(GB + (size_t)(r + k) * 1024 + c);
;         float w0[8], w1[8], w2[8];
; #pragma unroll
;         for (int e = 0; e < 8; ++e) { w0[e] = cw[c + e]; w1[e] = cw[1024 + c + e]; w2[e] = cw[2048 + c + e]; }
;         float za[8], zb[8], zc[8];
.LBB0_783:
	v_ashrrev_i32_e32 v28, 4, v108
	v_and_b32_e32 v104, -8, v28
	v_and_b32_e32 v0, 0x7f80, v108
	v_cmp_ne_u32_e32 vcc, 0, v0
	v_add_u32_e32 v0, -2, v104
	v_and_b32_e32 v70, 0x3f8, v107
	v_cndmask_b32_e32 v0, v104, v0, vcc
	v_lshlrev_b32_e32 v152, 1, v70
	v_ashrrev_i32_e32 v1, 31, v0
	v_lshl_add_u64 v[4:5], s[8:9], 0, v[152:153]
	v_lshlrev_b64 v[0:1], 11, v[0:1]
	v_lshl_add_u64 v[0:1], v[4:5], 0, v[0:1]
	global_load_dwordx4 v[0:3], v[0:1], off
	v_ashrrev_i32_e32 v105, 31, v104
	v_or_b32_e32 v102, 1, v104
	v_lshlrev_b64 v[6:7], 11, v[104:105]
	v_ashrrev_i32_e32 v103, 31, v102
	v_or_b32_e32 v100, 2, v104
	v_lshlrev_b64 v[12:13], 11, v[102:103]
	v_ashrrev_i32_e32 v101, 31, v100
	v_or_b32_e32 v98, 3, v104
	v_lshlrev_b64 v[14:15], 11, v[100:101]
	v_ashrrev_i32_e32 v99, 31, v98
	v_or_b32_e32 v96, 4, v104
	v_lshlrev_b64 v[20:21], 11, v[98:99]
	v_ashrrev_i32_e32 v97, 31, v96
	v_or_b32_e32 v94, 5, v104
	v_lshlrev_b64 v[22:23], 11, v[96:97]
	v_ashrrev_i32_e32 v95, 31, v94
	v_or_b32_e32 v92, 6, v104
	v_lshlrev_b64 v[64:65], 11, v[94:95]
	v_ashrrev_i32_e32 v93, 31, v92
	v_or_b32_e32 v90, 7, v28
	v_lshlrev_b64 v[66:67], 11, v[92:93]
	v_ashrrev_i32_e32 v91, 31, v90
	v_lshlrev_b64 v[68:69], 11, v[90:91]
	v_add_u32_e32 v108, s59, v108
	v_add_u32_e32 v107, s11, v107
	s_waitcnt vmcnt(0)
	v_cndmask_b32_e32 v111, 0, v0, vcc
	v_subbrev_co_u32_e64 v0, s[0:1], 0, v104, vcc
	v_cndmask_b32_e32 v126, 0, v1, vcc
	v_ashrrev_i32_e32 v1, 31, v0
	v_lshlrev_b64 v[0:1], 11, v[0:1]
	v_lshl_add_u64 v[0:1], v[4:5], 0, v[0:1]
	v_cndmask_b32_e32 v109, 0, v3, vcc
	v_cndmask_b32_e32 v120, 0, v2, vcc
	global_load_dwordx4 v[0:3], v[0:1], off
	s_mov_b64 s[0:1], 0x2000
	v_lshlrev_b32_e32 v110, 16, v111
	v_and_b32_e32 v111, 0xffff0000, v111
	s_waitcnt vmcnt(0)
	v_cndmask_b32_e32 v127, 0, v1, vcc
	v_cndmask_b32_e32 v113, 0, v0, vcc
	v_lshl_add_u64 v[0:1], v[4:5], 0, v[6:7]
	global_load_dwordx4 v[56:59], v[0:1], off
	v_lshl_add_u64 v[0:1], v[4:5], 0, v[12:13]
	global_load_dwordx4 v[48:51], v[0:1], off
	v_lshl_add_u64 v[0:1], v[4:5], 0, v[14:15]
	global_load_dwordx4 v[40:43], v[0:1], off
	v_lshl_add_u64 v[0:1], v[4:5], 0, v[20:21]
	global_load_dwordx4 v[32:35], v[0:1], off
	v_lshl_add_u64 v[0:1], v[4:5], 0, v[22:23]
	global_load_dwordx4 v[24:27], v[0:1], off
	v_lshl_add_u64 v[0:1], v[4:5], 0, v[64:65]
	global_load_dwordx4 v[16:19], v[0:1], off
	v_lshl_add_u64 v[0:1], v[4:5], 0, v[66:67]
	global_load_dwordx4 v[8:11], v[0:1], off
	v_lshl_add_u64 v[0:1], v[4:5], 0, v[68:69]
	v_lshl_add_u64 v[4:5], s[6:7], 0, v[152:153]
	v_lshl_add_u64 v[6:7], v[4:5], 0, v[6:7]
	global_load_dwordx4 v[60:63], v[6:7], off
	v_lshl_add_u64 v[6:7], v[4:5], 0, v[12:13]
	global_load_dwordx4 v[52:55], v[6:7], off
	v_lshl_add_u64 v[6:7], v[4:5], 0, v[14:15]
	global_load_dwordx4 v[44:47], v[6:7], off
	v_lshl_add_u64 v[6:7], v[4:5], 0, v[20:21]
	global_load_dwordx4 v[36:39], v[6:7], off
	v_lshl_add_u64 v[6:7], v[4:5], 0, v[22:23]
	global_load_dwordx4 v[28:31], v[6:7], off
	v_lshl_add_u64 v[6:7], v[4:5], 0, v[64:65]
	global_load_dwordx4 v[20:23], v[6:7], off
	v_lshl_add_u64 v[6:7], v[4:5], 0, v[66:67]
	v_lshl_add_u64 v[4:5], v[4:5], 0, v[68:69]
	v_lshlrev_b32_e32 v68, 2, v70
	v_mov_b32_e32 v69, v153
	v_lshl_add_u64 v[70:71], s[4:5], 0, v[68:69]
	v_cndmask_b32_e32 v128, 0, v3, vcc
	v_cndmask_b32_e32 v121, 0, v2, vcc
	global_load_dwordx4 v[0:3], v[0:1], off
	v_add_co_u32_e32 v84, vcc, s29, v70
	global_load_dwordx4 v[12:15], v[6:7], off
	v_lshl_add_u64 v[72:73], v[70:71], 0, s[34:35]
	global_load_dwordx4 v[4:7], v[4:5], off
	s_nop 0
	global_load_dwordx4 v[64:67], v68, s[4:5] offset:16
	global_load_dwordx4 v[76:79], v68, s[4:5]
	v_lshl_add_u64 v[74:75], v[70:71], 0, s[0:1]
	v_addc_co_u32_e32 v85, vcc, 0, v71, vcc
	global_load_dwordx4 v[80:83], v[84:85], off offset:-4096
	global_load_dwordx4 v[68:71], v[72:73], off offset:16
	s_nop 0
	global_load_dwordx4 v[84:87], v[84:85], off
	s_nop 0
	global_load_dwordx4 v[72:75], v[74:75], off offset:16
	v_lshlrev_b32_e32 v112, 16, v113
	v_and_b32_e32 v113, 0xffff0000, v113
	s_mov_b32 s0, 0x1ffff
	v_cmp_lt_i32_e32 vcc, s0, v108
	s_or_b64 s[12:13], vcc, s[12:13]
	s_waitcnt vmcnt(21)
	v_lshlrev_b32_e32 v114, 16, v56
	v_and_b32_e32 v115, 0xffff0000, v56
	v_and_b32_e32 v129, 0xffff0000, v59
	s_waitcnt vmcnt(14)
	v_lshlrev_b32_e32 v116, 16, v60
	v_and_b32_e32 v117, 0xffff0000, v60
	v_lshlrev_b32_e32 v122, 16, v62
	v_and_b32_e32 v123, 0xffff0000, v62
	v_lshlrev_b32_e32 v56, 16, v61
	s_waitcnt vmcnt(3)
	v_pk_mul_f32 v[118:119], v[80:81], v[112:113]
	s_nop 0
	v_pk_fma_f32 v[110:111], v[76:77], v[110:111], v[118:119]
	v_lshlrev_b32_e32 v118, 16, v121
	s_waitcnt vmcnt(1)
	v_pk_fma_f32 v[110:111], v[84:85], v[114:115], v[110:111]
	v_and_b32_e32 v119, 0xffff0000, v121
	v_pk_mul_f32 v[110:111], v[110:111], v[116:117]
	v_lshlrev_b32_e32 v116, 16, v120
	v_and_b32_e32 v117, 0xffff0000, v120
	v_pk_mul_f32 v[124:125], v[68:69], v[118:119]
	v_lshlrev_b32_e32 v120, 16, v58
	v_and_b32_e32 v121, 0xffff0000, v58
	v_pk_fma_f32 v[116:117], v[64:65], v[116:117], v[124:125]
	v_lshlrev_b32_e32 v124, 16, v127
	s_waitcnt vmcnt(0)
; DI u32x4 pk8(f32x4 a, f32x4 b) { u32x4 w; w.x = pk2(a[0], a[1]); w.y = pk2(a[2], a[3]); w.z = pk2(b[0], b[1]); w.w = pk2(b[2], b[3]); return w; }
; DI void conv_prompt(const bf16* GB, const bf16* Z, const float* cw, bf16* CAT, int gtid, int GT) {
;     ...
;         unpack8(zr[0], za); unpack8(zr[1], zb);
; #pragma unroll
;         for (int k = 0; k < 8; ++k) {
;             float g[8]; unpack8(zr[k + 2], zc); unpack8(gr[k], g);
;             f32x4 oa, ob;
; #pragma unroll
;             for (int e = 0; e < 4; ++e) { oa[e] = g[e] * (w0[e] * za[e] + w1[e] * zb[e] + w2[e] * zc[e]); ob[e] = g[4 + e] * (w0[4 + e] * za[4 + e] + w1[4 + e] * zb[4 + e] + w2[4 + e] * zc[4 + e]); }
;             *(u32x4*)(CAT + (size_t)(r + k) * DM + 1024 + c) = pk8(oa, ob);
; #pragma unroll
;             for (int e = 0; e < 8; ++e) { za[e] = zb[e]; zb[e] = zc[e]; }
;         }
	v_pk_fma_f32 v[116:117], v[72:73], v[120:121], v[116:117]
	v_and_b32_e32 v125, 0xffff0000, v127
	v_pk_mul_f32 v[116:117], v[116:117], v[122:123]
	v_lshlrev_b32_e32 v122, 16, v126
	v_and_b32_e32 v123, 0xffff0000, v126
	v_lshlrev_b32_e32 v126, 16, v57
	v_and_b32_e32 v127, 0xffff0000, v57
	v_and_b32_e32 v57, 0xffff0000, v61
	v_pk_mul_f32 v[60:61], v[82:83], v[124:125]
	v_lshlrev_b32_e32 v58, 16, v63
	v_pk_fma_f32 v[60:61], v[78:79], v[122:123], v[60:61]
	v_lshlrev_b32_e32 v122, 16, v128
	v_pk_fma_f32 v[60:61], v[86:87], v[126:127], v[60:61]
	v_and_b32_e32 v123, 0xffff0000, v128
	v_pk_mul_f32 v[60:61], v[60:61], v[56:57]
	v_lshlrev_b32_e32 v56, 16, v109
	v_and_b32_e32 v57, 0xffff0000, v109
	v_lshlrev_b32_e32 v128, 16, v59
	v_and_b32_e32 v59, 0xffff0000, v63
	v_pk_mul_f32 v[62:63], v[70:71], v[122:123]
	s_nop 0
	v_pk_fma_f32 v[56:57], v[66:67], v[56:57], v[62:63]
	s_nop 0
	v_pk_fma_f32 v[56:57], v[74:75], v[128:129], v[56:57]
	s_nop 0
	v_pk_mul_f32 v[62:63], v[56:57], v[58:59]
	v_cvt_pk_bf16_f32 v57, v60, v61
	v_lshlrev_b64 v[60:61], 12, v[104:105]
	v_lshl_add_u64 v[60:61], s[86:87], 0, v[60:61]
	v_cvt_pk_bf16_f32 v56, v110, v111
	v_cvt_pk_bf16_f32 v58, v116, v117
	v_cvt_pk_bf16_f32 v59, v62, v63
	v_lshl_add_u64 v[60:61], v[60:61], 0, v[152:153]
	global_store_dwordx4 v[60:61], v[56:59], off offset:2048 sc1
	v_pk_mul_f32 v[60:61], v[80:81], v[114:115]
	v_pk_mul_f32 v[104:105], v[68:69], v[120:121]
	v_lshlrev_b32_e32 v56, 16, v48
	v_and_b32_e32 v57, 0xffff0000, v48
	v_pk_fma_f32 v[60:61], v[76:77], v[112:113], v[60:61]
	v_lshlrev_b32_e32 v58, 16, v52
	v_and_b32_e32 v59, 0xffff0000, v52
	v_pk_fma_f32 v[60:61], v[84:85], v[56:57], v[60:61]
	v_pk_fma_f32 v[104:105], v[64:65], v[118:119], v[104:105]
	v_pk_mul_f32 v[58:59], v[60:61], v[58:59]
	v_lshlrev_b32_e32 v60, 16, v50
	v_and_b32_e32 v61, 0xffff0000, v50
	v_lshlrev_b32_e32 v62, 16, v54
	v_and_b32_e32 v63, 0xffff0000, v54
	v_pk_fma_f32 v[104:105], v[72:73], v[60:61], v[104:105]
	v_lshlrev_b32_e32 v48, 16, v53
	v_pk_mul_f32 v[62:63], v[104:105], v[62:63]
	v_lshlrev_b32_e32 v104, 16, v49
	v_and_b32_e32 v105, 0xffff0000, v49
	v_and_b32_e32 v49, 0xffff0000, v53
	v_pk_mul_f32 v[52:53], v[82:83], v[126:127]
	v_lshlrev_b32_e32 v110, 16, v51
	v_pk_fma_f32 v[52:53], v[78:79], v[124:125], v[52:53]
	v_and_b32_e32 v111, 0xffff0000, v51
	v_pk_mul_f32 v[50:51], v[70:71], v[128:129]
	v_pk_fma_f32 v[52:53], v[86:87], v[104:105], v[52:53]
	v_pk_fma_f32 v[50:51], v[66:67], v[122:123], v[50:51]
	v_pk_mul_f32 v[52:53], v[52:53], v[48:49]
	v_lshlrev_b32_e32 v48, 16, v55
	v_and_b32_e32 v49, 0xffff0000, v55
	v_pk_fma_f32 v[50:51], v[74:75], v[110:111], v[50:51]
	s_nop 0
	v_pk_mul_f32 v[54:55], v[50:51], v[48:49]
	v_cvt_pk_bf16_f32 v49, v52, v53
	v_lshlrev_b64 v[52:53], 12, v[102:103]
	v_lshl_add_u64 v[52:53], s[86:87], 0, v[52:53]
	v_cvt_pk_bf16_f32 v48, v58, v59
	v_cvt_pk_bf16_f32 v50, v62, v63
	v_cvt_pk_bf16_f32 v51, v54, v55
	v_lshl_add_u64 v[52:53], v[52:53], 0, v[152:153]
	global_store_dwordx4 v[52:53], v[48:51], off offset:2048 sc1
	v_pk_mul_f32 v[52:53], v[80:81], v[56:57]
	v_pk_mul_f32 v[58:59], v[68:69], v[60:61]
	v_lshlrev_b32_e32 v48, 16, v40
	v_and_b32_e32 v49, 0xffff0000, v40
	v_pk_fma_f32 v[52:53], v[76:77], v[114:115], v[52:53]
	v_lshlrev_b32_e32 v50, 16, v44
	v_and_b32_e32 v51, 0xffff0000, v44
	v_pk_fma_f32 v[52:53], v[84:85], v[48:49], v[52:53]
	v_pk_fma_f32 v[58:59], v[64:65], v[120:121], v[58:59]
	v_pk_mul_f32 v[50:51], v[52:53], v[50:51]
	v_lshlrev_b32_e32 v52, 16, v42
	v_and_b32_e32 v53, 0xffff0000, v42
	v_lshlrev_b32_e32 v54, 16, v46
	v_and_b32_e32 v55, 0xffff0000, v46
	v_pk_fma_f32 v[58:59], v[72:73], v[52:53], v[58:59]
	v_lshlrev_b32_e32 v40, 16, v45
	v_pk_mul_f32 v[54:55], v[58:59], v[54:55]
	v_lshlrev_b32_e32 v58, 16, v41
	v_and_b32_e32 v59, 0xffff0000, v41
	v_and_b32_e32 v41, 0xffff0000, v45
	v_pk_mul_f32 v[44:45], v[82:83], v[104:105]
	v_lshlrev_b32_e32 v62, 16, v43
	v_pk_fma_f32 v[44:45], v[78:79], v[126:127], v[44:45]
	v_and_b32_e32 v63, 0xffff0000, v43
	v_pk_mul_f32 v[42:43], v[70:71], v[110:111]
	v_pk_fma_f32 v[44:45], v[86:87], v[58:59], v[44:45]
	v_pk_fma_f32 v[42:43], v[66:67], v[128:129], v[42:43]
	v_pk_mul_f32 v[44:45], v[44:45], v[40:41]
	v_lshlrev_b32_e32 v40, 16, v47
	v_and_b32_e32 v41, 0xffff0000, v47
	v_pk_fma_f32 v[42:43], v[74:75], v[62:63], v[42:43]
	s_nop 0
	v_pk_mul_f32 v[46:47], v[42:43], v[40:41]
	v_cvt_pk_bf16_f32 v41, v44, v45
	v_lshlrev_b64 v[44:45], 12, v[100:101]
	v_lshl_add_u64 v[44:45], s[86:87], 0, v[44:45]
	v_cvt_pk_bf16_f32 v40, v50, v51
	v_cvt_pk_bf16_f32 v42, v54, v55
	v_cvt_pk_bf16_f32 v43, v46, v47
	v_lshl_add_u64 v[44:45], v[44:45], 0, v[152:153]
	global_store_dwordx4 v[44:45], v[40:43], off offset:2048 sc1
	v_pk_mul_f32 v[44:45], v[80:81], v[48:49]
	v_pk_mul_f32 v[50:51], v[68:69], v[52:53]
	v_lshlrev_b32_e32 v40, 16, v32
	v_and_b32_e32 v41, 0xffff0000, v32
	v_pk_fma_f32 v[44:45], v[76:77], v[56:57], v[44:45]
	v_lshlrev_b32_e32 v42, 16, v36
	v_and_b32_e32 v43, 0xffff0000, v36
	v_pk_fma_f32 v[44:45], v[84:85], v[40:41], v[44:45]
	v_pk_fma_f32 v[50:51], v[64:65], v[60:61], v[50:51]
	v_pk_mul_f32 v[42:43], v[44:45], v[42:43]
	v_lshlrev_b32_e32 v44, 16, v34
	v_and_b32_e32 v45, 0xffff0000, v34
	v_lshlrev_b32_e32 v46, 16, v38
	v_and_b32_e32 v47, 0xffff0000, v38
	v_pk_fma_f32 v[50:51], v[72:73], v[44:45], v[50:51]
	v_lshlrev_b32_e32 v32, 16, v37
	v_pk_mul_f32 v[46:47], v[50:51], v[46:47]
	v_lshlrev_b32_e32 v50, 16, v33
	v_and_b32_e32 v51, 0xffff0000, v33
	v_and_b32_e32 v33, 0xffff0000, v37
	v_pk_mul_f32 v[36:37], v[82:83], v[58:59]
	v_lshlrev_b32_e32 v54, 16, v35
	v_pk_fma_f32 v[36:37], v[78:79], v[104:105], v[36:37]
	v_and_b32_e32 v55, 0xffff0000, v35
; DI u32x4 pk8(f32x4 a, f32x4 b) { u32x4 w; w.x = pk2(a[0], a[1]); w.y = pk2(a[2], a[3]); w.z = pk2(b[0], b[1]); w.w = pk2(b[2], b[3]); return w; }
; DI void conv_prompt(const bf16* GB, const bf16* Z, const float* cw, bf16* CAT, int gtid, int GT) {
;     ...
;         for (int k = 0; k < 8; ++k) {
;             float g[8]; unpack8(zr[k + 2], zc); unpack8(gr[k], g);
;             f32x4 oa, ob;
; #pragma unroll
;             for (int e = 0; e < 4; ++e) { oa[e] = g[e] * (w0[e] * za[e] + w1[e] * zb[e] + w2[e] * zc[e]); ob[e] = g[4 + e] * (w0[4 + e] * za[4 + e] + w1[4 + e] * zb[4 + e] + w2[4 + e] * zc[4 + e]); }
;             *(u32x4*)(CAT + (size_t)(r + k) * DM + 1024 + c) = pk8(oa, ob);
; #pragma unroll
;             for (int e = 0; e < 8; ++e) { za[e] = zb[e]; zb[e] = zc[e]; }
;         }
	v_pk_mul_f32 v[34:35], v[70:71], v[62:63]
	v_pk_fma_f32 v[36:37], v[86:87], v[50:51], v[36:37]
	v_pk_fma_f32 v[34:35], v[66:67], v[110:111], v[34:35]
	v_pk_mul_f32 v[36:37], v[36:37], v[32:33]
	v_lshlrev_b32_e32 v32, 16, v39
	v_and_b32_e32 v33, 0xffff0000, v39
	v_pk_fma_f32 v[34:35], v[74:75], v[54:55], v[34:35]
	s_nop 0
	v_pk_mul_f32 v[38:39], v[34:35], v[32:33]
	v_cvt_pk_bf16_f32 v33, v36, v37
	v_lshlrev_b64 v[36:37], 12, v[98:99]
	v_lshl_add_u64 v[36:37], s[86:87], 0, v[36:37]
	v_cvt_pk_bf16_f32 v32, v42, v43
	v_cvt_pk_bf16_f32 v34, v46, v47
	v_cvt_pk_bf16_f32 v35, v38, v39
	v_lshl_add_u64 v[36:37], v[36:37], 0, v[152:153]
	global_store_dwordx4 v[36:37], v[32:35], off offset:2048 sc1
	v_pk_mul_f32 v[36:37], v[80:81], v[40:41]
	v_pk_mul_f32 v[42:43], v[68:69], v[44:45]
	v_lshlrev_b32_e32 v32, 16, v24
	v_and_b32_e32 v33, 0xffff0000, v24
	v_pk_fma_f32 v[36:37], v[76:77], v[48:49], v[36:37]
	v_lshlrev_b32_e32 v34, 16, v28
	v_and_b32_e32 v35, 0xffff0000, v28
	v_pk_fma_f32 v[36:37], v[84:85], v[32:33], v[36:37]
	v_pk_fma_f32 v[42:43], v[64:65], v[52:53], v[42:43]
	v_pk_mul_f32 v[34:35], v[36:37], v[34:35]
	v_lshlrev_b32_e32 v36, 16, v26
	v_and_b32_e32 v37, 0xffff0000, v26
	v_lshlrev_b32_e32 v38, 16, v30
	v_and_b32_e32 v39, 0xffff0000, v30
	v_pk_fma_f32 v[42:43], v[72:73], v[36:37], v[42:43]
	v_lshlrev_b32_e32 v24, 16, v29
	v_pk_mul_f32 v[38:39], v[42:43], v[38:39]
	v_lshlrev_b32_e32 v42, 16, v25
	v_and_b32_e32 v43, 0xffff0000, v25
	v_and_b32_e32 v25, 0xffff0000, v29
	v_pk_mul_f32 v[28:29], v[82:83], v[50:51]
	v_lshlrev_b32_e32 v46, 16, v27
	v_pk_fma_f32 v[28:29], v[78:79], v[58:59], v[28:29]
	v_and_b32_e32 v47, 0xffff0000, v27
	v_pk_mul_f32 v[26:27], v[70:71], v[54:55]
	v_pk_fma_f32 v[28:29], v[86:87], v[42:43], v[28:29]
	v_pk_fma_f32 v[26:27], v[66:67], v[62:63], v[26:27]
	v_pk_mul_f32 v[28:29], v[28:29], v[24:25]
	v_lshlrev_b32_e32 v24, 16, v31
	v_and_b32_e32 v25, 0xffff0000, v31
	v_pk_fma_f32 v[26:27], v[74:75], v[46:47], v[26:27]
	s_nop 0
	v_pk_mul_f32 v[30:31], v[26:27], v[24:25]
	v_cvt_pk_bf16_f32 v25, v28, v29
	v_lshlrev_b64 v[28:29], 12, v[96:97]
	v_lshl_add_u64 v[28:29], s[86:87], 0, v[28:29]
	v_cvt_pk_bf16_f32 v24, v34, v35
	v_cvt_pk_bf16_f32 v26, v38, v39
	v_cvt_pk_bf16_f32 v27, v30, v31
	v_lshl_add_u64 v[28:29], v[28:29], 0, v[152:153]
	global_store_dwordx4 v[28:29], v[24:27], off offset:2048 sc1
	v_pk_mul_f32 v[28:29], v[80:81], v[32:33]
	v_pk_mul_f32 v[34:35], v[68:69], v[36:37]
	v_lshlrev_b32_e32 v24, 16, v16
	v_and_b32_e32 v25, 0xffff0000, v16
	v_pk_fma_f32 v[28:29], v[76:77], v[40:41], v[28:29]
	v_lshlrev_b32_e32 v26, 16, v20
	v_and_b32_e32 v27, 0xffff0000, v20
	v_pk_fma_f32 v[28:29], v[84:85], v[24:25], v[28:29]
	v_pk_fma_f32 v[34:35], v[64:65], v[44:45], v[34:35]
	v_pk_mul_f32 v[26:27], v[28:29], v[26:27]
	v_lshlrev_b32_e32 v28, 16, v18
	v_and_b32_e32 v29, 0xffff0000, v18
	v_lshlrev_b32_e32 v30, 16, v22
	v_and_b32_e32 v31, 0xffff0000, v22
	v_pk_fma_f32 v[34:35], v[72:73], v[28:29], v[34:35]
	v_lshlrev_b32_e32 v16, 16, v21
	v_pk_mul_f32 v[30:31], v[34:35], v[30:31]
	v_lshlrev_b32_e32 v34, 16, v17
	v_and_b32_e32 v35, 0xffff0000, v17
	v_and_b32_e32 v17, 0xffff0000, v21
	v_pk_mul_f32 v[20:21], v[82:83], v[42:43]
	v_lshlrev_b32_e32 v38, 16, v19
	v_pk_fma_f32 v[20:21], v[78:79], v[50:51], v[20:21]
	v_and_b32_e32 v39, 0xffff0000, v19
	v_pk_mul_f32 v[18:19], v[70:71], v[46:47]
	v_pk_fma_f32 v[20:21], v[86:87], v[34:35], v[20:21]
	v_pk_fma_f32 v[18:19], v[66:67], v[54:55], v[18:19]
	v_pk_mul_f32 v[20:21], v[20:21], v[16:17]
	v_lshlrev_b32_e32 v16, 16, v23
	v_and_b32_e32 v17, 0xffff0000, v23
	v_pk_fma_f32 v[18:19], v[74:75], v[38:39], v[18:19]
	s_nop 0
; DI u32x4 pk8(f32x4 a, f32x4 b) { u32x4 w; w.x = pk2(a[0], a[1]); w.y = pk2(a[2], a[3]); w.z = pk2(b[0], b[1]); w.w = pk2(b[2], b[3]); return w; }
; DI void conv_prompt(const bf16* GB, const bf16* Z, const float* cw, bf16* CAT, int gtid, int GT) {
;     ...
;         for (int k = 0; k < 8; ++k) {
;             float g[8]; unpack8(zr[k + 2], zc); unpack8(gr[k], g);
;             f32x4 oa, ob;
; #pragma unroll
;             for (int e = 0; e < 4; ++e) { oa[e] = g[e] * (w0[e] * za[e] + w1[e] * zb[e] + w2[e] * zc[e]); ob[e] = g[4 + e] * (w0[4 + e] * za[4 + e] + w1[4 + e] * zb[4 + e] + w2[4 + e] * zc[4 + e]); }
;             *(u32x4*)(CAT + (size_t)(r + k) * DM + 1024 + c) = pk8(oa, ob);
; #pragma unroll
;             for (int e = 0; e < 8; ++e) { za[e] = zb[e]; zb[e] = zc[e]; }
;         }
	v_pk_mul_f32 v[22:23], v[18:19], v[16:17]
	v_cvt_pk_bf16_f32 v17, v20, v21
	v_lshlrev_b64 v[20:21], 12, v[94:95]
	v_lshl_add_u64 v[20:21], s[86:87], 0, v[20:21]
	v_cvt_pk_bf16_f32 v16, v26, v27
	v_cvt_pk_bf16_f32 v18, v30, v31
	v_cvt_pk_bf16_f32 v19, v22, v23
	v_lshl_add_u64 v[20:21], v[20:21], 0, v[152:153]
	global_store_dwordx4 v[20:21], v[16:19], off offset:2048 sc1
	v_pk_mul_f32 v[20:21], v[80:81], v[24:25]
	v_pk_mul_f32 v[26:27], v[68:69], v[28:29]
	v_lshlrev_b32_e32 v16, 16, v8
	v_and_b32_e32 v17, 0xffff0000, v8
	v_pk_fma_f32 v[20:21], v[76:77], v[32:33], v[20:21]
	v_lshlrev_b32_e32 v18, 16, v12
	v_and_b32_e32 v19, 0xffff0000, v12
	v_pk_fma_f32 v[20:21], v[84:85], v[16:17], v[20:21]
	v_pk_fma_f32 v[26:27], v[64:65], v[36:37], v[26:27]
	v_pk_mul_f32 v[18:19], v[20:21], v[18:19]
	v_lshlrev_b32_e32 v20, 16, v10
	v_and_b32_e32 v21, 0xffff0000, v10
	v_lshlrev_b32_e32 v22, 16, v14
	v_and_b32_e32 v23, 0xffff0000, v14
	v_pk_fma_f32 v[26:27], v[72:73], v[20:21], v[26:27]
	v_lshlrev_b32_e32 v8, 16, v13
	v_pk_mul_f32 v[22:23], v[26:27], v[22:23]
	v_lshlrev_b32_e32 v26, 16, v9
	v_and_b32_e32 v27, 0xffff0000, v9
	v_and_b32_e32 v9, 0xffff0000, v13
	v_pk_mul_f32 v[12:13], v[82:83], v[34:35]
	v_lshlrev_b32_e32 v30, 16, v11
	v_pk_fma_f32 v[12:13], v[78:79], v[42:43], v[12:13]
	v_and_b32_e32 v31, 0xffff0000, v11
	v_pk_mul_f32 v[10:11], v[70:71], v[38:39]
	v_pk_fma_f32 v[12:13], v[86:87], v[26:27], v[12:13]
	v_pk_fma_f32 v[10:11], v[66:67], v[46:47], v[10:11]
	v_pk_mul_f32 v[12:13], v[12:13], v[8:9]
	v_lshlrev_b32_e32 v8, 16, v15
	v_and_b32_e32 v9, 0xffff0000, v15
	v_pk_fma_f32 v[10:11], v[74:75], v[30:31], v[10:11]
	s_nop 0
	v_pk_mul_f32 v[14:15], v[10:11], v[8:9]
	v_cvt_pk_bf16_f32 v9, v12, v13
	v_lshlrev_b64 v[12:13], 12, v[92:93]
	v_lshl_add_u64 v[12:13], s[86:87], 0, v[12:13]
	v_cvt_pk_bf16_f32 v8, v18, v19
	v_cvt_pk_bf16_f32 v10, v22, v23
	v_cvt_pk_bf16_f32 v11, v14, v15
	v_lshl_add_u64 v[12:13], v[12:13], 0, v[152:153]
	global_store_dwordx4 v[12:13], v[8:11], off offset:2048 sc1
	v_pk_mul_f32 v[12:13], v[80:81], v[16:17]
	v_pk_mul_f32 v[14:15], v[68:69], v[20:21]
	v_lshlrev_b32_e32 v8, 16, v0
	v_and_b32_e32 v9, 0xffff0000, v0
	v_pk_fma_f32 v[12:13], v[76:77], v[24:25], v[12:13]
	v_lshlrev_b32_e32 v10, 16, v4
	v_and_b32_e32 v11, 0xffff0000, v4
	v_pk_fma_f32 v[8:9], v[84:85], v[8:9], v[12:13]
	v_pk_fma_f32 v[14:15], v[64:65], v[28:29], v[14:15]
	v_pk_mul_f32 v[8:9], v[8:9], v[10:11]
	v_lshlrev_b32_e32 v10, 16, v2
	v_and_b32_e32 v11, 0xffff0000, v2
	v_lshlrev_b32_e32 v12, 16, v6
	v_and_b32_e32 v13, 0xffff0000, v6
	v_pk_fma_f32 v[10:11], v[72:73], v[10:11], v[14:15]
	v_lshlrev_b32_e32 v0, 16, v1
	v_pk_mul_f32 v[10:11], v[10:11], v[12:13]
	v_pk_mul_f32 v[12:13], v[82:83], v[26:27]
	v_and_b32_e32 v1, 0xffff0000, v1
	v_pk_fma_f32 v[12:13], v[78:79], v[34:35], v[12:13]
	v_lshlrev_b32_e32 v4, 16, v5
	v_and_b32_e32 v5, 0xffff0000, v5
	v_pk_fma_f32 v[0:1], v[86:87], v[0:1], v[12:13]
	v_lshlrev_b32_e32 v2, 16, v7
	v_pk_mul_f32 v[4:5], v[0:1], v[4:5]
	v_lshlrev_b32_e32 v0, 16, v3
	v_and_b32_e32 v1, 0xffff0000, v3
	v_and_b32_e32 v3, 0xffff0000, v7
	v_pk_mul_f32 v[6:7], v[70:71], v[30:31]
	s_nop 0
	v_pk_fma_f32 v[6:7], v[66:67], v[38:39], v[6:7]
	s_nop 0
	v_pk_fma_f32 v[0:1], v[74:75], v[0:1], v[6:7]
	s_nop 0
	v_pk_mul_f32 v[6:7], v[0:1], v[2:3]
	v_cvt_pk_bf16_f32 v1, v4, v5
	v_lshlrev_b64 v[4:5], 12, v[90:91]
	v_lshl_add_u64 v[4:5], s[86:87], 0, v[4:5]
	v_cvt_pk_bf16_f32 v0, v8, v9
	v_cvt_pk_bf16_f32 v2, v10, v11
	v_cvt_pk_bf16_f32 v3, v6, v7
	v_lshl_add_u64 v[4:5], v[4:5], 0, v[152:153]
	global_store_dwordx4 v[4:5], v[0:3], off offset:2048 sc1
	s_andn2_b64 exec, exec, s[12:13]
	s_cbranch_execnz .LBB0_783

; DI void sample_even_misc(const float* PS, const float* ck, const float* cv, const float* stc, const float* cw, const float* cosS, const float* sinS,
;                          bf16* CAT, float* outKs, float* outVs, float* outCs, int gtid, int GT) {
;     for (int it = gtid; it < 2 * DBS * 64; it += GT) {
;         const int which = it >> 11, i2 = it & 2047, b = i2 >> 6, w = 127, c4 = i2 & 63;
;         f32x4 v;
;         {
;             const float* ps = PS + (size_t)b * EPROJ;
;             if (which) v = *(const f32x4*)(ps + 1280 + 4 * c4);
;             else { const int kvh = c4 >> 4, d0 = (c4 & 15) * 4; const f32x4 x = *(const f32x4*)(ps + 1024 + kvh * 64 + d0), y = *(const f32x4*)(ps + 1024 + kvh * 64 + (d0 ^ 32));
;                 const f32x4 c = *(const f32x4*)(cosS + (d0 & 31)), s = *(const f32x4*)(sinS + (d0 & 31));
;                 v = (d0 < 32) ? x * c - y * s : x * c + y * s; }
;         }
;         *(f32x4*)((which ? outVs : outKs) + ((size_t)(b * 128 + w)) * 256 + 4 * c4) = v;
;     }
.LBB0_790:
	s_or_b64 exec, exec, s[18:19]
	v_lshl_add_u64 v[8:9], s[8:9], 0, v[10:11]
	v_lshlrev_b32_e32 v152, 17, v14
	v_lshl_add_u64 v[8:9], v[8:9], 0, v[152:153]
	v_mov_b32_e32 v7, v153
	v_lshl_add_u64 v[6:7], v[8:9], 0, v[6:7]
	v_add_co_u32_e32 v6, vcc, 0x1f000, v6
	v_add_u32_e32 v13, s59, v13
	s_nop 0
	v_addc_co_u32_e32 v7, vcc, 0, v7, vcc
	s_movk_i32 s18, 0xfff
	v_cmp_lt_i32_e32 vcc, s18, v13
	s_or_b64 s[16:17], vcc, s[16:17]
	v_add_u32_e32 v12, s64, v12
	s_waitcnt vmcnt(0)
	global_store_dwordx4 v[6:7], v[0:3], off offset:3072 sc1
	s_andn2_b64 exec, exec, s[16:17]
	s_cbranch_execz .LBB0_795

; DI unsigned pk2(float a, float b) { f32x2 v = {a, b}; hbf16x2 r = __builtin_convertvector(v, hbf16x2); return __builtin_bit_cast(unsigned, r); }
; DI void sample_even_misc(const float* PS, const float* ck, const float* cv, const float* stc, const float* cw, const float* cosS, const float* sinS,
;                          bf16* CAT, float* outKs, float* outVs, float* outCs, int gtid, int GT) {
;     ...
;     for (int it = gtid; it < DBS * 256; it += GT) {
;         const int b = it >> 8, c = (it & 255) * 4; const float* ps = PS + (size_t)b * EPROJ;
;         const f32x4 gb = *(const f32x4*)(ps + 1536 + c), gc = *(const f32x4*)(ps + 2560 + c), hc = *(const f32x4*)(ps + 3584 + c);
;         const f32x4 z = gc * hc, st0 = *(const f32x4*)(stc + ((size_t)b * 2 + 0) * 1024 + c), st1 = *(const f32x4*)(stc + ((size_t)b * 2 + 1) * 1024 + c);
;         const f32x4 w0 = *(const f32x4*)(cw + c), w1 = *(const f32x4*)(cw + 1024 + c), w2 = *(const f32x4*)(cw + 2048 + c);
;         const f32x4 o = gb * (w0 * st0 + w1 * st1 + w2 * z);
;         u32x2 w; w.x = pk2(o[0], o[1]); w.y = pk2(o[2], o[3]);
;         *(u32x2*)(CAT + (size_t)(MP + b) * DM + 1024 + c) = w;
;         *(f32x4*)(outCs + ((size_t)b * 2 + 0) * 1024 + c) = st1; *(f32x4*)(outCs + ((size_t)b * 2 + 1) * 1024 + c) = z;
;     }
.LBB0_797:
	v_ashrrev_i32_e32 v30, 8, v106
	v_and_b32_e32 v4, 0x3fc, v5
	v_mul_hi_i32_i24_e32 v1, 0x4800, v30
	v_mul_i32_i24_e32 v0, 0x4800, v30
	v_lshl_add_u64 v[0:1], s[0:1], 0, v[0:1]
	v_lshlrev_b32_e32 v152, 2, v4
	v_lshl_add_u64 v[10:11], v[0:1], 0, v[152:153]
	v_add_co_u32_e32 v0, vcc, 0x1000, v10
	v_ashrrev_i32_e32 v31, 31, v30
	s_nop 0
	v_addc_co_u32_e32 v1, vcc, 0, v11, vcc
	global_load_dwordx4 v[6:9], v[0:1], off offset:2048
	v_add_co_u32_e32 v0, vcc, s29, v10
	v_lshlrev_b64 v[32:33], 13, v[30:31]
	s_nop 0
	v_addc_co_u32_e32 v1, vcc, 0, v11, vcc
	v_add_co_u32_e32 v10, vcc, s30, v10
	global_load_dwordx4 v[0:3], v[0:1], off offset:2048
	s_nop 0
	v_addc_co_u32_e32 v11, vcc, 0, v11, vcc
	global_load_dwordx4 v[10:13], v[10:11], off offset:2048
	v_or_b32_e32 v34, 0x1000, v32
	v_mov_b32_e32 v35, v33
	v_lshl_add_u64 v[14:15], s[6:7], 0, v[34:35]
	v_lshl_add_u64 v[14:15], v[14:15], 0, v[152:153]
	s_brev_b32 s16, 64
	v_add_u32_e32 v106, s59, v106
	v_add_u32_e32 v5, s64, v5
	s_waitcnt vmcnt(0)
	v_pk_mul_f32 v[0:1], v[0:1], v[10:11]
	v_lshl_add_u64 v[10:11], s[6:7], 0, v[32:33]
	v_lshl_add_u64 v[10:11], v[10:11], 0, v[152:153]
	v_pk_mul_f32 v[2:3], v[2:3], v[12:13]
	global_load_dwordx4 v[10:13], v[10:11], off
	s_nop 0
	global_load_dwordx4 v[14:17], v[14:15], off
	s_nop 0
	global_load_dwordx4 v[18:21], v152, s[4:5]
	global_load_dwordx4 v[22:25], v152, s[10:11]
	global_load_dwordx4 v[26:29], v152, s[12:13]
	s_waitcnt vmcnt(1)
	v_pk_mul_f32 v[24:25], v[16:17], v[24:25]
	v_pk_mul_f32 v[22:23], v[14:15], v[22:23]
	v_pk_fma_f32 v[12:13], v[12:13], v[20:21], v[24:25]
	v_pk_fma_f32 v[10:11], v[10:11], v[18:19], v[22:23]
	s_waitcnt vmcnt(0)
	v_pk_fma_f32 v[12:13], v[2:3], v[28:29], v[12:13]
	v_pk_fma_f32 v[10:11], v[0:1], v[26:27], v[10:11]
	v_pk_mul_f32 v[8:9], v[8:9], v[12:13]
	v_pk_mul_f32 v[6:7], v[6:7], v[10:11]
	v_lshlrev_b32_e32 v10, 1, v4
	v_cvt_pk_bf16_f32 v6, v6, v7
	v_cvt_pk_bf16_f32 v7, v8, v9
	v_lshlrev_b64 v[8:9], 12, v[30:31]
	v_lshl_add_u64 v[8:9], s[86:87], 0, v[8:9]
	v_mov_b32_e32 v11, v153
	v_lshl_add_u64 v[8:9], v[8:9], 0, v[10:11]
	v_add_co_u32_e32 v8, vcc, s16, v8
	s_movk_i32 s16, 0x1fff
	s_nop 0
	v_addc_co_u32_e32 v9, vcc, 0, v9, vcc
	global_store_dwordx2 v[8:9], v[6:7], off offset:2048
	v_lshl_add_u64 v[6:7], s[8:9], 0, v[32:33]
	v_lshl_add_u64 v[6:7], v[6:7], 0, v[152:153]
	global_store_dwordx4 v[6:7], v[14:17], off sc1
	v_lshl_add_u64 v[6:7], s[8:9], 0, v[34:35]
	v_cmp_lt_i32_e32 vcc, s16, v106
	v_lshl_add_u64 v[6:7], v[6:7], 0, v[152:153]
	s_or_b64 s[14:15], vcc, s[14:15]
	global_store_dwordx4 v[6:7], v[0:3], off sc1
	s_andn2_b64 exec, exec, s[14:15]
	s_cbranch_execnz .LBB0_797

; DI u32x4 pk8(f32x4 a, f32x4 b) { u32x4 w; w.x = pk2(a[0], a[1]); w.y = pk2(a[2], a[3]); w.z = pk2(b[0], b[1]); w.w = pk2(b[2], b[3]); return w; }
;     DI void operator()(const f32x4 (&acc)[2][2][4][2], const Unit& u, int wr, int wc, int fr, int fq) const {
;     ...
;             for (int m = 0; m < 4; ++m) { bf16* rowp = O + (size_t)(row0 + ai * HALF + m * 16) * ldc + col0; const float rs = RS[row0 + ai * HALF + m * 16];
; #pragma unroll
;                 for (int bj = 0; bj < 2; ++bj) { f32x4 v0 = acc[ai][bj][m][0], v1 = acc[ai][bj][m][1];
; #pragma unroll
;                     for (int e = 0; e < 4; ++e) { const float a = fmaxf(v0[e] * rs, 0.f), b = fmaxf(v1[e] * rs, 0.f); v0[e] = a * a; v1[e] = b * b; }
;                     *(u32x4*)(rowp + bj * HALF) = pk8(v0, v1); } }
.LBB0_1061:
	v_mov_b32_e32 v138, v142
	v_mov_b32_e32 v146, v143
	s_lshl_b32 s19, s46, 8
	s_add_i32 s19, s19, s40
	v_add_u32_e32 v138, s19, v138
	v_ashrrev_i32_e32 v139, 31, v138
	v_lshl_add_u64 v[140:141], v[138:139], 2, s[14:15]
	global_load_dword v148, v[140:141], off
	global_load_dword v200, v[140:141], off offset:64
	global_load_dword v201, v[140:141], off offset:128
	global_load_dword v202, v[140:141], off offset:192
	global_load_dword v203, v[140:141], off offset:512
	global_load_dword v204, v[140:141], off offset:576
	global_load_dword v205, v[140:141], off offset:640
	global_load_dword v206, v[140:141], off offset:704
	s_lshl_b32 s19, s45, 8
	s_or_b32 s19, s19, s41
	v_lshl_add_u32 v146, v146, 3, s19
	v_lshlrev_b64 v[138:139], 14, v[138:139]
	v_ashrrev_i32_e32 v147, 31, v146
	v_lshl_add_u64 v[138:139], s[4:5], 0, v[138:139]
	v_lshl_add_u64 v[138:139], v[146:147], 1, v[138:139]
	s_mov_b32 s19, 0x40000
	s_mov_b64 s[26:27], 0x40000
	s_waitcnt vmcnt(0)
	v_mul_f32_e32 v124, v124, v148
	v_mul_f32_e32 v120, v120, v148
	v_mul_f32_e32 v125, v125, v148
	v_mul_f32_e32 v121, v121, v148
	v_mul_f32_e32 v126, v126, v148
	v_mul_f32_e32 v122, v122, v148
	v_mul_f32_e32 v127, v127, v148
	v_mul_f32_e32 v123, v123, v148
	v_mul_f32_e32 v146, v116, v148
	v_mul_f32_e32 v147, v112, v148
	v_mul_f32_e32 v149, v117, v148
	v_mul_f32_e32 v150, v113, v148
	v_mul_f32_e32 v151, v118, v148
	v_mul_f32_e32 v164, v114, v148
	v_mul_f32_e32 v165, v119, v148
	v_mul_f32_e32 v148, v115, v148
	v_max_f32_e32 v112, 0, v124
	v_max_f32_e32 v114, 0, v120
	v_max_f32_e32 v113, 0, v125
	v_max_f32_e32 v115, 0, v121
	v_max_f32_e32 v116, 0, v126
	v_max_f32_e32 v118, 0, v122
	v_max_f32_e32 v117, 0, v127
	v_max_f32_e32 v119, 0, v123
	v_max_f32_e32 v120, 0, v146
	v_max_f32_e32 v122, 0, v147
	v_max_f32_e32 v121, 0, v149
	v_max_f32_e32 v123, 0, v150
	v_max_f32_e32 v124, 0, v151
	v_max_f32_e32 v126, 0, v164
	v_max_f32_e32 v125, 0, v165
	v_max_f32_e32 v127, 0, v148
	v_pk_mul_f32 v[112:113], v[112:113], v[112:113]
	v_pk_mul_f32 v[114:115], v[114:115], v[114:115]
	v_pk_mul_f32 v[116:117], v[116:117], v[116:117]
	v_pk_mul_f32 v[118:119], v[118:119], v[118:119]
	v_pk_mul_f32 v[120:121], v[120:121], v[120:121]
	v_pk_mul_f32 v[122:123], v[122:123], v[122:123]
	v_pk_mul_f32 v[124:125], v[124:125], v[124:125]
	v_pk_mul_f32 v[126:127], v[126:127], v[126:127]
	v_cvt_pk_bf16_f32 v112, v112, v113
	v_cvt_pk_bf16_f32 v113, v116, v117
	v_cvt_pk_bf16_f32 v114, v114, v115
	v_cvt_pk_bf16_f32 v115, v118, v119
	v_cvt_pk_bf16_f32 v116, v120, v121
	v_cvt_pk_bf16_f32 v117, v124, v125
	v_cvt_pk_bf16_f32 v118, v122, v123
	v_cvt_pk_bf16_f32 v119, v126, v127
	global_store_dwordx4 v[138:139], v[112:115], off sc1
	global_store_dwordx4 v[138:139], v[116:119], off offset:256 sc1
	s_nop 0
	v_add_co_u32_e32 v114, vcc, s19, v138
	v_lshl_add_u64 v[112:113], v[138:139], 0, s[26:27]
	s_nop 0
	v_addc_co_u32_e32 v115, vcc, 0, v139, vcc
	s_mov_b32 s19, 0x80000
	s_mov_b64 s[26:27], 0x80000
	v_mov_b32_e32 v116, v200
	v_mul_f32_e32 v108, v108, v116
	v_mul_f32_e32 v104, v104, v116
	v_mul_f32_e32 v109, v109, v116
	v_mul_f32_e32 v105, v105, v116
	v_mul_f32_e32 v110, v110, v116
	v_mul_f32_e32 v106, v106, v116
	v_mul_f32_e32 v111, v111, v116
	v_mul_f32_e32 v107, v107, v116
	v_mul_f32_e32 v117, v100, v116
	v_mul_f32_e32 v118, v96, v116
	v_mul_f32_e32 v119, v101, v116
	v_mul_f32_e32 v120, v97, v116
	v_mul_f32_e32 v121, v102, v116
	v_mul_f32_e32 v122, v98, v116
	v_mul_f32_e32 v123, v103, v116
	v_mul_f32_e32 v116, v99, v116
	v_max_f32_e32 v96, 0, v108
	v_max_f32_e32 v98, 0, v104
	v_max_f32_e32 v97, 0, v109
	v_max_f32_e32 v99, 0, v105
	v_max_f32_e32 v100, 0, v110
	v_max_f32_e32 v102, 0, v106
	v_max_f32_e32 v101, 0, v111
	v_max_f32_e32 v103, 0, v107
	v_max_f32_e32 v104, 0, v117
	v_max_f32_e32 v106, 0, v118
	v_max_f32_e32 v105, 0, v119
	v_max_f32_e32 v107, 0, v120
	v_max_f32_e32 v108, 0, v121
	v_max_f32_e32 v110, 0, v122
	v_max_f32_e32 v109, 0, v123
	v_max_f32_e32 v111, 0, v116
	v_pk_mul_f32 v[96:97], v[96:97], v[96:97]
	v_pk_mul_f32 v[98:99], v[98:99], v[98:99]
	v_pk_mul_f32 v[100:101], v[100:101], v[100:101]
	v_pk_mul_f32 v[102:103], v[102:103], v[102:103]
	v_pk_mul_f32 v[104:105], v[104:105], v[104:105]
	v_pk_mul_f32 v[106:107], v[106:107], v[106:107]
	v_pk_mul_f32 v[108:109], v[108:109], v[108:109]
	v_pk_mul_f32 v[110:111], v[110:111], v[110:111]
	v_cvt_pk_bf16_f32 v96, v96, v97
	v_cvt_pk_bf16_f32 v97, v100, v101
	v_cvt_pk_bf16_f32 v98, v98, v99
	v_cvt_pk_bf16_f32 v99, v102, v103
	v_cvt_pk_bf16_f32 v100, v104, v105
	v_cvt_pk_bf16_f32 v101, v108, v109
	v_cvt_pk_bf16_f32 v102, v106, v107
	v_cvt_pk_bf16_f32 v103, v110, v111
	global_store_dwordx4 v[114:115], v[96:99], off sc1
	global_store_dwordx4 v[112:113], v[100:103], off offset:256 sc1
	s_nop 0
	v_add_co_u32_e32 v98, vcc, s19, v138
	v_lshl_add_u64 v[96:97], v[138:139], 0, s[26:27]
	s_nop 0
	v_addc_co_u32_e32 v99, vcc, 0, v139, vcc
	s_mov_b32 s19, 0xc0000
	s_mov_b64 s[26:27], 0xc0000
	v_mov_b32_e32 v100, v201
	v_mul_f32_e32 v92, v92, v100
	v_mul_f32_e32 v88, v88, v100
	v_mul_f32_e32 v93, v93, v100
	v_mul_f32_e32 v89, v89, v100
	v_mul_f32_e32 v94, v94, v100
	v_mul_f32_e32 v90, v90, v100
	v_mul_f32_e32 v95, v95, v100
	v_mul_f32_e32 v91, v91, v100
	v_mul_f32_e32 v101, v84, v100
	v_mul_f32_e32 v102, v80, v100
	v_mul_f32_e32 v103, v85, v100
	v_mul_f32_e32 v104, v81, v100
	v_mul_f32_e32 v105, v86, v100
	v_mul_f32_e32 v106, v82, v100
	v_mul_f32_e32 v107, v87, v100
	v_mul_f32_e32 v100, v83, v100
	v_max_f32_e32 v80, 0, v92
	v_max_f32_e32 v82, 0, v88
	v_max_f32_e32 v81, 0, v93
	v_max_f32_e32 v83, 0, v89
	v_max_f32_e32 v84, 0, v94
	v_max_f32_e32 v86, 0, v90
	v_max_f32_e32 v85, 0, v95
	v_max_f32_e32 v87, 0, v91
; DI u32x4 pk8(f32x4 a, f32x4 b) { u32x4 w; w.x = pk2(a[0], a[1]); w.y = pk2(a[2], a[3]); w.z = pk2(b[0], b[1]); w.w = pk2(b[2], b[3]); return w; }
;     DI void operator()(const f32x4 (&acc)[2][2][4][2], const Unit& u, int wr, int wc, int fr, int fq) const {
;     ...
;             for (int m = 0; m < 4; ++m) { bf16* rowp = O + (size_t)(row0 + ai * HALF + m * 16) * ldc + col0; const float rs = RS[row0 + ai * HALF + m * 16];
; #pragma unroll
;                 for (int bj = 0; bj < 2; ++bj) { f32x4 v0 = acc[ai][bj][m][0], v1 = acc[ai][bj][m][1];
; #pragma unroll
;                     for (int e = 0; e < 4; ++e) { const float a = fmaxf(v0[e] * rs, 0.f), b = fmaxf(v1[e] * rs, 0.f); v0[e] = a * a; v1[e] = b * b; }
;                     *(u32x4*)(rowp + bj * HALF) = pk8(v0, v1); } }
	v_max_f32_e32 v88, 0, v101
	v_max_f32_e32 v90, 0, v102
	v_max_f32_e32 v89, 0, v103
	v_max_f32_e32 v91, 0, v104
	v_max_f32_e32 v92, 0, v105
	v_max_f32_e32 v94, 0, v106
	v_max_f32_e32 v93, 0, v107
	v_max_f32_e32 v95, 0, v100
	v_pk_mul_f32 v[80:81], v[80:81], v[80:81]
	v_pk_mul_f32 v[82:83], v[82:83], v[82:83]
	v_pk_mul_f32 v[84:85], v[84:85], v[84:85]
	v_pk_mul_f32 v[86:87], v[86:87], v[86:87]
	v_pk_mul_f32 v[88:89], v[88:89], v[88:89]
	v_pk_mul_f32 v[90:91], v[90:91], v[90:91]
	v_pk_mul_f32 v[92:93], v[92:93], v[92:93]
	v_pk_mul_f32 v[94:95], v[94:95], v[94:95]
	v_cvt_pk_bf16_f32 v80, v80, v81
	v_cvt_pk_bf16_f32 v81, v84, v85
	v_cvt_pk_bf16_f32 v82, v82, v83
	v_cvt_pk_bf16_f32 v83, v86, v87
	v_cvt_pk_bf16_f32 v84, v88, v89
	v_cvt_pk_bf16_f32 v85, v92, v93
	v_cvt_pk_bf16_f32 v86, v90, v91
	v_cvt_pk_bf16_f32 v87, v94, v95
	global_store_dwordx4 v[98:99], v[80:83], off sc1
	global_store_dwordx4 v[96:97], v[84:87], off offset:256 sc1
	s_nop 0
	v_add_co_u32_e32 v82, vcc, s19, v138
	v_lshl_add_u64 v[80:81], v[138:139], 0, s[26:27]
	s_nop 0
	v_addc_co_u32_e32 v83, vcc, 0, v139, vcc
	s_mov_b32 s19, 0x200000
	s_mov_b64 s[26:27], 0x200000
	v_mov_b32_e32 v84, v202
	v_mul_f32_e32 v76, v76, v84
	v_mul_f32_e32 v72, v72, v84
	v_mul_f32_e32 v77, v77, v84
	v_mul_f32_e32 v73, v73, v84
	v_mul_f32_e32 v78, v78, v84
	v_mul_f32_e32 v74, v74, v84
	v_mul_f32_e32 v79, v79, v84
	v_mul_f32_e32 v75, v75, v84
	v_mul_f32_e32 v85, v68, v84
	v_mul_f32_e32 v86, v64, v84
	v_mul_f32_e32 v87, v69, v84
	v_mul_f32_e32 v88, v65, v84
	v_mul_f32_e32 v89, v70, v84
	v_mul_f32_e32 v90, v66, v84
	v_mul_f32_e32 v91, v71, v84
	v_mul_f32_e32 v84, v67, v84
	v_max_f32_e32 v64, 0, v76
	v_max_f32_e32 v66, 0, v72
	v_max_f32_e32 v65, 0, v77
	v_max_f32_e32 v67, 0, v73
	v_max_f32_e32 v68, 0, v78
	v_max_f32_e32 v70, 0, v74
	v_max_f32_e32 v69, 0, v79
	v_max_f32_e32 v71, 0, v75
	v_max_f32_e32 v72, 0, v85
	v_max_f32_e32 v74, 0, v86
	v_max_f32_e32 v73, 0, v87
	v_max_f32_e32 v75, 0, v88
	v_max_f32_e32 v76, 0, v89
	v_max_f32_e32 v78, 0, v90
	v_max_f32_e32 v77, 0, v91
	v_max_f32_e32 v79, 0, v84
	v_pk_mul_f32 v[64:65], v[64:65], v[64:65]
	v_pk_mul_f32 v[66:67], v[66:67], v[66:67]
	v_pk_mul_f32 v[68:69], v[68:69], v[68:69]
	v_pk_mul_f32 v[70:71], v[70:71], v[70:71]
	v_pk_mul_f32 v[72:73], v[72:73], v[72:73]
	v_pk_mul_f32 v[74:75], v[74:75], v[74:75]
	v_pk_mul_f32 v[76:77], v[76:77], v[76:77]
	v_pk_mul_f32 v[78:79], v[78:79], v[78:79]
	v_cvt_pk_bf16_f32 v64, v64, v65
	v_cvt_pk_bf16_f32 v65, v68, v69
	v_cvt_pk_bf16_f32 v66, v66, v67
	v_cvt_pk_bf16_f32 v67, v70, v71
	v_cvt_pk_bf16_f32 v68, v72, v73
	v_cvt_pk_bf16_f32 v69, v76, v77
	v_cvt_pk_bf16_f32 v70, v74, v75
	v_cvt_pk_bf16_f32 v71, v78, v79
	global_store_dwordx4 v[82:83], v[64:67], off sc1
	global_store_dwordx4 v[80:81], v[68:71], off offset:256 sc1
	s_nop 0
	v_add_co_u32_e32 v66, vcc, s19, v138
	v_lshl_add_u64 v[64:65], v[138:139], 0, s[26:27]
	s_nop 0
	v_addc_co_u32_e32 v67, vcc, 0, v139, vcc
	s_mov_b32 s19, 0x240000
	s_mov_b64 s[26:27], 0x240000
	v_mov_b32_e32 v68, v203
	v_mul_f32_e32 v60, v60, v68
	v_mul_f32_e32 v56, v56, v68
	v_mul_f32_e32 v61, v61, v68
	v_mul_f32_e32 v57, v57, v68
	v_mul_f32_e32 v62, v62, v68
	v_mul_f32_e32 v58, v58, v68
	v_mul_f32_e32 v63, v63, v68
	v_mul_f32_e32 v59, v59, v68
	v_mul_f32_e32 v69, v52, v68
	v_mul_f32_e32 v70, v48, v68
	v_mul_f32_e32 v71, v53, v68
	v_mul_f32_e32 v72, v49, v68
	v_mul_f32_e32 v73, v54, v68
	v_mul_f32_e32 v74, v50, v68
	v_mul_f32_e32 v75, v55, v68
	v_mul_f32_e32 v68, v51, v68
	v_max_f32_e32 v48, 0, v60
	v_max_f32_e32 v50, 0, v56
	v_max_f32_e32 v49, 0, v61
	v_max_f32_e32 v51, 0, v57
	v_max_f32_e32 v52, 0, v62
	v_max_f32_e32 v54, 0, v58
	v_max_f32_e32 v53, 0, v63
	v_max_f32_e32 v55, 0, v59
	v_max_f32_e32 v56, 0, v69
	v_max_f32_e32 v58, 0, v70
	v_max_f32_e32 v57, 0, v71
	v_max_f32_e32 v59, 0, v72
	v_max_f32_e32 v60, 0, v73
	v_max_f32_e32 v62, 0, v74
	v_max_f32_e32 v61, 0, v75
	v_max_f32_e32 v63, 0, v68
	v_pk_mul_f32 v[48:49], v[48:49], v[48:49]
	v_pk_mul_f32 v[50:51], v[50:51], v[50:51]
	v_pk_mul_f32 v[52:53], v[52:53], v[52:53]
	v_pk_mul_f32 v[54:55], v[54:55], v[54:55]
	v_pk_mul_f32 v[56:57], v[56:57], v[56:57]
	v_pk_mul_f32 v[58:59], v[58:59], v[58:59]
	v_pk_mul_f32 v[60:61], v[60:61], v[60:61]
	v_pk_mul_f32 v[62:63], v[62:63], v[62:63]
	v_cvt_pk_bf16_f32 v48, v48, v49
	v_cvt_pk_bf16_f32 v49, v52, v53
	v_cvt_pk_bf16_f32 v50, v50, v51
	v_cvt_pk_bf16_f32 v51, v54, v55
	v_cvt_pk_bf16_f32 v52, v56, v57
	v_cvt_pk_bf16_f32 v53, v60, v61
	v_cvt_pk_bf16_f32 v54, v58, v59
	v_cvt_pk_bf16_f32 v55, v62, v63
	global_store_dwordx4 v[66:67], v[48:51], off sc1
	global_store_dwordx4 v[64:65], v[52:55], off offset:256 sc1
	s_nop 0
	v_add_co_u32_e32 v50, vcc, s19, v138
	v_lshl_add_u64 v[48:49], v[138:139], 0, s[26:27]
	s_nop 0
	v_addc_co_u32_e32 v51, vcc, 0, v139, vcc
	s_mov_b32 s19, 0x280000
	s_mov_b64 s[26:27], 0x280000
	v_mov_b32_e32 v52, v204
	v_mul_f32_e32 v44, v44, v52
	v_mul_f32_e32 v40, v40, v52
	v_mul_f32_e32 v45, v45, v52
	v_mul_f32_e32 v41, v41, v52
	v_mul_f32_e32 v46, v46, v52
	v_mul_f32_e32 v42, v42, v52
	v_mul_f32_e32 v47, v47, v52
	v_mul_f32_e32 v43, v43, v52
	v_mul_f32_e32 v53, v36, v52
; DI u32x4 pk8(f32x4 a, f32x4 b) { u32x4 w; w.x = pk2(a[0], a[1]); w.y = pk2(a[2], a[3]); w.z = pk2(b[0], b[1]); w.w = pk2(b[2], b[3]); return w; }
;     DI void operator()(const f32x4 (&acc)[2][2][4][2], const Unit& u, int wr, int wc, int fr, int fq) const {
;     ...
;             for (int m = 0; m < 4; ++m) { bf16* rowp = O + (size_t)(row0 + ai * HALF + m * 16) * ldc + col0; const float rs = RS[row0 + ai * HALF + m * 16];
; #pragma unroll
;                 for (int bj = 0; bj < 2; ++bj) { f32x4 v0 = acc[ai][bj][m][0], v1 = acc[ai][bj][m][1];
; #pragma unroll
;                     for (int e = 0; e < 4; ++e) { const float a = fmaxf(v0[e] * rs, 0.f), b = fmaxf(v1[e] * rs, 0.f); v0[e] = a * a; v1[e] = b * b; }
;                     *(u32x4*)(rowp + bj * HALF) = pk8(v0, v1); } }
	v_mul_f32_e32 v54, v32, v52
	v_mul_f32_e32 v55, v37, v52
	v_mul_f32_e32 v56, v33, v52
	v_mul_f32_e32 v57, v38, v52
	v_mul_f32_e32 v58, v34, v52
	v_mul_f32_e32 v59, v39, v52
	v_mul_f32_e32 v52, v35, v52
	v_max_f32_e32 v32, 0, v44
	v_max_f32_e32 v34, 0, v40
	v_max_f32_e32 v33, 0, v45
	v_max_f32_e32 v35, 0, v41
	v_max_f32_e32 v36, 0, v46
	v_max_f32_e32 v38, 0, v42
	v_max_f32_e32 v37, 0, v47
	v_max_f32_e32 v39, 0, v43
	v_max_f32_e32 v40, 0, v53
	v_max_f32_e32 v42, 0, v54
	v_max_f32_e32 v41, 0, v55
	v_max_f32_e32 v43, 0, v56
	v_max_f32_e32 v44, 0, v57
	v_max_f32_e32 v46, 0, v58
	v_max_f32_e32 v45, 0, v59
	v_max_f32_e32 v47, 0, v52
	v_pk_mul_f32 v[32:33], v[32:33], v[32:33]
	v_pk_mul_f32 v[34:35], v[34:35], v[34:35]
	v_pk_mul_f32 v[36:37], v[36:37], v[36:37]
	v_pk_mul_f32 v[38:39], v[38:39], v[38:39]
	v_pk_mul_f32 v[40:41], v[40:41], v[40:41]
	v_pk_mul_f32 v[42:43], v[42:43], v[42:43]
	v_pk_mul_f32 v[44:45], v[44:45], v[44:45]
	v_pk_mul_f32 v[46:47], v[46:47], v[46:47]
	v_cvt_pk_bf16_f32 v32, v32, v33
	v_cvt_pk_bf16_f32 v33, v36, v37
	v_cvt_pk_bf16_f32 v34, v34, v35
	v_cvt_pk_bf16_f32 v35, v38, v39
	v_cvt_pk_bf16_f32 v36, v40, v41
	v_cvt_pk_bf16_f32 v37, v44, v45
	v_cvt_pk_bf16_f32 v38, v42, v43
	v_cvt_pk_bf16_f32 v39, v46, v47
	global_store_dwordx4 v[50:51], v[32:35], off sc1
	global_store_dwordx4 v[48:49], v[36:39], off offset:256 sc1
	s_nop 0
	v_add_co_u32_e32 v34, vcc, s19, v138
	v_lshl_add_u64 v[32:33], v[138:139], 0, s[26:27]
	s_nop 0
	v_addc_co_u32_e32 v35, vcc, 0, v139, vcc
	s_andn2_b64 vcc, exec, s[0:1]
	s_mov_b64 s[0:1], 0x2c0000
	v_mov_b32_e32 v36, v205
	v_mul_f32_e32 v28, v28, v36
	v_mul_f32_e32 v24, v24, v36
	v_mul_f32_e32 v29, v29, v36
	v_mul_f32_e32 v25, v25, v36
	v_mul_f32_e32 v30, v30, v36
	v_mul_f32_e32 v26, v26, v36
	v_mul_f32_e32 v31, v31, v36
	v_mul_f32_e32 v27, v27, v36
	v_mul_f32_e32 v37, v20, v36
	v_mul_f32_e32 v38, v16, v36
	v_mul_f32_e32 v39, v21, v36
	v_mul_f32_e32 v40, v17, v36
	v_mul_f32_e32 v41, v22, v36
	v_mul_f32_e32 v42, v18, v36
	v_mul_f32_e32 v43, v23, v36
	v_mul_f32_e32 v36, v19, v36
	v_max_f32_e32 v16, 0, v28
	v_max_f32_e32 v18, 0, v24
	v_max_f32_e32 v17, 0, v29
	v_max_f32_e32 v19, 0, v25
	v_max_f32_e32 v20, 0, v30
	v_max_f32_e32 v22, 0, v26
	v_max_f32_e32 v21, 0, v31
	v_max_f32_e32 v23, 0, v27
	v_max_f32_e32 v24, 0, v37
	v_max_f32_e32 v26, 0, v38
	v_max_f32_e32 v25, 0, v39
	v_max_f32_e32 v27, 0, v40
	v_max_f32_e32 v28, 0, v41
	v_max_f32_e32 v30, 0, v42
	v_max_f32_e32 v29, 0, v43
	v_max_f32_e32 v31, 0, v36
	v_pk_mul_f32 v[16:17], v[16:17], v[16:17]
	v_pk_mul_f32 v[18:19], v[18:19], v[18:19]
	v_pk_mul_f32 v[20:21], v[20:21], v[20:21]
	v_pk_mul_f32 v[22:23], v[22:23], v[22:23]
	v_pk_mul_f32 v[24:25], v[24:25], v[24:25]
	v_pk_mul_f32 v[26:27], v[26:27], v[26:27]
	v_pk_mul_f32 v[28:29], v[28:29], v[28:29]
	v_pk_mul_f32 v[30:31], v[30:31], v[30:31]
	v_cvt_pk_bf16_f32 v16, v16, v17
	v_cvt_pk_bf16_f32 v17, v20, v21
	v_cvt_pk_bf16_f32 v18, v18, v19
	v_cvt_pk_bf16_f32 v19, v22, v23
	v_cvt_pk_bf16_f32 v20, v24, v25
	v_cvt_pk_bf16_f32 v21, v28, v29
	v_cvt_pk_bf16_f32 v22, v26, v27
	v_cvt_pk_bf16_f32 v23, v30, v31
	global_store_dwordx4 v[34:35], v[16:19], off sc1
	global_store_dwordx4 v[32:33], v[20:23], off offset:256 sc1
	s_nop 0
	v_lshl_add_u64 v[16:17], v[138:139], 0, s[0:1]
	s_mov_b32 s0, 0x2c0000
	v_add_co_u32_e64 v18, s[0:1], s0, v138
	v_mov_b32_e32 v20, v206
	v_mul_f32_e32 v12, v12, v20
	v_mul_f32_e32 v8, v8, v20
	v_mul_f32_e32 v13, v13, v20
	v_mul_f32_e32 v9, v9, v20
	v_mul_f32_e32 v14, v14, v20
	v_mul_f32_e32 v10, v10, v20
	v_mul_f32_e32 v15, v15, v20
	v_mul_f32_e32 v11, v11, v20
	v_mul_f32_e32 v21, v4, v20
	v_mul_f32_e32 v22, v0, v20
	v_mul_f32_e32 v23, v5, v20
	v_mul_f32_e32 v24, v1, v20
	v_mul_f32_e32 v25, v6, v20
	v_mul_f32_e32 v26, v2, v20
	v_mul_f32_e32 v27, v7, v20
	v_mul_f32_e32 v20, v3, v20
	v_max_f32_e32 v0, 0, v12
	v_max_f32_e32 v2, 0, v8
	v_max_f32_e32 v1, 0, v13
	v_max_f32_e32 v3, 0, v9
	v_max_f32_e32 v4, 0, v14
	v_max_f32_e32 v6, 0, v10
	v_max_f32_e32 v5, 0, v15
	v_max_f32_e32 v7, 0, v11
	v_addc_co_u32_e64 v19, s[0:1], 0, v139, s[0:1]
	v_max_f32_e32 v8, 0, v21
	v_max_f32_e32 v10, 0, v22
	v_max_f32_e32 v9, 0, v23
	v_max_f32_e32 v11, 0, v24
	v_max_f32_e32 v12, 0, v25
	v_max_f32_e32 v14, 0, v26
	v_max_f32_e32 v13, 0, v27
	v_max_f32_e32 v15, 0, v20
	v_pk_mul_f32 v[0:1], v[0:1], v[0:1]
	v_pk_mul_f32 v[2:3], v[2:3], v[2:3]
	v_pk_mul_f32 v[4:5], v[4:5], v[4:5]
	v_pk_mul_f32 v[6:7], v[6:7], v[6:7]
	v_pk_mul_f32 v[8:9], v[8:9], v[8:9]
	v_pk_mul_f32 v[10:11], v[10:11], v[10:11]
	v_pk_mul_f32 v[12:13], v[12:13], v[12:13]
	v_pk_mul_f32 v[14:15], v[14:15], v[14:15]
	v_cvt_pk_bf16_f32 v0, v0, v1
	v_cvt_pk_bf16_f32 v1, v4, v5
	v_cvt_pk_bf16_f32 v2, v2, v3
	v_cvt_pk_bf16_f32 v3, v6, v7
	s_mov_b64 s[0:1], -1
	v_cvt_pk_bf16_f32 v4, v8, v9
	v_cvt_pk_bf16_f32 v5, v12, v13
	v_cvt_pk_bf16_f32 v6, v10, v11
	v_cvt_pk_bf16_f32 v7, v14, v15
	global_store_dwordx4 v[18:19], v[0:3], off sc1
	global_store_dwordx4 v[16:17], v[4:7], off offset:256 sc1
	s_nop 0
	s_nop 0
	s_nop 0
	s_cbranch_vccnz .LBB0_1050
	s_andn2_b64 vcc, exec, s[2:3]
	s_cbranch_vccnz .LBB0_1049
	s_barrier
	s_branch .LBB0_1049
